# GEMM K-loops: barrier one MFMA early, the trailing MFMA issued at priority 2 after the release (fills the burst hand-off)
# baseline (speedup 1.0000x reference)
; #define PG8_WAIT_V(n) asm volatile("s_waitcnt vmcnt(" #n ")" ::: "memory")
; #define PG8_BAR __builtin_amdgcn_s_barrier()
; template <class Epi, class Sched, bool ALIGN_EPI = false, bool SP2 = false>
; __device__ __forceinline__ void gemm_phase(PG8_LAS unsigned char* lds, const Gemm g, const Sched& S, const Epi& E, const int wid) {
;     ...
;         const bool has_next = S.next(ui + 1, nxt);
;         const char* nA = has_next ? (const char*)g.A + (size_t)nxt.pm * tstep : cA; const char* nB = has_next ? (const char*)g.Bt + (size_t)nxt.pn * tstep : cB;
;         for (int t = 0; t < nt; t += 2) {
;             const bool last = (t == nt - 2);
;             const char* a1 = cA + (size_t)(t + 1) * kstep;
;             const char* a2 = last ? nA : cA + (size_t)(t + 2) * kstep; const char* b2 = last ? nB : cB + (size_t)(t + 2) * kstep;
;             const char* a3 = a2 + kstep; const char* b3 = b2 + kstep;
;             if (last && has_next) S.a_ready(nxt);
;             if constexpr (SP2) {
;             PG8_LDB(B0, 0, 0); PG8_LDB(B1, 0, 1); PG8_SCHED; PG8_LDA(At, 0, 0); PG8_STAGE(PG8_SA(1, 1), a1 + hstep, voffA);
;             PG8_WAIT_V(8); PG8_WAIT_L(0); PG8_BAR; PG8_MMA(0, 0, At, B0); PG8_MMA(0, 1, At, B1); PG8_BAR; PG8_SCHED;
;             PG8_LDA(At, 0, 1); PG8_STAGE(PG8_SB(0, 0), b2, voffB); PG8_STAGE(PG8_SB(0, 1), b2 + hstep, voffB); PG8_STAGE(PG8_SA(0, 0), a2, voffA);
;             PG8_WAIT_V(8); PG8_WAIT_L(0); PG8_BAR; PG8_MMA(1, 0, At, B0); PG8_MMA(1, 1, At, B1); PG8_BAR; PG8_SCHED;
;             PG8_LDB(B0, 1, 0); PG8_LDB(B1, 1, 1); PG8_SCHED; PG8_LDA(At, 1, 0); PG8_STAGE(PG8_SA(0, 1), a2 + hstep, voffA);
;             PG8_WAIT_V(8); PG8_WAIT_L(0); PG8_BAR; PG8_MMA(0, 0, At, B0); PG8_MMA(0, 1, At, B1); PG8_BAR; PG8_SCHED;
;             PG8_LDA(At, 1, 1); PG8_STAGE(PG8_SB(1, 0), b3, voffB); PG8_STAGE(PG8_SB(1, 1), b3 + hstep, voffB); PG8_STAGE(PG8_SA(1, 0), a3, voffA);
;             PG8_WAIT_V(8); PG8_WAIT_L(0); PG8_BAR; PG8_MMA(1, 0, At, B0); PG8_MMA(1, 1, At, B1); PG8_BAR; PG8_SCHED;
;             } else {
;             PG8_LDB(B0, 0, 0); PG8_SCHED; PG8_LDA(At, 0, 0); PG8_STAGE(PG8_SA(1, 1), a1 + hstep, voffA);
;             PG8_WAIT_L(8); PG8_BAR; PG8_WAIT_L(0); PG8_MMA(0, 0, At, B0); PG8_BAR; PG8_SCHED;
;             PG8_LDB(B1, 0, 1); PG8_STAGE(PG8_SB(0, 0), b2, voffB);
;             PG8_BAR; PG8_WAIT_L(0); PG8_MMA(0, 1, At, B1); PG8_BAR;
.LBB0_18:
	s_andn2_b64 vcc, exec, s[24:25]
	s_cbranch_vccnz .Lz_G1A
	s_add_u32 s4, s38, 0x80
	s_addc_u32 s5, s39, 0
	s_add_u32 s0, s36, 0x100
	s_addc_u32 s1, s37, 0
	s_mov_b32 s36, 0
	ds_read_b128 v[128:131], v165
	ds_read_b128 v[146:149], v165 offset:1024
	ds_read_b128 v[150:153], v165 offset:2048
	ds_read_b128 v[154:157], v165 offset:3072
	ds_read_b128 v[158:161], v166
	ds_read_b128 v[172:175], v166 offset:1024
	ds_read_b128 v[176:179], v166 offset:2048
	ds_read_b128 v[180:183], v166 offset:3072
	s_add_i32 s38, s36, 2
	s_add_u32 s33, s4, 0x80
	s_addc_u32 s37, s5, 0
	s_cmp_eq_u32 s57, s36
	s_cselect_b32 s36, s30, s33
	s_cselect_b32 s37, s31, s37
	s_cselect_b32 s71, s35, s1
	s_cselect_b32 s70, s34, s0
	v_lshl_add_u64 v[216:217], s[4:5], 0, v[140:141]
	s_add_i32 m0, s47, 0xc000
	ds_read_b128 v[184:187], v167
	ds_read_b128 v[188:191], v167 offset:1024
	ds_read_b128 v[192:195], v167 offset:2048
	ds_read_b128 v[196:199], v167 offset:3072
	ds_read_b128 v[200:203], v167 offset:4096
	ds_read_b128 v[204:207], v167 offset:5120
	ds_read_b128 v[208:211], v167 offset:6144
	ds_read_b128 v[212:215], v167 offset:7168
	global_load_lds_dwordx4 v[216:217], off
	v_lshl_add_u64 v[216:217], s[4:5], 0, v[142:143]
	s_add_i32 m0, s47, 0xe000
	s_nop 0
	global_load_lds_dwordx4 v[216:217], off
	s_waitcnt vmcnt(8)
	s_waitcnt lgkmcnt(0)
	s_setprio 1
	s_barrier
	v_mfma_f32_16x16x32_bf16 v[124:127], v[128:131], v[184:187], 0
	v_mfma_f32_16x16x32_bf16 v[120:123], v[150:153], v[184:187], 0
	v_mfma_f32_16x16x32_bf16 v[108:111], v[128:131], v[192:195], 0
	v_mfma_f32_16x16x32_bf16 v[104:107], v[150:153], v[192:195], 0
	v_mfma_f32_16x16x32_bf16 v[92:95], v[128:131], v[200:203], 0
	v_mfma_f32_16x16x32_bf16 v[88:91], v[150:153], v[200:203], 0
	v_mfma_f32_16x16x32_bf16 v[76:79], v[128:131], v[208:211], 0
	v_mfma_f32_16x16x32_bf16 v[72:75], v[150:153], v[208:211], 0
	v_mfma_f32_16x16x32_bf16 v[124:127], v[146:149], v[188:191], v[124:127]
	v_mfma_f32_16x16x32_bf16 v[120:123], v[154:157], v[188:191], v[120:123]
	v_mfma_f32_16x16x32_bf16 v[108:111], v[146:149], v[196:199], v[108:111]
	v_mfma_f32_16x16x32_bf16 v[104:107], v[154:157], v[196:199], v[104:107]
	v_mfma_f32_16x16x32_bf16 v[92:95], v[146:149], v[204:207], v[92:95]
	v_mfma_f32_16x16x32_bf16 v[88:91], v[154:157], v[204:207], v[88:91]
	v_mfma_f32_16x16x32_bf16 v[76:79], v[146:149], v[212:215], v[76:79]
	v_mfma_f32_16x16x32_bf16 v[72:75], v[154:157], v[212:215], v[72:75]
	v_mfma_f32_16x16x32_bf16 v[116:119], v[158:161], v[184:187], 0
	v_mfma_f32_16x16x32_bf16 v[112:115], v[176:179], v[184:187], 0
	v_mfma_f32_16x16x32_bf16 v[100:103], v[158:161], v[192:195], 0
	v_mfma_f32_16x16x32_bf16 v[96:99], v[176:179], v[192:195], 0
	v_mfma_f32_16x16x32_bf16 v[84:87], v[158:161], v[200:203], 0
	v_mfma_f32_16x16x32_bf16 v[80:83], v[176:179], v[200:203], 0
	v_mfma_f32_16x16x32_bf16 v[68:71], v[158:161], v[208:211], 0
	v_mfma_f32_16x16x32_bf16 v[64:67], v[176:179], v[208:211], 0
	v_mfma_f32_16x16x32_bf16 v[116:119], v[172:175], v[188:191], v[116:119]
	v_mfma_f32_16x16x32_bf16 v[112:115], v[180:183], v[188:191], v[112:115]
	v_mfma_f32_16x16x32_bf16 v[100:103], v[172:175], v[196:199], v[100:103]
	v_mfma_f32_16x16x32_bf16 v[96:99], v[180:183], v[196:199], v[96:99]
	v_mfma_f32_16x16x32_bf16 v[84:87], v[172:175], v[204:207], v[84:87]
	v_mfma_f32_16x16x32_bf16 v[80:83], v[180:183], v[204:207], v[80:83]
	v_mfma_f32_16x16x32_bf16 v[68:71], v[172:175], v[212:215], v[68:71]
	s_setprio 2
	s_barrier
	v_mfma_f32_16x16x32_bf16 v[64:67], v[180:183], v[212:215], v[64:67]
	s_setprio 0
	s_add_i32 s33, s60, s40
	v_lshl_add_u64 v[216:217], s[70:71], 0, v[136:137]
	s_mov_b32 m0, s33
	ds_read_b128 v[184:187], v167 offset:16384
	ds_read_b128 v[188:191], v167 offset:17408
	ds_read_b128 v[192:195], v167 offset:18432
	ds_read_b128 v[196:199], v167 offset:19456
	ds_read_b128 v[200:203], v167 offset:20480
	ds_read_b128 v[204:207], v167 offset:21504
	ds_read_b128 v[208:211], v167 offset:22528
	ds_read_b128 v[212:215], v167 offset:23552
	global_load_lds_dwordx4 v[216:217], off
	s_add_i32 m0, s33, 0x2000
	v_lshl_add_u64 v[218:219], s[70:71], 0, v[132:133]
	s_add_u32 s70, s70, s6
	s_addc_u32 s71, s71, s7
	s_add_i32 s33, s61, s40
	global_load_lds_dwordx4 v[218:219], off
	v_lshl_add_u64 v[220:221], s[70:71], 0, v[136:137]
	s_mov_b32 m0, s33
	v_lshl_add_u64 v[222:223], s[70:71], 0, v[132:133]
	global_load_lds_dwordx4 v[220:221], off
	s_add_i32 m0, s33, 0x2000
	v_lshl_add_u64 v[224:225], s[36:37], 0, v[138:139]
	global_load_lds_dwordx4 v[222:223], off
	s_mov_b32 m0, s47
	v_lshl_add_u64 v[226:227], s[36:37], 0, v[134:135]
	global_load_lds_dwordx4 v[224:225], off
	s_mov_b32 m0, s49
	s_nop 0
	global_load_lds_dwordx4 v[226:227], off
	s_waitcnt vmcnt(8)
	s_waitcnt lgkmcnt(0)
	s_setprio 1
	s_barrier
; #define PG8_STAGE(bufoff, gbase, voff) do { _Pragma("unroll") for (int _i = 0; _i < 2; ++_i) \
;         __builtin_amdgcn_global_load_lds((const unsigned*)((const char*)(gbase) + (voff)[_i]), (PG8_LAS unsigned*)(lds + (bufoff) + ldsw + _i * 8192), 16, 0, 0); } while (0)
; #define PG8_LDA(dst, b, h) do { _Pragma("unroll") for (int m = 0; m < 4; ++m) _Pragma("unroll") for (int k = 0; k < 2; ++k) dst[m][k] = *(const PG8_LAS bf16x8*)(lds + PG8_SA(b, h) + aoff + m * 2048 + k * 1024); } while (0)
; #define PG8_LDB(dst, b, h) do { _Pragma("unroll") for (int n = 0; n < 2; ++n) _Pragma("unroll") for (int k = 0; k < 2; ++k) dst[n][k] = *(const PG8_LAS bf16x8*)(lds + PG8_SB(b, h) + boff + n * 2048 + k * 1024); } while (0)
; #define PG8_MMA(ai, bj, At, Bt) do { __builtin_amdgcn_s_setprio(1); _Pragma("unroll") for (int m = 0; m < 4; ++m) _Pragma("unroll") for (int n = 0; n < 2; ++n) _Pragma("unroll") for (int k = 0; k < 2; ++k) \
;         acc[ai][bj][m][n] = __builtin_amdgcn_mfma_f32_16x16x32_bf16(Bt[n][k], At[m][k], acc[ai][bj][m][n], 0, 0, 0); __builtin_amdgcn_s_setprio(0); } while (0)
; #define PG8_WAIT_V(n) asm volatile("s_waitcnt vmcnt(" #n ")" ::: "memory")
; #define PG8_WAIT_L(n) asm volatile("s_waitcnt lgkmcnt(" #n ")" ::: "memory")
; template <class Epi, class Sched, bool ALIGN_EPI = false, bool SP2 = false>
; __device__ __forceinline__ void gemm_phase(PG8_LAS unsigned char* lds, const Gemm g, const Sched& S, const Epi& E, const int wid) {
;     ...
;             PG8_WAIT_V(8); PG8_WAIT_L(0); PG8_BAR; PG8_MMA(0, 0, At, B0); PG8_MMA(0, 1, At, B1); PG8_BAR; PG8_SCHED;
;             PG8_LDA(At, 0, 1); PG8_STAGE(PG8_SB(0, 0), b2, voffB); PG8_STAGE(PG8_SB(0, 1), b2 + hstep, voffB); PG8_STAGE(PG8_SA(0, 0), a2, voffA);
;             PG8_WAIT_V(8); PG8_WAIT_L(0); PG8_BAR; PG8_MMA(1, 0, At, B0); PG8_MMA(1, 1, At, B1); PG8_BAR; PG8_SCHED;
;             PG8_LDB(B0, 1, 0); PG8_LDB(B1, 1, 1); PG8_SCHED; PG8_LDA(At, 1, 0); PG8_STAGE(PG8_SA(0, 1), a2 + hstep, voffA);
;             PG8_WAIT_V(8); PG8_WAIT_L(0); PG8_BAR; PG8_MMA(0, 0, At, B0); PG8_MMA(0, 1, At, B1); PG8_BAR; PG8_SCHED;
;             PG8_LDA(At, 1, 1); PG8_STAGE(PG8_SB(1, 0), b3, voffB); PG8_STAGE(PG8_SB(1, 1), b3 + hstep, voffB); PG8_STAGE(PG8_SA(1, 0), a3, voffA);
;             PG8_WAIT_V(8); PG8_WAIT_L(0); PG8_BAR; PG8_MMA(1, 0, At, B0); PG8_MMA(1, 1, At, B1); PG8_BAR; PG8_SCHED;
	v_mfma_f32_16x16x32_bf16 v[60:63], v[128:131], v[184:187], 0
	v_mfma_f32_16x16x32_bf16 v[56:59], v[150:153], v[184:187], 0
	v_mfma_f32_16x16x32_bf16 v[44:47], v[128:131], v[192:195], 0
	v_mfma_f32_16x16x32_bf16 v[40:43], v[150:153], v[192:195], 0
	v_mfma_f32_16x16x32_bf16 v[28:31], v[128:131], v[200:203], 0
	v_mfma_f32_16x16x32_bf16 v[24:27], v[150:153], v[200:203], 0
	v_mfma_f32_16x16x32_bf16 v[12:15], v[128:131], v[208:211], 0
	v_mfma_f32_16x16x32_bf16 v[8:11], v[150:153], v[208:211], 0
	v_mfma_f32_16x16x32_bf16 v[60:63], v[146:149], v[188:191], v[60:63]
	v_mfma_f32_16x16x32_bf16 v[56:59], v[154:157], v[188:191], v[56:59]
	v_mfma_f32_16x16x32_bf16 v[44:47], v[146:149], v[196:199], v[44:47]
	v_mfma_f32_16x16x32_bf16 v[40:43], v[154:157], v[196:199], v[40:43]
	v_mfma_f32_16x16x32_bf16 v[28:31], v[146:149], v[204:207], v[28:31]
	v_mfma_f32_16x16x32_bf16 v[24:27], v[154:157], v[204:207], v[24:27]
	v_mfma_f32_16x16x32_bf16 v[12:15], v[146:149], v[212:215], v[12:15]
	v_mfma_f32_16x16x32_bf16 v[8:11], v[154:157], v[212:215], v[8:11]
	v_mfma_f32_16x16x32_bf16 v[52:55], v[158:161], v[184:187], 0
	v_mfma_f32_16x16x32_bf16 v[48:51], v[176:179], v[184:187], 0
	v_mfma_f32_16x16x32_bf16 v[36:39], v[158:161], v[192:195], 0
	v_mfma_f32_16x16x32_bf16 v[32:35], v[176:179], v[192:195], 0
	v_mfma_f32_16x16x32_bf16 v[20:23], v[158:161], v[200:203], 0
	v_mfma_f32_16x16x32_bf16 v[16:19], v[176:179], v[200:203], 0
	v_mfma_f32_16x16x32_bf16 v[4:7], v[158:161], v[208:211], 0
	v_mfma_f32_16x16x32_bf16 v[0:3], v[176:179], v[208:211], 0
	v_mfma_f32_16x16x32_bf16 v[52:55], v[172:175], v[188:191], v[52:55]
	v_mfma_f32_16x16x32_bf16 v[48:51], v[180:183], v[188:191], v[48:51]
	v_mfma_f32_16x16x32_bf16 v[36:39], v[172:175], v[196:199], v[36:39]
	v_mfma_f32_16x16x32_bf16 v[32:35], v[180:183], v[196:199], v[32:35]
	v_mfma_f32_16x16x32_bf16 v[20:23], v[172:175], v[204:207], v[20:23]
	v_mfma_f32_16x16x32_bf16 v[16:19], v[180:183], v[204:207], v[16:19]
	v_mfma_f32_16x16x32_bf16 v[4:7], v[172:175], v[212:215], v[4:7]
	s_setprio 2
	s_barrier
	v_mfma_f32_16x16x32_bf16 v[0:3], v[180:183], v[212:215], v[0:3]
	s_setprio 0
	s_add_i32 s33, 0, 0x18000
	s_add_i32 s39, 0, 0x1c000
	v_add_u32_e32 v154, s33, v164
	v_add_u32_e32 v180, s39, v164
	ds_read_b128 v[128:131], v154
	ds_read_b128 v[146:149], v154 offset:1024
	ds_read_b128 v[150:153], v154 offset:2048
	ds_read_b128 v[154:157], v154 offset:3072
	ds_read_b128 v[158:161], v180
	ds_read_b128 v[172:175], v180 offset:1024
	ds_read_b128 v[176:179], v180 offset:2048
	ds_read_b128 v[180:183], v180 offset:3072
	s_add_u32 s36, s36, s6
	s_addc_u32 s37, s37, s7
	s_mov_b32 m0, s50
	v_lshl_add_u64 v[228:229], s[36:37], 0, v[138:139]
	ds_read_b128 v[184:187], v167 offset:32768
	ds_read_b128 v[188:191], v167 offset:33792
	ds_read_b128 v[192:195], v167 offset:34816
	ds_read_b128 v[196:199], v167 offset:35840
	ds_read_b128 v[200:203], v167 offset:36864
	ds_read_b128 v[204:207], v167 offset:37888
	ds_read_b128 v[208:211], v167 offset:38912
	ds_read_b128 v[212:215], v167 offset:39936
	global_load_lds_dwordx4 v[228:229], off
	v_lshl_add_u64 v[228:229], s[36:37], 0, v[134:135]
	s_mov_b32 m0, s51
	s_nop 0
	global_load_lds_dwordx4 v[228:229], off
	s_waitcnt vmcnt(8)
	s_waitcnt lgkmcnt(0)
	s_setprio 1
	s_barrier
	v_mfma_f32_16x16x32_bf16 v[124:127], v[128:131], v[184:187], v[124:127]
	v_mfma_f32_16x16x32_bf16 v[120:123], v[150:153], v[184:187], v[120:123]
	v_mfma_f32_16x16x32_bf16 v[108:111], v[128:131], v[192:195], v[108:111]
	v_mfma_f32_16x16x32_bf16 v[104:107], v[150:153], v[192:195], v[104:107]
	v_mfma_f32_16x16x32_bf16 v[92:95], v[128:131], v[200:203], v[92:95]
	v_mfma_f32_16x16x32_bf16 v[88:91], v[150:153], v[200:203], v[88:91]
	v_mfma_f32_16x16x32_bf16 v[76:79], v[128:131], v[208:211], v[76:79]
	v_mfma_f32_16x16x32_bf16 v[72:75], v[150:153], v[208:211], v[72:75]
	v_mfma_f32_16x16x32_bf16 v[124:127], v[146:149], v[188:191], v[124:127]
	v_mfma_f32_16x16x32_bf16 v[120:123], v[154:157], v[188:191], v[120:123]
	v_mfma_f32_16x16x32_bf16 v[108:111], v[146:149], v[196:199], v[108:111]
	v_mfma_f32_16x16x32_bf16 v[104:107], v[154:157], v[196:199], v[104:107]
	v_mfma_f32_16x16x32_bf16 v[92:95], v[146:149], v[204:207], v[92:95]
	v_mfma_f32_16x16x32_bf16 v[88:91], v[154:157], v[204:207], v[88:91]
	v_mfma_f32_16x16x32_bf16 v[76:79], v[146:149], v[212:215], v[76:79]
	v_mfma_f32_16x16x32_bf16 v[72:75], v[154:157], v[212:215], v[72:75]
	v_mfma_f32_16x16x32_bf16 v[116:119], v[158:161], v[184:187], v[116:119]
	v_mfma_f32_16x16x32_bf16 v[112:115], v[176:179], v[184:187], v[112:115]
	v_mfma_f32_16x16x32_bf16 v[100:103], v[158:161], v[192:195], v[100:103]
	v_mfma_f32_16x16x32_bf16 v[96:99], v[176:179], v[192:195], v[96:99]
	v_mfma_f32_16x16x32_bf16 v[84:87], v[158:161], v[200:203], v[84:87]
	v_mfma_f32_16x16x32_bf16 v[80:83], v[176:179], v[200:203], v[80:83]
	v_mfma_f32_16x16x32_bf16 v[68:71], v[158:161], v[208:211], v[68:71]
	v_mfma_f32_16x16x32_bf16 v[64:67], v[176:179], v[208:211], v[64:67]
	v_mfma_f32_16x16x32_bf16 v[116:119], v[172:175], v[188:191], v[116:119]
	v_mfma_f32_16x16x32_bf16 v[112:115], v[180:183], v[188:191], v[112:115]
	v_mfma_f32_16x16x32_bf16 v[100:103], v[172:175], v[196:199], v[100:103]
	v_mfma_f32_16x16x32_bf16 v[96:99], v[180:183], v[196:199], v[96:99]
	v_mfma_f32_16x16x32_bf16 v[84:87], v[172:175], v[204:207], v[84:87]
	v_mfma_f32_16x16x32_bf16 v[80:83], v[180:183], v[204:207], v[80:83]
	v_mfma_f32_16x16x32_bf16 v[68:71], v[172:175], v[212:215], v[68:71]
	s_setprio 2
	s_barrier
; #define PG8_STAGE(bufoff, gbase, voff) do { _Pragma("unroll") for (int _i = 0; _i < 2; ++_i) \
;         __builtin_amdgcn_global_load_lds((const unsigned*)((const char*)(gbase) + (voff)[_i]), (PG8_LAS unsigned*)(lds + (bufoff) + ldsw + _i * 8192), 16, 0, 0); } while (0)
; #define PG8_LDA(dst, b, h) do { _Pragma("unroll") for (int m = 0; m < 4; ++m) _Pragma("unroll") for (int k = 0; k < 2; ++k) dst[m][k] = *(const PG8_LAS bf16x8*)(lds + PG8_SA(b, h) + aoff + m * 2048 + k * 1024); } while (0)
; #define PG8_WAIT_V(n) asm volatile("s_waitcnt vmcnt(" #n ")" ::: "memory")
; #define PG8_WAIT_L(n) asm volatile("s_waitcnt lgkmcnt(" #n ")" ::: "memory")
; #define PG8_BAR __builtin_amdgcn_s_barrier()
; template <class Epi, class Sched, bool ALIGN_EPI = false, bool SP2 = false>
; __device__ __forceinline__ void gemm_phase(PG8_LAS unsigned char* lds, const Gemm g, const Sched& S, const Epi& E, const int wid) {
;     ...
;         for (int t = 0; t < nt; t += 2) {
;             const bool last = (t == nt - 2);
;             const char* a1 = cA + (size_t)(t + 1) * kstep;
;             const char* a2 = last ? nA : cA + (size_t)(t + 2) * kstep; const char* b2 = last ? nB : cB + (size_t)(t + 2) * kstep;
;             const char* a3 = a2 + kstep; const char* b3 = b2 + kstep;
;             if (last && has_next) S.a_ready(nxt);
;             if constexpr (SP2) {
;             PG8_LDB(B0, 0, 0); PG8_LDB(B1, 0, 1); PG8_SCHED; PG8_LDA(At, 0, 0); PG8_STAGE(PG8_SA(1, 1), a1 + hstep, voffA);
;             PG8_WAIT_V(8); PG8_WAIT_L(0); PG8_BAR; PG8_MMA(0, 0, At, B0); PG8_MMA(0, 1, At, B1); PG8_BAR; PG8_SCHED;
;             PG8_LDA(At, 0, 1); PG8_STAGE(PG8_SB(0, 0), b2, voffB); PG8_STAGE(PG8_SB(0, 1), b2 + hstep, voffB); PG8_STAGE(PG8_SA(0, 0), a2, voffA);
;             PG8_WAIT_V(8); PG8_WAIT_L(0); PG8_BAR; PG8_MMA(1, 0, At, B0); PG8_MMA(1, 1, At, B1); PG8_BAR; PG8_SCHED;
;             PG8_LDB(B0, 1, 0); PG8_LDB(B1, 1, 1); PG8_SCHED; PG8_LDA(At, 1, 0); PG8_STAGE(PG8_SA(0, 1), a2 + hstep, voffA);
;             PG8_WAIT_V(8); PG8_WAIT_L(0); PG8_BAR; PG8_MMA(0, 0, At, B0); PG8_MMA(0, 1, At, B1); PG8_BAR; PG8_SCHED;
;             PG8_LDA(At, 1, 1); PG8_STAGE(PG8_SB(1, 0), b3, voffB); PG8_STAGE(PG8_SB(1, 1), b3 + hstep, voffB); PG8_STAGE(PG8_SA(1, 0), a3, voffA);
;             PG8_WAIT_V(8); PG8_WAIT_L(0); PG8_BAR; PG8_MMA(1, 0, At, B0); PG8_MMA(1, 1, At, B1); PG8_BAR; PG8_SCHED;
	v_mfma_f32_16x16x32_bf16 v[64:67], v[180:183], v[212:215], v[64:67]
	s_setprio 0
	s_add_i32 s33, s33, s40
	v_lshl_add_u64 v[216:217], v[216:217], 0, s[22:23]
	s_mov_b32 m0, s33
	ds_read_b128 v[184:187], v167 offset:49152
	ds_read_b128 v[188:191], v167 offset:50176
	ds_read_b128 v[192:195], v167 offset:51200
	ds_read_b128 v[196:199], v167 offset:52224
	ds_read_b128 v[200:203], v167 offset:53248
	ds_read_b128 v[204:207], v167 offset:54272
	ds_read_b128 v[208:211], v167 offset:55296
	ds_read_b128 v[212:215], v167 offset:56320
	global_load_lds_dwordx4 v[216:217], off
	v_lshl_add_u64 v[216:217], v[218:219], 0, s[22:23]
	s_add_i32 m0, s33, 0x2000
	s_add_i32 s33, s39, s40
	global_load_lds_dwordx4 v[216:217], off
	v_lshl_add_u64 v[216:217], v[220:221], 0, s[22:23]
	s_mov_b32 m0, s33
	s_nop 0
	global_load_lds_dwordx4 v[216:217], off
	v_lshl_add_u64 v[216:217], v[222:223], 0, s[22:23]
	s_add_i32 m0, s33, 0x2000
	s_nop 0
	global_load_lds_dwordx4 v[216:217], off
	v_lshl_add_u64 v[216:217], v[224:225], 0, s[22:23]
	s_mov_b32 m0, s53
	s_nop 0
	global_load_lds_dwordx4 v[216:217], off
	v_lshl_add_u64 v[216:217], v[226:227], 0, s[22:23]
	s_mov_b32 m0, s54
	s_nop 0
	global_load_lds_dwordx4 v[216:217], off
	s_waitcnt vmcnt(8)
	s_waitcnt lgkmcnt(0)
	s_setprio 1
	s_barrier
	v_mfma_f32_16x16x32_bf16 v[60:63], v[128:131], v[184:187], v[60:63]
	v_mfma_f32_16x16x32_bf16 v[56:59], v[150:153], v[184:187], v[56:59]
	v_mfma_f32_16x16x32_bf16 v[44:47], v[128:131], v[192:195], v[44:47]
	v_mfma_f32_16x16x32_bf16 v[40:43], v[150:153], v[192:195], v[40:43]
	v_mfma_f32_16x16x32_bf16 v[28:31], v[128:131], v[200:203], v[28:31]
	v_mfma_f32_16x16x32_bf16 v[24:27], v[150:153], v[200:203], v[24:27]
	v_mfma_f32_16x16x32_bf16 v[12:15], v[128:131], v[208:211], v[12:15]
	v_mfma_f32_16x16x32_bf16 v[8:11], v[150:153], v[208:211], v[8:11]
	v_mfma_f32_16x16x32_bf16 v[60:63], v[146:149], v[188:191], v[60:63]
	v_mfma_f32_16x16x32_bf16 v[56:59], v[154:157], v[188:191], v[56:59]
	v_mfma_f32_16x16x32_bf16 v[44:47], v[146:149], v[196:199], v[44:47]
	v_mfma_f32_16x16x32_bf16 v[40:43], v[154:157], v[196:199], v[40:43]
	v_mfma_f32_16x16x32_bf16 v[28:31], v[146:149], v[204:207], v[28:31]
	v_mfma_f32_16x16x32_bf16 v[24:27], v[154:157], v[204:207], v[24:27]
	v_mfma_f32_16x16x32_bf16 v[12:15], v[146:149], v[212:215], v[12:15]
	v_mfma_f32_16x16x32_bf16 v[8:11], v[154:157], v[212:215], v[8:11]
	v_mfma_f32_16x16x32_bf16 v[52:55], v[158:161], v[184:187], v[52:55]
	v_mfma_f32_16x16x32_bf16 v[48:51], v[176:179], v[184:187], v[48:51]
	v_mfma_f32_16x16x32_bf16 v[36:39], v[158:161], v[192:195], v[36:39]
	v_mfma_f32_16x16x32_bf16 v[32:35], v[176:179], v[192:195], v[32:35]
	v_mfma_f32_16x16x32_bf16 v[20:23], v[158:161], v[200:203], v[20:23]
	v_mfma_f32_16x16x32_bf16 v[16:19], v[176:179], v[200:203], v[16:19]
	v_mfma_f32_16x16x32_bf16 v[4:7], v[158:161], v[208:211], v[4:7]
	v_mfma_f32_16x16x32_bf16 v[0:3], v[176:179], v[208:211], v[0:3]
	v_mfma_f32_16x16x32_bf16 v[52:55], v[172:175], v[188:191], v[52:55]
	v_mfma_f32_16x16x32_bf16 v[48:51], v[180:183], v[188:191], v[48:51]
	v_mfma_f32_16x16x32_bf16 v[36:39], v[172:175], v[196:199], v[36:39]
	v_mfma_f32_16x16x32_bf16 v[32:35], v[180:183], v[196:199], v[32:35]
	v_mfma_f32_16x16x32_bf16 v[20:23], v[172:175], v[204:207], v[20:23]
	v_mfma_f32_16x16x32_bf16 v[16:19], v[180:183], v[204:207], v[16:19]
	v_mfma_f32_16x16x32_bf16 v[4:7], v[172:175], v[212:215], v[4:7]
	s_setprio 2
	s_barrier
	v_mfma_f32_16x16x32_bf16 v[0:3], v[180:183], v[212:215], v[0:3]
	s_setprio 0
	s_add_u32 s4, s4, 0x100
	s_addc_u32 s5, s5, 0
	s_add_u32 s0, s0, 0x100
	s_addc_u32 s1, s1, 0
	s_cmp_ge_i32 s38, s55
	s_mov_b32 s36, s38
	s_cbranch_scc1 .LBB0_21
.LBB0_20:
	ds_read_b128 v[128:131], v165
	ds_read_b128 v[146:149], v165 offset:1024
	ds_read_b128 v[150:153], v165 offset:2048
	ds_read_b128 v[154:157], v165 offset:3072
	ds_read_b128 v[158:161], v166
	ds_read_b128 v[172:175], v166 offset:1024
	ds_read_b128 v[176:179], v166 offset:2048
	ds_read_b128 v[180:183], v166 offset:3072
	s_add_i32 s38, s36, 2
	s_add_u32 s33, s4, 0x80
	s_addc_u32 s37, s5, 0
	s_cmp_eq_u32 s57, s36
	s_cselect_b32 s36, s30, s33
	s_cselect_b32 s37, s31, s37
	s_cselect_b32 s71, s35, s1
	s_cselect_b32 s70, s34, s0
	v_lshl_add_u64 v[216:217], s[4:5], 0, v[140:141]
	s_add_i32 m0, s47, 0xc000
	ds_read_b128 v[184:187], v167
	ds_read_b128 v[188:191], v167 offset:1024
	ds_read_b128 v[192:195], v167 offset:2048
	ds_read_b128 v[196:199], v167 offset:3072
	ds_read_b128 v[200:203], v167 offset:4096
	ds_read_b128 v[204:207], v167 offset:5120
	ds_read_b128 v[208:211], v167 offset:6144
	ds_read_b128 v[212:215], v167 offset:7168
	global_load_lds_dwordx4 v[216:217], off
	v_lshl_add_u64 v[216:217], s[4:5], 0, v[142:143]
	s_add_i32 m0, s47, 0xe000
	s_nop 0
	global_load_lds_dwordx4 v[216:217], off
	s_waitcnt vmcnt(8)
	s_waitcnt lgkmcnt(0)
	s_setprio 1
	s_barrier
; #define PG8_STAGE(bufoff, gbase, voff) do { _Pragma("unroll") for (int _i = 0; _i < 2; ++_i) \
;         __builtin_amdgcn_global_load_lds((const unsigned*)((const char*)(gbase) + (voff)[_i]), (PG8_LAS unsigned*)(lds + (bufoff) + ldsw + _i * 8192), 16, 0, 0); } while (0)
; #define PG8_LDA(dst, b, h) do { _Pragma("unroll") for (int m = 0; m < 4; ++m) _Pragma("unroll") for (int k = 0; k < 2; ++k) dst[m][k] = *(const PG8_LAS bf16x8*)(lds + PG8_SA(b, h) + aoff + m * 2048 + k * 1024); } while (0)
; #define PG8_WAIT_V(n) asm volatile("s_waitcnt vmcnt(" #n ")" ::: "memory")
; #define PG8_WAIT_L(n) asm volatile("s_waitcnt lgkmcnt(" #n ")" ::: "memory")
; #define PG8_BAR __builtin_amdgcn_s_barrier()
; template <class Epi, class Sched, bool ALIGN_EPI = false, bool SP2 = false>
; __device__ __forceinline__ void gemm_phase(PG8_LAS unsigned char* lds, const Gemm g, const Sched& S, const Epi& E, const int wid) {
;     ...
;         for (int t = 0; t < nt; t += 2) {
;             const bool last = (t == nt - 2);
;             const char* a1 = cA + (size_t)(t + 1) * kstep;
;             const char* a2 = last ? nA : cA + (size_t)(t + 2) * kstep; const char* b2 = last ? nB : cB + (size_t)(t + 2) * kstep;
;             const char* a3 = a2 + kstep; const char* b3 = b2 + kstep;
;             if (last && has_next) S.a_ready(nxt);
;             if constexpr (SP2) {
;             PG8_LDB(B0, 0, 0); PG8_LDB(B1, 0, 1); PG8_SCHED; PG8_LDA(At, 0, 0); PG8_STAGE(PG8_SA(1, 1), a1 + hstep, voffA);
;             PG8_WAIT_V(8); PG8_WAIT_L(0); PG8_BAR; PG8_MMA(0, 0, At, B0); PG8_MMA(0, 1, At, B1); PG8_BAR; PG8_SCHED;
;             PG8_LDA(At, 0, 1); PG8_STAGE(PG8_SB(0, 0), b2, voffB); PG8_STAGE(PG8_SB(0, 1), b2 + hstep, voffB); PG8_STAGE(PG8_SA(0, 0), a2, voffA);
;             PG8_WAIT_V(8); PG8_WAIT_L(0); PG8_BAR; PG8_MMA(1, 0, At, B0); PG8_MMA(1, 1, At, B1); PG8_BAR; PG8_SCHED;
;             PG8_LDB(B0, 1, 0); PG8_LDB(B1, 1, 1); PG8_SCHED; PG8_LDA(At, 1, 0); PG8_STAGE(PG8_SA(0, 1), a2 + hstep, voffA);
;             PG8_WAIT_V(8); PG8_WAIT_L(0); PG8_BAR; PG8_MMA(0, 0, At, B0); PG8_MMA(0, 1, At, B1); PG8_BAR; PG8_SCHED;
;             PG8_LDA(At, 1, 1); PG8_STAGE(PG8_SB(1, 0), b3, voffB); PG8_STAGE(PG8_SB(1, 1), b3 + hstep, voffB); PG8_STAGE(PG8_SA(1, 0), a3, voffA);
;             PG8_WAIT_V(8); PG8_WAIT_L(0); PG8_BAR; PG8_MMA(1, 0, At, B0); PG8_MMA(1, 1, At, B1); PG8_BAR; PG8_SCHED;
	v_mfma_f32_16x16x32_bf16 v[124:127], v[128:131], v[184:187], v[124:127]
	v_mfma_f32_16x16x32_bf16 v[120:123], v[150:153], v[184:187], v[120:123]
	v_mfma_f32_16x16x32_bf16 v[108:111], v[128:131], v[192:195], v[108:111]
	v_mfma_f32_16x16x32_bf16 v[104:107], v[150:153], v[192:195], v[104:107]
	v_mfma_f32_16x16x32_bf16 v[92:95], v[128:131], v[200:203], v[92:95]
	v_mfma_f32_16x16x32_bf16 v[88:91], v[150:153], v[200:203], v[88:91]
	v_mfma_f32_16x16x32_bf16 v[76:79], v[128:131], v[208:211], v[76:79]
	v_mfma_f32_16x16x32_bf16 v[72:75], v[150:153], v[208:211], v[72:75]
	v_mfma_f32_16x16x32_bf16 v[124:127], v[146:149], v[188:191], v[124:127]
	v_mfma_f32_16x16x32_bf16 v[120:123], v[154:157], v[188:191], v[120:123]
	v_mfma_f32_16x16x32_bf16 v[108:111], v[146:149], v[196:199], v[108:111]
	v_mfma_f32_16x16x32_bf16 v[104:107], v[154:157], v[196:199], v[104:107]
	v_mfma_f32_16x16x32_bf16 v[92:95], v[146:149], v[204:207], v[92:95]
	v_mfma_f32_16x16x32_bf16 v[88:91], v[154:157], v[204:207], v[88:91]
	v_mfma_f32_16x16x32_bf16 v[76:79], v[146:149], v[212:215], v[76:79]
	v_mfma_f32_16x16x32_bf16 v[72:75], v[154:157], v[212:215], v[72:75]
	v_mfma_f32_16x16x32_bf16 v[116:119], v[158:161], v[184:187], v[116:119]
	v_mfma_f32_16x16x32_bf16 v[112:115], v[176:179], v[184:187], v[112:115]
	v_mfma_f32_16x16x32_bf16 v[100:103], v[158:161], v[192:195], v[100:103]
	v_mfma_f32_16x16x32_bf16 v[96:99], v[176:179], v[192:195], v[96:99]
	v_mfma_f32_16x16x32_bf16 v[84:87], v[158:161], v[200:203], v[84:87]
	v_mfma_f32_16x16x32_bf16 v[80:83], v[176:179], v[200:203], v[80:83]
	v_mfma_f32_16x16x32_bf16 v[68:71], v[158:161], v[208:211], v[68:71]
	v_mfma_f32_16x16x32_bf16 v[64:67], v[176:179], v[208:211], v[64:67]
	v_mfma_f32_16x16x32_bf16 v[116:119], v[172:175], v[188:191], v[116:119]
	v_mfma_f32_16x16x32_bf16 v[112:115], v[180:183], v[188:191], v[112:115]
	v_mfma_f32_16x16x32_bf16 v[100:103], v[172:175], v[196:199], v[100:103]
	v_mfma_f32_16x16x32_bf16 v[96:99], v[180:183], v[196:199], v[96:99]
	v_mfma_f32_16x16x32_bf16 v[84:87], v[172:175], v[204:207], v[84:87]
	v_mfma_f32_16x16x32_bf16 v[80:83], v[180:183], v[204:207], v[80:83]
	v_mfma_f32_16x16x32_bf16 v[68:71], v[172:175], v[212:215], v[68:71]
	s_setprio 2
	s_barrier
	v_mfma_f32_16x16x32_bf16 v[64:67], v[180:183], v[212:215], v[64:67]
	s_setprio 0
	s_add_i32 s33, s60, s40
	v_lshl_add_u64 v[216:217], s[70:71], 0, v[136:137]
	s_mov_b32 m0, s33
	ds_read_b128 v[184:187], v167 offset:16384
	ds_read_b128 v[188:191], v167 offset:17408
	ds_read_b128 v[192:195], v167 offset:18432
	ds_read_b128 v[196:199], v167 offset:19456
	ds_read_b128 v[200:203], v167 offset:20480
	ds_read_b128 v[204:207], v167 offset:21504
	ds_read_b128 v[208:211], v167 offset:22528
	ds_read_b128 v[212:215], v167 offset:23552
	global_load_lds_dwordx4 v[216:217], off
	s_add_i32 m0, s33, 0x2000
	v_lshl_add_u64 v[218:219], s[70:71], 0, v[132:133]
	s_add_u32 s70, s70, s6
	s_addc_u32 s71, s71, s7
	s_add_i32 s33, s61, s40
	global_load_lds_dwordx4 v[218:219], off
	v_lshl_add_u64 v[220:221], s[70:71], 0, v[136:137]
	s_mov_b32 m0, s33
	v_lshl_add_u64 v[222:223], s[70:71], 0, v[132:133]
	global_load_lds_dwordx4 v[220:221], off
	s_add_i32 m0, s33, 0x2000
	v_lshl_add_u64 v[224:225], s[36:37], 0, v[138:139]
	global_load_lds_dwordx4 v[222:223], off
	s_mov_b32 m0, s47
	v_lshl_add_u64 v[226:227], s[36:37], 0, v[134:135]
	global_load_lds_dwordx4 v[224:225], off
	s_mov_b32 m0, s49
	s_nop 0
	global_load_lds_dwordx4 v[226:227], off
	s_waitcnt vmcnt(8)
	s_waitcnt lgkmcnt(0)
	s_setprio 1
	s_barrier
	v_mfma_f32_16x16x32_bf16 v[60:63], v[128:131], v[184:187], v[60:63]
	v_mfma_f32_16x16x32_bf16 v[56:59], v[150:153], v[184:187], v[56:59]
	v_mfma_f32_16x16x32_bf16 v[44:47], v[128:131], v[192:195], v[44:47]
	v_mfma_f32_16x16x32_bf16 v[40:43], v[150:153], v[192:195], v[40:43]
	v_mfma_f32_16x16x32_bf16 v[28:31], v[128:131], v[200:203], v[28:31]
	v_mfma_f32_16x16x32_bf16 v[24:27], v[150:153], v[200:203], v[24:27]
	v_mfma_f32_16x16x32_bf16 v[12:15], v[128:131], v[208:211], v[12:15]
	v_mfma_f32_16x16x32_bf16 v[8:11], v[150:153], v[208:211], v[8:11]
	v_mfma_f32_16x16x32_bf16 v[60:63], v[146:149], v[188:191], v[60:63]
	v_mfma_f32_16x16x32_bf16 v[56:59], v[154:157], v[188:191], v[56:59]
	v_mfma_f32_16x16x32_bf16 v[44:47], v[146:149], v[196:199], v[44:47]
	v_mfma_f32_16x16x32_bf16 v[40:43], v[154:157], v[196:199], v[40:43]
	v_mfma_f32_16x16x32_bf16 v[28:31], v[146:149], v[204:207], v[28:31]
	v_mfma_f32_16x16x32_bf16 v[24:27], v[154:157], v[204:207], v[24:27]
	v_mfma_f32_16x16x32_bf16 v[12:15], v[146:149], v[212:215], v[12:15]
	v_mfma_f32_16x16x32_bf16 v[8:11], v[154:157], v[212:215], v[8:11]
	v_mfma_f32_16x16x32_bf16 v[52:55], v[158:161], v[184:187], v[52:55]
	v_mfma_f32_16x16x32_bf16 v[48:51], v[176:179], v[184:187], v[48:51]
	v_mfma_f32_16x16x32_bf16 v[36:39], v[158:161], v[192:195], v[36:39]
	v_mfma_f32_16x16x32_bf16 v[32:35], v[176:179], v[192:195], v[32:35]
	v_mfma_f32_16x16x32_bf16 v[20:23], v[158:161], v[200:203], v[20:23]
	v_mfma_f32_16x16x32_bf16 v[16:19], v[176:179], v[200:203], v[16:19]
	v_mfma_f32_16x16x32_bf16 v[4:7], v[158:161], v[208:211], v[4:7]
	v_mfma_f32_16x16x32_bf16 v[0:3], v[176:179], v[208:211], v[0:3]
	v_mfma_f32_16x16x32_bf16 v[52:55], v[172:175], v[188:191], v[52:55]
	v_mfma_f32_16x16x32_bf16 v[48:51], v[180:183], v[188:191], v[48:51]
	v_mfma_f32_16x16x32_bf16 v[36:39], v[172:175], v[196:199], v[36:39]
	v_mfma_f32_16x16x32_bf16 v[32:35], v[180:183], v[196:199], v[32:35]
	v_mfma_f32_16x16x32_bf16 v[20:23], v[172:175], v[204:207], v[20:23]
	v_mfma_f32_16x16x32_bf16 v[16:19], v[180:183], v[204:207], v[16:19]
	v_mfma_f32_16x16x32_bf16 v[4:7], v[172:175], v[212:215], v[4:7]
	s_setprio 2
	s_barrier
; #define PG8_STAGE(bufoff, gbase, voff) do { _Pragma("unroll") for (int _i = 0; _i < 2; ++_i) \
;         __builtin_amdgcn_global_load_lds((const unsigned*)((const char*)(gbase) + (voff)[_i]), (PG8_LAS unsigned*)(lds + (bufoff) + ldsw + _i * 8192), 16, 0, 0); } while (0)
; #define PG8_LDA(dst, b, h) do { _Pragma("unroll") for (int m = 0; m < 4; ++m) _Pragma("unroll") for (int k = 0; k < 2; ++k) dst[m][k] = *(const PG8_LAS bf16x8*)(lds + PG8_SA(b, h) + aoff + m * 2048 + k * 1024); } while (0)
; #define PG8_WAIT_V(n) asm volatile("s_waitcnt vmcnt(" #n ")" ::: "memory")
; #define PG8_WAIT_L(n) asm volatile("s_waitcnt lgkmcnt(" #n ")" ::: "memory")
; #define PG8_BAR __builtin_amdgcn_s_barrier()
; template <class Epi, class Sched, bool ALIGN_EPI = false, bool SP2 = false>
; __device__ __forceinline__ void gemm_phase(PG8_LAS unsigned char* lds, const Gemm g, const Sched& S, const Epi& E, const int wid) {
;     ...
;         for (int t = 0; t < nt; t += 2) {
;             const bool last = (t == nt - 2);
;             const char* a1 = cA + (size_t)(t + 1) * kstep;
;             const char* a2 = last ? nA : cA + (size_t)(t + 2) * kstep; const char* b2 = last ? nB : cB + (size_t)(t + 2) * kstep;
;             const char* a3 = a2 + kstep; const char* b3 = b2 + kstep;
;             if (last && has_next) S.a_ready(nxt);
;             if constexpr (SP2) {
;             PG8_LDB(B0, 0, 0); PG8_LDB(B1, 0, 1); PG8_SCHED; PG8_LDA(At, 0, 0); PG8_STAGE(PG8_SA(1, 1), a1 + hstep, voffA);
;             PG8_WAIT_V(8); PG8_WAIT_L(0); PG8_BAR; PG8_MMA(0, 0, At, B0); PG8_MMA(0, 1, At, B1); PG8_BAR; PG8_SCHED;
;             PG8_LDA(At, 0, 1); PG8_STAGE(PG8_SB(0, 0), b2, voffB); PG8_STAGE(PG8_SB(0, 1), b2 + hstep, voffB); PG8_STAGE(PG8_SA(0, 0), a2, voffA);
;             PG8_WAIT_V(8); PG8_WAIT_L(0); PG8_BAR; PG8_MMA(1, 0, At, B0); PG8_MMA(1, 1, At, B1); PG8_BAR; PG8_SCHED;
;             PG8_LDB(B0, 1, 0); PG8_LDB(B1, 1, 1); PG8_SCHED; PG8_LDA(At, 1, 0); PG8_STAGE(PG8_SA(0, 1), a2 + hstep, voffA);
;             PG8_WAIT_V(8); PG8_WAIT_L(0); PG8_BAR; PG8_MMA(0, 0, At, B0); PG8_MMA(0, 1, At, B1); PG8_BAR; PG8_SCHED;
;             PG8_LDA(At, 1, 1); PG8_STAGE(PG8_SB(1, 0), b3, voffB); PG8_STAGE(PG8_SB(1, 1), b3 + hstep, voffB); PG8_STAGE(PG8_SA(1, 0), a3, voffA);
;             PG8_WAIT_V(8); PG8_WAIT_L(0); PG8_BAR; PG8_MMA(1, 0, At, B0); PG8_MMA(1, 1, At, B1); PG8_BAR; PG8_SCHED;
	v_mfma_f32_16x16x32_bf16 v[0:3], v[180:183], v[212:215], v[0:3]
	s_setprio 0
	s_add_i32 s33, 0, 0x18000
	s_add_i32 s39, 0, 0x1c000
	v_add_u32_e32 v154, s33, v164
	v_add_u32_e32 v180, s39, v164
	ds_read_b128 v[128:131], v154
	ds_read_b128 v[146:149], v154 offset:1024
	ds_read_b128 v[150:153], v154 offset:2048
	ds_read_b128 v[154:157], v154 offset:3072
	ds_read_b128 v[158:161], v180
	ds_read_b128 v[172:175], v180 offset:1024
	ds_read_b128 v[176:179], v180 offset:2048
	ds_read_b128 v[180:183], v180 offset:3072
	s_add_u32 s36, s36, s6
	s_addc_u32 s37, s37, s7
	s_mov_b32 m0, s50
	v_lshl_add_u64 v[228:229], s[36:37], 0, v[138:139]
	ds_read_b128 v[184:187], v167 offset:32768
	ds_read_b128 v[188:191], v167 offset:33792
	ds_read_b128 v[192:195], v167 offset:34816
	ds_read_b128 v[196:199], v167 offset:35840
	ds_read_b128 v[200:203], v167 offset:36864
	ds_read_b128 v[204:207], v167 offset:37888
	ds_read_b128 v[208:211], v167 offset:38912
	ds_read_b128 v[212:215], v167 offset:39936
	global_load_lds_dwordx4 v[228:229], off
	v_lshl_add_u64 v[228:229], s[36:37], 0, v[134:135]
	s_mov_b32 m0, s51
	s_nop 0
	global_load_lds_dwordx4 v[228:229], off
	s_waitcnt vmcnt(8)
	s_waitcnt lgkmcnt(0)
	s_setprio 1
	s_barrier
	v_mfma_f32_16x16x32_bf16 v[124:127], v[128:131], v[184:187], v[124:127]
	v_mfma_f32_16x16x32_bf16 v[120:123], v[150:153], v[184:187], v[120:123]
	v_mfma_f32_16x16x32_bf16 v[108:111], v[128:131], v[192:195], v[108:111]
	v_mfma_f32_16x16x32_bf16 v[104:107], v[150:153], v[192:195], v[104:107]
	v_mfma_f32_16x16x32_bf16 v[92:95], v[128:131], v[200:203], v[92:95]
	v_mfma_f32_16x16x32_bf16 v[88:91], v[150:153], v[200:203], v[88:91]
	v_mfma_f32_16x16x32_bf16 v[76:79], v[128:131], v[208:211], v[76:79]
	v_mfma_f32_16x16x32_bf16 v[72:75], v[150:153], v[208:211], v[72:75]
	v_mfma_f32_16x16x32_bf16 v[124:127], v[146:149], v[188:191], v[124:127]
	v_mfma_f32_16x16x32_bf16 v[120:123], v[154:157], v[188:191], v[120:123]
	v_mfma_f32_16x16x32_bf16 v[108:111], v[146:149], v[196:199], v[108:111]
	v_mfma_f32_16x16x32_bf16 v[104:107], v[154:157], v[196:199], v[104:107]
	v_mfma_f32_16x16x32_bf16 v[92:95], v[146:149], v[204:207], v[92:95]
	v_mfma_f32_16x16x32_bf16 v[88:91], v[154:157], v[204:207], v[88:91]
	v_mfma_f32_16x16x32_bf16 v[76:79], v[146:149], v[212:215], v[76:79]
	v_mfma_f32_16x16x32_bf16 v[72:75], v[154:157], v[212:215], v[72:75]
	v_mfma_f32_16x16x32_bf16 v[116:119], v[158:161], v[184:187], v[116:119]
	v_mfma_f32_16x16x32_bf16 v[112:115], v[176:179], v[184:187], v[112:115]
	v_mfma_f32_16x16x32_bf16 v[100:103], v[158:161], v[192:195], v[100:103]
	v_mfma_f32_16x16x32_bf16 v[96:99], v[176:179], v[192:195], v[96:99]
	v_mfma_f32_16x16x32_bf16 v[84:87], v[158:161], v[200:203], v[84:87]
	v_mfma_f32_16x16x32_bf16 v[80:83], v[176:179], v[200:203], v[80:83]
	v_mfma_f32_16x16x32_bf16 v[68:71], v[158:161], v[208:211], v[68:71]
	v_mfma_f32_16x16x32_bf16 v[64:67], v[176:179], v[208:211], v[64:67]
	v_mfma_f32_16x16x32_bf16 v[116:119], v[172:175], v[188:191], v[116:119]
	v_mfma_f32_16x16x32_bf16 v[112:115], v[180:183], v[188:191], v[112:115]
	v_mfma_f32_16x16x32_bf16 v[100:103], v[172:175], v[196:199], v[100:103]
	v_mfma_f32_16x16x32_bf16 v[96:99], v[180:183], v[196:199], v[96:99]
	v_mfma_f32_16x16x32_bf16 v[84:87], v[172:175], v[204:207], v[84:87]
	v_mfma_f32_16x16x32_bf16 v[80:83], v[180:183], v[204:207], v[80:83]
	v_mfma_f32_16x16x32_bf16 v[68:71], v[172:175], v[212:215], v[68:71]
	s_setprio 2
	s_barrier
; #define PG8_STAGE(bufoff, gbase, voff) do { _Pragma("unroll") for (int _i = 0; _i < 2; ++_i) \
;         __builtin_amdgcn_global_load_lds((const unsigned*)((const char*)(gbase) + (voff)[_i]), (PG8_LAS unsigned*)(lds + (bufoff) + ldsw + _i * 8192), 16, 0, 0); } while (0)
; #define PG8_LDA(dst, b, h) do { _Pragma("unroll") for (int m = 0; m < 4; ++m) _Pragma("unroll") for (int k = 0; k < 2; ++k) dst[m][k] = *(const PG8_LAS bf16x8*)(lds + PG8_SA(b, h) + aoff + m * 2048 + k * 1024); } while (0)
; #define PG8_WAIT_V(n) asm volatile("s_waitcnt vmcnt(" #n ")" ::: "memory")
; #define PG8_WAIT_L(n) asm volatile("s_waitcnt lgkmcnt(" #n ")" ::: "memory")
; #define PG8_BAR __builtin_amdgcn_s_barrier()
; template <class Epi, class Sched, bool ALIGN_EPI = false, bool SP2 = false>
; __device__ __forceinline__ void gemm_phase(PG8_LAS unsigned char* lds, const Gemm g, const Sched& S, const Epi& E, const int wid) {
;     ...
;         for (int t = 0; t < nt; t += 2) {
;             const bool last = (t == nt - 2);
;             const char* a1 = cA + (size_t)(t + 1) * kstep;
;             const char* a2 = last ? nA : cA + (size_t)(t + 2) * kstep; const char* b2 = last ? nB : cB + (size_t)(t + 2) * kstep;
;             const char* a3 = a2 + kstep; const char* b3 = b2 + kstep;
;             if (last && has_next) S.a_ready(nxt);
;             if constexpr (SP2) {
;             PG8_LDB(B0, 0, 0); PG8_LDB(B1, 0, 1); PG8_SCHED; PG8_LDA(At, 0, 0); PG8_STAGE(PG8_SA(1, 1), a1 + hstep, voffA);
;             PG8_WAIT_V(8); PG8_WAIT_L(0); PG8_BAR; PG8_MMA(0, 0, At, B0); PG8_MMA(0, 1, At, B1); PG8_BAR; PG8_SCHED;
;             PG8_LDA(At, 0, 1); PG8_STAGE(PG8_SB(0, 0), b2, voffB); PG8_STAGE(PG8_SB(0, 1), b2 + hstep, voffB); PG8_STAGE(PG8_SA(0, 0), a2, voffA);
;             PG8_WAIT_V(8); PG8_WAIT_L(0); PG8_BAR; PG8_MMA(1, 0, At, B0); PG8_MMA(1, 1, At, B1); PG8_BAR; PG8_SCHED;
;             PG8_LDB(B0, 1, 0); PG8_LDB(B1, 1, 1); PG8_SCHED; PG8_LDA(At, 1, 0); PG8_STAGE(PG8_SA(0, 1), a2 + hstep, voffA);
;             PG8_WAIT_V(8); PG8_WAIT_L(0); PG8_BAR; PG8_MMA(0, 0, At, B0); PG8_MMA(0, 1, At, B1); PG8_BAR; PG8_SCHED;
;             PG8_LDA(At, 1, 1); PG8_STAGE(PG8_SB(1, 0), b3, voffB); PG8_STAGE(PG8_SB(1, 1), b3 + hstep, voffB); PG8_STAGE(PG8_SA(1, 0), a3, voffA);
;             PG8_WAIT_V(8); PG8_WAIT_L(0); PG8_BAR; PG8_MMA(1, 0, At, B0); PG8_MMA(1, 1, At, B1); PG8_BAR; PG8_SCHED;
	v_mfma_f32_16x16x32_bf16 v[64:67], v[180:183], v[212:215], v[64:67]
	s_setprio 0
	s_add_i32 s33, s33, s40
	v_lshl_add_u64 v[216:217], v[216:217], 0, s[22:23]
	s_mov_b32 m0, s33
	ds_read_b128 v[184:187], v167 offset:49152
	ds_read_b128 v[188:191], v167 offset:50176
	ds_read_b128 v[192:195], v167 offset:51200
	ds_read_b128 v[196:199], v167 offset:52224
	ds_read_b128 v[200:203], v167 offset:53248
	ds_read_b128 v[204:207], v167 offset:54272
	ds_read_b128 v[208:211], v167 offset:55296
	ds_read_b128 v[212:215], v167 offset:56320
	global_load_lds_dwordx4 v[216:217], off
	v_lshl_add_u64 v[216:217], v[218:219], 0, s[22:23]
	s_add_i32 m0, s33, 0x2000
	s_add_i32 s33, s39, s40
	global_load_lds_dwordx4 v[216:217], off
	v_lshl_add_u64 v[216:217], v[220:221], 0, s[22:23]
	s_mov_b32 m0, s33
	s_nop 0
	global_load_lds_dwordx4 v[216:217], off
	v_lshl_add_u64 v[216:217], v[222:223], 0, s[22:23]
	s_add_i32 m0, s33, 0x2000
	s_nop 0
	global_load_lds_dwordx4 v[216:217], off
	v_lshl_add_u64 v[216:217], v[224:225], 0, s[22:23]
	s_mov_b32 m0, s53
	s_nop 0
	global_load_lds_dwordx4 v[216:217], off
	v_lshl_add_u64 v[216:217], v[226:227], 0, s[22:23]
	s_mov_b32 m0, s54
	s_nop 0
	global_load_lds_dwordx4 v[216:217], off
	s_waitcnt vmcnt(8)
	s_waitcnt lgkmcnt(0)
	s_setprio 1
	s_barrier
	v_mfma_f32_16x16x32_bf16 v[60:63], v[128:131], v[184:187], v[60:63]
	v_mfma_f32_16x16x32_bf16 v[56:59], v[150:153], v[184:187], v[56:59]
	v_mfma_f32_16x16x32_bf16 v[44:47], v[128:131], v[192:195], v[44:47]
	v_mfma_f32_16x16x32_bf16 v[40:43], v[150:153], v[192:195], v[40:43]
	v_mfma_f32_16x16x32_bf16 v[28:31], v[128:131], v[200:203], v[28:31]
	v_mfma_f32_16x16x32_bf16 v[24:27], v[150:153], v[200:203], v[24:27]
	v_mfma_f32_16x16x32_bf16 v[12:15], v[128:131], v[208:211], v[12:15]
	v_mfma_f32_16x16x32_bf16 v[8:11], v[150:153], v[208:211], v[8:11]
	v_mfma_f32_16x16x32_bf16 v[60:63], v[146:149], v[188:191], v[60:63]
	v_mfma_f32_16x16x32_bf16 v[56:59], v[154:157], v[188:191], v[56:59]
	v_mfma_f32_16x16x32_bf16 v[44:47], v[146:149], v[196:199], v[44:47]
	v_mfma_f32_16x16x32_bf16 v[40:43], v[154:157], v[196:199], v[40:43]
	v_mfma_f32_16x16x32_bf16 v[28:31], v[146:149], v[204:207], v[28:31]
	v_mfma_f32_16x16x32_bf16 v[24:27], v[154:157], v[204:207], v[24:27]
	v_mfma_f32_16x16x32_bf16 v[12:15], v[146:149], v[212:215], v[12:15]
	v_mfma_f32_16x16x32_bf16 v[8:11], v[154:157], v[212:215], v[8:11]
	v_mfma_f32_16x16x32_bf16 v[52:55], v[158:161], v[184:187], v[52:55]
	v_mfma_f32_16x16x32_bf16 v[48:51], v[176:179], v[184:187], v[48:51]
	v_mfma_f32_16x16x32_bf16 v[36:39], v[158:161], v[192:195], v[36:39]
	v_mfma_f32_16x16x32_bf16 v[32:35], v[176:179], v[192:195], v[32:35]
	v_mfma_f32_16x16x32_bf16 v[20:23], v[158:161], v[200:203], v[20:23]
	v_mfma_f32_16x16x32_bf16 v[16:19], v[176:179], v[200:203], v[16:19]
	v_mfma_f32_16x16x32_bf16 v[4:7], v[158:161], v[208:211], v[4:7]
	v_mfma_f32_16x16x32_bf16 v[0:3], v[176:179], v[208:211], v[0:3]
	v_mfma_f32_16x16x32_bf16 v[52:55], v[172:175], v[188:191], v[52:55]
	v_mfma_f32_16x16x32_bf16 v[48:51], v[180:183], v[188:191], v[48:51]
	v_mfma_f32_16x16x32_bf16 v[36:39], v[172:175], v[196:199], v[36:39]
	v_mfma_f32_16x16x32_bf16 v[32:35], v[180:183], v[196:199], v[32:35]
	v_mfma_f32_16x16x32_bf16 v[20:23], v[172:175], v[204:207], v[20:23]
	v_mfma_f32_16x16x32_bf16 v[16:19], v[180:183], v[204:207], v[16:19]
	v_mfma_f32_16x16x32_bf16 v[4:7], v[172:175], v[212:215], v[4:7]
	s_setprio 2
	s_barrier
	v_mfma_f32_16x16x32_bf16 v[0:3], v[180:183], v[212:215], v[0:3]
	s_setprio 0
	s_add_u32 s4, s4, 0x100
	s_addc_u32 s5, s5, 0
	s_add_u32 s0, s0, 0x100
	s_addc_u32 s1, s1, 0
	s_cmp_ge_i32 s38, s55
	s_mov_b32 s36, s38
	s_cbranch_scc0 .LBB0_20

; #define PG8_WAIT_V(n) asm volatile("s_waitcnt vmcnt(" #n ")" ::: "memory")
; #define PG8_BAR __builtin_amdgcn_s_barrier()
; template <class Epi, class Sched, bool ALIGN_EPI = false, bool SP2 = false>
; __device__ __forceinline__ void gemm_phase(PG8_LAS unsigned char* lds, const Gemm g, const Sched& S, const Epi& E, const int wid) {
;     ...
;         const bool has_next = S.next(ui + 1, nxt);
;         const char* nA = has_next ? (const char*)g.A + (size_t)nxt.pm * tstep : cA; const char* nB = has_next ? (const char*)g.Bt + (size_t)nxt.pn * tstep : cB;
;         for (int t = 0; t < nt; t += 2) {
;             const bool last = (t == nt - 2);
;             const char* a1 = cA + (size_t)(t + 1) * kstep;
;             const char* a2 = last ? nA : cA + (size_t)(t + 2) * kstep; const char* b2 = last ? nB : cB + (size_t)(t + 2) * kstep;
;             const char* a3 = a2 + kstep; const char* b3 = b2 + kstep;
;             if (last && has_next) S.a_ready(nxt);
;             if constexpr (SP2) {
;             PG8_LDB(B0, 0, 0); PG8_LDB(B1, 0, 1); PG8_SCHED; PG8_LDA(At, 0, 0); PG8_STAGE(PG8_SA(1, 1), a1 + hstep, voffA);
;             PG8_WAIT_V(8); PG8_WAIT_L(0); PG8_BAR; PG8_MMA(0, 0, At, B0); PG8_MMA(0, 1, At, B1); PG8_BAR; PG8_SCHED;
;             PG8_LDA(At, 0, 1); PG8_STAGE(PG8_SB(0, 0), b2, voffB); PG8_STAGE(PG8_SB(0, 1), b2 + hstep, voffB); PG8_STAGE(PG8_SA(0, 0), a2, voffA);
;             PG8_WAIT_V(8); PG8_WAIT_L(0); PG8_BAR; PG8_MMA(1, 0, At, B0); PG8_MMA(1, 1, At, B1); PG8_BAR; PG8_SCHED;
;             PG8_LDB(B0, 1, 0); PG8_LDB(B1, 1, 1); PG8_SCHED; PG8_LDA(At, 1, 0); PG8_STAGE(PG8_SA(0, 1), a2 + hstep, voffA);
;             PG8_WAIT_V(8); PG8_WAIT_L(0); PG8_BAR; PG8_MMA(0, 0, At, B0); PG8_MMA(0, 1, At, B1); PG8_BAR; PG8_SCHED;
;             PG8_LDA(At, 1, 1); PG8_STAGE(PG8_SB(1, 0), b3, voffB); PG8_STAGE(PG8_SB(1, 1), b3 + hstep, voffB); PG8_STAGE(PG8_SA(1, 0), a3, voffA);
;             PG8_WAIT_V(8); PG8_WAIT_L(0); PG8_BAR; PG8_MMA(1, 0, At, B0); PG8_MMA(1, 1, At, B1); PG8_BAR; PG8_SCHED;
;             } else {
;             PG8_LDB(B0, 0, 0); PG8_SCHED; PG8_LDA(At, 0, 0); PG8_STAGE(PG8_SA(1, 1), a1 + hstep, voffA);
;             PG8_WAIT_L(8); PG8_BAR; PG8_WAIT_L(0); PG8_MMA(0, 0, At, B0); PG8_BAR; PG8_SCHED;
;             PG8_LDB(B1, 0, 1); PG8_STAGE(PG8_SB(0, 0), b2, voffB);
;             PG8_BAR; PG8_WAIT_L(0); PG8_MMA(0, 1, At, B1); PG8_BAR;
.LBB0_1098:
	s_andn2_b64 vcc, exec, s[28:29]
	s_cbranch_vccnz .Lz_G1B
	s_add_u32 s4, s8, 0x80
	s_addc_u32 s5, s9, 0
	s_add_u32 s0, s6, 0x100
	s_addc_u32 s1, s7, 0
	s_mov_b32 s6, 0
	ds_read_b128 v[44:47], v163
	ds_read_b128 v[52:55], v163 offset:1024
	ds_read_b128 v[60:63], v163 offset:2048
	ds_read_b128 v[68:71], v163 offset:3072
	ds_read_b128 v[166:169], v164
	ds_read_b128 v[170:173], v164 offset:1024
	ds_read_b128 v[174:177], v164 offset:2048
	ds_read_b128 v[178:181], v164 offset:3072
	s_add_i32 s8, s6, 2
	s_add_u32 s9, s4, 0x80
	s_addc_u32 s7, s5, 0
	s_cmp_eq_u32 s72, s6
	s_cselect_b32 s6, s48, s9
	s_cselect_b32 s7, s49, s7
	s_cselect_b32 s77, s51, s1
	s_cselect_b32 s76, s50, s0
	v_lshl_add_u64 v[158:159], s[4:5], 0, v[152:153]
	s_add_i32 m0, s63, 0xc000
	ds_read_b128 v[182:185], v165
	ds_read_b128 v[186:189], v165 offset:1024
	ds_read_b128 v[190:193], v165 offset:2048
	ds_read_b128 v[194:197], v165 offset:3072
	ds_read_b128 v[198:201], v165 offset:4096
	ds_read_b128 v[202:205], v165 offset:5120
	ds_read_b128 v[206:209], v165 offset:6144
	ds_read_b128 v[210:213], v165 offset:7168
	global_load_lds_dwordx4 v[158:159], off
	v_lshl_add_u64 v[158:159], s[4:5], 0, v[154:155]
	s_add_i32 m0, s63, 0xe000
	s_nop 0
	global_load_lds_dwordx4 v[158:159], off
	s_waitcnt vmcnt(8)
	s_waitcnt lgkmcnt(0)
	s_setprio 1
	s_barrier
	v_mfma_f32_16x16x32_bf16 v[140:143], v[44:47], v[182:185], 0
	v_mfma_f32_16x16x32_bf16 v[136:139], v[60:63], v[182:185], 0
	v_mfma_f32_16x16x32_bf16 v[124:127], v[44:47], v[190:193], 0
	v_mfma_f32_16x16x32_bf16 v[120:123], v[60:63], v[190:193], 0
	v_mfma_f32_16x16x32_bf16 v[108:111], v[44:47], v[198:201], 0
	v_mfma_f32_16x16x32_bf16 v[104:107], v[60:63], v[198:201], 0
	v_mfma_f32_16x16x32_bf16 v[92:95], v[44:47], v[206:209], 0
	v_mfma_f32_16x16x32_bf16 v[88:91], v[60:63], v[206:209], 0
	v_mfma_f32_16x16x32_bf16 v[140:143], v[52:55], v[186:189], v[140:143]
	v_mfma_f32_16x16x32_bf16 v[136:139], v[68:71], v[186:189], v[136:139]
	v_mfma_f32_16x16x32_bf16 v[124:127], v[52:55], v[194:197], v[124:127]
	v_mfma_f32_16x16x32_bf16 v[120:123], v[68:71], v[194:197], v[120:123]
	v_mfma_f32_16x16x32_bf16 v[108:111], v[52:55], v[202:205], v[108:111]
	v_mfma_f32_16x16x32_bf16 v[104:107], v[68:71], v[202:205], v[104:107]
	v_mfma_f32_16x16x32_bf16 v[92:95], v[52:55], v[210:213], v[92:95]
	v_mfma_f32_16x16x32_bf16 v[88:91], v[68:71], v[210:213], v[88:91]
	v_mfma_f32_16x16x32_bf16 v[132:135], v[166:169], v[182:185], 0
	v_mfma_f32_16x16x32_bf16 v[128:131], v[174:177], v[182:185], 0
	v_mfma_f32_16x16x32_bf16 v[116:119], v[166:169], v[190:193], 0
	v_mfma_f32_16x16x32_bf16 v[112:115], v[174:177], v[190:193], 0
	v_mfma_f32_16x16x32_bf16 v[100:103], v[166:169], v[198:201], 0
	v_mfma_f32_16x16x32_bf16 v[96:99], v[174:177], v[198:201], 0
	v_mfma_f32_16x16x32_bf16 v[84:87], v[166:169], v[206:209], 0
	v_mfma_f32_16x16x32_bf16 v[80:83], v[174:177], v[206:209], 0
	v_mfma_f32_16x16x32_bf16 v[132:135], v[170:173], v[186:189], v[132:135]
	v_mfma_f32_16x16x32_bf16 v[128:131], v[178:181], v[186:189], v[128:131]
	v_mfma_f32_16x16x32_bf16 v[116:119], v[170:173], v[194:197], v[116:119]
	v_mfma_f32_16x16x32_bf16 v[112:115], v[178:181], v[194:197], v[112:115]
	v_mfma_f32_16x16x32_bf16 v[100:103], v[170:173], v[202:205], v[100:103]
	v_mfma_f32_16x16x32_bf16 v[96:99], v[178:181], v[202:205], v[96:99]
	v_mfma_f32_16x16x32_bf16 v[84:87], v[170:173], v[210:213], v[84:87]
	s_setprio 2
	s_barrier
	v_mfma_f32_16x16x32_bf16 v[80:83], v[178:181], v[210:213], v[80:83]
	s_setprio 0
	s_add_i32 s9, s75, s55
	v_lshl_add_u64 v[158:159], s[76:77], 0, v[148:149]
	s_mov_b32 m0, s9
	ds_read_b128 v[182:185], v165 offset:16384
	ds_read_b128 v[186:189], v165 offset:17408
	ds_read_b128 v[190:193], v165 offset:18432
	ds_read_b128 v[194:197], v165 offset:19456
	ds_read_b128 v[198:201], v165 offset:20480
	ds_read_b128 v[202:205], v165 offset:21504
	ds_read_b128 v[206:209], v165 offset:22528
	ds_read_b128 v[210:213], v165 offset:23552
	global_load_lds_dwordx4 v[158:159], off
	s_add_i32 m0, s9, 0x2000
	v_lshl_add_u64 v[214:215], s[76:77], 0, v[144:145]
	s_add_u32 s76, s76, s12
	s_addc_u32 s77, s77, s13
	s_add_i32 s9, s78, s55
	global_load_lds_dwordx4 v[214:215], off
	v_lshl_add_u64 v[216:217], s[76:77], 0, v[148:149]
	s_mov_b32 m0, s9
	v_lshl_add_u64 v[218:219], s[76:77], 0, v[144:145]
	global_load_lds_dwordx4 v[216:217], off
	s_add_i32 m0, s9, 0x2000
	v_lshl_add_u64 v[220:221], s[6:7], 0, v[150:151]
	global_load_lds_dwordx4 v[218:219], off
	s_mov_b32 m0, s63
	v_lshl_add_u64 v[222:223], s[6:7], 0, v[146:147]
	global_load_lds_dwordx4 v[220:221], off
	s_mov_b32 m0, s64
	s_nop 0
	global_load_lds_dwordx4 v[222:223], off
	s_waitcnt vmcnt(8)
	s_waitcnt lgkmcnt(0)
	s_setprio 1
	s_barrier
; #define PG8_STAGE(bufoff, gbase, voff) do { _Pragma("unroll") for (int _i = 0; _i < 2; ++_i) \
;         __builtin_amdgcn_global_load_lds((const unsigned*)((const char*)(gbase) + (voff)[_i]), (PG8_LAS unsigned*)(lds + (bufoff) + ldsw + _i * 8192), 16, 0, 0); } while (0)
; #define PG8_LDA(dst, b, h) do { _Pragma("unroll") for (int m = 0; m < 4; ++m) _Pragma("unroll") for (int k = 0; k < 2; ++k) dst[m][k] = *(const PG8_LAS bf16x8*)(lds + PG8_SA(b, h) + aoff + m * 2048 + k * 1024); } while (0)
; #define PG8_LDB(dst, b, h) do { _Pragma("unroll") for (int n = 0; n < 2; ++n) _Pragma("unroll") for (int k = 0; k < 2; ++k) dst[n][k] = *(const PG8_LAS bf16x8*)(lds + PG8_SB(b, h) + boff + n * 2048 + k * 1024); } while (0)
; #define PG8_MMA(ai, bj, At, Bt) do { __builtin_amdgcn_s_setprio(1); _Pragma("unroll") for (int m = 0; m < 4; ++m) _Pragma("unroll") for (int n = 0; n < 2; ++n) _Pragma("unroll") for (int k = 0; k < 2; ++k) \
;         acc[ai][bj][m][n] = __builtin_amdgcn_mfma_f32_16x16x32_bf16(Bt[n][k], At[m][k], acc[ai][bj][m][n], 0, 0, 0); __builtin_amdgcn_s_setprio(0); } while (0)
; #define PG8_WAIT_V(n) asm volatile("s_waitcnt vmcnt(" #n ")" ::: "memory")
; #define PG8_WAIT_L(n) asm volatile("s_waitcnt lgkmcnt(" #n ")" ::: "memory")
; template <class Epi, class Sched, bool ALIGN_EPI = false, bool SP2 = false>
; __device__ __forceinline__ void gemm_phase(PG8_LAS unsigned char* lds, const Gemm g, const Sched& S, const Epi& E, const int wid) {
;     ...
;             PG8_WAIT_V(8); PG8_WAIT_L(0); PG8_BAR; PG8_MMA(0, 0, At, B0); PG8_MMA(0, 1, At, B1); PG8_BAR; PG8_SCHED;
;             PG8_LDA(At, 0, 1); PG8_STAGE(PG8_SB(0, 0), b2, voffB); PG8_STAGE(PG8_SB(0, 1), b2 + hstep, voffB); PG8_STAGE(PG8_SA(0, 0), a2, voffA);
;             PG8_WAIT_V(8); PG8_WAIT_L(0); PG8_BAR; PG8_MMA(1, 0, At, B0); PG8_MMA(1, 1, At, B1); PG8_BAR; PG8_SCHED;
;             PG8_LDB(B0, 1, 0); PG8_LDB(B1, 1, 1); PG8_SCHED; PG8_LDA(At, 1, 0); PG8_STAGE(PG8_SA(0, 1), a2 + hstep, voffA);
;             PG8_WAIT_V(8); PG8_WAIT_L(0); PG8_BAR; PG8_MMA(0, 0, At, B0); PG8_MMA(0, 1, At, B1); PG8_BAR; PG8_SCHED;
;             PG8_LDA(At, 1, 1); PG8_STAGE(PG8_SB(1, 0), b3, voffB); PG8_STAGE(PG8_SB(1, 1), b3 + hstep, voffB); PG8_STAGE(PG8_SA(1, 0), a3, voffA);
;             PG8_WAIT_V(8); PG8_WAIT_L(0); PG8_BAR; PG8_MMA(1, 0, At, B0); PG8_MMA(1, 1, At, B1); PG8_BAR; PG8_SCHED;
	v_mfma_f32_16x16x32_bf16 v[76:79], v[44:47], v[182:185], 0
	v_mfma_f32_16x16x32_bf16 v[72:75], v[60:63], v[182:185], 0
	v_mfma_f32_16x16x32_bf16 v[48:51], v[44:47], v[190:193], 0
	v_mfma_f32_16x16x32_bf16 v[40:43], v[60:63], v[190:193], 0
	v_mfma_f32_16x16x32_bf16 v[28:31], v[44:47], v[198:201], 0
	v_mfma_f32_16x16x32_bf16 v[24:27], v[60:63], v[198:201], 0
	v_mfma_f32_16x16x32_bf16 v[12:15], v[44:47], v[206:209], 0
	v_mfma_f32_16x16x32_bf16 v[8:11], v[60:63], v[206:209], 0
	v_mfma_f32_16x16x32_bf16 v[76:79], v[52:55], v[186:189], v[76:79]
	v_mfma_f32_16x16x32_bf16 v[72:75], v[68:71], v[186:189], v[72:75]
	v_mfma_f32_16x16x32_bf16 v[48:51], v[52:55], v[194:197], v[48:51]
	v_mfma_f32_16x16x32_bf16 v[40:43], v[68:71], v[194:197], v[40:43]
	v_mfma_f32_16x16x32_bf16 v[28:31], v[52:55], v[202:205], v[28:31]
	v_mfma_f32_16x16x32_bf16 v[24:27], v[68:71], v[202:205], v[24:27]
	v_mfma_f32_16x16x32_bf16 v[12:15], v[52:55], v[210:213], v[12:15]
	v_mfma_f32_16x16x32_bf16 v[8:11], v[68:71], v[210:213], v[8:11]
	v_mfma_f32_16x16x32_bf16 v[36:39], v[166:169], v[190:193], 0
	v_mfma_f32_16x16x32_bf16 v[32:35], v[174:177], v[190:193], 0
	v_mfma_f32_16x16x32_bf16 v[20:23], v[166:169], v[198:201], 0
	v_mfma_f32_16x16x32_bf16 v[16:19], v[174:177], v[198:201], 0
	v_mfma_f32_16x16x32_bf16 v[4:7], v[166:169], v[206:209], 0
	v_mfma_f32_16x16x32_bf16 v[0:3], v[174:177], v[206:209], 0
	v_mfma_f32_16x16x32_bf16 v[44:47], v[166:169], v[182:185], 0
	v_mfma_f32_16x16x32_bf16 v[52:55], v[174:177], v[182:185], 0
	v_mfma_f32_16x16x32_bf16 v[36:39], v[170:173], v[194:197], v[36:39]
	v_mfma_f32_16x16x32_bf16 v[32:35], v[178:181], v[194:197], v[32:35]
	v_mfma_f32_16x16x32_bf16 v[20:23], v[170:173], v[202:205], v[20:23]
	v_mfma_f32_16x16x32_bf16 v[16:19], v[178:181], v[202:205], v[16:19]
	v_mfma_f32_16x16x32_bf16 v[4:7], v[170:173], v[210:213], v[4:7]
	v_mfma_f32_16x16x32_bf16 v[0:3], v[178:181], v[210:213], v[0:3]
	v_mfma_f32_16x16x32_bf16 v[44:47], v[170:173], v[186:189], v[44:47]
	s_setprio 2
	s_barrier
	v_mfma_f32_16x16x32_bf16 v[52:55], v[178:181], v[186:189], v[52:55]
	s_setprio 0
	s_add_i32 s9, 0, 0x18000
	s_add_i32 s33, 0, 0x1c000
	v_add_u32_e32 v68, s9, v162
	v_add_u32_e32 v178, s33, v162
	ds_read_b128 v[56:59], v68
	ds_read_b128 v[60:63], v68 offset:1024
	ds_read_b128 v[64:67], v68 offset:2048
	ds_read_b128 v[68:71], v68 offset:3072
	ds_read_b128 v[166:169], v178
	ds_read_b128 v[170:173], v178 offset:1024
	ds_read_b128 v[174:177], v178 offset:2048
	ds_read_b128 v[178:181], v178 offset:3072
	s_add_u32 s6, s6, s12
	s_addc_u32 s7, s7, s13
	s_mov_b32 m0, s65
	v_lshl_add_u64 v[224:225], s[6:7], 0, v[150:151]
	ds_read_b128 v[182:185], v165 offset:32768
	ds_read_b128 v[186:189], v165 offset:33792
	ds_read_b128 v[190:193], v165 offset:34816
	ds_read_b128 v[194:197], v165 offset:35840
	ds_read_b128 v[198:201], v165 offset:36864
	ds_read_b128 v[202:205], v165 offset:37888
	ds_read_b128 v[206:209], v165 offset:38912
	ds_read_b128 v[210:213], v165 offset:39936
	global_load_lds_dwordx4 v[224:225], off
	v_lshl_add_u64 v[224:225], s[6:7], 0, v[146:147]
	s_mov_b32 m0, s66
	s_nop 0
	global_load_lds_dwordx4 v[224:225], off
	s_waitcnt vmcnt(8)
	s_waitcnt lgkmcnt(0)
	s_setprio 1
	s_barrier
	v_mfma_f32_16x16x32_bf16 v[140:143], v[56:59], v[182:185], v[140:143]
	v_mfma_f32_16x16x32_bf16 v[136:139], v[64:67], v[182:185], v[136:139]
	v_mfma_f32_16x16x32_bf16 v[124:127], v[56:59], v[190:193], v[124:127]
	v_mfma_f32_16x16x32_bf16 v[120:123], v[64:67], v[190:193], v[120:123]
	v_mfma_f32_16x16x32_bf16 v[108:111], v[56:59], v[198:201], v[108:111]
	v_mfma_f32_16x16x32_bf16 v[104:107], v[64:67], v[198:201], v[104:107]
	v_mfma_f32_16x16x32_bf16 v[92:95], v[56:59], v[206:209], v[92:95]
	v_mfma_f32_16x16x32_bf16 v[88:91], v[64:67], v[206:209], v[88:91]
	v_mfma_f32_16x16x32_bf16 v[140:143], v[60:63], v[186:189], v[140:143]
	v_mfma_f32_16x16x32_bf16 v[136:139], v[68:71], v[186:189], v[136:139]
	v_mfma_f32_16x16x32_bf16 v[124:127], v[60:63], v[194:197], v[124:127]
	v_mfma_f32_16x16x32_bf16 v[120:123], v[68:71], v[194:197], v[120:123]
	v_mfma_f32_16x16x32_bf16 v[108:111], v[60:63], v[202:205], v[108:111]
	v_mfma_f32_16x16x32_bf16 v[104:107], v[68:71], v[202:205], v[104:107]
	v_mfma_f32_16x16x32_bf16 v[92:95], v[60:63], v[210:213], v[92:95]
	v_mfma_f32_16x16x32_bf16 v[88:91], v[68:71], v[210:213], v[88:91]
	v_mfma_f32_16x16x32_bf16 v[132:135], v[166:169], v[182:185], v[132:135]
	v_mfma_f32_16x16x32_bf16 v[128:131], v[174:177], v[182:185], v[128:131]
	v_mfma_f32_16x16x32_bf16 v[116:119], v[166:169], v[190:193], v[116:119]
	v_mfma_f32_16x16x32_bf16 v[112:115], v[174:177], v[190:193], v[112:115]
	v_mfma_f32_16x16x32_bf16 v[100:103], v[166:169], v[198:201], v[100:103]
	v_mfma_f32_16x16x32_bf16 v[96:99], v[174:177], v[198:201], v[96:99]
	v_mfma_f32_16x16x32_bf16 v[84:87], v[166:169], v[206:209], v[84:87]
	v_mfma_f32_16x16x32_bf16 v[80:83], v[174:177], v[206:209], v[80:83]
	v_mfma_f32_16x16x32_bf16 v[132:135], v[170:173], v[186:189], v[132:135]
	v_mfma_f32_16x16x32_bf16 v[128:131], v[178:181], v[186:189], v[128:131]
	v_mfma_f32_16x16x32_bf16 v[116:119], v[170:173], v[194:197], v[116:119]
	v_mfma_f32_16x16x32_bf16 v[112:115], v[178:181], v[194:197], v[112:115]
	v_mfma_f32_16x16x32_bf16 v[100:103], v[170:173], v[202:205], v[100:103]
	v_mfma_f32_16x16x32_bf16 v[96:99], v[178:181], v[202:205], v[96:99]
	v_mfma_f32_16x16x32_bf16 v[84:87], v[170:173], v[210:213], v[84:87]
	s_setprio 2
	s_barrier
; #define PG8_STAGE(bufoff, gbase, voff) do { _Pragma("unroll") for (int _i = 0; _i < 2; ++_i) \
;         __builtin_amdgcn_global_load_lds((const unsigned*)((const char*)(gbase) + (voff)[_i]), (PG8_LAS unsigned*)(lds + (bufoff) + ldsw + _i * 8192), 16, 0, 0); } while (0)
; #define PG8_LDA(dst, b, h) do { _Pragma("unroll") for (int m = 0; m < 4; ++m) _Pragma("unroll") for (int k = 0; k < 2; ++k) dst[m][k] = *(const PG8_LAS bf16x8*)(lds + PG8_SA(b, h) + aoff + m * 2048 + k * 1024); } while (0)
; #define PG8_WAIT_V(n) asm volatile("s_waitcnt vmcnt(" #n ")" ::: "memory")
; #define PG8_WAIT_L(n) asm volatile("s_waitcnt lgkmcnt(" #n ")" ::: "memory")
; #define PG8_BAR __builtin_amdgcn_s_barrier()
; template <class Epi, class Sched, bool ALIGN_EPI = false, bool SP2 = false>
; __device__ __forceinline__ void gemm_phase(PG8_LAS unsigned char* lds, const Gemm g, const Sched& S, const Epi& E, const int wid) {
;     ...
;         for (int t = 0; t < nt; t += 2) {
;             const bool last = (t == nt - 2);
;             const char* a1 = cA + (size_t)(t + 1) * kstep;
;             const char* a2 = last ? nA : cA + (size_t)(t + 2) * kstep; const char* b2 = last ? nB : cB + (size_t)(t + 2) * kstep;
;             const char* a3 = a2 + kstep; const char* b3 = b2 + kstep;
;             if (last && has_next) S.a_ready(nxt);
;             if constexpr (SP2) {
;             PG8_LDB(B0, 0, 0); PG8_LDB(B1, 0, 1); PG8_SCHED; PG8_LDA(At, 0, 0); PG8_STAGE(PG8_SA(1, 1), a1 + hstep, voffA);
;             PG8_WAIT_V(8); PG8_WAIT_L(0); PG8_BAR; PG8_MMA(0, 0, At, B0); PG8_MMA(0, 1, At, B1); PG8_BAR; PG8_SCHED;
;             PG8_LDA(At, 0, 1); PG8_STAGE(PG8_SB(0, 0), b2, voffB); PG8_STAGE(PG8_SB(0, 1), b2 + hstep, voffB); PG8_STAGE(PG8_SA(0, 0), a2, voffA);
;             PG8_WAIT_V(8); PG8_WAIT_L(0); PG8_BAR; PG8_MMA(1, 0, At, B0); PG8_MMA(1, 1, At, B1); PG8_BAR; PG8_SCHED;
;             PG8_LDB(B0, 1, 0); PG8_LDB(B1, 1, 1); PG8_SCHED; PG8_LDA(At, 1, 0); PG8_STAGE(PG8_SA(0, 1), a2 + hstep, voffA);
;             PG8_WAIT_V(8); PG8_WAIT_L(0); PG8_BAR; PG8_MMA(0, 0, At, B0); PG8_MMA(0, 1, At, B1); PG8_BAR; PG8_SCHED;
;             PG8_LDA(At, 1, 1); PG8_STAGE(PG8_SB(1, 0), b3, voffB); PG8_STAGE(PG8_SB(1, 1), b3 + hstep, voffB); PG8_STAGE(PG8_SA(1, 0), a3, voffA);
;             PG8_WAIT_V(8); PG8_WAIT_L(0); PG8_BAR; PG8_MMA(1, 0, At, B0); PG8_MMA(1, 1, At, B1); PG8_BAR; PG8_SCHED;
	v_mfma_f32_16x16x32_bf16 v[80:83], v[178:181], v[210:213], v[80:83]
	s_setprio 0
	s_add_i32 s6, s9, s55
	v_lshl_add_u64 v[158:159], v[158:159], 0, s[26:27]
	s_mov_b32 m0, s6
	ds_read_b128 v[182:185], v165 offset:49152
	ds_read_b128 v[186:189], v165 offset:50176
	ds_read_b128 v[190:193], v165 offset:51200
	ds_read_b128 v[194:197], v165 offset:52224
	ds_read_b128 v[198:201], v165 offset:53248
	ds_read_b128 v[202:205], v165 offset:54272
	ds_read_b128 v[206:209], v165 offset:55296
	ds_read_b128 v[210:213], v165 offset:56320
	global_load_lds_dwordx4 v[158:159], off
	v_lshl_add_u64 v[158:159], v[214:215], 0, s[26:27]
	s_add_i32 m0, s6, 0x2000
	s_add_i32 s6, s33, s55
	global_load_lds_dwordx4 v[158:159], off
	v_lshl_add_u64 v[158:159], v[216:217], 0, s[26:27]
	s_mov_b32 m0, s6
	s_nop 0
	global_load_lds_dwordx4 v[158:159], off
	v_lshl_add_u64 v[158:159], v[218:219], 0, s[26:27]
	s_add_i32 m0, s6, 0x2000
	s_nop 0
	global_load_lds_dwordx4 v[158:159], off
	v_lshl_add_u64 v[158:159], v[220:221], 0, s[26:27]
	s_mov_b32 m0, s68
	s_nop 0
	global_load_lds_dwordx4 v[158:159], off
	v_lshl_add_u64 v[158:159], v[222:223], 0, s[26:27]
	s_mov_b32 m0, s69
	s_nop 0
	global_load_lds_dwordx4 v[158:159], off
	s_waitcnt vmcnt(8)
	s_waitcnt lgkmcnt(0)
	s_setprio 1
	s_barrier
	v_mfma_f32_16x16x32_bf16 v[76:79], v[56:59], v[182:185], v[76:79]
	v_mfma_f32_16x16x32_bf16 v[72:75], v[64:67], v[182:185], v[72:75]
	v_mfma_f32_16x16x32_bf16 v[48:51], v[56:59], v[190:193], v[48:51]
	v_mfma_f32_16x16x32_bf16 v[40:43], v[64:67], v[190:193], v[40:43]
	v_mfma_f32_16x16x32_bf16 v[28:31], v[56:59], v[198:201], v[28:31]
	v_mfma_f32_16x16x32_bf16 v[24:27], v[64:67], v[198:201], v[24:27]
	v_mfma_f32_16x16x32_bf16 v[12:15], v[56:59], v[206:209], v[12:15]
	v_mfma_f32_16x16x32_bf16 v[8:11], v[64:67], v[206:209], v[8:11]
	v_mfma_f32_16x16x32_bf16 v[76:79], v[60:63], v[186:189], v[76:79]
	v_mfma_f32_16x16x32_bf16 v[72:75], v[68:71], v[186:189], v[72:75]
	v_mfma_f32_16x16x32_bf16 v[48:51], v[60:63], v[194:197], v[48:51]
	v_mfma_f32_16x16x32_bf16 v[40:43], v[68:71], v[194:197], v[40:43]
	v_mfma_f32_16x16x32_bf16 v[28:31], v[60:63], v[202:205], v[28:31]
	v_mfma_f32_16x16x32_bf16 v[24:27], v[68:71], v[202:205], v[24:27]
	v_mfma_f32_16x16x32_bf16 v[12:15], v[60:63], v[210:213], v[12:15]
	v_mfma_f32_16x16x32_bf16 v[8:11], v[68:71], v[210:213], v[8:11]
	v_mfma_f32_16x16x32_bf16 v[44:47], v[166:169], v[182:185], v[44:47]
	v_mfma_f32_16x16x32_bf16 v[64:67], v[170:173], v[186:189], v[44:47]
	v_mfma_f32_16x16x32_bf16 v[44:47], v[174:177], v[182:185], v[52:55]
	v_mfma_f32_16x16x32_bf16 v[36:39], v[166:169], v[190:193], v[36:39]
	v_mfma_f32_16x16x32_bf16 v[32:35], v[174:177], v[190:193], v[32:35]
	v_mfma_f32_16x16x32_bf16 v[20:23], v[166:169], v[198:201], v[20:23]
	v_mfma_f32_16x16x32_bf16 v[16:19], v[174:177], v[198:201], v[16:19]
	v_mfma_f32_16x16x32_bf16 v[4:7], v[166:169], v[206:209], v[4:7]
	v_mfma_f32_16x16x32_bf16 v[0:3], v[174:177], v[206:209], v[0:3]
	v_mfma_f32_16x16x32_bf16 v[56:59], v[178:181], v[186:189], v[44:47]
	v_mfma_f32_16x16x32_bf16 v[36:39], v[170:173], v[194:197], v[36:39]
	v_mfma_f32_16x16x32_bf16 v[32:35], v[178:181], v[194:197], v[32:35]
	v_mfma_f32_16x16x32_bf16 v[20:23], v[170:173], v[202:205], v[20:23]
	v_mfma_f32_16x16x32_bf16 v[16:19], v[178:181], v[202:205], v[16:19]
	v_mfma_f32_16x16x32_bf16 v[4:7], v[170:173], v[210:213], v[4:7]
	s_setprio 2
	s_barrier
	v_mfma_f32_16x16x32_bf16 v[0:3], v[178:181], v[210:213], v[0:3]
	s_setprio 0
	s_add_u32 s4, s4, 0x100
	s_addc_u32 s5, s5, 0
	s_add_u32 s0, s0, 0x100
	s_addc_u32 s1, s1, 0
	s_cmp_ge_i32 s8, s70
	s_mov_b32 s6, s8
	s_cbranch_scc1 .LBB0_1101
.LBB0_1100:
	ds_read_b128 v[44:47], v163
	ds_read_b128 v[52:55], v163 offset:1024
	ds_read_b128 v[60:63], v163 offset:2048
	ds_read_b128 v[68:71], v163 offset:3072
	ds_read_b128 v[166:169], v164
	ds_read_b128 v[170:173], v164 offset:1024
	ds_read_b128 v[174:177], v164 offset:2048
	ds_read_b128 v[178:181], v164 offset:3072
	s_add_i32 s8, s6, 2
	s_add_u32 s9, s4, 0x80
	s_addc_u32 s7, s5, 0
	s_cmp_eq_u32 s72, s6
	s_cselect_b32 s6, s48, s9
	s_cselect_b32 s7, s49, s7
	s_cselect_b32 s77, s51, s1
	s_cselect_b32 s76, s50, s0
	v_lshl_add_u64 v[158:159], s[4:5], 0, v[152:153]
	s_add_i32 m0, s63, 0xc000
	ds_read_b128 v[182:185], v165
	ds_read_b128 v[186:189], v165 offset:1024
	ds_read_b128 v[190:193], v165 offset:2048
	ds_read_b128 v[194:197], v165 offset:3072
	ds_read_b128 v[198:201], v165 offset:4096
	ds_read_b128 v[202:205], v165 offset:5120
	ds_read_b128 v[206:209], v165 offset:6144
	ds_read_b128 v[210:213], v165 offset:7168
	global_load_lds_dwordx4 v[158:159], off
	v_lshl_add_u64 v[158:159], s[4:5], 0, v[154:155]
	s_add_i32 m0, s63, 0xe000
	s_nop 0
	global_load_lds_dwordx4 v[158:159], off
	s_waitcnt vmcnt(8)
	s_waitcnt lgkmcnt(0)
	s_setprio 1
	s_barrier
; #define PG8_STAGE(bufoff, gbase, voff) do { _Pragma("unroll") for (int _i = 0; _i < 2; ++_i) \
;         __builtin_amdgcn_global_load_lds((const unsigned*)((const char*)(gbase) + (voff)[_i]), (PG8_LAS unsigned*)(lds + (bufoff) + ldsw + _i * 8192), 16, 0, 0); } while (0)
; #define PG8_LDA(dst, b, h) do { _Pragma("unroll") for (int m = 0; m < 4; ++m) _Pragma("unroll") for (int k = 0; k < 2; ++k) dst[m][k] = *(const PG8_LAS bf16x8*)(lds + PG8_SA(b, h) + aoff + m * 2048 + k * 1024); } while (0)
; #define PG8_WAIT_V(n) asm volatile("s_waitcnt vmcnt(" #n ")" ::: "memory")
; #define PG8_WAIT_L(n) asm volatile("s_waitcnt lgkmcnt(" #n ")" ::: "memory")
; #define PG8_BAR __builtin_amdgcn_s_barrier()
; template <class Epi, class Sched, bool ALIGN_EPI = false, bool SP2 = false>
; __device__ __forceinline__ void gemm_phase(PG8_LAS unsigned char* lds, const Gemm g, const Sched& S, const Epi& E, const int wid) {
;     ...
;         for (int t = 0; t < nt; t += 2) {
;             const bool last = (t == nt - 2);
;             const char* a1 = cA + (size_t)(t + 1) * kstep;
;             const char* a2 = last ? nA : cA + (size_t)(t + 2) * kstep; const char* b2 = last ? nB : cB + (size_t)(t + 2) * kstep;
;             const char* a3 = a2 + kstep; const char* b3 = b2 + kstep;
;             if (last && has_next) S.a_ready(nxt);
;             if constexpr (SP2) {
;             PG8_LDB(B0, 0, 0); PG8_LDB(B1, 0, 1); PG8_SCHED; PG8_LDA(At, 0, 0); PG8_STAGE(PG8_SA(1, 1), a1 + hstep, voffA);
;             PG8_WAIT_V(8); PG8_WAIT_L(0); PG8_BAR; PG8_MMA(0, 0, At, B0); PG8_MMA(0, 1, At, B1); PG8_BAR; PG8_SCHED;
;             PG8_LDA(At, 0, 1); PG8_STAGE(PG8_SB(0, 0), b2, voffB); PG8_STAGE(PG8_SB(0, 1), b2 + hstep, voffB); PG8_STAGE(PG8_SA(0, 0), a2, voffA);
;             PG8_WAIT_V(8); PG8_WAIT_L(0); PG8_BAR; PG8_MMA(1, 0, At, B0); PG8_MMA(1, 1, At, B1); PG8_BAR; PG8_SCHED;
;             PG8_LDB(B0, 1, 0); PG8_LDB(B1, 1, 1); PG8_SCHED; PG8_LDA(At, 1, 0); PG8_STAGE(PG8_SA(0, 1), a2 + hstep, voffA);
;             PG8_WAIT_V(8); PG8_WAIT_L(0); PG8_BAR; PG8_MMA(0, 0, At, B0); PG8_MMA(0, 1, At, B1); PG8_BAR; PG8_SCHED;
;             PG8_LDA(At, 1, 1); PG8_STAGE(PG8_SB(1, 0), b3, voffB); PG8_STAGE(PG8_SB(1, 1), b3 + hstep, voffB); PG8_STAGE(PG8_SA(1, 0), a3, voffA);
;             PG8_WAIT_V(8); PG8_WAIT_L(0); PG8_BAR; PG8_MMA(1, 0, At, B0); PG8_MMA(1, 1, At, B1); PG8_BAR; PG8_SCHED;
	v_mfma_f32_16x16x32_bf16 v[140:143], v[44:47], v[182:185], v[140:143]
	v_mfma_f32_16x16x32_bf16 v[136:139], v[60:63], v[182:185], v[136:139]
	v_mfma_f32_16x16x32_bf16 v[124:127], v[44:47], v[190:193], v[124:127]
	v_mfma_f32_16x16x32_bf16 v[120:123], v[60:63], v[190:193], v[120:123]
	v_mfma_f32_16x16x32_bf16 v[108:111], v[44:47], v[198:201], v[108:111]
	v_mfma_f32_16x16x32_bf16 v[104:107], v[60:63], v[198:201], v[104:107]
	v_mfma_f32_16x16x32_bf16 v[92:95], v[44:47], v[206:209], v[92:95]
	v_mfma_f32_16x16x32_bf16 v[88:91], v[60:63], v[206:209], v[88:91]
	v_mfma_f32_16x16x32_bf16 v[140:143], v[52:55], v[186:189], v[140:143]
	v_mfma_f32_16x16x32_bf16 v[136:139], v[68:71], v[186:189], v[136:139]
	v_mfma_f32_16x16x32_bf16 v[124:127], v[52:55], v[194:197], v[124:127]
	v_mfma_f32_16x16x32_bf16 v[120:123], v[68:71], v[194:197], v[120:123]
	v_mfma_f32_16x16x32_bf16 v[108:111], v[52:55], v[202:205], v[108:111]
	v_mfma_f32_16x16x32_bf16 v[104:107], v[68:71], v[202:205], v[104:107]
	v_mfma_f32_16x16x32_bf16 v[92:95], v[52:55], v[210:213], v[92:95]
	v_mfma_f32_16x16x32_bf16 v[88:91], v[68:71], v[210:213], v[88:91]
	v_mfma_f32_16x16x32_bf16 v[132:135], v[166:169], v[182:185], v[132:135]
	v_mfma_f32_16x16x32_bf16 v[128:131], v[174:177], v[182:185], v[128:131]
	v_mfma_f32_16x16x32_bf16 v[116:119], v[166:169], v[190:193], v[116:119]
	v_mfma_f32_16x16x32_bf16 v[112:115], v[174:177], v[190:193], v[112:115]
	v_mfma_f32_16x16x32_bf16 v[100:103], v[166:169], v[198:201], v[100:103]
	v_mfma_f32_16x16x32_bf16 v[96:99], v[174:177], v[198:201], v[96:99]
	v_mfma_f32_16x16x32_bf16 v[84:87], v[166:169], v[206:209], v[84:87]
	v_mfma_f32_16x16x32_bf16 v[80:83], v[174:177], v[206:209], v[80:83]
	v_mfma_f32_16x16x32_bf16 v[132:135], v[170:173], v[186:189], v[132:135]
	v_mfma_f32_16x16x32_bf16 v[128:131], v[178:181], v[186:189], v[128:131]
	v_mfma_f32_16x16x32_bf16 v[116:119], v[170:173], v[194:197], v[116:119]
	v_mfma_f32_16x16x32_bf16 v[112:115], v[178:181], v[194:197], v[112:115]
	v_mfma_f32_16x16x32_bf16 v[100:103], v[170:173], v[202:205], v[100:103]
	v_mfma_f32_16x16x32_bf16 v[96:99], v[178:181], v[202:205], v[96:99]
	v_mfma_f32_16x16x32_bf16 v[84:87], v[170:173], v[210:213], v[84:87]
	s_setprio 2
	s_barrier
	v_mfma_f32_16x16x32_bf16 v[80:83], v[178:181], v[210:213], v[80:83]
	s_setprio 0
	s_add_i32 s9, s75, s55
	v_lshl_add_u64 v[158:159], s[76:77], 0, v[148:149]
	s_mov_b32 m0, s9
	ds_read_b128 v[182:185], v165 offset:16384
	ds_read_b128 v[186:189], v165 offset:17408
	ds_read_b128 v[190:193], v165 offset:18432
	ds_read_b128 v[194:197], v165 offset:19456
	ds_read_b128 v[198:201], v165 offset:20480
	ds_read_b128 v[202:205], v165 offset:21504
	ds_read_b128 v[206:209], v165 offset:22528
	ds_read_b128 v[210:213], v165 offset:23552
	global_load_lds_dwordx4 v[158:159], off
	s_add_i32 m0, s9, 0x2000
	v_lshl_add_u64 v[214:215], s[76:77], 0, v[144:145]
	s_add_u32 s76, s76, s12
	s_addc_u32 s77, s77, s13
	s_add_i32 s9, s78, s55
	global_load_lds_dwordx4 v[214:215], off
	v_lshl_add_u64 v[216:217], s[76:77], 0, v[148:149]
	s_mov_b32 m0, s9
	v_lshl_add_u64 v[218:219], s[76:77], 0, v[144:145]
	global_load_lds_dwordx4 v[216:217], off
	s_add_i32 m0, s9, 0x2000
	v_lshl_add_u64 v[220:221], s[6:7], 0, v[150:151]
	global_load_lds_dwordx4 v[218:219], off
	s_mov_b32 m0, s63
	v_lshl_add_u64 v[222:223], s[6:7], 0, v[146:147]
	global_load_lds_dwordx4 v[220:221], off
	s_mov_b32 m0, s64
	s_nop 0
	global_load_lds_dwordx4 v[222:223], off
	s_waitcnt vmcnt(8)
	s_waitcnt lgkmcnt(0)
	s_setprio 1
	s_barrier
	v_mfma_f32_16x16x32_bf16 v[76:79], v[44:47], v[182:185], v[76:79]
	v_mfma_f32_16x16x32_bf16 v[72:75], v[60:63], v[182:185], v[72:75]
	v_mfma_f32_16x16x32_bf16 v[48:51], v[44:47], v[190:193], v[48:51]
	v_mfma_f32_16x16x32_bf16 v[40:43], v[60:63], v[190:193], v[40:43]
	v_mfma_f32_16x16x32_bf16 v[28:31], v[44:47], v[198:201], v[28:31]
	v_mfma_f32_16x16x32_bf16 v[24:27], v[60:63], v[198:201], v[24:27]
	v_mfma_f32_16x16x32_bf16 v[12:15], v[44:47], v[206:209], v[12:15]
	v_mfma_f32_16x16x32_bf16 v[8:11], v[60:63], v[206:209], v[8:11]
	v_mfma_f32_16x16x32_bf16 v[76:79], v[52:55], v[186:189], v[76:79]
	v_mfma_f32_16x16x32_bf16 v[72:75], v[68:71], v[186:189], v[72:75]
	v_mfma_f32_16x16x32_bf16 v[48:51], v[52:55], v[194:197], v[48:51]
	v_mfma_f32_16x16x32_bf16 v[40:43], v[68:71], v[194:197], v[40:43]
	v_mfma_f32_16x16x32_bf16 v[28:31], v[52:55], v[202:205], v[28:31]
	v_mfma_f32_16x16x32_bf16 v[24:27], v[68:71], v[202:205], v[24:27]
	v_mfma_f32_16x16x32_bf16 v[12:15], v[52:55], v[210:213], v[12:15]
	v_mfma_f32_16x16x32_bf16 v[8:11], v[68:71], v[210:213], v[8:11]
	v_mfma_f32_16x16x32_bf16 v[36:39], v[166:169], v[190:193], v[36:39]
	v_mfma_f32_16x16x32_bf16 v[32:35], v[174:177], v[190:193], v[32:35]
	v_mfma_f32_16x16x32_bf16 v[20:23], v[166:169], v[198:201], v[20:23]
	v_mfma_f32_16x16x32_bf16 v[16:19], v[174:177], v[198:201], v[16:19]
	v_mfma_f32_16x16x32_bf16 v[4:7], v[166:169], v[206:209], v[4:7]
	v_mfma_f32_16x16x32_bf16 v[0:3], v[174:177], v[206:209], v[0:3]
	v_mfma_f32_16x16x32_bf16 v[44:47], v[166:169], v[182:185], v[64:67]
	v_mfma_f32_16x16x32_bf16 v[52:55], v[174:177], v[182:185], v[56:59]
	v_mfma_f32_16x16x32_bf16 v[36:39], v[170:173], v[194:197], v[36:39]
	v_mfma_f32_16x16x32_bf16 v[32:35], v[178:181], v[194:197], v[32:35]
	v_mfma_f32_16x16x32_bf16 v[20:23], v[170:173], v[202:205], v[20:23]
	v_mfma_f32_16x16x32_bf16 v[16:19], v[178:181], v[202:205], v[16:19]
	v_mfma_f32_16x16x32_bf16 v[4:7], v[170:173], v[210:213], v[4:7]
	v_mfma_f32_16x16x32_bf16 v[0:3], v[178:181], v[210:213], v[0:3]
	v_mfma_f32_16x16x32_bf16 v[44:47], v[170:173], v[186:189], v[44:47]
	s_setprio 2
	s_barrier
; #define PG8_STAGE(bufoff, gbase, voff) do { _Pragma("unroll") for (int _i = 0; _i < 2; ++_i) \
;         __builtin_amdgcn_global_load_lds((const unsigned*)((const char*)(gbase) + (voff)[_i]), (PG8_LAS unsigned*)(lds + (bufoff) + ldsw + _i * 8192), 16, 0, 0); } while (0)
; #define PG8_LDA(dst, b, h) do { _Pragma("unroll") for (int m = 0; m < 4; ++m) _Pragma("unroll") for (int k = 0; k < 2; ++k) dst[m][k] = *(const PG8_LAS bf16x8*)(lds + PG8_SA(b, h) + aoff + m * 2048 + k * 1024); } while (0)
; #define PG8_LDB(dst, b, h) do { _Pragma("unroll") for (int n = 0; n < 2; ++n) _Pragma("unroll") for (int k = 0; k < 2; ++k) dst[n][k] = *(const PG8_LAS bf16x8*)(lds + PG8_SB(b, h) + boff + n * 2048 + k * 1024); } while (0)
; #define PG8_MMA(ai, bj, At, Bt) do { __builtin_amdgcn_s_setprio(1); _Pragma("unroll") for (int m = 0; m < 4; ++m) _Pragma("unroll") for (int n = 0; n < 2; ++n) _Pragma("unroll") for (int k = 0; k < 2; ++k) \
;         acc[ai][bj][m][n] = __builtin_amdgcn_mfma_f32_16x16x32_bf16(Bt[n][k], At[m][k], acc[ai][bj][m][n], 0, 0, 0); __builtin_amdgcn_s_setprio(0); } while (0)
; #define PG8_BAR __builtin_amdgcn_s_barrier()
; template <class Epi, class Sched, bool ALIGN_EPI = false, bool SP2 = false>
; __device__ __forceinline__ void gemm_phase(PG8_LAS unsigned char* lds, const Gemm g, const Sched& S, const Epi& E, const int wid) {
;     ...
;             PG8_LDB(B0, 0, 0); PG8_LDB(B1, 0, 1); PG8_SCHED; PG8_LDA(At, 0, 0); PG8_STAGE(PG8_SA(1, 1), a1 + hstep, voffA);
;             PG8_WAIT_V(8); PG8_WAIT_L(0); PG8_BAR; PG8_MMA(0, 0, At, B0); PG8_MMA(0, 1, At, B1); PG8_BAR; PG8_SCHED;
;             PG8_LDA(At, 0, 1); PG8_STAGE(PG8_SB(0, 0), b2, voffB); PG8_STAGE(PG8_SB(0, 1), b2 + hstep, voffB); PG8_STAGE(PG8_SA(0, 0), a2, voffA);
;             PG8_WAIT_V(8); PG8_WAIT_L(0); PG8_BAR; PG8_MMA(1, 0, At, B0); PG8_MMA(1, 1, At, B1); PG8_BAR; PG8_SCHED;
;             PG8_LDB(B0, 1, 0); PG8_LDB(B1, 1, 1); PG8_SCHED; PG8_LDA(At, 1, 0); PG8_STAGE(PG8_SA(0, 1), a2 + hstep, voffA);
;             PG8_WAIT_V(8); PG8_WAIT_L(0); PG8_BAR; PG8_MMA(0, 0, At, B0); PG8_MMA(0, 1, At, B1); PG8_BAR; PG8_SCHED;
;             PG8_LDA(At, 1, 1); PG8_STAGE(PG8_SB(1, 0), b3, voffB); PG8_STAGE(PG8_SB(1, 1), b3 + hstep, voffB); PG8_STAGE(PG8_SA(1, 0), a3, voffA);
;             PG8_WAIT_V(8); PG8_WAIT_L(0); PG8_BAR; PG8_MMA(1, 0, At, B0); PG8_MMA(1, 1, At, B1); PG8_BAR; PG8_SCHED;
	v_mfma_f32_16x16x32_bf16 v[52:55], v[178:181], v[186:189], v[52:55]
	s_setprio 0
	s_add_i32 s9, 0, 0x18000
	s_add_i32 s33, 0, 0x1c000
	v_add_u32_e32 v68, s9, v162
	v_add_u32_e32 v178, s33, v162
	ds_read_b128 v[56:59], v68
	ds_read_b128 v[60:63], v68 offset:1024
	ds_read_b128 v[64:67], v68 offset:2048
	ds_read_b128 v[68:71], v68 offset:3072
	ds_read_b128 v[166:169], v178
	ds_read_b128 v[170:173], v178 offset:1024
	ds_read_b128 v[174:177], v178 offset:2048
	ds_read_b128 v[178:181], v178 offset:3072
	s_add_u32 s6, s6, s12
	s_addc_u32 s7, s7, s13
	s_mov_b32 m0, s65
	v_lshl_add_u64 v[224:225], s[6:7], 0, v[150:151]
	ds_read_b128 v[182:185], v165 offset:32768
	ds_read_b128 v[186:189], v165 offset:33792
	ds_read_b128 v[190:193], v165 offset:34816
	ds_read_b128 v[194:197], v165 offset:35840
	ds_read_b128 v[198:201], v165 offset:36864
	ds_read_b128 v[202:205], v165 offset:37888
	ds_read_b128 v[206:209], v165 offset:38912
	ds_read_b128 v[210:213], v165 offset:39936
	global_load_lds_dwordx4 v[224:225], off
	v_lshl_add_u64 v[224:225], s[6:7], 0, v[146:147]
	s_mov_b32 m0, s66
	s_nop 0
	global_load_lds_dwordx4 v[224:225], off
	s_waitcnt vmcnt(8)
	s_waitcnt lgkmcnt(0)
	s_setprio 1
	s_barrier
	v_mfma_f32_16x16x32_bf16 v[140:143], v[56:59], v[182:185], v[140:143]
	v_mfma_f32_16x16x32_bf16 v[136:139], v[64:67], v[182:185], v[136:139]
	v_mfma_f32_16x16x32_bf16 v[124:127], v[56:59], v[190:193], v[124:127]
	v_mfma_f32_16x16x32_bf16 v[120:123], v[64:67], v[190:193], v[120:123]
	v_mfma_f32_16x16x32_bf16 v[108:111], v[56:59], v[198:201], v[108:111]
	v_mfma_f32_16x16x32_bf16 v[104:107], v[64:67], v[198:201], v[104:107]
	v_mfma_f32_16x16x32_bf16 v[92:95], v[56:59], v[206:209], v[92:95]
	v_mfma_f32_16x16x32_bf16 v[88:91], v[64:67], v[206:209], v[88:91]
	v_mfma_f32_16x16x32_bf16 v[140:143], v[60:63], v[186:189], v[140:143]
	v_mfma_f32_16x16x32_bf16 v[136:139], v[68:71], v[186:189], v[136:139]
	v_mfma_f32_16x16x32_bf16 v[124:127], v[60:63], v[194:197], v[124:127]
	v_mfma_f32_16x16x32_bf16 v[120:123], v[68:71], v[194:197], v[120:123]
	v_mfma_f32_16x16x32_bf16 v[108:111], v[60:63], v[202:205], v[108:111]
	v_mfma_f32_16x16x32_bf16 v[104:107], v[68:71], v[202:205], v[104:107]
	v_mfma_f32_16x16x32_bf16 v[92:95], v[60:63], v[210:213], v[92:95]
	v_mfma_f32_16x16x32_bf16 v[88:91], v[68:71], v[210:213], v[88:91]
	v_mfma_f32_16x16x32_bf16 v[132:135], v[166:169], v[182:185], v[132:135]
	v_mfma_f32_16x16x32_bf16 v[128:131], v[174:177], v[182:185], v[128:131]
	v_mfma_f32_16x16x32_bf16 v[116:119], v[166:169], v[190:193], v[116:119]
	v_mfma_f32_16x16x32_bf16 v[112:115], v[174:177], v[190:193], v[112:115]
	v_mfma_f32_16x16x32_bf16 v[100:103], v[166:169], v[198:201], v[100:103]
	v_mfma_f32_16x16x32_bf16 v[96:99], v[174:177], v[198:201], v[96:99]
	v_mfma_f32_16x16x32_bf16 v[84:87], v[166:169], v[206:209], v[84:87]
	v_mfma_f32_16x16x32_bf16 v[80:83], v[174:177], v[206:209], v[80:83]
	v_mfma_f32_16x16x32_bf16 v[132:135], v[170:173], v[186:189], v[132:135]
	v_mfma_f32_16x16x32_bf16 v[128:131], v[178:181], v[186:189], v[128:131]
	v_mfma_f32_16x16x32_bf16 v[116:119], v[170:173], v[194:197], v[116:119]
	v_mfma_f32_16x16x32_bf16 v[112:115], v[178:181], v[194:197], v[112:115]
	v_mfma_f32_16x16x32_bf16 v[100:103], v[170:173], v[202:205], v[100:103]
	v_mfma_f32_16x16x32_bf16 v[96:99], v[178:181], v[202:205], v[96:99]
	v_mfma_f32_16x16x32_bf16 v[84:87], v[170:173], v[210:213], v[84:87]
	s_setprio 2
	s_barrier
	v_mfma_f32_16x16x32_bf16 v[80:83], v[178:181], v[210:213], v[80:83]
	s_setprio 0
	s_add_i32 s6, s9, s55
	v_lshl_add_u64 v[158:159], v[158:159], 0, s[26:27]
	s_mov_b32 m0, s6
	ds_read_b128 v[182:185], v165 offset:49152
	ds_read_b128 v[186:189], v165 offset:50176
	ds_read_b128 v[190:193], v165 offset:51200
	ds_read_b128 v[194:197], v165 offset:52224
	ds_read_b128 v[198:201], v165 offset:53248
	ds_read_b128 v[202:205], v165 offset:54272
	ds_read_b128 v[206:209], v165 offset:55296
	ds_read_b128 v[210:213], v165 offset:56320
	global_load_lds_dwordx4 v[158:159], off
	v_lshl_add_u64 v[158:159], v[214:215], 0, s[26:27]
	s_add_i32 m0, s6, 0x2000
	s_add_i32 s6, s33, s55
	global_load_lds_dwordx4 v[158:159], off
	v_lshl_add_u64 v[158:159], v[216:217], 0, s[26:27]
	s_mov_b32 m0, s6
	s_nop 0
	global_load_lds_dwordx4 v[158:159], off
	v_lshl_add_u64 v[158:159], v[218:219], 0, s[26:27]
	s_add_i32 m0, s6, 0x2000
	s_nop 0
	global_load_lds_dwordx4 v[158:159], off
	v_lshl_add_u64 v[158:159], v[220:221], 0, s[26:27]
	s_mov_b32 m0, s68
	s_nop 0
	global_load_lds_dwordx4 v[158:159], off
	v_lshl_add_u64 v[158:159], v[222:223], 0, s[26:27]
	s_mov_b32 m0, s69
	s_nop 0
	global_load_lds_dwordx4 v[158:159], off
	s_waitcnt vmcnt(8)
	s_waitcnt lgkmcnt(0)
	s_setprio 1
	s_barrier
	v_mfma_f32_16x16x32_bf16 v[76:79], v[56:59], v[182:185], v[76:79]
	v_mfma_f32_16x16x32_bf16 v[72:75], v[64:67], v[182:185], v[72:75]
	v_mfma_f32_16x16x32_bf16 v[48:51], v[56:59], v[190:193], v[48:51]
	v_mfma_f32_16x16x32_bf16 v[40:43], v[64:67], v[190:193], v[40:43]
	v_mfma_f32_16x16x32_bf16 v[28:31], v[56:59], v[198:201], v[28:31]
	v_mfma_f32_16x16x32_bf16 v[24:27], v[64:67], v[198:201], v[24:27]
	v_mfma_f32_16x16x32_bf16 v[12:15], v[56:59], v[206:209], v[12:15]
	v_mfma_f32_16x16x32_bf16 v[8:11], v[64:67], v[206:209], v[8:11]
	v_mfma_f32_16x16x32_bf16 v[76:79], v[60:63], v[186:189], v[76:79]
	v_mfma_f32_16x16x32_bf16 v[72:75], v[68:71], v[186:189], v[72:75]
	v_mfma_f32_16x16x32_bf16 v[48:51], v[60:63], v[194:197], v[48:51]
	v_mfma_f32_16x16x32_bf16 v[40:43], v[68:71], v[194:197], v[40:43]
	v_mfma_f32_16x16x32_bf16 v[28:31], v[60:63], v[202:205], v[28:31]
	v_mfma_f32_16x16x32_bf16 v[24:27], v[68:71], v[202:205], v[24:27]
	v_mfma_f32_16x16x32_bf16 v[12:15], v[60:63], v[210:213], v[12:15]
	v_mfma_f32_16x16x32_bf16 v[8:11], v[68:71], v[210:213], v[8:11]
	v_mfma_f32_16x16x32_bf16 v[44:47], v[166:169], v[182:185], v[44:47]
	v_mfma_f32_16x16x32_bf16 v[64:67], v[170:173], v[186:189], v[44:47]
	v_mfma_f32_16x16x32_bf16 v[44:47], v[174:177], v[182:185], v[52:55]
	v_mfma_f32_16x16x32_bf16 v[36:39], v[166:169], v[190:193], v[36:39]
	v_mfma_f32_16x16x32_bf16 v[32:35], v[174:177], v[190:193], v[32:35]
	v_mfma_f32_16x16x32_bf16 v[20:23], v[166:169], v[198:201], v[20:23]
	v_mfma_f32_16x16x32_bf16 v[16:19], v[174:177], v[198:201], v[16:19]
	v_mfma_f32_16x16x32_bf16 v[4:7], v[166:169], v[206:209], v[4:7]
	v_mfma_f32_16x16x32_bf16 v[0:3], v[174:177], v[206:209], v[0:3]
	v_mfma_f32_16x16x32_bf16 v[56:59], v[178:181], v[186:189], v[44:47]
	v_mfma_f32_16x16x32_bf16 v[36:39], v[170:173], v[194:197], v[36:39]
	v_mfma_f32_16x16x32_bf16 v[32:35], v[178:181], v[194:197], v[32:35]
	v_mfma_f32_16x16x32_bf16 v[20:23], v[170:173], v[202:205], v[20:23]
	v_mfma_f32_16x16x32_bf16 v[16:19], v[178:181], v[202:205], v[16:19]
	v_mfma_f32_16x16x32_bf16 v[4:7], v[170:173], v[210:213], v[4:7]
	s_setprio 2
	s_barrier
	v_mfma_f32_16x16x32_bf16 v[0:3], v[178:181], v[210:213], v[0:3]
	s_setprio 0
	s_add_u32 s4, s4, 0x100
	s_addc_u32 s5, s5, 0
	s_add_u32 s0, s0, 0x100
	s_addc_u32 s1, s1, 0
	s_cmp_ge_i32 s8, s70
	s_mov_b32 s6, s8
	s_cbranch_scc0 .LBB0_1100

; #define PG8_WAIT_V(n) asm volatile("s_waitcnt vmcnt(" #n ")" ::: "memory")
; #define PG8_WAIT_L(n) asm volatile("s_waitcnt lgkmcnt(" #n ")" ::: "memory")
; #define PG8_BAR __builtin_amdgcn_s_barrier()
; template <class Epi, class Sched, bool ALIGN_EPI = false, bool SP2 = false>
; __device__ __forceinline__ void gemm_phase(PG8_LAS unsigned char* lds, const Gemm g, const Sched& S, const Epi& E, const int wid) {
;     ...
;     for (;;) {
;         const bool has_next = S.next(ui + 1, nxt);
;         const char* nA = has_next ? (const char*)g.A + (size_t)nxt.pm * tstep : cA; const char* nB = has_next ? (const char*)g.Bt + (size_t)nxt.pn * tstep : cB;
;         for (int t = 0; t < nt; t += 2) {
;             const bool last = (t == nt - 2);
;             const char* a1 = cA + (size_t)(t + 1) * kstep;
;             const char* a2 = last ? nA : cA + (size_t)(t + 2) * kstep; const char* b2 = last ? nB : cB + (size_t)(t + 2) * kstep;
;             const char* a3 = a2 + kstep; const char* b3 = b2 + kstep;
;             if (last && has_next) S.a_ready(nxt);
;             if constexpr (SP2) {
;             PG8_LDB(B0, 0, 0); PG8_LDB(B1, 0, 1); PG8_SCHED; PG8_LDA(At, 0, 0); PG8_STAGE(PG8_SA(1, 1), a1 + hstep, voffA);
;             PG8_WAIT_V(8); PG8_WAIT_L(0); PG8_BAR; PG8_MMA(0, 0, At, B0); PG8_MMA(0, 1, At, B1); PG8_BAR; PG8_SCHED;
;             PG8_LDA(At, 0, 1); PG8_STAGE(PG8_SB(0, 0), b2, voffB); PG8_STAGE(PG8_SB(0, 1), b2 + hstep, voffB); PG8_STAGE(PG8_SA(0, 0), a2, voffA);
;             PG8_WAIT_V(8); PG8_WAIT_L(0); PG8_BAR; PG8_MMA(1, 0, At, B0); PG8_MMA(1, 1, At, B1); PG8_BAR; PG8_SCHED;
;             PG8_LDB(B0, 1, 0); PG8_LDB(B1, 1, 1); PG8_SCHED; PG8_LDA(At, 1, 0); PG8_STAGE(PG8_SA(0, 1), a2 + hstep, voffA);
;             PG8_WAIT_V(8); PG8_WAIT_L(0); PG8_BAR; PG8_MMA(0, 0, At, B0); PG8_MMA(0, 1, At, B1); PG8_BAR; PG8_SCHED;
;             PG8_LDA(At, 1, 1); PG8_STAGE(PG8_SB(1, 0), b3, voffB); PG8_STAGE(PG8_SB(1, 1), b3 + hstep, voffB); PG8_STAGE(PG8_SA(1, 0), a3, voffA);
;             PG8_WAIT_V(8); PG8_WAIT_L(0); PG8_BAR; PG8_MMA(1, 0, At, B0); PG8_MMA(1, 1, At, B1); PG8_BAR; PG8_SCHED;
;     ...
;         for (int a = 0; a < 2; ++a)
; #pragma unroll
;             for (int b = 0; b < 2; ++b)
; #pragma unroll
;                 for (int m = 0; m < 4; ++m)
; #pragma unroll
;                     for (int n = 0; n < 2; ++n) acc[a][b][m][n] = (f32x4){0.f, 0.f, 0.f, 0.f};
.LBB0_1177:
	s_andn2_b64 vcc, exec, s[20:21]
	s_cbranch_vccnz .Lz_GMA
	s_add_u32 s26, s26, 0x80
	s_addc_u32 s27, s27, 0
	s_add_u32 s0, s28, 0x100
	s_addc_u32 s1, s29, 0
	s_mov_b32 s28, 0
	ds_read_b128 v[142:145], v149
	ds_read_b128 v[152:155], v149 offset:1024
	ds_read_b128 v[156:159], v149 offset:2048
	ds_read_b128 v[160:163], v149 offset:3072
	ds_read_b128 v[164:167], v150
	ds_read_b128 v[168:171], v150 offset:1024
	ds_read_b128 v[172:175], v150 offset:2048
	ds_read_b128 v[176:179], v150 offset:3072
	s_add_i32 s61, s28, 2
	s_add_u32 s33, s26, 0x80
	s_addc_u32 s29, s27, 0
	s_cmp_eq_u32 s53, s28
	s_cselect_b32 s28, s4, s33
	s_cselect_b32 s29, s5, s29
	s_cselect_b32 s63, s25, s1
	s_cselect_b32 s62, s24, s0
	v_lshl_add_u64 v[212:213], s[26:27], 0, v[136:137]
	s_add_i32 m0, s42, 0xc000
	ds_read_b128 v[180:183], v151
	ds_read_b128 v[184:187], v151 offset:1024
	ds_read_b128 v[188:191], v151 offset:2048
	ds_read_b128 v[192:195], v151 offset:3072
	ds_read_b128 v[196:199], v151 offset:4096
	ds_read_b128 v[200:203], v151 offset:5120
	ds_read_b128 v[204:207], v151 offset:6144
	ds_read_b128 v[208:211], v151 offset:7168
	global_load_lds_dwordx4 v[212:213], off
	v_lshl_add_u64 v[212:213], s[26:27], 0, v[138:139]
	s_add_i32 m0, s42, 0xe000
	s_nop 0
	global_load_lds_dwordx4 v[212:213], off
	s_waitcnt vmcnt(8)
	s_waitcnt lgkmcnt(0)
	s_setprio 1
	s_barrier
	v_mfma_f32_16x16x32_bf16 v[124:127], v[142:145], v[180:183], 0
	v_mfma_f32_16x16x32_bf16 v[120:123], v[156:159], v[180:183], 0
	v_mfma_f32_16x16x32_bf16 v[108:111], v[142:145], v[188:191], 0
	v_mfma_f32_16x16x32_bf16 v[104:107], v[156:159], v[188:191], 0
	v_mfma_f32_16x16x32_bf16 v[92:95], v[142:145], v[196:199], 0
	v_mfma_f32_16x16x32_bf16 v[88:91], v[156:159], v[196:199], 0
	v_mfma_f32_16x16x32_bf16 v[76:79], v[142:145], v[204:207], 0
	v_mfma_f32_16x16x32_bf16 v[72:75], v[156:159], v[204:207], 0
	v_mfma_f32_16x16x32_bf16 v[124:127], v[152:155], v[184:187], v[124:127]
	v_mfma_f32_16x16x32_bf16 v[120:123], v[160:163], v[184:187], v[120:123]
	v_mfma_f32_16x16x32_bf16 v[108:111], v[152:155], v[192:195], v[108:111]
	v_mfma_f32_16x16x32_bf16 v[104:107], v[160:163], v[192:195], v[104:107]
	v_mfma_f32_16x16x32_bf16 v[92:95], v[152:155], v[200:203], v[92:95]
	v_mfma_f32_16x16x32_bf16 v[88:91], v[160:163], v[200:203], v[88:91]
	v_mfma_f32_16x16x32_bf16 v[76:79], v[152:155], v[208:211], v[76:79]
	v_mfma_f32_16x16x32_bf16 v[72:75], v[160:163], v[208:211], v[72:75]
	v_mfma_f32_16x16x32_bf16 v[116:119], v[164:167], v[180:183], 0
	v_mfma_f32_16x16x32_bf16 v[112:115], v[172:175], v[180:183], 0
	v_mfma_f32_16x16x32_bf16 v[100:103], v[164:167], v[188:191], 0
	v_mfma_f32_16x16x32_bf16 v[96:99], v[172:175], v[188:191], 0
	v_mfma_f32_16x16x32_bf16 v[84:87], v[164:167], v[196:199], 0
	v_mfma_f32_16x16x32_bf16 v[80:83], v[172:175], v[196:199], 0
	v_mfma_f32_16x16x32_bf16 v[68:71], v[164:167], v[204:207], 0
	v_mfma_f32_16x16x32_bf16 v[64:67], v[172:175], v[204:207], 0
	v_mfma_f32_16x16x32_bf16 v[116:119], v[168:171], v[184:187], v[116:119]
	v_mfma_f32_16x16x32_bf16 v[112:115], v[176:179], v[184:187], v[112:115]
	v_mfma_f32_16x16x32_bf16 v[100:103], v[168:171], v[192:195], v[100:103]
	v_mfma_f32_16x16x32_bf16 v[96:99], v[176:179], v[192:195], v[96:99]
	v_mfma_f32_16x16x32_bf16 v[84:87], v[168:171], v[200:203], v[84:87]
	v_mfma_f32_16x16x32_bf16 v[80:83], v[176:179], v[200:203], v[80:83]
	v_mfma_f32_16x16x32_bf16 v[68:71], v[168:171], v[208:211], v[68:71]
	s_setprio 2
	s_barrier
	v_mfma_f32_16x16x32_bf16 v[64:67], v[176:179], v[208:211], v[64:67]
	s_setprio 0
	s_add_i32 s33, s55, s34
	v_lshl_add_u64 v[212:213], s[62:63], 0, v[132:133]
	s_mov_b32 m0, s33
	ds_read_b128 v[180:183], v151 offset:16384
	ds_read_b128 v[184:187], v151 offset:17408
	ds_read_b128 v[188:191], v151 offset:18432
	ds_read_b128 v[192:195], v151 offset:19456
	ds_read_b128 v[196:199], v151 offset:20480
	ds_read_b128 v[200:203], v151 offset:21504
	ds_read_b128 v[204:207], v151 offset:22528
	ds_read_b128 v[208:211], v151 offset:23552
	global_load_lds_dwordx4 v[212:213], off
	s_add_i32 m0, s33, 0x2000
	v_lshl_add_u64 v[214:215], s[62:63], 0, v[128:129]
	s_add_u32 s62, s62, s8
	s_addc_u32 s63, s63, s9
	s_add_i32 s33, s56, s34
	global_load_lds_dwordx4 v[214:215], off
	v_lshl_add_u64 v[216:217], s[62:63], 0, v[132:133]
	s_mov_b32 m0, s33
	v_lshl_add_u64 v[218:219], s[62:63], 0, v[128:129]
	global_load_lds_dwordx4 v[216:217], off
	s_add_i32 m0, s33, 0x2000
	v_lshl_add_u64 v[220:221], s[28:29], 0, v[134:135]
	global_load_lds_dwordx4 v[218:219], off
	s_mov_b32 m0, s42
	v_lshl_add_u64 v[222:223], s[28:29], 0, v[130:131]
	global_load_lds_dwordx4 v[220:221], off
	s_mov_b32 m0, s43
	s_nop 0
	global_load_lds_dwordx4 v[222:223], off
	s_waitcnt vmcnt(8)
	s_waitcnt lgkmcnt(0)
	s_setprio 1
	s_barrier
; #define PG8_STAGE(bufoff, gbase, voff) do { _Pragma("unroll") for (int _i = 0; _i < 2; ++_i) \
;         __builtin_amdgcn_global_load_lds((const unsigned*)((const char*)(gbase) + (voff)[_i]), (PG8_LAS unsigned*)(lds + (bufoff) + ldsw + _i * 8192), 16, 0, 0); } while (0)
; #define PG8_LDA(dst, b, h) do { _Pragma("unroll") for (int m = 0; m < 4; ++m) _Pragma("unroll") for (int k = 0; k < 2; ++k) dst[m][k] = *(const PG8_LAS bf16x8*)(lds + PG8_SA(b, h) + aoff + m * 2048 + k * 1024); } while (0)
; #define PG8_LDB(dst, b, h) do { _Pragma("unroll") for (int n = 0; n < 2; ++n) _Pragma("unroll") for (int k = 0; k < 2; ++k) dst[n][k] = *(const PG8_LAS bf16x8*)(lds + PG8_SB(b, h) + boff + n * 2048 + k * 1024); } while (0)
; #define PG8_MMA(ai, bj, At, Bt) do { __builtin_amdgcn_s_setprio(1); _Pragma("unroll") for (int m = 0; m < 4; ++m) _Pragma("unroll") for (int n = 0; n < 2; ++n) _Pragma("unroll") for (int k = 0; k < 2; ++k) \
;         acc[ai][bj][m][n] = __builtin_amdgcn_mfma_f32_16x16x32_bf16(Bt[n][k], At[m][k], acc[ai][bj][m][n], 0, 0, 0); __builtin_amdgcn_s_setprio(0); } while (0)
; #define PG8_BAR __builtin_amdgcn_s_barrier()
; template <class Epi, class Sched, bool ALIGN_EPI = false, bool SP2 = false>
; __device__ __forceinline__ void gemm_phase(PG8_LAS unsigned char* lds, const Gemm g, const Sched& S, const Epi& E, const int wid) {
;     ...
;             PG8_LDB(B0, 0, 0); PG8_LDB(B1, 0, 1); PG8_SCHED; PG8_LDA(At, 0, 0); PG8_STAGE(PG8_SA(1, 1), a1 + hstep, voffA);
;             PG8_WAIT_V(8); PG8_WAIT_L(0); PG8_BAR; PG8_MMA(0, 0, At, B0); PG8_MMA(0, 1, At, B1); PG8_BAR; PG8_SCHED;
;             PG8_LDA(At, 0, 1); PG8_STAGE(PG8_SB(0, 0), b2, voffB); PG8_STAGE(PG8_SB(0, 1), b2 + hstep, voffB); PG8_STAGE(PG8_SA(0, 0), a2, voffA);
;             PG8_WAIT_V(8); PG8_WAIT_L(0); PG8_BAR; PG8_MMA(1, 0, At, B0); PG8_MMA(1, 1, At, B1); PG8_BAR; PG8_SCHED;
;             PG8_LDB(B0, 1, 0); PG8_LDB(B1, 1, 1); PG8_SCHED; PG8_LDA(At, 1, 0); PG8_STAGE(PG8_SA(0, 1), a2 + hstep, voffA);
;             PG8_WAIT_V(8); PG8_WAIT_L(0); PG8_BAR; PG8_MMA(0, 0, At, B0); PG8_MMA(0, 1, At, B1); PG8_BAR; PG8_SCHED;
;             PG8_LDA(At, 1, 1); PG8_STAGE(PG8_SB(1, 0), b3, voffB); PG8_STAGE(PG8_SB(1, 1), b3 + hstep, voffB); PG8_STAGE(PG8_SA(1, 0), a3, voffA);
;             PG8_WAIT_V(8); PG8_WAIT_L(0); PG8_BAR; PG8_MMA(1, 0, At, B0); PG8_MMA(1, 1, At, B1); PG8_BAR; PG8_SCHED;
	v_mfma_f32_16x16x32_bf16 v[60:63], v[142:145], v[180:183], 0
	v_mfma_f32_16x16x32_bf16 v[56:59], v[156:159], v[180:183], 0
	v_mfma_f32_16x16x32_bf16 v[44:47], v[142:145], v[188:191], 0
	v_mfma_f32_16x16x32_bf16 v[40:43], v[156:159], v[188:191], 0
	v_mfma_f32_16x16x32_bf16 v[28:31], v[142:145], v[196:199], 0
	v_mfma_f32_16x16x32_bf16 v[24:27], v[156:159], v[196:199], 0
	v_mfma_f32_16x16x32_bf16 v[12:15], v[142:145], v[204:207], 0
	v_mfma_f32_16x16x32_bf16 v[8:11], v[156:159], v[204:207], 0
	v_mfma_f32_16x16x32_bf16 v[60:63], v[152:155], v[184:187], v[60:63]
	v_mfma_f32_16x16x32_bf16 v[56:59], v[160:163], v[184:187], v[56:59]
	v_mfma_f32_16x16x32_bf16 v[44:47], v[152:155], v[192:195], v[44:47]
	v_mfma_f32_16x16x32_bf16 v[40:43], v[160:163], v[192:195], v[40:43]
	v_mfma_f32_16x16x32_bf16 v[28:31], v[152:155], v[200:203], v[28:31]
	v_mfma_f32_16x16x32_bf16 v[24:27], v[160:163], v[200:203], v[24:27]
	v_mfma_f32_16x16x32_bf16 v[12:15], v[152:155], v[208:211], v[12:15]
	v_mfma_f32_16x16x32_bf16 v[8:11], v[160:163], v[208:211], v[8:11]
	v_mfma_f32_16x16x32_bf16 v[52:55], v[164:167], v[180:183], 0
	v_mfma_f32_16x16x32_bf16 v[48:51], v[172:175], v[180:183], 0
	v_mfma_f32_16x16x32_bf16 v[36:39], v[164:167], v[188:191], 0
	v_mfma_f32_16x16x32_bf16 v[32:35], v[172:175], v[188:191], 0
	v_mfma_f32_16x16x32_bf16 v[20:23], v[164:167], v[196:199], 0
	v_mfma_f32_16x16x32_bf16 v[16:19], v[172:175], v[196:199], 0
	v_mfma_f32_16x16x32_bf16 v[4:7], v[164:167], v[204:207], 0
	v_mfma_f32_16x16x32_bf16 v[0:3], v[172:175], v[204:207], 0
	v_mfma_f32_16x16x32_bf16 v[52:55], v[168:171], v[184:187], v[52:55]
	v_mfma_f32_16x16x32_bf16 v[48:51], v[176:179], v[184:187], v[48:51]
	v_mfma_f32_16x16x32_bf16 v[36:39], v[168:171], v[192:195], v[36:39]
	v_mfma_f32_16x16x32_bf16 v[32:35], v[176:179], v[192:195], v[32:35]
	v_mfma_f32_16x16x32_bf16 v[20:23], v[168:171], v[200:203], v[20:23]
	v_mfma_f32_16x16x32_bf16 v[16:19], v[176:179], v[200:203], v[16:19]
	v_mfma_f32_16x16x32_bf16 v[4:7], v[168:171], v[208:211], v[4:7]
	s_setprio 2
	s_barrier
	v_mfma_f32_16x16x32_bf16 v[0:3], v[176:179], v[208:211], v[0:3]
	s_setprio 0
	s_add_i32 s33, 0, 0x18000
	s_add_i32 s62, 0, 0x1c000
	v_add_u32_e32 v160, s33, v148
	v_add_u32_e32 v176, s62, v148
	ds_read_b128 v[142:145], v160
	ds_read_b128 v[152:155], v160 offset:1024
	ds_read_b128 v[156:159], v160 offset:2048
	ds_read_b128 v[160:163], v160 offset:3072
	ds_read_b128 v[164:167], v176
	ds_read_b128 v[168:171], v176 offset:1024
	ds_read_b128 v[172:175], v176 offset:2048
	ds_read_b128 v[176:179], v176 offset:3072
	s_add_u32 s28, s28, s8
	s_addc_u32 s29, s29, s9
	s_mov_b32 m0, s44
	v_lshl_add_u64 v[224:225], s[28:29], 0, v[134:135]
	ds_read_b128 v[180:183], v151 offset:32768
	ds_read_b128 v[184:187], v151 offset:33792
	ds_read_b128 v[188:191], v151 offset:34816
	ds_read_b128 v[192:195], v151 offset:35840
	ds_read_b128 v[196:199], v151 offset:36864
	ds_read_b128 v[200:203], v151 offset:37888
	ds_read_b128 v[204:207], v151 offset:38912
	ds_read_b128 v[208:211], v151 offset:39936
	global_load_lds_dwordx4 v[224:225], off
	v_lshl_add_u64 v[224:225], s[28:29], 0, v[130:131]
	s_mov_b32 m0, s45
	s_nop 0
	global_load_lds_dwordx4 v[224:225], off
	s_waitcnt vmcnt(8)
	s_waitcnt lgkmcnt(0)
	s_setprio 1
	s_barrier
	v_mfma_f32_16x16x32_bf16 v[124:127], v[142:145], v[180:183], v[124:127]
	v_mfma_f32_16x16x32_bf16 v[120:123], v[156:159], v[180:183], v[120:123]
	v_mfma_f32_16x16x32_bf16 v[108:111], v[142:145], v[188:191], v[108:111]
	v_mfma_f32_16x16x32_bf16 v[104:107], v[156:159], v[188:191], v[104:107]
	v_mfma_f32_16x16x32_bf16 v[92:95], v[142:145], v[196:199], v[92:95]
	v_mfma_f32_16x16x32_bf16 v[88:91], v[156:159], v[196:199], v[88:91]
	v_mfma_f32_16x16x32_bf16 v[76:79], v[142:145], v[204:207], v[76:79]
	v_mfma_f32_16x16x32_bf16 v[72:75], v[156:159], v[204:207], v[72:75]
	v_mfma_f32_16x16x32_bf16 v[124:127], v[152:155], v[184:187], v[124:127]
	v_mfma_f32_16x16x32_bf16 v[120:123], v[160:163], v[184:187], v[120:123]
	v_mfma_f32_16x16x32_bf16 v[108:111], v[152:155], v[192:195], v[108:111]
	v_mfma_f32_16x16x32_bf16 v[104:107], v[160:163], v[192:195], v[104:107]
	v_mfma_f32_16x16x32_bf16 v[92:95], v[152:155], v[200:203], v[92:95]
	v_mfma_f32_16x16x32_bf16 v[88:91], v[160:163], v[200:203], v[88:91]
	v_mfma_f32_16x16x32_bf16 v[76:79], v[152:155], v[208:211], v[76:79]
	v_mfma_f32_16x16x32_bf16 v[72:75], v[160:163], v[208:211], v[72:75]
	v_mfma_f32_16x16x32_bf16 v[116:119], v[164:167], v[180:183], v[116:119]
	v_mfma_f32_16x16x32_bf16 v[112:115], v[172:175], v[180:183], v[112:115]
	v_mfma_f32_16x16x32_bf16 v[100:103], v[164:167], v[188:191], v[100:103]
	v_mfma_f32_16x16x32_bf16 v[96:99], v[172:175], v[188:191], v[96:99]
	v_mfma_f32_16x16x32_bf16 v[84:87], v[164:167], v[196:199], v[84:87]
	v_mfma_f32_16x16x32_bf16 v[80:83], v[172:175], v[196:199], v[80:83]
	v_mfma_f32_16x16x32_bf16 v[68:71], v[164:167], v[204:207], v[68:71]
	v_mfma_f32_16x16x32_bf16 v[64:67], v[172:175], v[204:207], v[64:67]
	v_mfma_f32_16x16x32_bf16 v[116:119], v[168:171], v[184:187], v[116:119]
	v_mfma_f32_16x16x32_bf16 v[112:115], v[176:179], v[184:187], v[112:115]
	v_mfma_f32_16x16x32_bf16 v[100:103], v[168:171], v[192:195], v[100:103]
	v_mfma_f32_16x16x32_bf16 v[96:99], v[176:179], v[192:195], v[96:99]
	v_mfma_f32_16x16x32_bf16 v[84:87], v[168:171], v[200:203], v[84:87]
	v_mfma_f32_16x16x32_bf16 v[80:83], v[176:179], v[200:203], v[80:83]
	v_mfma_f32_16x16x32_bf16 v[68:71], v[168:171], v[208:211], v[68:71]
	s_setprio 2
	s_barrier
; #define PG8_STAGE(bufoff, gbase, voff) do { _Pragma("unroll") for (int _i = 0; _i < 2; ++_i) \
;         __builtin_amdgcn_global_load_lds((const unsigned*)((const char*)(gbase) + (voff)[_i]), (PG8_LAS unsigned*)(lds + (bufoff) + ldsw + _i * 8192), 16, 0, 0); } while (0)
; #define PG8_WAIT_V(n) asm volatile("s_waitcnt vmcnt(" #n ")" ::: "memory")
; #define PG8_WAIT_L(n) asm volatile("s_waitcnt lgkmcnt(" #n ")" ::: "memory")
; #define PG8_BAR __builtin_amdgcn_s_barrier()
; template <class Epi, class Sched, bool ALIGN_EPI = false, bool SP2 = false>
; __device__ __forceinline__ void gemm_phase(PG8_LAS unsigned char* lds, const Gemm g, const Sched& S, const Epi& E, const int wid) {
;     ...
;     for (;;) {
;         const bool has_next = S.next(ui + 1, nxt);
;         const char* nA = has_next ? (const char*)g.A + (size_t)nxt.pm * tstep : cA; const char* nB = has_next ? (const char*)g.Bt + (size_t)nxt.pn * tstep : cB;
;         for (int t = 0; t < nt; t += 2) {
;             const bool last = (t == nt - 2);
;             const char* a1 = cA + (size_t)(t + 1) * kstep;
;             const char* a2 = last ? nA : cA + (size_t)(t + 2) * kstep; const char* b2 = last ? nB : cB + (size_t)(t + 2) * kstep;
;             const char* a3 = a2 + kstep; const char* b3 = b2 + kstep;
;             if (last && has_next) S.a_ready(nxt);
;             if constexpr (SP2) {
;             PG8_LDB(B0, 0, 0); PG8_LDB(B1, 0, 1); PG8_SCHED; PG8_LDA(At, 0, 0); PG8_STAGE(PG8_SA(1, 1), a1 + hstep, voffA);
;             PG8_WAIT_V(8); PG8_WAIT_L(0); PG8_BAR; PG8_MMA(0, 0, At, B0); PG8_MMA(0, 1, At, B1); PG8_BAR; PG8_SCHED;
;             PG8_LDA(At, 0, 1); PG8_STAGE(PG8_SB(0, 0), b2, voffB); PG8_STAGE(PG8_SB(0, 1), b2 + hstep, voffB); PG8_STAGE(PG8_SA(0, 0), a2, voffA);
;             PG8_WAIT_V(8); PG8_WAIT_L(0); PG8_BAR; PG8_MMA(1, 0, At, B0); PG8_MMA(1, 1, At, B1); PG8_BAR; PG8_SCHED;
;             PG8_LDB(B0, 1, 0); PG8_LDB(B1, 1, 1); PG8_SCHED; PG8_LDA(At, 1, 0); PG8_STAGE(PG8_SA(0, 1), a2 + hstep, voffA);
;             PG8_WAIT_V(8); PG8_WAIT_L(0); PG8_BAR; PG8_MMA(0, 0, At, B0); PG8_MMA(0, 1, At, B1); PG8_BAR; PG8_SCHED;
;             PG8_LDA(At, 1, 1); PG8_STAGE(PG8_SB(1, 0), b3, voffB); PG8_STAGE(PG8_SB(1, 1), b3 + hstep, voffB); PG8_STAGE(PG8_SA(1, 0), a3, voffA);
;             PG8_WAIT_V(8); PG8_WAIT_L(0); PG8_BAR; PG8_MMA(1, 0, At, B0); PG8_MMA(1, 1, At, B1); PG8_BAR; PG8_SCHED;
	v_mfma_f32_16x16x32_bf16 v[64:67], v[176:179], v[208:211], v[64:67]
	s_setprio 0
	s_add_i32 s28, s33, s34
	v_lshl_add_u64 v[212:213], v[212:213], 0, s[18:19]
	s_mov_b32 m0, s28
	ds_read_b128 v[180:183], v151 offset:49152
	ds_read_b128 v[184:187], v151 offset:50176
	ds_read_b128 v[188:191], v151 offset:51200
	ds_read_b128 v[192:195], v151 offset:52224
	ds_read_b128 v[196:199], v151 offset:53248
	ds_read_b128 v[200:203], v151 offset:54272
	ds_read_b128 v[204:207], v151 offset:55296
	ds_read_b128 v[208:211], v151 offset:56320
	global_load_lds_dwordx4 v[212:213], off
	v_lshl_add_u64 v[212:213], v[214:215], 0, s[18:19]
	s_add_i32 m0, s28, 0x2000
	s_add_i32 s28, s62, s34
	global_load_lds_dwordx4 v[212:213], off
	v_lshl_add_u64 v[212:213], v[216:217], 0, s[18:19]
	s_mov_b32 m0, s28
	s_nop 0
	global_load_lds_dwordx4 v[212:213], off
	v_lshl_add_u64 v[212:213], v[218:219], 0, s[18:19]
	s_add_i32 m0, s28, 0x2000
	s_nop 0
	global_load_lds_dwordx4 v[212:213], off
	v_lshl_add_u64 v[212:213], v[220:221], 0, s[18:19]
	s_mov_b32 m0, s47
	s_nop 0
	global_load_lds_dwordx4 v[212:213], off
	v_lshl_add_u64 v[212:213], v[222:223], 0, s[18:19]
	s_mov_b32 m0, s49
	s_nop 0
	global_load_lds_dwordx4 v[212:213], off
	s_waitcnt vmcnt(8)
	s_waitcnt lgkmcnt(0)
	s_setprio 1
	s_barrier
	v_mfma_f32_16x16x32_bf16 v[60:63], v[142:145], v[180:183], v[60:63]
	v_mfma_f32_16x16x32_bf16 v[56:59], v[156:159], v[180:183], v[56:59]
	v_mfma_f32_16x16x32_bf16 v[44:47], v[142:145], v[188:191], v[44:47]
	v_mfma_f32_16x16x32_bf16 v[40:43], v[156:159], v[188:191], v[40:43]
	v_mfma_f32_16x16x32_bf16 v[28:31], v[142:145], v[196:199], v[28:31]
	v_mfma_f32_16x16x32_bf16 v[24:27], v[156:159], v[196:199], v[24:27]
	v_mfma_f32_16x16x32_bf16 v[12:15], v[142:145], v[204:207], v[12:15]
	v_mfma_f32_16x16x32_bf16 v[8:11], v[156:159], v[204:207], v[8:11]
	v_mfma_f32_16x16x32_bf16 v[60:63], v[152:155], v[184:187], v[60:63]
	v_mfma_f32_16x16x32_bf16 v[56:59], v[160:163], v[184:187], v[56:59]
	v_mfma_f32_16x16x32_bf16 v[44:47], v[152:155], v[192:195], v[44:47]
	v_mfma_f32_16x16x32_bf16 v[40:43], v[160:163], v[192:195], v[40:43]
	v_mfma_f32_16x16x32_bf16 v[28:31], v[152:155], v[200:203], v[28:31]
	v_mfma_f32_16x16x32_bf16 v[24:27], v[160:163], v[200:203], v[24:27]
	v_mfma_f32_16x16x32_bf16 v[12:15], v[152:155], v[208:211], v[12:15]
	v_mfma_f32_16x16x32_bf16 v[8:11], v[160:163], v[208:211], v[8:11]
	v_mfma_f32_16x16x32_bf16 v[52:55], v[164:167], v[180:183], v[52:55]
	v_mfma_f32_16x16x32_bf16 v[48:51], v[172:175], v[180:183], v[48:51]
	v_mfma_f32_16x16x32_bf16 v[36:39], v[164:167], v[188:191], v[36:39]
	v_mfma_f32_16x16x32_bf16 v[32:35], v[172:175], v[188:191], v[32:35]
	v_mfma_f32_16x16x32_bf16 v[20:23], v[164:167], v[196:199], v[20:23]
	v_mfma_f32_16x16x32_bf16 v[16:19], v[172:175], v[196:199], v[16:19]
	v_mfma_f32_16x16x32_bf16 v[4:7], v[164:167], v[204:207], v[4:7]
	v_mfma_f32_16x16x32_bf16 v[0:3], v[172:175], v[204:207], v[0:3]
	v_mfma_f32_16x16x32_bf16 v[52:55], v[168:171], v[184:187], v[52:55]
	v_mfma_f32_16x16x32_bf16 v[48:51], v[176:179], v[184:187], v[48:51]
	v_mfma_f32_16x16x32_bf16 v[36:39], v[168:171], v[192:195], v[36:39]
	v_mfma_f32_16x16x32_bf16 v[32:35], v[176:179], v[192:195], v[32:35]
	v_mfma_f32_16x16x32_bf16 v[20:23], v[168:171], v[200:203], v[20:23]
	v_mfma_f32_16x16x32_bf16 v[16:19], v[176:179], v[200:203], v[16:19]
	v_mfma_f32_16x16x32_bf16 v[4:7], v[168:171], v[208:211], v[4:7]
	s_setprio 2
	s_barrier
	v_mfma_f32_16x16x32_bf16 v[0:3], v[176:179], v[208:211], v[0:3]
	s_setprio 0
	s_add_u32 s26, s26, 0x100
	s_addc_u32 s27, s27, 0
	s_add_u32 s0, s0, 0x100
	s_addc_u32 s1, s1, 0
	s_cmp_ge_i32 s61, s50
	s_mov_b32 s28, s61
	s_cbranch_scc1 .LBB0_1180
.LBB0_1179:
	ds_read_b128 v[142:145], v149
	ds_read_b128 v[152:155], v149 offset:1024
	ds_read_b128 v[156:159], v149 offset:2048
	ds_read_b128 v[160:163], v149 offset:3072
	ds_read_b128 v[164:167], v150
	ds_read_b128 v[168:171], v150 offset:1024
	ds_read_b128 v[172:175], v150 offset:2048
	ds_read_b128 v[176:179], v150 offset:3072
	s_add_i32 s61, s28, 2
	s_add_u32 s33, s26, 0x80
	s_addc_u32 s29, s27, 0
	s_cmp_eq_u32 s53, s28
	s_cselect_b32 s28, s4, s33
	s_cselect_b32 s29, s5, s29
	s_cselect_b32 s63, s25, s1
	s_cselect_b32 s62, s24, s0
	v_lshl_add_u64 v[212:213], s[26:27], 0, v[136:137]
	s_add_i32 m0, s42, 0xc000
	ds_read_b128 v[180:183], v151
	ds_read_b128 v[184:187], v151 offset:1024
	ds_read_b128 v[188:191], v151 offset:2048
	ds_read_b128 v[192:195], v151 offset:3072
	ds_read_b128 v[196:199], v151 offset:4096
	ds_read_b128 v[200:203], v151 offset:5120
	ds_read_b128 v[204:207], v151 offset:6144
	ds_read_b128 v[208:211], v151 offset:7168
	global_load_lds_dwordx4 v[212:213], off
	v_lshl_add_u64 v[212:213], s[26:27], 0, v[138:139]
	s_add_i32 m0, s42, 0xe000
	s_nop 0
	global_load_lds_dwordx4 v[212:213], off
	s_waitcnt vmcnt(8)
	s_waitcnt lgkmcnt(0)
	s_setprio 1
	s_barrier
; #define PG8_STAGE(bufoff, gbase, voff) do { _Pragma("unroll") for (int _i = 0; _i < 2; ++_i) \
;         __builtin_amdgcn_global_load_lds((const unsigned*)((const char*)(gbase) + (voff)[_i]), (PG8_LAS unsigned*)(lds + (bufoff) + ldsw + _i * 8192), 16, 0, 0); } while (0)
; #define PG8_LDA(dst, b, h) do { _Pragma("unroll") for (int m = 0; m < 4; ++m) _Pragma("unroll") for (int k = 0; k < 2; ++k) dst[m][k] = *(const PG8_LAS bf16x8*)(lds + PG8_SA(b, h) + aoff + m * 2048 + k * 1024); } while (0)
; #define PG8_LDB(dst, b, h) do { _Pragma("unroll") for (int n = 0; n < 2; ++n) _Pragma("unroll") for (int k = 0; k < 2; ++k) dst[n][k] = *(const PG8_LAS bf16x8*)(lds + PG8_SB(b, h) + boff + n * 2048 + k * 1024); } while (0)
; #define PG8_MMA(ai, bj, At, Bt) do { __builtin_amdgcn_s_setprio(1); _Pragma("unroll") for (int m = 0; m < 4; ++m) _Pragma("unroll") for (int n = 0; n < 2; ++n) _Pragma("unroll") for (int k = 0; k < 2; ++k) \
;         acc[ai][bj][m][n] = __builtin_amdgcn_mfma_f32_16x16x32_bf16(Bt[n][k], At[m][k], acc[ai][bj][m][n], 0, 0, 0); __builtin_amdgcn_s_setprio(0); } while (0)
; #define PG8_BAR __builtin_amdgcn_s_barrier()
; template <class Epi, class Sched, bool ALIGN_EPI = false, bool SP2 = false>
; __device__ __forceinline__ void gemm_phase(PG8_LAS unsigned char* lds, const Gemm g, const Sched& S, const Epi& E, const int wid) {
;     ...
;             PG8_LDB(B0, 0, 0); PG8_LDB(B1, 0, 1); PG8_SCHED; PG8_LDA(At, 0, 0); PG8_STAGE(PG8_SA(1, 1), a1 + hstep, voffA);
;             PG8_WAIT_V(8); PG8_WAIT_L(0); PG8_BAR; PG8_MMA(0, 0, At, B0); PG8_MMA(0, 1, At, B1); PG8_BAR; PG8_SCHED;
;             PG8_LDA(At, 0, 1); PG8_STAGE(PG8_SB(0, 0), b2, voffB); PG8_STAGE(PG8_SB(0, 1), b2 + hstep, voffB); PG8_STAGE(PG8_SA(0, 0), a2, voffA);
;             PG8_WAIT_V(8); PG8_WAIT_L(0); PG8_BAR; PG8_MMA(1, 0, At, B0); PG8_MMA(1, 1, At, B1); PG8_BAR; PG8_SCHED;
;             PG8_LDB(B0, 1, 0); PG8_LDB(B1, 1, 1); PG8_SCHED; PG8_LDA(At, 1, 0); PG8_STAGE(PG8_SA(0, 1), a2 + hstep, voffA);
;             PG8_WAIT_V(8); PG8_WAIT_L(0); PG8_BAR; PG8_MMA(0, 0, At, B0); PG8_MMA(0, 1, At, B1); PG8_BAR; PG8_SCHED;
;             PG8_LDA(At, 1, 1); PG8_STAGE(PG8_SB(1, 0), b3, voffB); PG8_STAGE(PG8_SB(1, 1), b3 + hstep, voffB); PG8_STAGE(PG8_SA(1, 0), a3, voffA);
;             PG8_WAIT_V(8); PG8_WAIT_L(0); PG8_BAR; PG8_MMA(1, 0, At, B0); PG8_MMA(1, 1, At, B1); PG8_BAR; PG8_SCHED;
	v_mfma_f32_16x16x32_bf16 v[124:127], v[142:145], v[180:183], v[124:127]
	v_mfma_f32_16x16x32_bf16 v[120:123], v[156:159], v[180:183], v[120:123]
	v_mfma_f32_16x16x32_bf16 v[108:111], v[142:145], v[188:191], v[108:111]
	v_mfma_f32_16x16x32_bf16 v[104:107], v[156:159], v[188:191], v[104:107]
	v_mfma_f32_16x16x32_bf16 v[92:95], v[142:145], v[196:199], v[92:95]
	v_mfma_f32_16x16x32_bf16 v[88:91], v[156:159], v[196:199], v[88:91]
	v_mfma_f32_16x16x32_bf16 v[76:79], v[142:145], v[204:207], v[76:79]
	v_mfma_f32_16x16x32_bf16 v[72:75], v[156:159], v[204:207], v[72:75]
	v_mfma_f32_16x16x32_bf16 v[124:127], v[152:155], v[184:187], v[124:127]
	v_mfma_f32_16x16x32_bf16 v[120:123], v[160:163], v[184:187], v[120:123]
	v_mfma_f32_16x16x32_bf16 v[108:111], v[152:155], v[192:195], v[108:111]
	v_mfma_f32_16x16x32_bf16 v[104:107], v[160:163], v[192:195], v[104:107]
	v_mfma_f32_16x16x32_bf16 v[92:95], v[152:155], v[200:203], v[92:95]
	v_mfma_f32_16x16x32_bf16 v[88:91], v[160:163], v[200:203], v[88:91]
	v_mfma_f32_16x16x32_bf16 v[76:79], v[152:155], v[208:211], v[76:79]
	v_mfma_f32_16x16x32_bf16 v[72:75], v[160:163], v[208:211], v[72:75]
	v_mfma_f32_16x16x32_bf16 v[116:119], v[164:167], v[180:183], v[116:119]
	v_mfma_f32_16x16x32_bf16 v[112:115], v[172:175], v[180:183], v[112:115]
	v_mfma_f32_16x16x32_bf16 v[100:103], v[164:167], v[188:191], v[100:103]
	v_mfma_f32_16x16x32_bf16 v[96:99], v[172:175], v[188:191], v[96:99]
	v_mfma_f32_16x16x32_bf16 v[84:87], v[164:167], v[196:199], v[84:87]
	v_mfma_f32_16x16x32_bf16 v[80:83], v[172:175], v[196:199], v[80:83]
	v_mfma_f32_16x16x32_bf16 v[68:71], v[164:167], v[204:207], v[68:71]
	v_mfma_f32_16x16x32_bf16 v[64:67], v[172:175], v[204:207], v[64:67]
	v_mfma_f32_16x16x32_bf16 v[116:119], v[168:171], v[184:187], v[116:119]
	v_mfma_f32_16x16x32_bf16 v[112:115], v[176:179], v[184:187], v[112:115]
	v_mfma_f32_16x16x32_bf16 v[100:103], v[168:171], v[192:195], v[100:103]
	v_mfma_f32_16x16x32_bf16 v[96:99], v[176:179], v[192:195], v[96:99]
	v_mfma_f32_16x16x32_bf16 v[84:87], v[168:171], v[200:203], v[84:87]
	v_mfma_f32_16x16x32_bf16 v[80:83], v[176:179], v[200:203], v[80:83]
	v_mfma_f32_16x16x32_bf16 v[68:71], v[168:171], v[208:211], v[68:71]
	s_setprio 2
	s_barrier
	v_mfma_f32_16x16x32_bf16 v[64:67], v[176:179], v[208:211], v[64:67]
	s_setprio 0
	s_add_i32 s33, s55, s34
	v_lshl_add_u64 v[212:213], s[62:63], 0, v[132:133]
	s_mov_b32 m0, s33
	ds_read_b128 v[180:183], v151 offset:16384
	ds_read_b128 v[184:187], v151 offset:17408
	ds_read_b128 v[188:191], v151 offset:18432
	ds_read_b128 v[192:195], v151 offset:19456
	ds_read_b128 v[196:199], v151 offset:20480
	ds_read_b128 v[200:203], v151 offset:21504
	ds_read_b128 v[204:207], v151 offset:22528
	ds_read_b128 v[208:211], v151 offset:23552
	global_load_lds_dwordx4 v[212:213], off
	s_add_i32 m0, s33, 0x2000
	v_lshl_add_u64 v[214:215], s[62:63], 0, v[128:129]
	s_add_u32 s62, s62, s8
	s_addc_u32 s63, s63, s9
	s_add_i32 s33, s56, s34
	global_load_lds_dwordx4 v[214:215], off
	v_lshl_add_u64 v[216:217], s[62:63], 0, v[132:133]
	s_mov_b32 m0, s33
	v_lshl_add_u64 v[218:219], s[62:63], 0, v[128:129]
	global_load_lds_dwordx4 v[216:217], off
	s_add_i32 m0, s33, 0x2000
	v_lshl_add_u64 v[220:221], s[28:29], 0, v[134:135]
	global_load_lds_dwordx4 v[218:219], off
	s_mov_b32 m0, s42
	v_lshl_add_u64 v[222:223], s[28:29], 0, v[130:131]
	global_load_lds_dwordx4 v[220:221], off
	s_mov_b32 m0, s43
	s_nop 0
	global_load_lds_dwordx4 v[222:223], off
	s_waitcnt vmcnt(8)
	s_waitcnt lgkmcnt(0)
	s_setprio 1
	s_barrier
	v_mfma_f32_16x16x32_bf16 v[60:63], v[142:145], v[180:183], v[60:63]
	v_mfma_f32_16x16x32_bf16 v[56:59], v[156:159], v[180:183], v[56:59]
	v_mfma_f32_16x16x32_bf16 v[44:47], v[142:145], v[188:191], v[44:47]
	v_mfma_f32_16x16x32_bf16 v[40:43], v[156:159], v[188:191], v[40:43]
	v_mfma_f32_16x16x32_bf16 v[28:31], v[142:145], v[196:199], v[28:31]
	v_mfma_f32_16x16x32_bf16 v[24:27], v[156:159], v[196:199], v[24:27]
	v_mfma_f32_16x16x32_bf16 v[12:15], v[142:145], v[204:207], v[12:15]
	v_mfma_f32_16x16x32_bf16 v[8:11], v[156:159], v[204:207], v[8:11]
	v_mfma_f32_16x16x32_bf16 v[60:63], v[152:155], v[184:187], v[60:63]
	v_mfma_f32_16x16x32_bf16 v[56:59], v[160:163], v[184:187], v[56:59]
	v_mfma_f32_16x16x32_bf16 v[44:47], v[152:155], v[192:195], v[44:47]
	v_mfma_f32_16x16x32_bf16 v[40:43], v[160:163], v[192:195], v[40:43]
	v_mfma_f32_16x16x32_bf16 v[28:31], v[152:155], v[200:203], v[28:31]
	v_mfma_f32_16x16x32_bf16 v[24:27], v[160:163], v[200:203], v[24:27]
	v_mfma_f32_16x16x32_bf16 v[12:15], v[152:155], v[208:211], v[12:15]
	v_mfma_f32_16x16x32_bf16 v[8:11], v[160:163], v[208:211], v[8:11]
	v_mfma_f32_16x16x32_bf16 v[52:55], v[164:167], v[180:183], v[52:55]
	v_mfma_f32_16x16x32_bf16 v[48:51], v[172:175], v[180:183], v[48:51]
	v_mfma_f32_16x16x32_bf16 v[36:39], v[164:167], v[188:191], v[36:39]
	v_mfma_f32_16x16x32_bf16 v[32:35], v[172:175], v[188:191], v[32:35]
	v_mfma_f32_16x16x32_bf16 v[20:23], v[164:167], v[196:199], v[20:23]
	v_mfma_f32_16x16x32_bf16 v[16:19], v[172:175], v[196:199], v[16:19]
	v_mfma_f32_16x16x32_bf16 v[4:7], v[164:167], v[204:207], v[4:7]
	v_mfma_f32_16x16x32_bf16 v[0:3], v[172:175], v[204:207], v[0:3]
	v_mfma_f32_16x16x32_bf16 v[52:55], v[168:171], v[184:187], v[52:55]
	v_mfma_f32_16x16x32_bf16 v[48:51], v[176:179], v[184:187], v[48:51]
	v_mfma_f32_16x16x32_bf16 v[36:39], v[168:171], v[192:195], v[36:39]
	v_mfma_f32_16x16x32_bf16 v[32:35], v[176:179], v[192:195], v[32:35]
	v_mfma_f32_16x16x32_bf16 v[20:23], v[168:171], v[200:203], v[20:23]
	v_mfma_f32_16x16x32_bf16 v[16:19], v[176:179], v[200:203], v[16:19]
	v_mfma_f32_16x16x32_bf16 v[4:7], v[168:171], v[208:211], v[4:7]
	s_setprio 2
	s_barrier
; #define PG8_STAGE(bufoff, gbase, voff) do { _Pragma("unroll") for (int _i = 0; _i < 2; ++_i) \
;         __builtin_amdgcn_global_load_lds((const unsigned*)((const char*)(gbase) + (voff)[_i]), (PG8_LAS unsigned*)(lds + (bufoff) + ldsw + _i * 8192), 16, 0, 0); } while (0)
; #define PG8_LDA(dst, b, h) do { _Pragma("unroll") for (int m = 0; m < 4; ++m) _Pragma("unroll") for (int k = 0; k < 2; ++k) dst[m][k] = *(const PG8_LAS bf16x8*)(lds + PG8_SA(b, h) + aoff + m * 2048 + k * 1024); } while (0)
; #define PG8_LDB(dst, b, h) do { _Pragma("unroll") for (int n = 0; n < 2; ++n) _Pragma("unroll") for (int k = 0; k < 2; ++k) dst[n][k] = *(const PG8_LAS bf16x8*)(lds + PG8_SB(b, h) + boff + n * 2048 + k * 1024); } while (0)
; #define PG8_MMA(ai, bj, At, Bt) do { __builtin_amdgcn_s_setprio(1); _Pragma("unroll") for (int m = 0; m < 4; ++m) _Pragma("unroll") for (int n = 0; n < 2; ++n) _Pragma("unroll") for (int k = 0; k < 2; ++k) \
;         acc[ai][bj][m][n] = __builtin_amdgcn_mfma_f32_16x16x32_bf16(Bt[n][k], At[m][k], acc[ai][bj][m][n], 0, 0, 0); __builtin_amdgcn_s_setprio(0); } while (0)
; #define PG8_BAR __builtin_amdgcn_s_barrier()
; template <class Epi, class Sched, bool ALIGN_EPI = false, bool SP2 = false>
; __device__ __forceinline__ void gemm_phase(PG8_LAS unsigned char* lds, const Gemm g, const Sched& S, const Epi& E, const int wid) {
;     ...
;             PG8_LDB(B0, 0, 0); PG8_LDB(B1, 0, 1); PG8_SCHED; PG8_LDA(At, 0, 0); PG8_STAGE(PG8_SA(1, 1), a1 + hstep, voffA);
;             PG8_WAIT_V(8); PG8_WAIT_L(0); PG8_BAR; PG8_MMA(0, 0, At, B0); PG8_MMA(0, 1, At, B1); PG8_BAR; PG8_SCHED;
;             PG8_LDA(At, 0, 1); PG8_STAGE(PG8_SB(0, 0), b2, voffB); PG8_STAGE(PG8_SB(0, 1), b2 + hstep, voffB); PG8_STAGE(PG8_SA(0, 0), a2, voffA);
;             PG8_WAIT_V(8); PG8_WAIT_L(0); PG8_BAR; PG8_MMA(1, 0, At, B0); PG8_MMA(1, 1, At, B1); PG8_BAR; PG8_SCHED;
;             PG8_LDB(B0, 1, 0); PG8_LDB(B1, 1, 1); PG8_SCHED; PG8_LDA(At, 1, 0); PG8_STAGE(PG8_SA(0, 1), a2 + hstep, voffA);
;             PG8_WAIT_V(8); PG8_WAIT_L(0); PG8_BAR; PG8_MMA(0, 0, At, B0); PG8_MMA(0, 1, At, B1); PG8_BAR; PG8_SCHED;
;             PG8_LDA(At, 1, 1); PG8_STAGE(PG8_SB(1, 0), b3, voffB); PG8_STAGE(PG8_SB(1, 1), b3 + hstep, voffB); PG8_STAGE(PG8_SA(1, 0), a3, voffA);
;             PG8_WAIT_V(8); PG8_WAIT_L(0); PG8_BAR; PG8_MMA(1, 0, At, B0); PG8_MMA(1, 1, At, B1); PG8_BAR; PG8_SCHED;
	v_mfma_f32_16x16x32_bf16 v[0:3], v[176:179], v[208:211], v[0:3]
	s_setprio 0
	s_add_i32 s33, 0, 0x18000
	s_add_i32 s62, 0, 0x1c000
	v_add_u32_e32 v160, s33, v148
	v_add_u32_e32 v176, s62, v148
	ds_read_b128 v[142:145], v160
	ds_read_b128 v[152:155], v160 offset:1024
	ds_read_b128 v[156:159], v160 offset:2048
	ds_read_b128 v[160:163], v160 offset:3072
	ds_read_b128 v[164:167], v176
	ds_read_b128 v[168:171], v176 offset:1024
	ds_read_b128 v[172:175], v176 offset:2048
	ds_read_b128 v[176:179], v176 offset:3072
	s_add_u32 s28, s28, s8
	s_addc_u32 s29, s29, s9
	s_mov_b32 m0, s44
	v_lshl_add_u64 v[224:225], s[28:29], 0, v[134:135]
	ds_read_b128 v[180:183], v151 offset:32768
	ds_read_b128 v[184:187], v151 offset:33792
	ds_read_b128 v[188:191], v151 offset:34816
	ds_read_b128 v[192:195], v151 offset:35840
	ds_read_b128 v[196:199], v151 offset:36864
	ds_read_b128 v[200:203], v151 offset:37888
	ds_read_b128 v[204:207], v151 offset:38912
	ds_read_b128 v[208:211], v151 offset:39936
	global_load_lds_dwordx4 v[224:225], off
	v_lshl_add_u64 v[224:225], s[28:29], 0, v[130:131]
	s_mov_b32 m0, s45
	s_nop 0
	global_load_lds_dwordx4 v[224:225], off
	s_waitcnt vmcnt(8)
	s_waitcnt lgkmcnt(0)
	s_setprio 1
	s_barrier
	v_mfma_f32_16x16x32_bf16 v[124:127], v[142:145], v[180:183], v[124:127]
	v_mfma_f32_16x16x32_bf16 v[120:123], v[156:159], v[180:183], v[120:123]
	v_mfma_f32_16x16x32_bf16 v[108:111], v[142:145], v[188:191], v[108:111]
	v_mfma_f32_16x16x32_bf16 v[104:107], v[156:159], v[188:191], v[104:107]
	v_mfma_f32_16x16x32_bf16 v[92:95], v[142:145], v[196:199], v[92:95]
	v_mfma_f32_16x16x32_bf16 v[88:91], v[156:159], v[196:199], v[88:91]
	v_mfma_f32_16x16x32_bf16 v[76:79], v[142:145], v[204:207], v[76:79]
	v_mfma_f32_16x16x32_bf16 v[72:75], v[156:159], v[204:207], v[72:75]
	v_mfma_f32_16x16x32_bf16 v[124:127], v[152:155], v[184:187], v[124:127]
	v_mfma_f32_16x16x32_bf16 v[120:123], v[160:163], v[184:187], v[120:123]
	v_mfma_f32_16x16x32_bf16 v[108:111], v[152:155], v[192:195], v[108:111]
	v_mfma_f32_16x16x32_bf16 v[104:107], v[160:163], v[192:195], v[104:107]
	v_mfma_f32_16x16x32_bf16 v[92:95], v[152:155], v[200:203], v[92:95]
	v_mfma_f32_16x16x32_bf16 v[88:91], v[160:163], v[200:203], v[88:91]
	v_mfma_f32_16x16x32_bf16 v[76:79], v[152:155], v[208:211], v[76:79]
	v_mfma_f32_16x16x32_bf16 v[72:75], v[160:163], v[208:211], v[72:75]
	v_mfma_f32_16x16x32_bf16 v[116:119], v[164:167], v[180:183], v[116:119]
	v_mfma_f32_16x16x32_bf16 v[112:115], v[172:175], v[180:183], v[112:115]
	v_mfma_f32_16x16x32_bf16 v[100:103], v[164:167], v[188:191], v[100:103]
	v_mfma_f32_16x16x32_bf16 v[96:99], v[172:175], v[188:191], v[96:99]
	v_mfma_f32_16x16x32_bf16 v[84:87], v[164:167], v[196:199], v[84:87]
	v_mfma_f32_16x16x32_bf16 v[80:83], v[172:175], v[196:199], v[80:83]
	v_mfma_f32_16x16x32_bf16 v[68:71], v[164:167], v[204:207], v[68:71]
	v_mfma_f32_16x16x32_bf16 v[64:67], v[172:175], v[204:207], v[64:67]
	v_mfma_f32_16x16x32_bf16 v[116:119], v[168:171], v[184:187], v[116:119]
	v_mfma_f32_16x16x32_bf16 v[112:115], v[176:179], v[184:187], v[112:115]
	v_mfma_f32_16x16x32_bf16 v[100:103], v[168:171], v[192:195], v[100:103]
	v_mfma_f32_16x16x32_bf16 v[96:99], v[176:179], v[192:195], v[96:99]
	v_mfma_f32_16x16x32_bf16 v[84:87], v[168:171], v[200:203], v[84:87]
	v_mfma_f32_16x16x32_bf16 v[80:83], v[176:179], v[200:203], v[80:83]
	v_mfma_f32_16x16x32_bf16 v[68:71], v[168:171], v[208:211], v[68:71]
	s_setprio 2
	s_barrier
; #define PG8_STAGE(bufoff, gbase, voff) do { _Pragma("unroll") for (int _i = 0; _i < 2; ++_i) \
;         __builtin_amdgcn_global_load_lds((const unsigned*)((const char*)(gbase) + (voff)[_i]), (PG8_LAS unsigned*)(lds + (bufoff) + ldsw + _i * 8192), 16, 0, 0); } while (0)
; #define PG8_LDA(dst, b, h) do { _Pragma("unroll") for (int m = 0; m < 4; ++m) _Pragma("unroll") for (int k = 0; k < 2; ++k) dst[m][k] = *(const PG8_LAS bf16x8*)(lds + PG8_SA(b, h) + aoff + m * 2048 + k * 1024); } while (0)
; #define PG8_LDB(dst, b, h) do { _Pragma("unroll") for (int n = 0; n < 2; ++n) _Pragma("unroll") for (int k = 0; k < 2; ++k) dst[n][k] = *(const PG8_LAS bf16x8*)(lds + PG8_SB(b, h) + boff + n * 2048 + k * 1024); } while (0)
; #define PG8_MMA(ai, bj, At, Bt) do { __builtin_amdgcn_s_setprio(1); _Pragma("unroll") for (int m = 0; m < 4; ++m) _Pragma("unroll") for (int n = 0; n < 2; ++n) _Pragma("unroll") for (int k = 0; k < 2; ++k) \
;         acc[ai][bj][m][n] = __builtin_amdgcn_mfma_f32_16x16x32_bf16(Bt[n][k], At[m][k], acc[ai][bj][m][n], 0, 0, 0); __builtin_amdgcn_s_setprio(0); } while (0)
; #define PG8_BAR __builtin_amdgcn_s_barrier()
; template <class Epi, class Sched, bool ALIGN_EPI = false, bool SP2 = false>
; __device__ __forceinline__ void gemm_phase(PG8_LAS unsigned char* lds, const Gemm g, const Sched& S, const Epi& E, const int wid) {
;     ...
;             PG8_LDB(B0, 0, 0); PG8_LDB(B1, 0, 1); PG8_SCHED; PG8_LDA(At, 0, 0); PG8_STAGE(PG8_SA(1, 1), a1 + hstep, voffA);
;             PG8_WAIT_V(8); PG8_WAIT_L(0); PG8_BAR; PG8_MMA(0, 0, At, B0); PG8_MMA(0, 1, At, B1); PG8_BAR; PG8_SCHED;
;             PG8_LDA(At, 0, 1); PG8_STAGE(PG8_SB(0, 0), b2, voffB); PG8_STAGE(PG8_SB(0, 1), b2 + hstep, voffB); PG8_STAGE(PG8_SA(0, 0), a2, voffA);
;             PG8_WAIT_V(8); PG8_WAIT_L(0); PG8_BAR; PG8_MMA(1, 0, At, B0); PG8_MMA(1, 1, At, B1); PG8_BAR; PG8_SCHED;
;             PG8_LDB(B0, 1, 0); PG8_LDB(B1, 1, 1); PG8_SCHED; PG8_LDA(At, 1, 0); PG8_STAGE(PG8_SA(0, 1), a2 + hstep, voffA);
;             PG8_WAIT_V(8); PG8_WAIT_L(0); PG8_BAR; PG8_MMA(0, 0, At, B0); PG8_MMA(0, 1, At, B1); PG8_BAR; PG8_SCHED;
;             PG8_LDA(At, 1, 1); PG8_STAGE(PG8_SB(1, 0), b3, voffB); PG8_STAGE(PG8_SB(1, 1), b3 + hstep, voffB); PG8_STAGE(PG8_SA(1, 0), a3, voffA);
;             PG8_WAIT_V(8); PG8_WAIT_L(0); PG8_BAR; PG8_MMA(1, 0, At, B0); PG8_MMA(1, 1, At, B1); PG8_BAR; PG8_SCHED;
	v_mfma_f32_16x16x32_bf16 v[64:67], v[176:179], v[208:211], v[64:67]
	s_setprio 0
	s_add_i32 s28, s33, s34
	v_lshl_add_u64 v[212:213], v[212:213], 0, s[18:19]
	s_mov_b32 m0, s28
	ds_read_b128 v[180:183], v151 offset:49152
	ds_read_b128 v[184:187], v151 offset:50176
	ds_read_b128 v[188:191], v151 offset:51200
	ds_read_b128 v[192:195], v151 offset:52224
	ds_read_b128 v[196:199], v151 offset:53248
	ds_read_b128 v[200:203], v151 offset:54272
	ds_read_b128 v[204:207], v151 offset:55296
	ds_read_b128 v[208:211], v151 offset:56320
	global_load_lds_dwordx4 v[212:213], off
	v_lshl_add_u64 v[212:213], v[214:215], 0, s[18:19]
	s_add_i32 m0, s28, 0x2000
	s_add_i32 s28, s62, s34
	global_load_lds_dwordx4 v[212:213], off
	v_lshl_add_u64 v[212:213], v[216:217], 0, s[18:19]
	s_mov_b32 m0, s28
	s_nop 0
	global_load_lds_dwordx4 v[212:213], off
	v_lshl_add_u64 v[212:213], v[218:219], 0, s[18:19]
	s_add_i32 m0, s28, 0x2000
	s_nop 0
	global_load_lds_dwordx4 v[212:213], off
	v_lshl_add_u64 v[212:213], v[220:221], 0, s[18:19]
	s_mov_b32 m0, s47
	s_nop 0
	global_load_lds_dwordx4 v[212:213], off
	v_lshl_add_u64 v[212:213], v[222:223], 0, s[18:19]
	s_mov_b32 m0, s49
	s_nop 0
	global_load_lds_dwordx4 v[212:213], off
	s_waitcnt vmcnt(8)
	s_waitcnt lgkmcnt(0)
	s_setprio 1
	s_barrier
	v_mfma_f32_16x16x32_bf16 v[60:63], v[142:145], v[180:183], v[60:63]
	v_mfma_f32_16x16x32_bf16 v[56:59], v[156:159], v[180:183], v[56:59]
	v_mfma_f32_16x16x32_bf16 v[44:47], v[142:145], v[188:191], v[44:47]
	v_mfma_f32_16x16x32_bf16 v[40:43], v[156:159], v[188:191], v[40:43]
	v_mfma_f32_16x16x32_bf16 v[28:31], v[142:145], v[196:199], v[28:31]
	v_mfma_f32_16x16x32_bf16 v[24:27], v[156:159], v[196:199], v[24:27]
	v_mfma_f32_16x16x32_bf16 v[12:15], v[142:145], v[204:207], v[12:15]
	v_mfma_f32_16x16x32_bf16 v[8:11], v[156:159], v[204:207], v[8:11]
	v_mfma_f32_16x16x32_bf16 v[60:63], v[152:155], v[184:187], v[60:63]
	v_mfma_f32_16x16x32_bf16 v[56:59], v[160:163], v[184:187], v[56:59]
	v_mfma_f32_16x16x32_bf16 v[44:47], v[152:155], v[192:195], v[44:47]
	v_mfma_f32_16x16x32_bf16 v[40:43], v[160:163], v[192:195], v[40:43]
	v_mfma_f32_16x16x32_bf16 v[28:31], v[152:155], v[200:203], v[28:31]
	v_mfma_f32_16x16x32_bf16 v[24:27], v[160:163], v[200:203], v[24:27]
	v_mfma_f32_16x16x32_bf16 v[12:15], v[152:155], v[208:211], v[12:15]
	v_mfma_f32_16x16x32_bf16 v[8:11], v[160:163], v[208:211], v[8:11]
	v_mfma_f32_16x16x32_bf16 v[52:55], v[164:167], v[180:183], v[52:55]
	v_mfma_f32_16x16x32_bf16 v[48:51], v[172:175], v[180:183], v[48:51]
	v_mfma_f32_16x16x32_bf16 v[36:39], v[164:167], v[188:191], v[36:39]
	v_mfma_f32_16x16x32_bf16 v[32:35], v[172:175], v[188:191], v[32:35]
	v_mfma_f32_16x16x32_bf16 v[20:23], v[164:167], v[196:199], v[20:23]
	v_mfma_f32_16x16x32_bf16 v[16:19], v[172:175], v[196:199], v[16:19]
	v_mfma_f32_16x16x32_bf16 v[4:7], v[164:167], v[204:207], v[4:7]
	v_mfma_f32_16x16x32_bf16 v[0:3], v[172:175], v[204:207], v[0:3]
	v_mfma_f32_16x16x32_bf16 v[52:55], v[168:171], v[184:187], v[52:55]
	v_mfma_f32_16x16x32_bf16 v[48:51], v[176:179], v[184:187], v[48:51]
	v_mfma_f32_16x16x32_bf16 v[36:39], v[168:171], v[192:195], v[36:39]
	v_mfma_f32_16x16x32_bf16 v[32:35], v[176:179], v[192:195], v[32:35]
	v_mfma_f32_16x16x32_bf16 v[20:23], v[168:171], v[200:203], v[20:23]
	v_mfma_f32_16x16x32_bf16 v[16:19], v[176:179], v[200:203], v[16:19]
	v_mfma_f32_16x16x32_bf16 v[4:7], v[168:171], v[208:211], v[4:7]
	s_setprio 2
	s_barrier
	v_mfma_f32_16x16x32_bf16 v[0:3], v[176:179], v[208:211], v[0:3]
	s_setprio 0
	s_add_u32 s26, s26, 0x100
	s_addc_u32 s27, s27, 0
	s_add_u32 s0, s0, 0x100
	s_addc_u32 s1, s1, 0
	s_cmp_ge_i32 s61, s50
	s_mov_b32 s28, s61
	s_cbranch_scc0 .LBB0_1179

; #define PG8_WAIT_V(n) asm volatile("s_waitcnt vmcnt(" #n ")" ::: "memory")
; #define PG8_WAIT_L(n) asm volatile("s_waitcnt lgkmcnt(" #n ")" ::: "memory")
; #define PG8_BAR __builtin_amdgcn_s_barrier()
; template <class Epi, class Sched, bool ALIGN_EPI = false, bool SP2 = false>
; __device__ __forceinline__ void gemm_phase(PG8_LAS unsigned char* lds, const Gemm g, const Sched& S, const Epi& E, const int wid) {
;     ...
;     for (;;) {
;         const bool has_next = S.next(ui + 1, nxt);
;         const char* nA = has_next ? (const char*)g.A + (size_t)nxt.pm * tstep : cA; const char* nB = has_next ? (const char*)g.Bt + (size_t)nxt.pn * tstep : cB;
;         for (int t = 0; t < nt; t += 2) {
;             const bool last = (t == nt - 2);
;             const char* a1 = cA + (size_t)(t + 1) * kstep;
;             const char* a2 = last ? nA : cA + (size_t)(t + 2) * kstep; const char* b2 = last ? nB : cB + (size_t)(t + 2) * kstep;
;             const char* a3 = a2 + kstep; const char* b3 = b2 + kstep;
;             if (last && has_next) S.a_ready(nxt);
;             if constexpr (SP2) {
;             PG8_LDB(B0, 0, 0); PG8_LDB(B1, 0, 1); PG8_SCHED; PG8_LDA(At, 0, 0); PG8_STAGE(PG8_SA(1, 1), a1 + hstep, voffA);
;             PG8_WAIT_V(8); PG8_WAIT_L(0); PG8_BAR; PG8_MMA(0, 0, At, B0); PG8_MMA(0, 1, At, B1); PG8_BAR; PG8_SCHED;
;             PG8_LDA(At, 0, 1); PG8_STAGE(PG8_SB(0, 0), b2, voffB); PG8_STAGE(PG8_SB(0, 1), b2 + hstep, voffB); PG8_STAGE(PG8_SA(0, 0), a2, voffA);
;             PG8_WAIT_V(8); PG8_WAIT_L(0); PG8_BAR; PG8_MMA(1, 0, At, B0); PG8_MMA(1, 1, At, B1); PG8_BAR; PG8_SCHED;
;             PG8_LDB(B0, 1, 0); PG8_LDB(B1, 1, 1); PG8_SCHED; PG8_LDA(At, 1, 0); PG8_STAGE(PG8_SA(0, 1), a2 + hstep, voffA);
;             PG8_WAIT_V(8); PG8_WAIT_L(0); PG8_BAR; PG8_MMA(0, 0, At, B0); PG8_MMA(0, 1, At, B1); PG8_BAR; PG8_SCHED;
;             PG8_LDA(At, 1, 1); PG8_STAGE(PG8_SB(1, 0), b3, voffB); PG8_STAGE(PG8_SB(1, 1), b3 + hstep, voffB); PG8_STAGE(PG8_SA(1, 0), a3, voffA);
;             PG8_WAIT_V(8); PG8_WAIT_L(0); PG8_BAR; PG8_MMA(1, 0, At, B0); PG8_MMA(1, 1, At, B1); PG8_BAR; PG8_SCHED;
;     ...
;         for (int a = 0; a < 2; ++a)
; #pragma unroll
;             for (int b = 0; b < 2; ++b)
; #pragma unroll
;                 for (int m = 0; m < 4; ++m)
; #pragma unroll
;                     for (int n = 0; n < 2; ++n) acc[a][b][m][n] = (f32x4){0.f, 0.f, 0.f, 0.f};
.LBB0_1256:
	s_andn2_b64 vcc, exec, s[20:21]
	s_cbranch_vccnz .Lz_GMB
	s_add_u32 s28, s28, 0x80
	s_addc_u32 s29, s29, 0
	s_add_u32 s0, s30, 0x100
	s_addc_u32 s1, s31, 0
	s_mov_b32 s30, 0
	ds_read_b128 v[142:145], v149
	ds_read_b128 v[152:155], v149 offset:1024
	ds_read_b128 v[156:159], v149 offset:2048
	ds_read_b128 v[160:163], v149 offset:3072
	ds_read_b128 v[164:167], v150
	ds_read_b128 v[168:171], v150 offset:1024
	ds_read_b128 v[172:175], v150 offset:2048
	ds_read_b128 v[176:179], v150 offset:3072
	s_add_i32 s66, s30, 2
	s_add_u32 s33, s28, 0x80
	s_addc_u32 s31, s29, 0
	s_cmp_eq_u32 s57, s30
	s_cselect_b32 s30, s4, s33
	s_cselect_b32 s31, s5, s31
	s_cselect_b32 s69, s27, s1
	s_cselect_b32 s68, s26, s0
	v_lshl_add_u64 v[212:213], s[28:29], 0, v[136:137]
	s_add_i32 m0, s46, 0xc000
	ds_read_b128 v[180:183], v151
	ds_read_b128 v[184:187], v151 offset:1024
	ds_read_b128 v[188:191], v151 offset:2048
	ds_read_b128 v[192:195], v151 offset:3072
	ds_read_b128 v[196:199], v151 offset:4096
	ds_read_b128 v[200:203], v151 offset:5120
	ds_read_b128 v[204:207], v151 offset:6144
	ds_read_b128 v[208:211], v151 offset:7168
	global_load_lds_dwordx4 v[212:213], off
	v_lshl_add_u64 v[212:213], s[28:29], 0, v[138:139]
	s_add_i32 m0, s46, 0xe000
	s_nop 0
	global_load_lds_dwordx4 v[212:213], off
	s_waitcnt vmcnt(8)
	s_waitcnt lgkmcnt(0)
	s_setprio 1
	s_barrier
	v_mfma_f32_16x16x32_bf16 v[124:127], v[142:145], v[180:183], 0
	v_mfma_f32_16x16x32_bf16 v[120:123], v[156:159], v[180:183], 0
	v_mfma_f32_16x16x32_bf16 v[108:111], v[142:145], v[188:191], 0
	v_mfma_f32_16x16x32_bf16 v[104:107], v[156:159], v[188:191], 0
	v_mfma_f32_16x16x32_bf16 v[92:95], v[142:145], v[196:199], 0
	v_mfma_f32_16x16x32_bf16 v[88:91], v[156:159], v[196:199], 0
	v_mfma_f32_16x16x32_bf16 v[76:79], v[142:145], v[204:207], 0
	v_mfma_f32_16x16x32_bf16 v[72:75], v[156:159], v[204:207], 0
	v_mfma_f32_16x16x32_bf16 v[124:127], v[152:155], v[184:187], v[124:127]
	v_mfma_f32_16x16x32_bf16 v[120:123], v[160:163], v[184:187], v[120:123]
	v_mfma_f32_16x16x32_bf16 v[108:111], v[152:155], v[192:195], v[108:111]
	v_mfma_f32_16x16x32_bf16 v[104:107], v[160:163], v[192:195], v[104:107]
	v_mfma_f32_16x16x32_bf16 v[92:95], v[152:155], v[200:203], v[92:95]
	v_mfma_f32_16x16x32_bf16 v[88:91], v[160:163], v[200:203], v[88:91]
	v_mfma_f32_16x16x32_bf16 v[76:79], v[152:155], v[208:211], v[76:79]
	v_mfma_f32_16x16x32_bf16 v[72:75], v[160:163], v[208:211], v[72:75]
	v_mfma_f32_16x16x32_bf16 v[116:119], v[164:167], v[180:183], 0
	v_mfma_f32_16x16x32_bf16 v[112:115], v[172:175], v[180:183], 0
	v_mfma_f32_16x16x32_bf16 v[100:103], v[164:167], v[188:191], 0
	v_mfma_f32_16x16x32_bf16 v[96:99], v[172:175], v[188:191], 0
	v_mfma_f32_16x16x32_bf16 v[84:87], v[164:167], v[196:199], 0
	v_mfma_f32_16x16x32_bf16 v[80:83], v[172:175], v[196:199], 0
	v_mfma_f32_16x16x32_bf16 v[68:71], v[164:167], v[204:207], 0
	v_mfma_f32_16x16x32_bf16 v[64:67], v[172:175], v[204:207], 0
	v_mfma_f32_16x16x32_bf16 v[116:119], v[168:171], v[184:187], v[116:119]
	v_mfma_f32_16x16x32_bf16 v[112:115], v[176:179], v[184:187], v[112:115]
	v_mfma_f32_16x16x32_bf16 v[100:103], v[168:171], v[192:195], v[100:103]
	v_mfma_f32_16x16x32_bf16 v[96:99], v[176:179], v[192:195], v[96:99]
	v_mfma_f32_16x16x32_bf16 v[84:87], v[168:171], v[200:203], v[84:87]
	v_mfma_f32_16x16x32_bf16 v[80:83], v[176:179], v[200:203], v[80:83]
	v_mfma_f32_16x16x32_bf16 v[68:71], v[168:171], v[208:211], v[68:71]
	s_setprio 2
	s_barrier
	v_mfma_f32_16x16x32_bf16 v[64:67], v[176:179], v[208:211], v[64:67]
	s_setprio 0
	s_add_i32 s33, s59, s38
	v_lshl_add_u64 v[212:213], s[68:69], 0, v[132:133]
	s_mov_b32 m0, s33
	ds_read_b128 v[180:183], v151 offset:16384
	ds_read_b128 v[184:187], v151 offset:17408
	ds_read_b128 v[188:191], v151 offset:18432
	ds_read_b128 v[192:195], v151 offset:19456
	ds_read_b128 v[196:199], v151 offset:20480
	ds_read_b128 v[200:203], v151 offset:21504
	ds_read_b128 v[204:207], v151 offset:22528
	ds_read_b128 v[208:211], v151 offset:23552
	global_load_lds_dwordx4 v[212:213], off
	s_add_i32 m0, s33, 0x2000
	v_lshl_add_u64 v[214:215], s[68:69], 0, v[128:129]
	s_add_u32 s68, s68, s8
	s_addc_u32 s69, s69, s9
	s_add_i32 s33, s60, s38
	global_load_lds_dwordx4 v[214:215], off
	v_lshl_add_u64 v[216:217], s[68:69], 0, v[132:133]
	s_mov_b32 m0, s33
	v_lshl_add_u64 v[218:219], s[68:69], 0, v[128:129]
	global_load_lds_dwordx4 v[216:217], off
	s_add_i32 m0, s33, 0x2000
	v_lshl_add_u64 v[220:221], s[30:31], 0, v[134:135]
	global_load_lds_dwordx4 v[218:219], off
	s_mov_b32 m0, s46
	v_lshl_add_u64 v[222:223], s[30:31], 0, v[130:131]
	global_load_lds_dwordx4 v[220:221], off
	s_mov_b32 m0, s47
	s_nop 0
	global_load_lds_dwordx4 v[222:223], off
	s_waitcnt vmcnt(8)
	s_waitcnt lgkmcnt(0)
	s_setprio 1
	s_barrier
; #define PG8_STAGE(bufoff, gbase, voff) do { _Pragma("unroll") for (int _i = 0; _i < 2; ++_i) \
;         __builtin_amdgcn_global_load_lds((const unsigned*)((const char*)(gbase) + (voff)[_i]), (PG8_LAS unsigned*)(lds + (bufoff) + ldsw + _i * 8192), 16, 0, 0); } while (0)
; #define PG8_LDA(dst, b, h) do { _Pragma("unroll") for (int m = 0; m < 4; ++m) _Pragma("unroll") for (int k = 0; k < 2; ++k) dst[m][k] = *(const PG8_LAS bf16x8*)(lds + PG8_SA(b, h) + aoff + m * 2048 + k * 1024); } while (0)
; #define PG8_LDB(dst, b, h) do { _Pragma("unroll") for (int n = 0; n < 2; ++n) _Pragma("unroll") for (int k = 0; k < 2; ++k) dst[n][k] = *(const PG8_LAS bf16x8*)(lds + PG8_SB(b, h) + boff + n * 2048 + k * 1024); } while (0)
; #define PG8_MMA(ai, bj, At, Bt) do { __builtin_amdgcn_s_setprio(1); _Pragma("unroll") for (int m = 0; m < 4; ++m) _Pragma("unroll") for (int n = 0; n < 2; ++n) _Pragma("unroll") for (int k = 0; k < 2; ++k) \
;         acc[ai][bj][m][n] = __builtin_amdgcn_mfma_f32_16x16x32_bf16(Bt[n][k], At[m][k], acc[ai][bj][m][n], 0, 0, 0); __builtin_amdgcn_s_setprio(0); } while (0)
; #define PG8_BAR __builtin_amdgcn_s_barrier()
; template <class Epi, class Sched, bool ALIGN_EPI = false, bool SP2 = false>
; __device__ __forceinline__ void gemm_phase(PG8_LAS unsigned char* lds, const Gemm g, const Sched& S, const Epi& E, const int wid) {
;     ...
;             PG8_LDB(B0, 0, 0); PG8_LDB(B1, 0, 1); PG8_SCHED; PG8_LDA(At, 0, 0); PG8_STAGE(PG8_SA(1, 1), a1 + hstep, voffA);
;             PG8_WAIT_V(8); PG8_WAIT_L(0); PG8_BAR; PG8_MMA(0, 0, At, B0); PG8_MMA(0, 1, At, B1); PG8_BAR; PG8_SCHED;
;             PG8_LDA(At, 0, 1); PG8_STAGE(PG8_SB(0, 0), b2, voffB); PG8_STAGE(PG8_SB(0, 1), b2 + hstep, voffB); PG8_STAGE(PG8_SA(0, 0), a2, voffA);
;             PG8_WAIT_V(8); PG8_WAIT_L(0); PG8_BAR; PG8_MMA(1, 0, At, B0); PG8_MMA(1, 1, At, B1); PG8_BAR; PG8_SCHED;
;             PG8_LDB(B0, 1, 0); PG8_LDB(B1, 1, 1); PG8_SCHED; PG8_LDA(At, 1, 0); PG8_STAGE(PG8_SA(0, 1), a2 + hstep, voffA);
;             PG8_WAIT_V(8); PG8_WAIT_L(0); PG8_BAR; PG8_MMA(0, 0, At, B0); PG8_MMA(0, 1, At, B1); PG8_BAR; PG8_SCHED;
;             PG8_LDA(At, 1, 1); PG8_STAGE(PG8_SB(1, 0), b3, voffB); PG8_STAGE(PG8_SB(1, 1), b3 + hstep, voffB); PG8_STAGE(PG8_SA(1, 0), a3, voffA);
;             PG8_WAIT_V(8); PG8_WAIT_L(0); PG8_BAR; PG8_MMA(1, 0, At, B0); PG8_MMA(1, 1, At, B1); PG8_BAR; PG8_SCHED;
	v_mfma_f32_16x16x32_bf16 v[60:63], v[142:145], v[180:183], 0
	v_mfma_f32_16x16x32_bf16 v[56:59], v[156:159], v[180:183], 0
	v_mfma_f32_16x16x32_bf16 v[44:47], v[142:145], v[188:191], 0
	v_mfma_f32_16x16x32_bf16 v[40:43], v[156:159], v[188:191], 0
	v_mfma_f32_16x16x32_bf16 v[28:31], v[142:145], v[196:199], 0
	v_mfma_f32_16x16x32_bf16 v[24:27], v[156:159], v[196:199], 0
	v_mfma_f32_16x16x32_bf16 v[12:15], v[142:145], v[204:207], 0
	v_mfma_f32_16x16x32_bf16 v[8:11], v[156:159], v[204:207], 0
	v_mfma_f32_16x16x32_bf16 v[60:63], v[152:155], v[184:187], v[60:63]
	v_mfma_f32_16x16x32_bf16 v[56:59], v[160:163], v[184:187], v[56:59]
	v_mfma_f32_16x16x32_bf16 v[44:47], v[152:155], v[192:195], v[44:47]
	v_mfma_f32_16x16x32_bf16 v[40:43], v[160:163], v[192:195], v[40:43]
	v_mfma_f32_16x16x32_bf16 v[28:31], v[152:155], v[200:203], v[28:31]
	v_mfma_f32_16x16x32_bf16 v[24:27], v[160:163], v[200:203], v[24:27]
	v_mfma_f32_16x16x32_bf16 v[12:15], v[152:155], v[208:211], v[12:15]
	v_mfma_f32_16x16x32_bf16 v[8:11], v[160:163], v[208:211], v[8:11]
	v_mfma_f32_16x16x32_bf16 v[52:55], v[164:167], v[180:183], 0
	v_mfma_f32_16x16x32_bf16 v[48:51], v[172:175], v[180:183], 0
	v_mfma_f32_16x16x32_bf16 v[36:39], v[164:167], v[188:191], 0
	v_mfma_f32_16x16x32_bf16 v[32:35], v[172:175], v[188:191], 0
	v_mfma_f32_16x16x32_bf16 v[20:23], v[164:167], v[196:199], 0
	v_mfma_f32_16x16x32_bf16 v[16:19], v[172:175], v[196:199], 0
	v_mfma_f32_16x16x32_bf16 v[4:7], v[164:167], v[204:207], 0
	v_mfma_f32_16x16x32_bf16 v[0:3], v[172:175], v[204:207], 0
	v_mfma_f32_16x16x32_bf16 v[52:55], v[168:171], v[184:187], v[52:55]
	v_mfma_f32_16x16x32_bf16 v[48:51], v[176:179], v[184:187], v[48:51]
	v_mfma_f32_16x16x32_bf16 v[36:39], v[168:171], v[192:195], v[36:39]
	v_mfma_f32_16x16x32_bf16 v[32:35], v[176:179], v[192:195], v[32:35]
	v_mfma_f32_16x16x32_bf16 v[20:23], v[168:171], v[200:203], v[20:23]
	v_mfma_f32_16x16x32_bf16 v[16:19], v[176:179], v[200:203], v[16:19]
	v_mfma_f32_16x16x32_bf16 v[4:7], v[168:171], v[208:211], v[4:7]
	s_setprio 2
	s_barrier
	v_mfma_f32_16x16x32_bf16 v[0:3], v[176:179], v[208:211], v[0:3]
	s_setprio 0
	s_add_i32 s33, 0, 0x18000
	s_add_i32 s67, 0, 0x1c000
	v_add_u32_e32 v160, s33, v148
	v_add_u32_e32 v176, s67, v148
	ds_read_b128 v[142:145], v160
	ds_read_b128 v[152:155], v160 offset:1024
	ds_read_b128 v[156:159], v160 offset:2048
	ds_read_b128 v[160:163], v160 offset:3072
	ds_read_b128 v[164:167], v176
	ds_read_b128 v[168:171], v176 offset:1024
	ds_read_b128 v[172:175], v176 offset:2048
	ds_read_b128 v[176:179], v176 offset:3072
	s_add_u32 s30, s30, s8
	s_addc_u32 s31, s31, s9
	s_mov_b32 m0, s49
	v_lshl_add_u64 v[224:225], s[30:31], 0, v[134:135]
	ds_read_b128 v[180:183], v151 offset:32768
	ds_read_b128 v[184:187], v151 offset:33792
	ds_read_b128 v[188:191], v151 offset:34816
	ds_read_b128 v[192:195], v151 offset:35840
	ds_read_b128 v[196:199], v151 offset:36864
	ds_read_b128 v[200:203], v151 offset:37888
	ds_read_b128 v[204:207], v151 offset:38912
	ds_read_b128 v[208:211], v151 offset:39936
	global_load_lds_dwordx4 v[224:225], off
	v_lshl_add_u64 v[224:225], s[30:31], 0, v[130:131]
	s_mov_b32 m0, s50
	s_nop 0
	global_load_lds_dwordx4 v[224:225], off
	s_waitcnt vmcnt(8)
	s_waitcnt lgkmcnt(0)
	s_setprio 1
	s_barrier
	v_mfma_f32_16x16x32_bf16 v[124:127], v[142:145], v[180:183], v[124:127]
	v_mfma_f32_16x16x32_bf16 v[120:123], v[156:159], v[180:183], v[120:123]
	v_mfma_f32_16x16x32_bf16 v[108:111], v[142:145], v[188:191], v[108:111]
	v_mfma_f32_16x16x32_bf16 v[104:107], v[156:159], v[188:191], v[104:107]
	v_mfma_f32_16x16x32_bf16 v[92:95], v[142:145], v[196:199], v[92:95]
	v_mfma_f32_16x16x32_bf16 v[88:91], v[156:159], v[196:199], v[88:91]
	v_mfma_f32_16x16x32_bf16 v[76:79], v[142:145], v[204:207], v[76:79]
	v_mfma_f32_16x16x32_bf16 v[72:75], v[156:159], v[204:207], v[72:75]
	v_mfma_f32_16x16x32_bf16 v[124:127], v[152:155], v[184:187], v[124:127]
	v_mfma_f32_16x16x32_bf16 v[120:123], v[160:163], v[184:187], v[120:123]
	v_mfma_f32_16x16x32_bf16 v[108:111], v[152:155], v[192:195], v[108:111]
	v_mfma_f32_16x16x32_bf16 v[104:107], v[160:163], v[192:195], v[104:107]
	v_mfma_f32_16x16x32_bf16 v[92:95], v[152:155], v[200:203], v[92:95]
	v_mfma_f32_16x16x32_bf16 v[88:91], v[160:163], v[200:203], v[88:91]
	v_mfma_f32_16x16x32_bf16 v[76:79], v[152:155], v[208:211], v[76:79]
	v_mfma_f32_16x16x32_bf16 v[72:75], v[160:163], v[208:211], v[72:75]
	v_mfma_f32_16x16x32_bf16 v[116:119], v[164:167], v[180:183], v[116:119]
	v_mfma_f32_16x16x32_bf16 v[112:115], v[172:175], v[180:183], v[112:115]
	v_mfma_f32_16x16x32_bf16 v[100:103], v[164:167], v[188:191], v[100:103]
	v_mfma_f32_16x16x32_bf16 v[96:99], v[172:175], v[188:191], v[96:99]
	v_mfma_f32_16x16x32_bf16 v[84:87], v[164:167], v[196:199], v[84:87]
	v_mfma_f32_16x16x32_bf16 v[80:83], v[172:175], v[196:199], v[80:83]
	v_mfma_f32_16x16x32_bf16 v[68:71], v[164:167], v[204:207], v[68:71]
	v_mfma_f32_16x16x32_bf16 v[64:67], v[172:175], v[204:207], v[64:67]
	v_mfma_f32_16x16x32_bf16 v[116:119], v[168:171], v[184:187], v[116:119]
	v_mfma_f32_16x16x32_bf16 v[112:115], v[176:179], v[184:187], v[112:115]
	v_mfma_f32_16x16x32_bf16 v[100:103], v[168:171], v[192:195], v[100:103]
	v_mfma_f32_16x16x32_bf16 v[96:99], v[176:179], v[192:195], v[96:99]
	v_mfma_f32_16x16x32_bf16 v[84:87], v[168:171], v[200:203], v[84:87]
	v_mfma_f32_16x16x32_bf16 v[80:83], v[176:179], v[200:203], v[80:83]
	v_mfma_f32_16x16x32_bf16 v[68:71], v[168:171], v[208:211], v[68:71]
	s_setprio 2
	s_barrier
; #define PG8_STAGE(bufoff, gbase, voff) do { _Pragma("unroll") for (int _i = 0; _i < 2; ++_i) \
;         __builtin_amdgcn_global_load_lds((const unsigned*)((const char*)(gbase) + (voff)[_i]), (PG8_LAS unsigned*)(lds + (bufoff) + ldsw + _i * 8192), 16, 0, 0); } while (0)
; #define PG8_WAIT_V(n) asm volatile("s_waitcnt vmcnt(" #n ")" ::: "memory")
; #define PG8_WAIT_L(n) asm volatile("s_waitcnt lgkmcnt(" #n ")" ::: "memory")
; #define PG8_BAR __builtin_amdgcn_s_barrier()
; template <class Epi, class Sched, bool ALIGN_EPI = false, bool SP2 = false>
; __device__ __forceinline__ void gemm_phase(PG8_LAS unsigned char* lds, const Gemm g, const Sched& S, const Epi& E, const int wid) {
;     ...
;     for (;;) {
;         const bool has_next = S.next(ui + 1, nxt);
;         const char* nA = has_next ? (const char*)g.A + (size_t)nxt.pm * tstep : cA; const char* nB = has_next ? (const char*)g.Bt + (size_t)nxt.pn * tstep : cB;
;         for (int t = 0; t < nt; t += 2) {
;             const bool last = (t == nt - 2);
;             const char* a1 = cA + (size_t)(t + 1) * kstep;
;             const char* a2 = last ? nA : cA + (size_t)(t + 2) * kstep; const char* b2 = last ? nB : cB + (size_t)(t + 2) * kstep;
;             const char* a3 = a2 + kstep; const char* b3 = b2 + kstep;
;             if (last && has_next) S.a_ready(nxt);
;             if constexpr (SP2) {
;             PG8_LDB(B0, 0, 0); PG8_LDB(B1, 0, 1); PG8_SCHED; PG8_LDA(At, 0, 0); PG8_STAGE(PG8_SA(1, 1), a1 + hstep, voffA);
;             PG8_WAIT_V(8); PG8_WAIT_L(0); PG8_BAR; PG8_MMA(0, 0, At, B0); PG8_MMA(0, 1, At, B1); PG8_BAR; PG8_SCHED;
;             PG8_LDA(At, 0, 1); PG8_STAGE(PG8_SB(0, 0), b2, voffB); PG8_STAGE(PG8_SB(0, 1), b2 + hstep, voffB); PG8_STAGE(PG8_SA(0, 0), a2, voffA);
;             PG8_WAIT_V(8); PG8_WAIT_L(0); PG8_BAR; PG8_MMA(1, 0, At, B0); PG8_MMA(1, 1, At, B1); PG8_BAR; PG8_SCHED;
;             PG8_LDB(B0, 1, 0); PG8_LDB(B1, 1, 1); PG8_SCHED; PG8_LDA(At, 1, 0); PG8_STAGE(PG8_SA(0, 1), a2 + hstep, voffA);
;             PG8_WAIT_V(8); PG8_WAIT_L(0); PG8_BAR; PG8_MMA(0, 0, At, B0); PG8_MMA(0, 1, At, B1); PG8_BAR; PG8_SCHED;
;             PG8_LDA(At, 1, 1); PG8_STAGE(PG8_SB(1, 0), b3, voffB); PG8_STAGE(PG8_SB(1, 1), b3 + hstep, voffB); PG8_STAGE(PG8_SA(1, 0), a3, voffA);
;             PG8_WAIT_V(8); PG8_WAIT_L(0); PG8_BAR; PG8_MMA(1, 0, At, B0); PG8_MMA(1, 1, At, B1); PG8_BAR; PG8_SCHED;
	v_mfma_f32_16x16x32_bf16 v[64:67], v[176:179], v[208:211], v[64:67]
	s_setprio 0
	s_add_i32 s30, s33, s38
	v_lshl_add_u64 v[212:213], v[212:213], 0, s[18:19]
	s_mov_b32 m0, s30
	ds_read_b128 v[180:183], v151 offset:49152
	ds_read_b128 v[184:187], v151 offset:50176
	ds_read_b128 v[188:191], v151 offset:51200
	ds_read_b128 v[192:195], v151 offset:52224
	ds_read_b128 v[196:199], v151 offset:53248
	ds_read_b128 v[200:203], v151 offset:54272
	ds_read_b128 v[204:207], v151 offset:55296
	ds_read_b128 v[208:211], v151 offset:56320
	global_load_lds_dwordx4 v[212:213], off
	v_lshl_add_u64 v[212:213], v[214:215], 0, s[18:19]
	s_add_i32 m0, s30, 0x2000
	s_add_i32 s30, s67, s38
	global_load_lds_dwordx4 v[212:213], off
	v_lshl_add_u64 v[212:213], v[216:217], 0, s[18:19]
	s_mov_b32 m0, s30
	s_nop 0
	global_load_lds_dwordx4 v[212:213], off
	v_lshl_add_u64 v[212:213], v[218:219], 0, s[18:19]
	s_add_i32 m0, s30, 0x2000
	s_nop 0
	global_load_lds_dwordx4 v[212:213], off
	v_lshl_add_u64 v[212:213], v[220:221], 0, s[18:19]
	s_mov_b32 m0, s52
	s_nop 0
	global_load_lds_dwordx4 v[212:213], off
	v_lshl_add_u64 v[212:213], v[222:223], 0, s[18:19]
	s_mov_b32 m0, s53
	s_nop 0
	global_load_lds_dwordx4 v[212:213], off
	s_waitcnt vmcnt(8)
	s_waitcnt lgkmcnt(0)
	s_setprio 1
	s_barrier
	v_mfma_f32_16x16x32_bf16 v[60:63], v[142:145], v[180:183], v[60:63]
	v_mfma_f32_16x16x32_bf16 v[56:59], v[156:159], v[180:183], v[56:59]
	v_mfma_f32_16x16x32_bf16 v[44:47], v[142:145], v[188:191], v[44:47]
	v_mfma_f32_16x16x32_bf16 v[40:43], v[156:159], v[188:191], v[40:43]
	v_mfma_f32_16x16x32_bf16 v[28:31], v[142:145], v[196:199], v[28:31]
	v_mfma_f32_16x16x32_bf16 v[24:27], v[156:159], v[196:199], v[24:27]
	v_mfma_f32_16x16x32_bf16 v[12:15], v[142:145], v[204:207], v[12:15]
	v_mfma_f32_16x16x32_bf16 v[8:11], v[156:159], v[204:207], v[8:11]
	v_mfma_f32_16x16x32_bf16 v[60:63], v[152:155], v[184:187], v[60:63]
	v_mfma_f32_16x16x32_bf16 v[56:59], v[160:163], v[184:187], v[56:59]
	v_mfma_f32_16x16x32_bf16 v[44:47], v[152:155], v[192:195], v[44:47]
	v_mfma_f32_16x16x32_bf16 v[40:43], v[160:163], v[192:195], v[40:43]
	v_mfma_f32_16x16x32_bf16 v[28:31], v[152:155], v[200:203], v[28:31]
	v_mfma_f32_16x16x32_bf16 v[24:27], v[160:163], v[200:203], v[24:27]
	v_mfma_f32_16x16x32_bf16 v[12:15], v[152:155], v[208:211], v[12:15]
	v_mfma_f32_16x16x32_bf16 v[8:11], v[160:163], v[208:211], v[8:11]
	v_mfma_f32_16x16x32_bf16 v[52:55], v[164:167], v[180:183], v[52:55]
	v_mfma_f32_16x16x32_bf16 v[48:51], v[172:175], v[180:183], v[48:51]
	v_mfma_f32_16x16x32_bf16 v[36:39], v[164:167], v[188:191], v[36:39]
	v_mfma_f32_16x16x32_bf16 v[32:35], v[172:175], v[188:191], v[32:35]
	v_mfma_f32_16x16x32_bf16 v[20:23], v[164:167], v[196:199], v[20:23]
	v_mfma_f32_16x16x32_bf16 v[16:19], v[172:175], v[196:199], v[16:19]
	v_mfma_f32_16x16x32_bf16 v[4:7], v[164:167], v[204:207], v[4:7]
	v_mfma_f32_16x16x32_bf16 v[0:3], v[172:175], v[204:207], v[0:3]
	v_mfma_f32_16x16x32_bf16 v[52:55], v[168:171], v[184:187], v[52:55]
	v_mfma_f32_16x16x32_bf16 v[48:51], v[176:179], v[184:187], v[48:51]
	v_mfma_f32_16x16x32_bf16 v[36:39], v[168:171], v[192:195], v[36:39]
	v_mfma_f32_16x16x32_bf16 v[32:35], v[176:179], v[192:195], v[32:35]
	v_mfma_f32_16x16x32_bf16 v[20:23], v[168:171], v[200:203], v[20:23]
	v_mfma_f32_16x16x32_bf16 v[16:19], v[176:179], v[200:203], v[16:19]
	v_mfma_f32_16x16x32_bf16 v[4:7], v[168:171], v[208:211], v[4:7]
	s_setprio 2
	s_barrier
	v_mfma_f32_16x16x32_bf16 v[0:3], v[176:179], v[208:211], v[0:3]
	s_setprio 0
	s_add_u32 s28, s28, 0x100
	s_addc_u32 s29, s29, 0
	s_add_u32 s0, s0, 0x100
	s_addc_u32 s1, s1, 0
	s_cmp_ge_i32 s66, s54
	s_mov_b32 s30, s66
	s_cbranch_scc1 .LBB0_1259
.LBB0_1258:
	ds_read_b128 v[142:145], v149
	ds_read_b128 v[152:155], v149 offset:1024
	ds_read_b128 v[156:159], v149 offset:2048
	ds_read_b128 v[160:163], v149 offset:3072
	ds_read_b128 v[164:167], v150
	ds_read_b128 v[168:171], v150 offset:1024
	ds_read_b128 v[172:175], v150 offset:2048
	ds_read_b128 v[176:179], v150 offset:3072
	s_add_i32 s66, s30, 2
	s_add_u32 s33, s28, 0x80
	s_addc_u32 s31, s29, 0
	s_cmp_eq_u32 s57, s30
	s_cselect_b32 s30, s4, s33
	s_cselect_b32 s31, s5, s31
	s_cselect_b32 s69, s27, s1
	s_cselect_b32 s68, s26, s0
	v_lshl_add_u64 v[212:213], s[28:29], 0, v[136:137]
	s_add_i32 m0, s46, 0xc000
	ds_read_b128 v[180:183], v151
	ds_read_b128 v[184:187], v151 offset:1024
	ds_read_b128 v[188:191], v151 offset:2048
	ds_read_b128 v[192:195], v151 offset:3072
	ds_read_b128 v[196:199], v151 offset:4096
	ds_read_b128 v[200:203], v151 offset:5120
	ds_read_b128 v[204:207], v151 offset:6144
	ds_read_b128 v[208:211], v151 offset:7168
	global_load_lds_dwordx4 v[212:213], off
	v_lshl_add_u64 v[212:213], s[28:29], 0, v[138:139]
	s_add_i32 m0, s46, 0xe000
	s_nop 0
	global_load_lds_dwordx4 v[212:213], off
	s_waitcnt vmcnt(8)
	s_waitcnt lgkmcnt(0)
	s_setprio 1
	s_barrier
; #define PG8_STAGE(bufoff, gbase, voff) do { _Pragma("unroll") for (int _i = 0; _i < 2; ++_i) \
;         __builtin_amdgcn_global_load_lds((const unsigned*)((const char*)(gbase) + (voff)[_i]), (PG8_LAS unsigned*)(lds + (bufoff) + ldsw + _i * 8192), 16, 0, 0); } while (0)
; #define PG8_LDA(dst, b, h) do { _Pragma("unroll") for (int m = 0; m < 4; ++m) _Pragma("unroll") for (int k = 0; k < 2; ++k) dst[m][k] = *(const PG8_LAS bf16x8*)(lds + PG8_SA(b, h) + aoff + m * 2048 + k * 1024); } while (0)
; #define PG8_LDB(dst, b, h) do { _Pragma("unroll") for (int n = 0; n < 2; ++n) _Pragma("unroll") for (int k = 0; k < 2; ++k) dst[n][k] = *(const PG8_LAS bf16x8*)(lds + PG8_SB(b, h) + boff + n * 2048 + k * 1024); } while (0)
; #define PG8_MMA(ai, bj, At, Bt) do { __builtin_amdgcn_s_setprio(1); _Pragma("unroll") for (int m = 0; m < 4; ++m) _Pragma("unroll") for (int n = 0; n < 2; ++n) _Pragma("unroll") for (int k = 0; k < 2; ++k) \
;         acc[ai][bj][m][n] = __builtin_amdgcn_mfma_f32_16x16x32_bf16(Bt[n][k], At[m][k], acc[ai][bj][m][n], 0, 0, 0); __builtin_amdgcn_s_setprio(0); } while (0)
; #define PG8_BAR __builtin_amdgcn_s_barrier()
; template <class Epi, class Sched, bool ALIGN_EPI = false, bool SP2 = false>
; __device__ __forceinline__ void gemm_phase(PG8_LAS unsigned char* lds, const Gemm g, const Sched& S, const Epi& E, const int wid) {
;     ...
;             PG8_LDB(B0, 0, 0); PG8_LDB(B1, 0, 1); PG8_SCHED; PG8_LDA(At, 0, 0); PG8_STAGE(PG8_SA(1, 1), a1 + hstep, voffA);
;             PG8_WAIT_V(8); PG8_WAIT_L(0); PG8_BAR; PG8_MMA(0, 0, At, B0); PG8_MMA(0, 1, At, B1); PG8_BAR; PG8_SCHED;
;             PG8_LDA(At, 0, 1); PG8_STAGE(PG8_SB(0, 0), b2, voffB); PG8_STAGE(PG8_SB(0, 1), b2 + hstep, voffB); PG8_STAGE(PG8_SA(0, 0), a2, voffA);
;             PG8_WAIT_V(8); PG8_WAIT_L(0); PG8_BAR; PG8_MMA(1, 0, At, B0); PG8_MMA(1, 1, At, B1); PG8_BAR; PG8_SCHED;
;             PG8_LDB(B0, 1, 0); PG8_LDB(B1, 1, 1); PG8_SCHED; PG8_LDA(At, 1, 0); PG8_STAGE(PG8_SA(0, 1), a2 + hstep, voffA);
;             PG8_WAIT_V(8); PG8_WAIT_L(0); PG8_BAR; PG8_MMA(0, 0, At, B0); PG8_MMA(0, 1, At, B1); PG8_BAR; PG8_SCHED;
;             PG8_LDA(At, 1, 1); PG8_STAGE(PG8_SB(1, 0), b3, voffB); PG8_STAGE(PG8_SB(1, 1), b3 + hstep, voffB); PG8_STAGE(PG8_SA(1, 0), a3, voffA);
;             PG8_WAIT_V(8); PG8_WAIT_L(0); PG8_BAR; PG8_MMA(1, 0, At, B0); PG8_MMA(1, 1, At, B1); PG8_BAR; PG8_SCHED;
	v_mfma_f32_16x16x32_bf16 v[124:127], v[142:145], v[180:183], v[124:127]
	v_mfma_f32_16x16x32_bf16 v[120:123], v[156:159], v[180:183], v[120:123]
	v_mfma_f32_16x16x32_bf16 v[108:111], v[142:145], v[188:191], v[108:111]
	v_mfma_f32_16x16x32_bf16 v[104:107], v[156:159], v[188:191], v[104:107]
	v_mfma_f32_16x16x32_bf16 v[92:95], v[142:145], v[196:199], v[92:95]
	v_mfma_f32_16x16x32_bf16 v[88:91], v[156:159], v[196:199], v[88:91]
	v_mfma_f32_16x16x32_bf16 v[76:79], v[142:145], v[204:207], v[76:79]
	v_mfma_f32_16x16x32_bf16 v[72:75], v[156:159], v[204:207], v[72:75]
	v_mfma_f32_16x16x32_bf16 v[124:127], v[152:155], v[184:187], v[124:127]
	v_mfma_f32_16x16x32_bf16 v[120:123], v[160:163], v[184:187], v[120:123]
	v_mfma_f32_16x16x32_bf16 v[108:111], v[152:155], v[192:195], v[108:111]
	v_mfma_f32_16x16x32_bf16 v[104:107], v[160:163], v[192:195], v[104:107]
	v_mfma_f32_16x16x32_bf16 v[92:95], v[152:155], v[200:203], v[92:95]
	v_mfma_f32_16x16x32_bf16 v[88:91], v[160:163], v[200:203], v[88:91]
	v_mfma_f32_16x16x32_bf16 v[76:79], v[152:155], v[208:211], v[76:79]
	v_mfma_f32_16x16x32_bf16 v[72:75], v[160:163], v[208:211], v[72:75]
	v_mfma_f32_16x16x32_bf16 v[116:119], v[164:167], v[180:183], v[116:119]
	v_mfma_f32_16x16x32_bf16 v[112:115], v[172:175], v[180:183], v[112:115]
	v_mfma_f32_16x16x32_bf16 v[100:103], v[164:167], v[188:191], v[100:103]
	v_mfma_f32_16x16x32_bf16 v[96:99], v[172:175], v[188:191], v[96:99]
	v_mfma_f32_16x16x32_bf16 v[84:87], v[164:167], v[196:199], v[84:87]
	v_mfma_f32_16x16x32_bf16 v[80:83], v[172:175], v[196:199], v[80:83]
	v_mfma_f32_16x16x32_bf16 v[68:71], v[164:167], v[204:207], v[68:71]
	v_mfma_f32_16x16x32_bf16 v[64:67], v[172:175], v[204:207], v[64:67]
	v_mfma_f32_16x16x32_bf16 v[116:119], v[168:171], v[184:187], v[116:119]
	v_mfma_f32_16x16x32_bf16 v[112:115], v[176:179], v[184:187], v[112:115]
	v_mfma_f32_16x16x32_bf16 v[100:103], v[168:171], v[192:195], v[100:103]
	v_mfma_f32_16x16x32_bf16 v[96:99], v[176:179], v[192:195], v[96:99]
	v_mfma_f32_16x16x32_bf16 v[84:87], v[168:171], v[200:203], v[84:87]
	v_mfma_f32_16x16x32_bf16 v[80:83], v[176:179], v[200:203], v[80:83]
	v_mfma_f32_16x16x32_bf16 v[68:71], v[168:171], v[208:211], v[68:71]
	s_setprio 2
	s_barrier
	v_mfma_f32_16x16x32_bf16 v[64:67], v[176:179], v[208:211], v[64:67]
	s_setprio 0
	s_add_i32 s33, s59, s38
	v_lshl_add_u64 v[212:213], s[68:69], 0, v[132:133]
	s_mov_b32 m0, s33
	ds_read_b128 v[180:183], v151 offset:16384
	ds_read_b128 v[184:187], v151 offset:17408
	ds_read_b128 v[188:191], v151 offset:18432
	ds_read_b128 v[192:195], v151 offset:19456
	ds_read_b128 v[196:199], v151 offset:20480
	ds_read_b128 v[200:203], v151 offset:21504
	ds_read_b128 v[204:207], v151 offset:22528
	ds_read_b128 v[208:211], v151 offset:23552
	global_load_lds_dwordx4 v[212:213], off
	s_add_i32 m0, s33, 0x2000
	v_lshl_add_u64 v[214:215], s[68:69], 0, v[128:129]
	s_add_u32 s68, s68, s8
	s_addc_u32 s69, s69, s9
	s_add_i32 s33, s60, s38
	global_load_lds_dwordx4 v[214:215], off
	v_lshl_add_u64 v[216:217], s[68:69], 0, v[132:133]
	s_mov_b32 m0, s33
	v_lshl_add_u64 v[218:219], s[68:69], 0, v[128:129]
	global_load_lds_dwordx4 v[216:217], off
	s_add_i32 m0, s33, 0x2000
	v_lshl_add_u64 v[220:221], s[30:31], 0, v[134:135]
	global_load_lds_dwordx4 v[218:219], off
	s_mov_b32 m0, s46
	v_lshl_add_u64 v[222:223], s[30:31], 0, v[130:131]
	global_load_lds_dwordx4 v[220:221], off
	s_mov_b32 m0, s47
	s_nop 0
	global_load_lds_dwordx4 v[222:223], off
	s_waitcnt vmcnt(8)
	s_waitcnt lgkmcnt(0)
	s_setprio 1
	s_barrier
	v_mfma_f32_16x16x32_bf16 v[60:63], v[142:145], v[180:183], v[60:63]
	v_mfma_f32_16x16x32_bf16 v[56:59], v[156:159], v[180:183], v[56:59]
	v_mfma_f32_16x16x32_bf16 v[44:47], v[142:145], v[188:191], v[44:47]
	v_mfma_f32_16x16x32_bf16 v[40:43], v[156:159], v[188:191], v[40:43]
	v_mfma_f32_16x16x32_bf16 v[28:31], v[142:145], v[196:199], v[28:31]
	v_mfma_f32_16x16x32_bf16 v[24:27], v[156:159], v[196:199], v[24:27]
	v_mfma_f32_16x16x32_bf16 v[12:15], v[142:145], v[204:207], v[12:15]
	v_mfma_f32_16x16x32_bf16 v[8:11], v[156:159], v[204:207], v[8:11]
	v_mfma_f32_16x16x32_bf16 v[60:63], v[152:155], v[184:187], v[60:63]
	v_mfma_f32_16x16x32_bf16 v[56:59], v[160:163], v[184:187], v[56:59]
	v_mfma_f32_16x16x32_bf16 v[44:47], v[152:155], v[192:195], v[44:47]
	v_mfma_f32_16x16x32_bf16 v[40:43], v[160:163], v[192:195], v[40:43]
	v_mfma_f32_16x16x32_bf16 v[28:31], v[152:155], v[200:203], v[28:31]
	v_mfma_f32_16x16x32_bf16 v[24:27], v[160:163], v[200:203], v[24:27]
	v_mfma_f32_16x16x32_bf16 v[12:15], v[152:155], v[208:211], v[12:15]
	v_mfma_f32_16x16x32_bf16 v[8:11], v[160:163], v[208:211], v[8:11]
	v_mfma_f32_16x16x32_bf16 v[52:55], v[164:167], v[180:183], v[52:55]
	v_mfma_f32_16x16x32_bf16 v[48:51], v[172:175], v[180:183], v[48:51]
	v_mfma_f32_16x16x32_bf16 v[36:39], v[164:167], v[188:191], v[36:39]
	v_mfma_f32_16x16x32_bf16 v[32:35], v[172:175], v[188:191], v[32:35]
	v_mfma_f32_16x16x32_bf16 v[20:23], v[164:167], v[196:199], v[20:23]
	v_mfma_f32_16x16x32_bf16 v[16:19], v[172:175], v[196:199], v[16:19]
	v_mfma_f32_16x16x32_bf16 v[4:7], v[164:167], v[204:207], v[4:7]
	v_mfma_f32_16x16x32_bf16 v[0:3], v[172:175], v[204:207], v[0:3]
	v_mfma_f32_16x16x32_bf16 v[52:55], v[168:171], v[184:187], v[52:55]
	v_mfma_f32_16x16x32_bf16 v[48:51], v[176:179], v[184:187], v[48:51]
	v_mfma_f32_16x16x32_bf16 v[36:39], v[168:171], v[192:195], v[36:39]
	v_mfma_f32_16x16x32_bf16 v[32:35], v[176:179], v[192:195], v[32:35]
	v_mfma_f32_16x16x32_bf16 v[20:23], v[168:171], v[200:203], v[20:23]
	v_mfma_f32_16x16x32_bf16 v[16:19], v[176:179], v[200:203], v[16:19]
	v_mfma_f32_16x16x32_bf16 v[4:7], v[168:171], v[208:211], v[4:7]
	s_setprio 2
	s_barrier
; #define PG8_STAGE(bufoff, gbase, voff) do { _Pragma("unroll") for (int _i = 0; _i < 2; ++_i) \
;         __builtin_amdgcn_global_load_lds((const unsigned*)((const char*)(gbase) + (voff)[_i]), (PG8_LAS unsigned*)(lds + (bufoff) + ldsw + _i * 8192), 16, 0, 0); } while (0)
; #define PG8_LDA(dst, b, h) do { _Pragma("unroll") for (int m = 0; m < 4; ++m) _Pragma("unroll") for (int k = 0; k < 2; ++k) dst[m][k] = *(const PG8_LAS bf16x8*)(lds + PG8_SA(b, h) + aoff + m * 2048 + k * 1024); } while (0)
; #define PG8_LDB(dst, b, h) do { _Pragma("unroll") for (int n = 0; n < 2; ++n) _Pragma("unroll") for (int k = 0; k < 2; ++k) dst[n][k] = *(const PG8_LAS bf16x8*)(lds + PG8_SB(b, h) + boff + n * 2048 + k * 1024); } while (0)
; #define PG8_MMA(ai, bj, At, Bt) do { __builtin_amdgcn_s_setprio(1); _Pragma("unroll") for (int m = 0; m < 4; ++m) _Pragma("unroll") for (int n = 0; n < 2; ++n) _Pragma("unroll") for (int k = 0; k < 2; ++k) \
;         acc[ai][bj][m][n] = __builtin_amdgcn_mfma_f32_16x16x32_bf16(Bt[n][k], At[m][k], acc[ai][bj][m][n], 0, 0, 0); __builtin_amdgcn_s_setprio(0); } while (0)
; #define PG8_BAR __builtin_amdgcn_s_barrier()
; template <class Epi, class Sched, bool ALIGN_EPI = false, bool SP2 = false>
; __device__ __forceinline__ void gemm_phase(PG8_LAS unsigned char* lds, const Gemm g, const Sched& S, const Epi& E, const int wid) {
;     ...
;             PG8_LDB(B0, 0, 0); PG8_LDB(B1, 0, 1); PG8_SCHED; PG8_LDA(At, 0, 0); PG8_STAGE(PG8_SA(1, 1), a1 + hstep, voffA);
;             PG8_WAIT_V(8); PG8_WAIT_L(0); PG8_BAR; PG8_MMA(0, 0, At, B0); PG8_MMA(0, 1, At, B1); PG8_BAR; PG8_SCHED;
;             PG8_LDA(At, 0, 1); PG8_STAGE(PG8_SB(0, 0), b2, voffB); PG8_STAGE(PG8_SB(0, 1), b2 + hstep, voffB); PG8_STAGE(PG8_SA(0, 0), a2, voffA);
;             PG8_WAIT_V(8); PG8_WAIT_L(0); PG8_BAR; PG8_MMA(1, 0, At, B0); PG8_MMA(1, 1, At, B1); PG8_BAR; PG8_SCHED;
;             PG8_LDB(B0, 1, 0); PG8_LDB(B1, 1, 1); PG8_SCHED; PG8_LDA(At, 1, 0); PG8_STAGE(PG8_SA(0, 1), a2 + hstep, voffA);
;             PG8_WAIT_V(8); PG8_WAIT_L(0); PG8_BAR; PG8_MMA(0, 0, At, B0); PG8_MMA(0, 1, At, B1); PG8_BAR; PG8_SCHED;
;             PG8_LDA(At, 1, 1); PG8_STAGE(PG8_SB(1, 0), b3, voffB); PG8_STAGE(PG8_SB(1, 1), b3 + hstep, voffB); PG8_STAGE(PG8_SA(1, 0), a3, voffA);
;             PG8_WAIT_V(8); PG8_WAIT_L(0); PG8_BAR; PG8_MMA(1, 0, At, B0); PG8_MMA(1, 1, At, B1); PG8_BAR; PG8_SCHED;
	v_mfma_f32_16x16x32_bf16 v[0:3], v[176:179], v[208:211], v[0:3]
	s_setprio 0
	s_add_i32 s33, 0, 0x18000
	s_add_i32 s67, 0, 0x1c000
	v_add_u32_e32 v160, s33, v148
	v_add_u32_e32 v176, s67, v148
	ds_read_b128 v[142:145], v160
	ds_read_b128 v[152:155], v160 offset:1024
	ds_read_b128 v[156:159], v160 offset:2048
	ds_read_b128 v[160:163], v160 offset:3072
	ds_read_b128 v[164:167], v176
	ds_read_b128 v[168:171], v176 offset:1024
	ds_read_b128 v[172:175], v176 offset:2048
	ds_read_b128 v[176:179], v176 offset:3072
	s_add_u32 s30, s30, s8
	s_addc_u32 s31, s31, s9
	s_mov_b32 m0, s49
	v_lshl_add_u64 v[224:225], s[30:31], 0, v[134:135]
	ds_read_b128 v[180:183], v151 offset:32768
	ds_read_b128 v[184:187], v151 offset:33792
	ds_read_b128 v[188:191], v151 offset:34816
	ds_read_b128 v[192:195], v151 offset:35840
	ds_read_b128 v[196:199], v151 offset:36864
	ds_read_b128 v[200:203], v151 offset:37888
	ds_read_b128 v[204:207], v151 offset:38912
	ds_read_b128 v[208:211], v151 offset:39936
	global_load_lds_dwordx4 v[224:225], off
	v_lshl_add_u64 v[224:225], s[30:31], 0, v[130:131]
	s_mov_b32 m0, s50
	s_nop 0
	global_load_lds_dwordx4 v[224:225], off
	s_waitcnt vmcnt(8)
	s_waitcnt lgkmcnt(0)
	s_setprio 1
	s_barrier
	v_mfma_f32_16x16x32_bf16 v[124:127], v[142:145], v[180:183], v[124:127]
	v_mfma_f32_16x16x32_bf16 v[120:123], v[156:159], v[180:183], v[120:123]
	v_mfma_f32_16x16x32_bf16 v[108:111], v[142:145], v[188:191], v[108:111]
	v_mfma_f32_16x16x32_bf16 v[104:107], v[156:159], v[188:191], v[104:107]
	v_mfma_f32_16x16x32_bf16 v[92:95], v[142:145], v[196:199], v[92:95]
	v_mfma_f32_16x16x32_bf16 v[88:91], v[156:159], v[196:199], v[88:91]
	v_mfma_f32_16x16x32_bf16 v[76:79], v[142:145], v[204:207], v[76:79]
	v_mfma_f32_16x16x32_bf16 v[72:75], v[156:159], v[204:207], v[72:75]
	v_mfma_f32_16x16x32_bf16 v[124:127], v[152:155], v[184:187], v[124:127]
	v_mfma_f32_16x16x32_bf16 v[120:123], v[160:163], v[184:187], v[120:123]
	v_mfma_f32_16x16x32_bf16 v[108:111], v[152:155], v[192:195], v[108:111]
	v_mfma_f32_16x16x32_bf16 v[104:107], v[160:163], v[192:195], v[104:107]
	v_mfma_f32_16x16x32_bf16 v[92:95], v[152:155], v[200:203], v[92:95]
	v_mfma_f32_16x16x32_bf16 v[88:91], v[160:163], v[200:203], v[88:91]
	v_mfma_f32_16x16x32_bf16 v[76:79], v[152:155], v[208:211], v[76:79]
	v_mfma_f32_16x16x32_bf16 v[72:75], v[160:163], v[208:211], v[72:75]
	v_mfma_f32_16x16x32_bf16 v[116:119], v[164:167], v[180:183], v[116:119]
	v_mfma_f32_16x16x32_bf16 v[112:115], v[172:175], v[180:183], v[112:115]
	v_mfma_f32_16x16x32_bf16 v[100:103], v[164:167], v[188:191], v[100:103]
	v_mfma_f32_16x16x32_bf16 v[96:99], v[172:175], v[188:191], v[96:99]
	v_mfma_f32_16x16x32_bf16 v[84:87], v[164:167], v[196:199], v[84:87]
	v_mfma_f32_16x16x32_bf16 v[80:83], v[172:175], v[196:199], v[80:83]
	v_mfma_f32_16x16x32_bf16 v[68:71], v[164:167], v[204:207], v[68:71]
	v_mfma_f32_16x16x32_bf16 v[64:67], v[172:175], v[204:207], v[64:67]
	v_mfma_f32_16x16x32_bf16 v[116:119], v[168:171], v[184:187], v[116:119]
	v_mfma_f32_16x16x32_bf16 v[112:115], v[176:179], v[184:187], v[112:115]
	v_mfma_f32_16x16x32_bf16 v[100:103], v[168:171], v[192:195], v[100:103]
	v_mfma_f32_16x16x32_bf16 v[96:99], v[176:179], v[192:195], v[96:99]
	v_mfma_f32_16x16x32_bf16 v[84:87], v[168:171], v[200:203], v[84:87]
	v_mfma_f32_16x16x32_bf16 v[80:83], v[176:179], v[200:203], v[80:83]
	v_mfma_f32_16x16x32_bf16 v[68:71], v[168:171], v[208:211], v[68:71]
	s_setprio 2
	s_barrier
; #define PG8_STAGE(bufoff, gbase, voff) do { _Pragma("unroll") for (int _i = 0; _i < 2; ++_i) \
;         __builtin_amdgcn_global_load_lds((const unsigned*)((const char*)(gbase) + (voff)[_i]), (PG8_LAS unsigned*)(lds + (bufoff) + ldsw + _i * 8192), 16, 0, 0); } while (0)
; #define PG8_LDA(dst, b, h) do { _Pragma("unroll") for (int m = 0; m < 4; ++m) _Pragma("unroll") for (int k = 0; k < 2; ++k) dst[m][k] = *(const PG8_LAS bf16x8*)(lds + PG8_SA(b, h) + aoff + m * 2048 + k * 1024); } while (0)
; #define PG8_LDB(dst, b, h) do { _Pragma("unroll") for (int n = 0; n < 2; ++n) _Pragma("unroll") for (int k = 0; k < 2; ++k) dst[n][k] = *(const PG8_LAS bf16x8*)(lds + PG8_SB(b, h) + boff + n * 2048 + k * 1024); } while (0)
; #define PG8_MMA(ai, bj, At, Bt) do { __builtin_amdgcn_s_setprio(1); _Pragma("unroll") for (int m = 0; m < 4; ++m) _Pragma("unroll") for (int n = 0; n < 2; ++n) _Pragma("unroll") for (int k = 0; k < 2; ++k) \
;         acc[ai][bj][m][n] = __builtin_amdgcn_mfma_f32_16x16x32_bf16(Bt[n][k], At[m][k], acc[ai][bj][m][n], 0, 0, 0); __builtin_amdgcn_s_setprio(0); } while (0)
; #define PG8_BAR __builtin_amdgcn_s_barrier()
; template <class Epi, class Sched, bool ALIGN_EPI = false, bool SP2 = false>
; __device__ __forceinline__ void gemm_phase(PG8_LAS unsigned char* lds, const Gemm g, const Sched& S, const Epi& E, const int wid) {
;     ...
;             PG8_LDB(B0, 0, 0); PG8_LDB(B1, 0, 1); PG8_SCHED; PG8_LDA(At, 0, 0); PG8_STAGE(PG8_SA(1, 1), a1 + hstep, voffA);
;             PG8_WAIT_V(8); PG8_WAIT_L(0); PG8_BAR; PG8_MMA(0, 0, At, B0); PG8_MMA(0, 1, At, B1); PG8_BAR; PG8_SCHED;
;             PG8_LDA(At, 0, 1); PG8_STAGE(PG8_SB(0, 0), b2, voffB); PG8_STAGE(PG8_SB(0, 1), b2 + hstep, voffB); PG8_STAGE(PG8_SA(0, 0), a2, voffA);
;             PG8_WAIT_V(8); PG8_WAIT_L(0); PG8_BAR; PG8_MMA(1, 0, At, B0); PG8_MMA(1, 1, At, B1); PG8_BAR; PG8_SCHED;
;             PG8_LDB(B0, 1, 0); PG8_LDB(B1, 1, 1); PG8_SCHED; PG8_LDA(At, 1, 0); PG8_STAGE(PG8_SA(0, 1), a2 + hstep, voffA);
;             PG8_WAIT_V(8); PG8_WAIT_L(0); PG8_BAR; PG8_MMA(0, 0, At, B0); PG8_MMA(0, 1, At, B1); PG8_BAR; PG8_SCHED;
;             PG8_LDA(At, 1, 1); PG8_STAGE(PG8_SB(1, 0), b3, voffB); PG8_STAGE(PG8_SB(1, 1), b3 + hstep, voffB); PG8_STAGE(PG8_SA(1, 0), a3, voffA);
;             PG8_WAIT_V(8); PG8_WAIT_L(0); PG8_BAR; PG8_MMA(1, 0, At, B0); PG8_MMA(1, 1, At, B1); PG8_BAR; PG8_SCHED;
	v_mfma_f32_16x16x32_bf16 v[64:67], v[176:179], v[208:211], v[64:67]
	s_setprio 0
	s_add_i32 s30, s33, s38
	v_lshl_add_u64 v[212:213], v[212:213], 0, s[18:19]
	s_mov_b32 m0, s30
	ds_read_b128 v[180:183], v151 offset:49152
	ds_read_b128 v[184:187], v151 offset:50176
	ds_read_b128 v[188:191], v151 offset:51200
	ds_read_b128 v[192:195], v151 offset:52224
	ds_read_b128 v[196:199], v151 offset:53248
	ds_read_b128 v[200:203], v151 offset:54272
	ds_read_b128 v[204:207], v151 offset:55296
	ds_read_b128 v[208:211], v151 offset:56320
	global_load_lds_dwordx4 v[212:213], off
	v_lshl_add_u64 v[212:213], v[214:215], 0, s[18:19]
	s_add_i32 m0, s30, 0x2000
	s_add_i32 s30, s67, s38
	global_load_lds_dwordx4 v[212:213], off
	v_lshl_add_u64 v[212:213], v[216:217], 0, s[18:19]
	s_mov_b32 m0, s30
	s_nop 0
	global_load_lds_dwordx4 v[212:213], off
	v_lshl_add_u64 v[212:213], v[218:219], 0, s[18:19]
	s_add_i32 m0, s30, 0x2000
	s_nop 0
	global_load_lds_dwordx4 v[212:213], off
	v_lshl_add_u64 v[212:213], v[220:221], 0, s[18:19]
	s_mov_b32 m0, s52
	s_nop 0
	global_load_lds_dwordx4 v[212:213], off
	v_lshl_add_u64 v[212:213], v[222:223], 0, s[18:19]
	s_mov_b32 m0, s53
	s_nop 0
	global_load_lds_dwordx4 v[212:213], off
	s_waitcnt vmcnt(8)
	s_waitcnt lgkmcnt(0)
	s_setprio 1
	s_barrier
	v_mfma_f32_16x16x32_bf16 v[60:63], v[142:145], v[180:183], v[60:63]
	v_mfma_f32_16x16x32_bf16 v[56:59], v[156:159], v[180:183], v[56:59]
	v_mfma_f32_16x16x32_bf16 v[44:47], v[142:145], v[188:191], v[44:47]
	v_mfma_f32_16x16x32_bf16 v[40:43], v[156:159], v[188:191], v[40:43]
	v_mfma_f32_16x16x32_bf16 v[28:31], v[142:145], v[196:199], v[28:31]
	v_mfma_f32_16x16x32_bf16 v[24:27], v[156:159], v[196:199], v[24:27]
	v_mfma_f32_16x16x32_bf16 v[12:15], v[142:145], v[204:207], v[12:15]
	v_mfma_f32_16x16x32_bf16 v[8:11], v[156:159], v[204:207], v[8:11]
	v_mfma_f32_16x16x32_bf16 v[60:63], v[152:155], v[184:187], v[60:63]
	v_mfma_f32_16x16x32_bf16 v[56:59], v[160:163], v[184:187], v[56:59]
	v_mfma_f32_16x16x32_bf16 v[44:47], v[152:155], v[192:195], v[44:47]
	v_mfma_f32_16x16x32_bf16 v[40:43], v[160:163], v[192:195], v[40:43]
	v_mfma_f32_16x16x32_bf16 v[28:31], v[152:155], v[200:203], v[28:31]
	v_mfma_f32_16x16x32_bf16 v[24:27], v[160:163], v[200:203], v[24:27]
	v_mfma_f32_16x16x32_bf16 v[12:15], v[152:155], v[208:211], v[12:15]
	v_mfma_f32_16x16x32_bf16 v[8:11], v[160:163], v[208:211], v[8:11]
	v_mfma_f32_16x16x32_bf16 v[52:55], v[164:167], v[180:183], v[52:55]
	v_mfma_f32_16x16x32_bf16 v[48:51], v[172:175], v[180:183], v[48:51]
	v_mfma_f32_16x16x32_bf16 v[36:39], v[164:167], v[188:191], v[36:39]
	v_mfma_f32_16x16x32_bf16 v[32:35], v[172:175], v[188:191], v[32:35]
	v_mfma_f32_16x16x32_bf16 v[20:23], v[164:167], v[196:199], v[20:23]
	v_mfma_f32_16x16x32_bf16 v[16:19], v[172:175], v[196:199], v[16:19]
	v_mfma_f32_16x16x32_bf16 v[4:7], v[164:167], v[204:207], v[4:7]
	v_mfma_f32_16x16x32_bf16 v[0:3], v[172:175], v[204:207], v[0:3]
	v_mfma_f32_16x16x32_bf16 v[52:55], v[168:171], v[184:187], v[52:55]
	v_mfma_f32_16x16x32_bf16 v[48:51], v[176:179], v[184:187], v[48:51]
	v_mfma_f32_16x16x32_bf16 v[36:39], v[168:171], v[192:195], v[36:39]
	v_mfma_f32_16x16x32_bf16 v[32:35], v[176:179], v[192:195], v[32:35]
	v_mfma_f32_16x16x32_bf16 v[20:23], v[168:171], v[200:203], v[20:23]
	v_mfma_f32_16x16x32_bf16 v[16:19], v[176:179], v[200:203], v[16:19]
	v_mfma_f32_16x16x32_bf16 v[4:7], v[168:171], v[208:211], v[4:7]
	s_setprio 2
	s_barrier
	v_mfma_f32_16x16x32_bf16 v[0:3], v[176:179], v[208:211], v[0:3]
	s_setprio 0
	s_add_u32 s28, s28, 0x100
	s_addc_u32 s29, s29, 0
	s_add_u32 s0, s0, 0x100
	s_addc_u32 s1, s1, 0
	s_cmp_ge_i32 s66, s54
	s_mov_b32 s30, s66
	s_cbranch_scc0 .LBB0_1258

; #define PG8_WAIT_V(n) asm volatile("s_waitcnt vmcnt(" #n ")" ::: "memory")
; #define PG8_WAIT_L(n) asm volatile("s_waitcnt lgkmcnt(" #n ")" ::: "memory")
; #define PG8_BAR __builtin_amdgcn_s_barrier()
; template <class Epi, class Sched, bool ALIGN_EPI = false, bool SP2 = false>
; __device__ __forceinline__ void gemm_phase(PG8_LAS unsigned char* lds, const Gemm g, const Sched& S, const Epi& E, const int wid) {
;     ...
;     for (;;) {
;         const bool has_next = S.next(ui + 1, nxt);
;         const char* nA = has_next ? (const char*)g.A + (size_t)nxt.pm * tstep : cA; const char* nB = has_next ? (const char*)g.Bt + (size_t)nxt.pn * tstep : cB;
;         for (int t = 0; t < nt; t += 2) {
;             const bool last = (t == nt - 2);
;             const char* a1 = cA + (size_t)(t + 1) * kstep;
;             const char* a2 = last ? nA : cA + (size_t)(t + 2) * kstep; const char* b2 = last ? nB : cB + (size_t)(t + 2) * kstep;
;             const char* a3 = a2 + kstep; const char* b3 = b2 + kstep;
;             if (last && has_next) S.a_ready(nxt);
;             if constexpr (SP2) {
;             PG8_LDB(B0, 0, 0); PG8_LDB(B1, 0, 1); PG8_SCHED; PG8_LDA(At, 0, 0); PG8_STAGE(PG8_SA(1, 1), a1 + hstep, voffA);
;             PG8_WAIT_V(8); PG8_WAIT_L(0); PG8_BAR; PG8_MMA(0, 0, At, B0); PG8_MMA(0, 1, At, B1); PG8_BAR; PG8_SCHED;
;             PG8_LDA(At, 0, 1); PG8_STAGE(PG8_SB(0, 0), b2, voffB); PG8_STAGE(PG8_SB(0, 1), b2 + hstep, voffB); PG8_STAGE(PG8_SA(0, 0), a2, voffA);
;             PG8_WAIT_V(8); PG8_WAIT_L(0); PG8_BAR; PG8_MMA(1, 0, At, B0); PG8_MMA(1, 1, At, B1); PG8_BAR; PG8_SCHED;
;             PG8_LDB(B0, 1, 0); PG8_LDB(B1, 1, 1); PG8_SCHED; PG8_LDA(At, 1, 0); PG8_STAGE(PG8_SA(0, 1), a2 + hstep, voffA);
;             PG8_WAIT_V(8); PG8_WAIT_L(0); PG8_BAR; PG8_MMA(0, 0, At, B0); PG8_MMA(0, 1, At, B1); PG8_BAR; PG8_SCHED;
;             PG8_LDA(At, 1, 1); PG8_STAGE(PG8_SB(1, 0), b3, voffB); PG8_STAGE(PG8_SB(1, 1), b3 + hstep, voffB); PG8_STAGE(PG8_SA(1, 0), a3, voffA);
;             PG8_WAIT_V(8); PG8_WAIT_L(0); PG8_BAR; PG8_MMA(1, 0, At, B0); PG8_MMA(1, 1, At, B1); PG8_BAR; PG8_SCHED;
;     ...
;         for (int a = 0; a < 2; ++a)
; #pragma unroll
;             for (int b = 0; b < 2; ++b)
; #pragma unroll
;                 for (int m = 0; m < 4; ++m)
; #pragma unroll
;                     for (int n = 0; n < 2; ++n) acc[a][b][m][n] = (f32x4){0.f, 0.f, 0.f, 0.f};
.LBB0_1337:
	s_andn2_b64 vcc, exec, s[24:25]
	s_waitcnt lgkmcnt(0)
	s_cbranch_vccnz .Lz_GOUT
	s_add_u32 s4, s36, 0x80
	s_addc_u32 s5, s37, 0
	s_add_u32 s0, s34, 0x100
	s_addc_u32 s1, s35, 0
	s_mov_b32 s34, 0
	ds_read_b128 v[142:145], v149
	ds_read_b128 v[154:157], v149 offset:1024
	ds_read_b128 v[158:161], v149 offset:2048
	ds_read_b128 v[162:165], v149 offset:3072
	ds_read_b128 v[166:169], v150
	ds_read_b128 v[170:173], v150 offset:1024
	ds_read_b128 v[174:177], v150 offset:2048
	ds_read_b128 v[178:181], v150 offset:3072
	s_add_i32 s36, s34, 2
	s_add_u32 s33, s4, 0x80
	s_addc_u32 s35, s5, 0
	s_cmp_eq_u32 s54, s34
	s_cselect_b32 s34, s28, s33
	s_cselect_b32 s35, s29, s35
	s_cselect_b32 s69, s31, s1
	s_cselect_b32 s68, s30, s0
	v_lshl_add_u64 v[214:215], s[4:5], 0, v[136:137]
	s_add_i32 m0, s43, 0xc000
	ds_read_b128 v[182:185], v151
	ds_read_b128 v[186:189], v151 offset:1024
	ds_read_b128 v[190:193], v151 offset:2048
	ds_read_b128 v[194:197], v151 offset:3072
	ds_read_b128 v[198:201], v151 offset:4096
	ds_read_b128 v[202:205], v151 offset:5120
	ds_read_b128 v[206:209], v151 offset:6144
	ds_read_b128 v[210:213], v151 offset:7168
	global_load_lds_dwordx4 v[214:215], off
	v_lshl_add_u64 v[214:215], s[4:5], 0, v[138:139]
	s_add_i32 m0, s43, 0xe000
	s_nop 0
	global_load_lds_dwordx4 v[214:215], off
	s_waitcnt vmcnt(8)
	s_waitcnt lgkmcnt(0)
	s_setprio 1
	s_barrier
	v_mfma_f32_16x16x32_bf16 v[120:123], v[142:145], v[182:185], 0
	v_mfma_f32_16x16x32_bf16 v[124:127], v[158:161], v[182:185], 0
	v_mfma_f32_16x16x32_bf16 v[108:111], v[142:145], v[190:193], 0
	v_mfma_f32_16x16x32_bf16 v[104:107], v[158:161], v[190:193], 0
	v_mfma_f32_16x16x32_bf16 v[92:95], v[142:145], v[198:201], 0
	v_mfma_f32_16x16x32_bf16 v[88:91], v[158:161], v[198:201], 0
	v_mfma_f32_16x16x32_bf16 v[76:79], v[142:145], v[206:209], 0
	v_mfma_f32_16x16x32_bf16 v[72:75], v[158:161], v[206:209], 0
	v_mfma_f32_16x16x32_bf16 v[120:123], v[154:157], v[186:189], v[120:123]
	v_mfma_f32_16x16x32_bf16 v[124:127], v[162:165], v[186:189], v[124:127]
	v_mfma_f32_16x16x32_bf16 v[108:111], v[154:157], v[194:197], v[108:111]
	v_mfma_f32_16x16x32_bf16 v[104:107], v[162:165], v[194:197], v[104:107]
	v_mfma_f32_16x16x32_bf16 v[92:95], v[154:157], v[202:205], v[92:95]
	v_mfma_f32_16x16x32_bf16 v[88:91], v[162:165], v[202:205], v[88:91]
	v_mfma_f32_16x16x32_bf16 v[76:79], v[154:157], v[210:213], v[76:79]
	v_mfma_f32_16x16x32_bf16 v[72:75], v[162:165], v[210:213], v[72:75]
	v_mfma_f32_16x16x32_bf16 v[116:119], v[166:169], v[182:185], 0
	v_mfma_f32_16x16x32_bf16 v[112:115], v[174:177], v[182:185], 0
	v_mfma_f32_16x16x32_bf16 v[100:103], v[166:169], v[190:193], 0
	v_mfma_f32_16x16x32_bf16 v[96:99], v[174:177], v[190:193], 0
	v_mfma_f32_16x16x32_bf16 v[84:87], v[166:169], v[198:201], 0
	v_mfma_f32_16x16x32_bf16 v[80:83], v[174:177], v[198:201], 0
	v_mfma_f32_16x16x32_bf16 v[68:71], v[166:169], v[206:209], 0
	v_mfma_f32_16x16x32_bf16 v[64:67], v[174:177], v[206:209], 0
	v_mfma_f32_16x16x32_bf16 v[116:119], v[170:173], v[186:189], v[116:119]
	v_mfma_f32_16x16x32_bf16 v[112:115], v[178:181], v[186:189], v[112:115]
	v_mfma_f32_16x16x32_bf16 v[100:103], v[170:173], v[194:197], v[100:103]
	v_mfma_f32_16x16x32_bf16 v[96:99], v[178:181], v[194:197], v[96:99]
	v_mfma_f32_16x16x32_bf16 v[84:87], v[170:173], v[202:205], v[84:87]
	v_mfma_f32_16x16x32_bf16 v[80:83], v[178:181], v[202:205], v[80:83]
	v_mfma_f32_16x16x32_bf16 v[68:71], v[170:173], v[210:213], v[68:71]
	s_setprio 2
	s_barrier
	v_mfma_f32_16x16x32_bf16 v[64:67], v[178:181], v[210:213], v[64:67]
	s_setprio 0
	s_add_i32 s33, s62, s42
	v_lshl_add_u64 v[214:215], s[68:69], 0, v[130:131]
	s_mov_b32 m0, s33
	ds_read_b128 v[182:185], v151 offset:16384
	ds_read_b128 v[186:189], v151 offset:17408
	ds_read_b128 v[190:193], v151 offset:18432
	ds_read_b128 v[194:197], v151 offset:19456
	ds_read_b128 v[198:201], v151 offset:20480
	ds_read_b128 v[202:205], v151 offset:21504
	ds_read_b128 v[206:209], v151 offset:22528
	ds_read_b128 v[210:213], v151 offset:23552
	global_load_lds_dwordx4 v[214:215], off
	s_add_i32 m0, s33, 0x2000
	v_lshl_add_u64 v[216:217], s[68:69], 0, v[134:135]
	s_add_u32 s68, s68, s8
	s_addc_u32 s69, s69, s9
	s_add_i32 s33, s63, s42
	global_load_lds_dwordx4 v[216:217], off
	v_lshl_add_u64 v[218:219], s[68:69], 0, v[130:131]
	s_mov_b32 m0, s33
	v_lshl_add_u64 v[220:221], s[68:69], 0, v[134:135]
	global_load_lds_dwordx4 v[218:219], off
	s_add_i32 m0, s33, 0x2000
	v_lshl_add_u64 v[222:223], s[34:35], 0, v[128:129]
	global_load_lds_dwordx4 v[220:221], off
	s_mov_b32 m0, s43
	v_lshl_add_u64 v[224:225], s[34:35], 0, v[132:133]
	global_load_lds_dwordx4 v[222:223], off
	s_mov_b32 m0, s44
	s_nop 0
	global_load_lds_dwordx4 v[224:225], off
	s_waitcnt vmcnt(8)
	s_waitcnt lgkmcnt(0)
	s_setprio 1
	s_barrier
; #define PG8_STAGE(bufoff, gbase, voff) do { _Pragma("unroll") for (int _i = 0; _i < 2; ++_i) \
;         __builtin_amdgcn_global_load_lds((const unsigned*)((const char*)(gbase) + (voff)[_i]), (PG8_LAS unsigned*)(lds + (bufoff) + ldsw + _i * 8192), 16, 0, 0); } while (0)
; #define PG8_LDA(dst, b, h) do { _Pragma("unroll") for (int m = 0; m < 4; ++m) _Pragma("unroll") for (int k = 0; k < 2; ++k) dst[m][k] = *(const PG8_LAS bf16x8*)(lds + PG8_SA(b, h) + aoff + m * 2048 + k * 1024); } while (0)
; #define PG8_LDB(dst, b, h) do { _Pragma("unroll") for (int n = 0; n < 2; ++n) _Pragma("unroll") for (int k = 0; k < 2; ++k) dst[n][k] = *(const PG8_LAS bf16x8*)(lds + PG8_SB(b, h) + boff + n * 2048 + k * 1024); } while (0)
; #define PG8_MMA(ai, bj, At, Bt) do { __builtin_amdgcn_s_setprio(1); _Pragma("unroll") for (int m = 0; m < 4; ++m) _Pragma("unroll") for (int n = 0; n < 2; ++n) _Pragma("unroll") for (int k = 0; k < 2; ++k) \
;         acc[ai][bj][m][n] = __builtin_amdgcn_mfma_f32_16x16x32_bf16(Bt[n][k], At[m][k], acc[ai][bj][m][n], 0, 0, 0); __builtin_amdgcn_s_setprio(0); } while (0)
; #define PG8_BAR __builtin_amdgcn_s_barrier()
; template <class Epi, class Sched, bool ALIGN_EPI = false, bool SP2 = false>
; __device__ __forceinline__ void gemm_phase(PG8_LAS unsigned char* lds, const Gemm g, const Sched& S, const Epi& E, const int wid) {
;     ...
;             PG8_LDB(B0, 0, 0); PG8_LDB(B1, 0, 1); PG8_SCHED; PG8_LDA(At, 0, 0); PG8_STAGE(PG8_SA(1, 1), a1 + hstep, voffA);
;             PG8_WAIT_V(8); PG8_WAIT_L(0); PG8_BAR; PG8_MMA(0, 0, At, B0); PG8_MMA(0, 1, At, B1); PG8_BAR; PG8_SCHED;
;             PG8_LDA(At, 0, 1); PG8_STAGE(PG8_SB(0, 0), b2, voffB); PG8_STAGE(PG8_SB(0, 1), b2 + hstep, voffB); PG8_STAGE(PG8_SA(0, 0), a2, voffA);
;             PG8_WAIT_V(8); PG8_WAIT_L(0); PG8_BAR; PG8_MMA(1, 0, At, B0); PG8_MMA(1, 1, At, B1); PG8_BAR; PG8_SCHED;
;             PG8_LDB(B0, 1, 0); PG8_LDB(B1, 1, 1); PG8_SCHED; PG8_LDA(At, 1, 0); PG8_STAGE(PG8_SA(0, 1), a2 + hstep, voffA);
;             PG8_WAIT_V(8); PG8_WAIT_L(0); PG8_BAR; PG8_MMA(0, 0, At, B0); PG8_MMA(0, 1, At, B1); PG8_BAR; PG8_SCHED;
;             PG8_LDA(At, 1, 1); PG8_STAGE(PG8_SB(1, 0), b3, voffB); PG8_STAGE(PG8_SB(1, 1), b3 + hstep, voffB); PG8_STAGE(PG8_SA(1, 0), a3, voffA);
;             PG8_WAIT_V(8); PG8_WAIT_L(0); PG8_BAR; PG8_MMA(1, 0, At, B0); PG8_MMA(1, 1, At, B1); PG8_BAR; PG8_SCHED;
	v_mfma_f32_16x16x32_bf16 v[60:63], v[142:145], v[182:185], 0
	v_mfma_f32_16x16x32_bf16 v[56:59], v[158:161], v[182:185], 0
	v_mfma_f32_16x16x32_bf16 v[44:47], v[142:145], v[190:193], 0
	v_mfma_f32_16x16x32_bf16 v[40:43], v[158:161], v[190:193], 0
	v_mfma_f32_16x16x32_bf16 v[28:31], v[142:145], v[198:201], 0
	v_mfma_f32_16x16x32_bf16 v[24:27], v[158:161], v[198:201], 0
	v_mfma_f32_16x16x32_bf16 v[12:15], v[142:145], v[206:209], 0
	v_mfma_f32_16x16x32_bf16 v[8:11], v[158:161], v[206:209], 0
	v_mfma_f32_16x16x32_bf16 v[60:63], v[154:157], v[186:189], v[60:63]
	v_mfma_f32_16x16x32_bf16 v[56:59], v[162:165], v[186:189], v[56:59]
	v_mfma_f32_16x16x32_bf16 v[44:47], v[154:157], v[194:197], v[44:47]
	v_mfma_f32_16x16x32_bf16 v[40:43], v[162:165], v[194:197], v[40:43]
	v_mfma_f32_16x16x32_bf16 v[28:31], v[154:157], v[202:205], v[28:31]
	v_mfma_f32_16x16x32_bf16 v[24:27], v[162:165], v[202:205], v[24:27]
	v_mfma_f32_16x16x32_bf16 v[12:15], v[154:157], v[210:213], v[12:15]
	v_mfma_f32_16x16x32_bf16 v[8:11], v[162:165], v[210:213], v[8:11]
	v_mfma_f32_16x16x32_bf16 v[52:55], v[166:169], v[182:185], 0
	v_mfma_f32_16x16x32_bf16 v[48:51], v[174:177], v[182:185], 0
	v_mfma_f32_16x16x32_bf16 v[36:39], v[166:169], v[190:193], 0
	v_mfma_f32_16x16x32_bf16 v[32:35], v[174:177], v[190:193], 0
	v_mfma_f32_16x16x32_bf16 v[20:23], v[166:169], v[198:201], 0
	v_mfma_f32_16x16x32_bf16 v[16:19], v[174:177], v[198:201], 0
	v_mfma_f32_16x16x32_bf16 v[4:7], v[166:169], v[206:209], 0
	v_mfma_f32_16x16x32_bf16 v[0:3], v[174:177], v[206:209], 0
	v_mfma_f32_16x16x32_bf16 v[52:55], v[170:173], v[186:189], v[52:55]
	v_mfma_f32_16x16x32_bf16 v[48:51], v[178:181], v[186:189], v[48:51]
	v_mfma_f32_16x16x32_bf16 v[36:39], v[170:173], v[194:197], v[36:39]
	v_mfma_f32_16x16x32_bf16 v[32:35], v[178:181], v[194:197], v[32:35]
	v_mfma_f32_16x16x32_bf16 v[20:23], v[170:173], v[202:205], v[20:23]
	v_mfma_f32_16x16x32_bf16 v[16:19], v[178:181], v[202:205], v[16:19]
	v_mfma_f32_16x16x32_bf16 v[4:7], v[170:173], v[210:213], v[4:7]
	s_setprio 2
	s_barrier
	v_mfma_f32_16x16x32_bf16 v[0:3], v[178:181], v[210:213], v[0:3]
	s_setprio 0
	s_add_i32 s33, 0, 0x18000
	v_add_u32_e32 v153, s33, v148
	s_add_i32 s37, 0, 0x1c000
	ds_read_b128 v[142:145], v153
	ds_read_b128 v[154:157], v153 offset:1024
	ds_read_b128 v[158:161], v153 offset:2048
	ds_read_b128 v[162:165], v153 offset:3072
	v_add_u32_e32 v153, s37, v148
	ds_read_b128 v[166:169], v153
	ds_read_b128 v[170:173], v153 offset:1024
	ds_read_b128 v[174:177], v153 offset:2048
	ds_read_b128 v[178:181], v153 offset:3072
	s_add_u32 s34, s34, s8
	s_addc_u32 s35, s35, s9
	s_mov_b32 m0, s45
	v_lshl_add_u64 v[226:227], s[34:35], 0, v[128:129]
	ds_read_b128 v[182:185], v151 offset:32768
	ds_read_b128 v[186:189], v151 offset:33792
	ds_read_b128 v[190:193], v151 offset:34816
	ds_read_b128 v[194:197], v151 offset:35840
	ds_read_b128 v[198:201], v151 offset:36864
	ds_read_b128 v[202:205], v151 offset:37888
	ds_read_b128 v[206:209], v151 offset:38912
	ds_read_b128 v[210:213], v151 offset:39936
	global_load_lds_dwordx4 v[226:227], off
	v_lshl_add_u64 v[226:227], s[34:35], 0, v[132:133]
	s_mov_b32 m0, s46
	s_nop 0
	global_load_lds_dwordx4 v[226:227], off
	s_waitcnt vmcnt(8)
	s_waitcnt lgkmcnt(0)
	s_setprio 1
	s_barrier
	v_mfma_f32_16x16x32_bf16 v[120:123], v[142:145], v[182:185], v[120:123]
	v_mfma_f32_16x16x32_bf16 v[124:127], v[158:161], v[182:185], v[124:127]
	v_mfma_f32_16x16x32_bf16 v[108:111], v[142:145], v[190:193], v[108:111]
	v_mfma_f32_16x16x32_bf16 v[104:107], v[158:161], v[190:193], v[104:107]
	v_mfma_f32_16x16x32_bf16 v[92:95], v[142:145], v[198:201], v[92:95]
	v_mfma_f32_16x16x32_bf16 v[88:91], v[158:161], v[198:201], v[88:91]
	v_mfma_f32_16x16x32_bf16 v[76:79], v[142:145], v[206:209], v[76:79]
	v_mfma_f32_16x16x32_bf16 v[72:75], v[158:161], v[206:209], v[72:75]
	v_mfma_f32_16x16x32_bf16 v[120:123], v[154:157], v[186:189], v[120:123]
	v_mfma_f32_16x16x32_bf16 v[124:127], v[162:165], v[186:189], v[124:127]
	v_mfma_f32_16x16x32_bf16 v[108:111], v[154:157], v[194:197], v[108:111]
	v_mfma_f32_16x16x32_bf16 v[104:107], v[162:165], v[194:197], v[104:107]
	v_mfma_f32_16x16x32_bf16 v[92:95], v[154:157], v[202:205], v[92:95]
	v_mfma_f32_16x16x32_bf16 v[88:91], v[162:165], v[202:205], v[88:91]
	v_mfma_f32_16x16x32_bf16 v[76:79], v[154:157], v[210:213], v[76:79]
	v_mfma_f32_16x16x32_bf16 v[72:75], v[162:165], v[210:213], v[72:75]
	v_mfma_f32_16x16x32_bf16 v[116:119], v[166:169], v[182:185], v[116:119]
	v_mfma_f32_16x16x32_bf16 v[112:115], v[174:177], v[182:185], v[112:115]
	v_mfma_f32_16x16x32_bf16 v[100:103], v[166:169], v[190:193], v[100:103]
	v_mfma_f32_16x16x32_bf16 v[96:99], v[174:177], v[190:193], v[96:99]
	v_mfma_f32_16x16x32_bf16 v[84:87], v[166:169], v[198:201], v[84:87]
	v_mfma_f32_16x16x32_bf16 v[80:83], v[174:177], v[198:201], v[80:83]
	v_mfma_f32_16x16x32_bf16 v[68:71], v[166:169], v[206:209], v[68:71]
	v_mfma_f32_16x16x32_bf16 v[64:67], v[174:177], v[206:209], v[64:67]
	v_mfma_f32_16x16x32_bf16 v[116:119], v[170:173], v[186:189], v[116:119]
	v_mfma_f32_16x16x32_bf16 v[112:115], v[178:181], v[186:189], v[112:115]
	v_mfma_f32_16x16x32_bf16 v[100:103], v[170:173], v[194:197], v[100:103]
	v_mfma_f32_16x16x32_bf16 v[96:99], v[178:181], v[194:197], v[96:99]
	v_mfma_f32_16x16x32_bf16 v[84:87], v[170:173], v[202:205], v[84:87]
	v_mfma_f32_16x16x32_bf16 v[80:83], v[178:181], v[202:205], v[80:83]
	v_mfma_f32_16x16x32_bf16 v[68:71], v[170:173], v[210:213], v[68:71]
	s_setprio 2
	s_barrier
; #define PG8_STAGE(bufoff, gbase, voff) do { _Pragma("unroll") for (int _i = 0; _i < 2; ++_i) \
;         __builtin_amdgcn_global_load_lds((const unsigned*)((const char*)(gbase) + (voff)[_i]), (PG8_LAS unsigned*)(lds + (bufoff) + ldsw + _i * 8192), 16, 0, 0); } while (0)
; #define PG8_WAIT_V(n) asm volatile("s_waitcnt vmcnt(" #n ")" ::: "memory")
; #define PG8_WAIT_L(n) asm volatile("s_waitcnt lgkmcnt(" #n ")" ::: "memory")
; #define PG8_BAR __builtin_amdgcn_s_barrier()
; template <class Epi, class Sched, bool ALIGN_EPI = false, bool SP2 = false>
; __device__ __forceinline__ void gemm_phase(PG8_LAS unsigned char* lds, const Gemm g, const Sched& S, const Epi& E, const int wid) {
;     ...
;     for (;;) {
;         const bool has_next = S.next(ui + 1, nxt);
;         const char* nA = has_next ? (const char*)g.A + (size_t)nxt.pm * tstep : cA; const char* nB = has_next ? (const char*)g.Bt + (size_t)nxt.pn * tstep : cB;
;         for (int t = 0; t < nt; t += 2) {
;             const bool last = (t == nt - 2);
;             const char* a1 = cA + (size_t)(t + 1) * kstep;
;             const char* a2 = last ? nA : cA + (size_t)(t + 2) * kstep; const char* b2 = last ? nB : cB + (size_t)(t + 2) * kstep;
;             const char* a3 = a2 + kstep; const char* b3 = b2 + kstep;
;             if (last && has_next) S.a_ready(nxt);
;             if constexpr (SP2) {
;             PG8_LDB(B0, 0, 0); PG8_LDB(B1, 0, 1); PG8_SCHED; PG8_LDA(At, 0, 0); PG8_STAGE(PG8_SA(1, 1), a1 + hstep, voffA);
;             PG8_WAIT_V(8); PG8_WAIT_L(0); PG8_BAR; PG8_MMA(0, 0, At, B0); PG8_MMA(0, 1, At, B1); PG8_BAR; PG8_SCHED;
;             PG8_LDA(At, 0, 1); PG8_STAGE(PG8_SB(0, 0), b2, voffB); PG8_STAGE(PG8_SB(0, 1), b2 + hstep, voffB); PG8_STAGE(PG8_SA(0, 0), a2, voffA);
;             PG8_WAIT_V(8); PG8_WAIT_L(0); PG8_BAR; PG8_MMA(1, 0, At, B0); PG8_MMA(1, 1, At, B1); PG8_BAR; PG8_SCHED;
;             PG8_LDB(B0, 1, 0); PG8_LDB(B1, 1, 1); PG8_SCHED; PG8_LDA(At, 1, 0); PG8_STAGE(PG8_SA(0, 1), a2 + hstep, voffA);
;             PG8_WAIT_V(8); PG8_WAIT_L(0); PG8_BAR; PG8_MMA(0, 0, At, B0); PG8_MMA(0, 1, At, B1); PG8_BAR; PG8_SCHED;
;             PG8_LDA(At, 1, 1); PG8_STAGE(PG8_SB(1, 0), b3, voffB); PG8_STAGE(PG8_SB(1, 1), b3 + hstep, voffB); PG8_STAGE(PG8_SA(1, 0), a3, voffA);
;             PG8_WAIT_V(8); PG8_WAIT_L(0); PG8_BAR; PG8_MMA(1, 0, At, B0); PG8_MMA(1, 1, At, B1); PG8_BAR; PG8_SCHED;
	v_mfma_f32_16x16x32_bf16 v[64:67], v[178:181], v[210:213], v[64:67]
	s_setprio 0
	s_add_i32 s33, s33, s42
	v_lshl_add_u64 v[214:215], v[214:215], 0, s[22:23]
	s_mov_b32 m0, s33
	ds_read_b128 v[182:185], v151 offset:49152
	ds_read_b128 v[186:189], v151 offset:50176
	ds_read_b128 v[190:193], v151 offset:51200
	ds_read_b128 v[194:197], v151 offset:52224
	ds_read_b128 v[198:201], v151 offset:53248
	ds_read_b128 v[202:205], v151 offset:54272
	ds_read_b128 v[206:209], v151 offset:55296
	ds_read_b128 v[210:213], v151 offset:56320
	global_load_lds_dwordx4 v[214:215], off
	v_lshl_add_u64 v[214:215], v[216:217], 0, s[22:23]
	s_add_i32 m0, s33, 0x2000
	s_add_i32 s33, s37, s42
	global_load_lds_dwordx4 v[214:215], off
	v_lshl_add_u64 v[214:215], v[218:219], 0, s[22:23]
	s_mov_b32 m0, s33
	s_nop 0
	global_load_lds_dwordx4 v[214:215], off
	v_lshl_add_u64 v[214:215], v[220:221], 0, s[22:23]
	s_add_i32 m0, s33, 0x2000
	s_nop 0
	global_load_lds_dwordx4 v[214:215], off
	v_lshl_add_u64 v[214:215], v[222:223], 0, s[22:23]
	s_mov_b32 m0, s47
	s_nop 0
	global_load_lds_dwordx4 v[214:215], off
	v_lshl_add_u64 v[214:215], v[224:225], 0, s[22:23]
	s_mov_b32 m0, s49
	s_nop 0
	global_load_lds_dwordx4 v[214:215], off
	s_waitcnt vmcnt(8)
	s_waitcnt lgkmcnt(0)
	s_setprio 1
	s_barrier
	v_mfma_f32_16x16x32_bf16 v[60:63], v[142:145], v[182:185], v[60:63]
	v_mfma_f32_16x16x32_bf16 v[56:59], v[158:161], v[182:185], v[56:59]
	v_mfma_f32_16x16x32_bf16 v[44:47], v[142:145], v[190:193], v[44:47]
	v_mfma_f32_16x16x32_bf16 v[40:43], v[158:161], v[190:193], v[40:43]
	v_mfma_f32_16x16x32_bf16 v[28:31], v[142:145], v[198:201], v[28:31]
	v_mfma_f32_16x16x32_bf16 v[24:27], v[158:161], v[198:201], v[24:27]
	v_mfma_f32_16x16x32_bf16 v[12:15], v[142:145], v[206:209], v[12:15]
	v_mfma_f32_16x16x32_bf16 v[8:11], v[158:161], v[206:209], v[8:11]
	v_mfma_f32_16x16x32_bf16 v[60:63], v[154:157], v[186:189], v[60:63]
	v_mfma_f32_16x16x32_bf16 v[56:59], v[162:165], v[186:189], v[56:59]
	v_mfma_f32_16x16x32_bf16 v[44:47], v[154:157], v[194:197], v[44:47]
	v_mfma_f32_16x16x32_bf16 v[40:43], v[162:165], v[194:197], v[40:43]
	v_mfma_f32_16x16x32_bf16 v[28:31], v[154:157], v[202:205], v[28:31]
	v_mfma_f32_16x16x32_bf16 v[24:27], v[162:165], v[202:205], v[24:27]
	v_mfma_f32_16x16x32_bf16 v[12:15], v[154:157], v[210:213], v[12:15]
	v_mfma_f32_16x16x32_bf16 v[8:11], v[162:165], v[210:213], v[8:11]
	v_mfma_f32_16x16x32_bf16 v[52:55], v[166:169], v[182:185], v[52:55]
	v_mfma_f32_16x16x32_bf16 v[48:51], v[174:177], v[182:185], v[48:51]
	v_mfma_f32_16x16x32_bf16 v[36:39], v[166:169], v[190:193], v[36:39]
	v_mfma_f32_16x16x32_bf16 v[32:35], v[174:177], v[190:193], v[32:35]
	v_mfma_f32_16x16x32_bf16 v[20:23], v[166:169], v[198:201], v[20:23]
	v_mfma_f32_16x16x32_bf16 v[16:19], v[174:177], v[198:201], v[16:19]
	v_mfma_f32_16x16x32_bf16 v[4:7], v[166:169], v[206:209], v[4:7]
	v_mfma_f32_16x16x32_bf16 v[0:3], v[174:177], v[206:209], v[0:3]
	v_mfma_f32_16x16x32_bf16 v[52:55], v[170:173], v[186:189], v[52:55]
	v_mfma_f32_16x16x32_bf16 v[48:51], v[178:181], v[186:189], v[48:51]
	v_mfma_f32_16x16x32_bf16 v[36:39], v[170:173], v[194:197], v[36:39]
	v_mfma_f32_16x16x32_bf16 v[32:35], v[178:181], v[194:197], v[32:35]
	v_mfma_f32_16x16x32_bf16 v[20:23], v[170:173], v[202:205], v[20:23]
	v_mfma_f32_16x16x32_bf16 v[16:19], v[178:181], v[202:205], v[16:19]
	v_mfma_f32_16x16x32_bf16 v[4:7], v[170:173], v[210:213], v[4:7]
	s_setprio 2
	s_barrier
	v_mfma_f32_16x16x32_bf16 v[0:3], v[178:181], v[210:213], v[0:3]
	s_setprio 0
	s_add_u32 s4, s4, 0x100
	s_addc_u32 s5, s5, 0
	s_add_u32 s0, s0, 0x100
	s_addc_u32 s1, s1, 0
	s_cmp_ge_i32 s36, s51
	s_mov_b32 s34, s36
	s_cbranch_scc1 .LBB0_1340
.LBB0_1339:
	ds_read_b128 v[142:145], v149
	ds_read_b128 v[154:157], v149 offset:1024
	ds_read_b128 v[158:161], v149 offset:2048
	ds_read_b128 v[162:165], v149 offset:3072
	ds_read_b128 v[166:169], v150
	ds_read_b128 v[170:173], v150 offset:1024
	ds_read_b128 v[174:177], v150 offset:2048
	ds_read_b128 v[178:181], v150 offset:3072
	s_add_i32 s36, s34, 2
	s_add_u32 s33, s4, 0x80
	s_addc_u32 s35, s5, 0
	s_cmp_eq_u32 s54, s34
	s_cselect_b32 s34, s28, s33
	s_cselect_b32 s35, s29, s35
	s_cselect_b32 s69, s31, s1
	s_cselect_b32 s68, s30, s0
	v_lshl_add_u64 v[214:215], s[4:5], 0, v[136:137]
	s_add_i32 m0, s43, 0xc000
	ds_read_b128 v[182:185], v151
	ds_read_b128 v[186:189], v151 offset:1024
	ds_read_b128 v[190:193], v151 offset:2048
	ds_read_b128 v[194:197], v151 offset:3072
	ds_read_b128 v[198:201], v151 offset:4096
	ds_read_b128 v[202:205], v151 offset:5120
	ds_read_b128 v[206:209], v151 offset:6144
	ds_read_b128 v[210:213], v151 offset:7168
	global_load_lds_dwordx4 v[214:215], off
	v_lshl_add_u64 v[214:215], s[4:5], 0, v[138:139]
	s_add_i32 m0, s43, 0xe000
	s_nop 0
	global_load_lds_dwordx4 v[214:215], off
	s_waitcnt vmcnt(8)
	s_waitcnt lgkmcnt(0)
	s_setprio 1
	s_barrier
; #define PG8_STAGE(bufoff, gbase, voff) do { _Pragma("unroll") for (int _i = 0; _i < 2; ++_i) \
;         __builtin_amdgcn_global_load_lds((const unsigned*)((const char*)(gbase) + (voff)[_i]), (PG8_LAS unsigned*)(lds + (bufoff) + ldsw + _i * 8192), 16, 0, 0); } while (0)
; #define PG8_LDA(dst, b, h) do { _Pragma("unroll") for (int m = 0; m < 4; ++m) _Pragma("unroll") for (int k = 0; k < 2; ++k) dst[m][k] = *(const PG8_LAS bf16x8*)(lds + PG8_SA(b, h) + aoff + m * 2048 + k * 1024); } while (0)
; #define PG8_LDB(dst, b, h) do { _Pragma("unroll") for (int n = 0; n < 2; ++n) _Pragma("unroll") for (int k = 0; k < 2; ++k) dst[n][k] = *(const PG8_LAS bf16x8*)(lds + PG8_SB(b, h) + boff + n * 2048 + k * 1024); } while (0)
; #define PG8_MMA(ai, bj, At, Bt) do { __builtin_amdgcn_s_setprio(1); _Pragma("unroll") for (int m = 0; m < 4; ++m) _Pragma("unroll") for (int n = 0; n < 2; ++n) _Pragma("unroll") for (int k = 0; k < 2; ++k) \
;         acc[ai][bj][m][n] = __builtin_amdgcn_mfma_f32_16x16x32_bf16(Bt[n][k], At[m][k], acc[ai][bj][m][n], 0, 0, 0); __builtin_amdgcn_s_setprio(0); } while (0)
; #define PG8_BAR __builtin_amdgcn_s_barrier()
; template <class Epi, class Sched, bool ALIGN_EPI = false, bool SP2 = false>
; __device__ __forceinline__ void gemm_phase(PG8_LAS unsigned char* lds, const Gemm g, const Sched& S, const Epi& E, const int wid) {
;     ...
;             PG8_LDB(B0, 0, 0); PG8_LDB(B1, 0, 1); PG8_SCHED; PG8_LDA(At, 0, 0); PG8_STAGE(PG8_SA(1, 1), a1 + hstep, voffA);
;             PG8_WAIT_V(8); PG8_WAIT_L(0); PG8_BAR; PG8_MMA(0, 0, At, B0); PG8_MMA(0, 1, At, B1); PG8_BAR; PG8_SCHED;
;             PG8_LDA(At, 0, 1); PG8_STAGE(PG8_SB(0, 0), b2, voffB); PG8_STAGE(PG8_SB(0, 1), b2 + hstep, voffB); PG8_STAGE(PG8_SA(0, 0), a2, voffA);
;             PG8_WAIT_V(8); PG8_WAIT_L(0); PG8_BAR; PG8_MMA(1, 0, At, B0); PG8_MMA(1, 1, At, B1); PG8_BAR; PG8_SCHED;
;             PG8_LDB(B0, 1, 0); PG8_LDB(B1, 1, 1); PG8_SCHED; PG8_LDA(At, 1, 0); PG8_STAGE(PG8_SA(0, 1), a2 + hstep, voffA);
;             PG8_WAIT_V(8); PG8_WAIT_L(0); PG8_BAR; PG8_MMA(0, 0, At, B0); PG8_MMA(0, 1, At, B1); PG8_BAR; PG8_SCHED;
;             PG8_LDA(At, 1, 1); PG8_STAGE(PG8_SB(1, 0), b3, voffB); PG8_STAGE(PG8_SB(1, 1), b3 + hstep, voffB); PG8_STAGE(PG8_SA(1, 0), a3, voffA);
;             PG8_WAIT_V(8); PG8_WAIT_L(0); PG8_BAR; PG8_MMA(1, 0, At, B0); PG8_MMA(1, 1, At, B1); PG8_BAR; PG8_SCHED;
	v_mfma_f32_16x16x32_bf16 v[120:123], v[142:145], v[182:185], v[120:123]
	v_mfma_f32_16x16x32_bf16 v[124:127], v[158:161], v[182:185], v[124:127]
	v_mfma_f32_16x16x32_bf16 v[108:111], v[142:145], v[190:193], v[108:111]
	v_mfma_f32_16x16x32_bf16 v[104:107], v[158:161], v[190:193], v[104:107]
	v_mfma_f32_16x16x32_bf16 v[92:95], v[142:145], v[198:201], v[92:95]
	v_mfma_f32_16x16x32_bf16 v[88:91], v[158:161], v[198:201], v[88:91]
	v_mfma_f32_16x16x32_bf16 v[76:79], v[142:145], v[206:209], v[76:79]
	v_mfma_f32_16x16x32_bf16 v[72:75], v[158:161], v[206:209], v[72:75]
	v_mfma_f32_16x16x32_bf16 v[120:123], v[154:157], v[186:189], v[120:123]
	v_mfma_f32_16x16x32_bf16 v[124:127], v[162:165], v[186:189], v[124:127]
	v_mfma_f32_16x16x32_bf16 v[108:111], v[154:157], v[194:197], v[108:111]
	v_mfma_f32_16x16x32_bf16 v[104:107], v[162:165], v[194:197], v[104:107]
	v_mfma_f32_16x16x32_bf16 v[92:95], v[154:157], v[202:205], v[92:95]
	v_mfma_f32_16x16x32_bf16 v[88:91], v[162:165], v[202:205], v[88:91]
	v_mfma_f32_16x16x32_bf16 v[76:79], v[154:157], v[210:213], v[76:79]
	v_mfma_f32_16x16x32_bf16 v[72:75], v[162:165], v[210:213], v[72:75]
	v_mfma_f32_16x16x32_bf16 v[116:119], v[166:169], v[182:185], v[116:119]
	v_mfma_f32_16x16x32_bf16 v[112:115], v[174:177], v[182:185], v[112:115]
	v_mfma_f32_16x16x32_bf16 v[100:103], v[166:169], v[190:193], v[100:103]
	v_mfma_f32_16x16x32_bf16 v[96:99], v[174:177], v[190:193], v[96:99]
	v_mfma_f32_16x16x32_bf16 v[84:87], v[166:169], v[198:201], v[84:87]
	v_mfma_f32_16x16x32_bf16 v[80:83], v[174:177], v[198:201], v[80:83]
	v_mfma_f32_16x16x32_bf16 v[68:71], v[166:169], v[206:209], v[68:71]
	v_mfma_f32_16x16x32_bf16 v[64:67], v[174:177], v[206:209], v[64:67]
	v_mfma_f32_16x16x32_bf16 v[116:119], v[170:173], v[186:189], v[116:119]
	v_mfma_f32_16x16x32_bf16 v[112:115], v[178:181], v[186:189], v[112:115]
	v_mfma_f32_16x16x32_bf16 v[100:103], v[170:173], v[194:197], v[100:103]
	v_mfma_f32_16x16x32_bf16 v[96:99], v[178:181], v[194:197], v[96:99]
	v_mfma_f32_16x16x32_bf16 v[84:87], v[170:173], v[202:205], v[84:87]
	v_mfma_f32_16x16x32_bf16 v[80:83], v[178:181], v[202:205], v[80:83]
	v_mfma_f32_16x16x32_bf16 v[68:71], v[170:173], v[210:213], v[68:71]
	s_setprio 2
	s_barrier
	v_mfma_f32_16x16x32_bf16 v[64:67], v[178:181], v[210:213], v[64:67]
	s_setprio 0
	s_add_i32 s33, s62, s42
	v_lshl_add_u64 v[214:215], s[68:69], 0, v[130:131]
	s_mov_b32 m0, s33
	ds_read_b128 v[182:185], v151 offset:16384
	ds_read_b128 v[186:189], v151 offset:17408
	ds_read_b128 v[190:193], v151 offset:18432
	ds_read_b128 v[194:197], v151 offset:19456
	ds_read_b128 v[198:201], v151 offset:20480
	ds_read_b128 v[202:205], v151 offset:21504
	ds_read_b128 v[206:209], v151 offset:22528
	ds_read_b128 v[210:213], v151 offset:23552
	global_load_lds_dwordx4 v[214:215], off
	s_add_i32 m0, s33, 0x2000
	v_lshl_add_u64 v[216:217], s[68:69], 0, v[134:135]
	s_add_u32 s68, s68, s8
	s_addc_u32 s69, s69, s9
	s_add_i32 s33, s63, s42
	global_load_lds_dwordx4 v[216:217], off
	v_lshl_add_u64 v[218:219], s[68:69], 0, v[130:131]
	s_mov_b32 m0, s33
	v_lshl_add_u64 v[220:221], s[68:69], 0, v[134:135]
	global_load_lds_dwordx4 v[218:219], off
	s_add_i32 m0, s33, 0x2000
	v_lshl_add_u64 v[222:223], s[34:35], 0, v[128:129]
	global_load_lds_dwordx4 v[220:221], off
	s_mov_b32 m0, s43
	v_lshl_add_u64 v[224:225], s[34:35], 0, v[132:133]
	global_load_lds_dwordx4 v[222:223], off
	s_mov_b32 m0, s44
	s_nop 0
	global_load_lds_dwordx4 v[224:225], off
	s_waitcnt vmcnt(8)
	s_waitcnt lgkmcnt(0)
	s_setprio 1
	s_barrier
	v_mfma_f32_16x16x32_bf16 v[60:63], v[142:145], v[182:185], v[60:63]
	v_mfma_f32_16x16x32_bf16 v[56:59], v[158:161], v[182:185], v[56:59]
	v_mfma_f32_16x16x32_bf16 v[44:47], v[142:145], v[190:193], v[44:47]
	v_mfma_f32_16x16x32_bf16 v[40:43], v[158:161], v[190:193], v[40:43]
	v_mfma_f32_16x16x32_bf16 v[28:31], v[142:145], v[198:201], v[28:31]
	v_mfma_f32_16x16x32_bf16 v[24:27], v[158:161], v[198:201], v[24:27]
	v_mfma_f32_16x16x32_bf16 v[12:15], v[142:145], v[206:209], v[12:15]
	v_mfma_f32_16x16x32_bf16 v[8:11], v[158:161], v[206:209], v[8:11]
	v_mfma_f32_16x16x32_bf16 v[60:63], v[154:157], v[186:189], v[60:63]
	v_mfma_f32_16x16x32_bf16 v[56:59], v[162:165], v[186:189], v[56:59]
	v_mfma_f32_16x16x32_bf16 v[44:47], v[154:157], v[194:197], v[44:47]
	v_mfma_f32_16x16x32_bf16 v[40:43], v[162:165], v[194:197], v[40:43]
	v_mfma_f32_16x16x32_bf16 v[28:31], v[154:157], v[202:205], v[28:31]
	v_mfma_f32_16x16x32_bf16 v[24:27], v[162:165], v[202:205], v[24:27]
	v_mfma_f32_16x16x32_bf16 v[12:15], v[154:157], v[210:213], v[12:15]
	v_mfma_f32_16x16x32_bf16 v[8:11], v[162:165], v[210:213], v[8:11]
	v_mfma_f32_16x16x32_bf16 v[52:55], v[166:169], v[182:185], v[52:55]
	v_mfma_f32_16x16x32_bf16 v[48:51], v[174:177], v[182:185], v[48:51]
	v_mfma_f32_16x16x32_bf16 v[36:39], v[166:169], v[190:193], v[36:39]
	v_mfma_f32_16x16x32_bf16 v[32:35], v[174:177], v[190:193], v[32:35]
	v_mfma_f32_16x16x32_bf16 v[20:23], v[166:169], v[198:201], v[20:23]
	v_mfma_f32_16x16x32_bf16 v[16:19], v[174:177], v[198:201], v[16:19]
	v_mfma_f32_16x16x32_bf16 v[4:7], v[166:169], v[206:209], v[4:7]
	v_mfma_f32_16x16x32_bf16 v[0:3], v[174:177], v[206:209], v[0:3]
	v_mfma_f32_16x16x32_bf16 v[52:55], v[170:173], v[186:189], v[52:55]
	v_mfma_f32_16x16x32_bf16 v[48:51], v[178:181], v[186:189], v[48:51]
	v_mfma_f32_16x16x32_bf16 v[36:39], v[170:173], v[194:197], v[36:39]
	v_mfma_f32_16x16x32_bf16 v[32:35], v[178:181], v[194:197], v[32:35]
	v_mfma_f32_16x16x32_bf16 v[20:23], v[170:173], v[202:205], v[20:23]
	v_mfma_f32_16x16x32_bf16 v[16:19], v[178:181], v[202:205], v[16:19]
	v_mfma_f32_16x16x32_bf16 v[4:7], v[170:173], v[210:213], v[4:7]
	s_setprio 2
	s_barrier
; #define PG8_STAGE(bufoff, gbase, voff) do { _Pragma("unroll") for (int _i = 0; _i < 2; ++_i) \
;         __builtin_amdgcn_global_load_lds((const unsigned*)((const char*)(gbase) + (voff)[_i]), (PG8_LAS unsigned*)(lds + (bufoff) + ldsw + _i * 8192), 16, 0, 0); } while (0)
; #define PG8_LDA(dst, b, h) do { _Pragma("unroll") for (int m = 0; m < 4; ++m) _Pragma("unroll") for (int k = 0; k < 2; ++k) dst[m][k] = *(const PG8_LAS bf16x8*)(lds + PG8_SA(b, h) + aoff + m * 2048 + k * 1024); } while (0)
; #define PG8_LDB(dst, b, h) do { _Pragma("unroll") for (int n = 0; n < 2; ++n) _Pragma("unroll") for (int k = 0; k < 2; ++k) dst[n][k] = *(const PG8_LAS bf16x8*)(lds + PG8_SB(b, h) + boff + n * 2048 + k * 1024); } while (0)
; #define PG8_MMA(ai, bj, At, Bt) do { __builtin_amdgcn_s_setprio(1); _Pragma("unroll") for (int m = 0; m < 4; ++m) _Pragma("unroll") for (int n = 0; n < 2; ++n) _Pragma("unroll") for (int k = 0; k < 2; ++k) \
;         acc[ai][bj][m][n] = __builtin_amdgcn_mfma_f32_16x16x32_bf16(Bt[n][k], At[m][k], acc[ai][bj][m][n], 0, 0, 0); __builtin_amdgcn_s_setprio(0); } while (0)
; #define PG8_BAR __builtin_amdgcn_s_barrier()
; template <class Epi, class Sched, bool ALIGN_EPI = false, bool SP2 = false>
; __device__ __forceinline__ void gemm_phase(PG8_LAS unsigned char* lds, const Gemm g, const Sched& S, const Epi& E, const int wid) {
;     ...
;             PG8_LDB(B0, 0, 0); PG8_LDB(B1, 0, 1); PG8_SCHED; PG8_LDA(At, 0, 0); PG8_STAGE(PG8_SA(1, 1), a1 + hstep, voffA);
;             PG8_WAIT_V(8); PG8_WAIT_L(0); PG8_BAR; PG8_MMA(0, 0, At, B0); PG8_MMA(0, 1, At, B1); PG8_BAR; PG8_SCHED;
;             PG8_LDA(At, 0, 1); PG8_STAGE(PG8_SB(0, 0), b2, voffB); PG8_STAGE(PG8_SB(0, 1), b2 + hstep, voffB); PG8_STAGE(PG8_SA(0, 0), a2, voffA);
;             PG8_WAIT_V(8); PG8_WAIT_L(0); PG8_BAR; PG8_MMA(1, 0, At, B0); PG8_MMA(1, 1, At, B1); PG8_BAR; PG8_SCHED;
;             PG8_LDB(B0, 1, 0); PG8_LDB(B1, 1, 1); PG8_SCHED; PG8_LDA(At, 1, 0); PG8_STAGE(PG8_SA(0, 1), a2 + hstep, voffA);
;             PG8_WAIT_V(8); PG8_WAIT_L(0); PG8_BAR; PG8_MMA(0, 0, At, B0); PG8_MMA(0, 1, At, B1); PG8_BAR; PG8_SCHED;
;             PG8_LDA(At, 1, 1); PG8_STAGE(PG8_SB(1, 0), b3, voffB); PG8_STAGE(PG8_SB(1, 1), b3 + hstep, voffB); PG8_STAGE(PG8_SA(1, 0), a3, voffA);
;             PG8_WAIT_V(8); PG8_WAIT_L(0); PG8_BAR; PG8_MMA(1, 0, At, B0); PG8_MMA(1, 1, At, B1); PG8_BAR; PG8_SCHED;
	v_mfma_f32_16x16x32_bf16 v[0:3], v[178:181], v[210:213], v[0:3]
	s_setprio 0
	s_add_i32 s33, 0, 0x18000
	v_add_u32_e32 v153, s33, v148
	s_add_i32 s37, 0, 0x1c000
	ds_read_b128 v[142:145], v153
	ds_read_b128 v[154:157], v153 offset:1024
	ds_read_b128 v[158:161], v153 offset:2048
	ds_read_b128 v[162:165], v153 offset:3072
	v_add_u32_e32 v153, s37, v148
	ds_read_b128 v[166:169], v153
	ds_read_b128 v[170:173], v153 offset:1024
	ds_read_b128 v[174:177], v153 offset:2048
	ds_read_b128 v[178:181], v153 offset:3072
	s_add_u32 s34, s34, s8
	s_addc_u32 s35, s35, s9
	s_mov_b32 m0, s45
	v_lshl_add_u64 v[226:227], s[34:35], 0, v[128:129]
	ds_read_b128 v[182:185], v151 offset:32768
	ds_read_b128 v[186:189], v151 offset:33792
	ds_read_b128 v[190:193], v151 offset:34816
	ds_read_b128 v[194:197], v151 offset:35840
	ds_read_b128 v[198:201], v151 offset:36864
	ds_read_b128 v[202:205], v151 offset:37888
	ds_read_b128 v[206:209], v151 offset:38912
	ds_read_b128 v[210:213], v151 offset:39936
	global_load_lds_dwordx4 v[226:227], off
	v_lshl_add_u64 v[226:227], s[34:35], 0, v[132:133]
	s_mov_b32 m0, s46
	s_nop 0
	global_load_lds_dwordx4 v[226:227], off
	s_waitcnt vmcnt(8)
	s_waitcnt lgkmcnt(0)
	s_setprio 1
	s_barrier
	v_mfma_f32_16x16x32_bf16 v[120:123], v[142:145], v[182:185], v[120:123]
	v_mfma_f32_16x16x32_bf16 v[124:127], v[158:161], v[182:185], v[124:127]
	v_mfma_f32_16x16x32_bf16 v[108:111], v[142:145], v[190:193], v[108:111]
	v_mfma_f32_16x16x32_bf16 v[104:107], v[158:161], v[190:193], v[104:107]
	v_mfma_f32_16x16x32_bf16 v[92:95], v[142:145], v[198:201], v[92:95]
	v_mfma_f32_16x16x32_bf16 v[88:91], v[158:161], v[198:201], v[88:91]
	v_mfma_f32_16x16x32_bf16 v[76:79], v[142:145], v[206:209], v[76:79]
	v_mfma_f32_16x16x32_bf16 v[72:75], v[158:161], v[206:209], v[72:75]
	v_mfma_f32_16x16x32_bf16 v[120:123], v[154:157], v[186:189], v[120:123]
	v_mfma_f32_16x16x32_bf16 v[124:127], v[162:165], v[186:189], v[124:127]
	v_mfma_f32_16x16x32_bf16 v[108:111], v[154:157], v[194:197], v[108:111]
	v_mfma_f32_16x16x32_bf16 v[104:107], v[162:165], v[194:197], v[104:107]
	v_mfma_f32_16x16x32_bf16 v[92:95], v[154:157], v[202:205], v[92:95]
	v_mfma_f32_16x16x32_bf16 v[88:91], v[162:165], v[202:205], v[88:91]
	v_mfma_f32_16x16x32_bf16 v[76:79], v[154:157], v[210:213], v[76:79]
	v_mfma_f32_16x16x32_bf16 v[72:75], v[162:165], v[210:213], v[72:75]
	v_mfma_f32_16x16x32_bf16 v[116:119], v[166:169], v[182:185], v[116:119]
	v_mfma_f32_16x16x32_bf16 v[112:115], v[174:177], v[182:185], v[112:115]
	v_mfma_f32_16x16x32_bf16 v[100:103], v[166:169], v[190:193], v[100:103]
	v_mfma_f32_16x16x32_bf16 v[96:99], v[174:177], v[190:193], v[96:99]
	v_mfma_f32_16x16x32_bf16 v[84:87], v[166:169], v[198:201], v[84:87]
	v_mfma_f32_16x16x32_bf16 v[80:83], v[174:177], v[198:201], v[80:83]
	v_mfma_f32_16x16x32_bf16 v[68:71], v[166:169], v[206:209], v[68:71]
	v_mfma_f32_16x16x32_bf16 v[64:67], v[174:177], v[206:209], v[64:67]
	v_mfma_f32_16x16x32_bf16 v[116:119], v[170:173], v[186:189], v[116:119]
	v_mfma_f32_16x16x32_bf16 v[112:115], v[178:181], v[186:189], v[112:115]
	v_mfma_f32_16x16x32_bf16 v[100:103], v[170:173], v[194:197], v[100:103]
	v_mfma_f32_16x16x32_bf16 v[96:99], v[178:181], v[194:197], v[96:99]
	v_mfma_f32_16x16x32_bf16 v[84:87], v[170:173], v[202:205], v[84:87]
	v_mfma_f32_16x16x32_bf16 v[80:83], v[178:181], v[202:205], v[80:83]
	v_mfma_f32_16x16x32_bf16 v[68:71], v[170:173], v[210:213], v[68:71]
	s_setprio 2
	s_barrier
; #define PG8_STAGE(bufoff, gbase, voff) do { _Pragma("unroll") for (int _i = 0; _i < 2; ++_i) \
;         __builtin_amdgcn_global_load_lds((const unsigned*)((const char*)(gbase) + (voff)[_i]), (PG8_LAS unsigned*)(lds + (bufoff) + ldsw + _i * 8192), 16, 0, 0); } while (0)
; #define PG8_LDA(dst, b, h) do { _Pragma("unroll") for (int m = 0; m < 4; ++m) _Pragma("unroll") for (int k = 0; k < 2; ++k) dst[m][k] = *(const PG8_LAS bf16x8*)(lds + PG8_SA(b, h) + aoff + m * 2048 + k * 1024); } while (0)
; #define PG8_LDB(dst, b, h) do { _Pragma("unroll") for (int n = 0; n < 2; ++n) _Pragma("unroll") for (int k = 0; k < 2; ++k) dst[n][k] = *(const PG8_LAS bf16x8*)(lds + PG8_SB(b, h) + boff + n * 2048 + k * 1024); } while (0)
; #define PG8_MMA(ai, bj, At, Bt) do { __builtin_amdgcn_s_setprio(1); _Pragma("unroll") for (int m = 0; m < 4; ++m) _Pragma("unroll") for (int n = 0; n < 2; ++n) _Pragma("unroll") for (int k = 0; k < 2; ++k) \
;         acc[ai][bj][m][n] = __builtin_amdgcn_mfma_f32_16x16x32_bf16(Bt[n][k], At[m][k], acc[ai][bj][m][n], 0, 0, 0); __builtin_amdgcn_s_setprio(0); } while (0)
; #define PG8_BAR __builtin_amdgcn_s_barrier()
; template <class Epi, class Sched, bool ALIGN_EPI = false, bool SP2 = false>
; __device__ __forceinline__ void gemm_phase(PG8_LAS unsigned char* lds, const Gemm g, const Sched& S, const Epi& E, const int wid) {
;     ...
;             PG8_LDB(B0, 0, 0); PG8_LDB(B1, 0, 1); PG8_SCHED; PG8_LDA(At, 0, 0); PG8_STAGE(PG8_SA(1, 1), a1 + hstep, voffA);
;             PG8_WAIT_V(8); PG8_WAIT_L(0); PG8_BAR; PG8_MMA(0, 0, At, B0); PG8_MMA(0, 1, At, B1); PG8_BAR; PG8_SCHED;
;             PG8_LDA(At, 0, 1); PG8_STAGE(PG8_SB(0, 0), b2, voffB); PG8_STAGE(PG8_SB(0, 1), b2 + hstep, voffB); PG8_STAGE(PG8_SA(0, 0), a2, voffA);
;             PG8_WAIT_V(8); PG8_WAIT_L(0); PG8_BAR; PG8_MMA(1, 0, At, B0); PG8_MMA(1, 1, At, B1); PG8_BAR; PG8_SCHED;
;             PG8_LDB(B0, 1, 0); PG8_LDB(B1, 1, 1); PG8_SCHED; PG8_LDA(At, 1, 0); PG8_STAGE(PG8_SA(0, 1), a2 + hstep, voffA);
;             PG8_WAIT_V(8); PG8_WAIT_L(0); PG8_BAR; PG8_MMA(0, 0, At, B0); PG8_MMA(0, 1, At, B1); PG8_BAR; PG8_SCHED;
;             PG8_LDA(At, 1, 1); PG8_STAGE(PG8_SB(1, 0), b3, voffB); PG8_STAGE(PG8_SB(1, 1), b3 + hstep, voffB); PG8_STAGE(PG8_SA(1, 0), a3, voffA);
;             PG8_WAIT_V(8); PG8_WAIT_L(0); PG8_BAR; PG8_MMA(1, 0, At, B0); PG8_MMA(1, 1, At, B1); PG8_BAR; PG8_SCHED;
	v_mfma_f32_16x16x32_bf16 v[64:67], v[178:181], v[210:213], v[64:67]
	s_setprio 0
	s_add_i32 s33, s33, s42
	v_lshl_add_u64 v[214:215], v[214:215], 0, s[22:23]
	s_mov_b32 m0, s33
	ds_read_b128 v[182:185], v151 offset:49152
	ds_read_b128 v[186:189], v151 offset:50176
	ds_read_b128 v[190:193], v151 offset:51200
	ds_read_b128 v[194:197], v151 offset:52224
	ds_read_b128 v[198:201], v151 offset:53248
	ds_read_b128 v[202:205], v151 offset:54272
	ds_read_b128 v[206:209], v151 offset:55296
	ds_read_b128 v[210:213], v151 offset:56320
	global_load_lds_dwordx4 v[214:215], off
	v_lshl_add_u64 v[214:215], v[216:217], 0, s[22:23]
	s_add_i32 m0, s33, 0x2000
	s_add_i32 s33, s37, s42
	global_load_lds_dwordx4 v[214:215], off
	v_lshl_add_u64 v[214:215], v[218:219], 0, s[22:23]
	s_mov_b32 m0, s33
	s_nop 0
	global_load_lds_dwordx4 v[214:215], off
	v_lshl_add_u64 v[214:215], v[220:221], 0, s[22:23]
	s_add_i32 m0, s33, 0x2000
	s_nop 0
	global_load_lds_dwordx4 v[214:215], off
	v_lshl_add_u64 v[214:215], v[222:223], 0, s[22:23]
	s_mov_b32 m0, s47
	s_nop 0
	global_load_lds_dwordx4 v[214:215], off
	v_lshl_add_u64 v[214:215], v[224:225], 0, s[22:23]
	s_mov_b32 m0, s49
	s_nop 0
	global_load_lds_dwordx4 v[214:215], off
	s_waitcnt vmcnt(8)
	s_waitcnt lgkmcnt(0)
	s_setprio 1
	s_barrier
	v_mfma_f32_16x16x32_bf16 v[60:63], v[142:145], v[182:185], v[60:63]
	v_mfma_f32_16x16x32_bf16 v[56:59], v[158:161], v[182:185], v[56:59]
	v_mfma_f32_16x16x32_bf16 v[44:47], v[142:145], v[190:193], v[44:47]
	v_mfma_f32_16x16x32_bf16 v[40:43], v[158:161], v[190:193], v[40:43]
	v_mfma_f32_16x16x32_bf16 v[28:31], v[142:145], v[198:201], v[28:31]
	v_mfma_f32_16x16x32_bf16 v[24:27], v[158:161], v[198:201], v[24:27]
	v_mfma_f32_16x16x32_bf16 v[12:15], v[142:145], v[206:209], v[12:15]
	v_mfma_f32_16x16x32_bf16 v[8:11], v[158:161], v[206:209], v[8:11]
	v_mfma_f32_16x16x32_bf16 v[60:63], v[154:157], v[186:189], v[60:63]
	v_mfma_f32_16x16x32_bf16 v[56:59], v[162:165], v[186:189], v[56:59]
	v_mfma_f32_16x16x32_bf16 v[44:47], v[154:157], v[194:197], v[44:47]
	v_mfma_f32_16x16x32_bf16 v[40:43], v[162:165], v[194:197], v[40:43]
	v_mfma_f32_16x16x32_bf16 v[28:31], v[154:157], v[202:205], v[28:31]
	v_mfma_f32_16x16x32_bf16 v[24:27], v[162:165], v[202:205], v[24:27]
	v_mfma_f32_16x16x32_bf16 v[12:15], v[154:157], v[210:213], v[12:15]
	v_mfma_f32_16x16x32_bf16 v[8:11], v[162:165], v[210:213], v[8:11]
	v_mfma_f32_16x16x32_bf16 v[52:55], v[166:169], v[182:185], v[52:55]
	v_mfma_f32_16x16x32_bf16 v[48:51], v[174:177], v[182:185], v[48:51]
	v_mfma_f32_16x16x32_bf16 v[36:39], v[166:169], v[190:193], v[36:39]
	v_mfma_f32_16x16x32_bf16 v[32:35], v[174:177], v[190:193], v[32:35]
	v_mfma_f32_16x16x32_bf16 v[20:23], v[166:169], v[198:201], v[20:23]
	v_mfma_f32_16x16x32_bf16 v[16:19], v[174:177], v[198:201], v[16:19]
	v_mfma_f32_16x16x32_bf16 v[4:7], v[166:169], v[206:209], v[4:7]
	v_mfma_f32_16x16x32_bf16 v[0:3], v[174:177], v[206:209], v[0:3]
	v_mfma_f32_16x16x32_bf16 v[52:55], v[170:173], v[186:189], v[52:55]
	v_mfma_f32_16x16x32_bf16 v[48:51], v[178:181], v[186:189], v[48:51]
	v_mfma_f32_16x16x32_bf16 v[36:39], v[170:173], v[194:197], v[36:39]
	v_mfma_f32_16x16x32_bf16 v[32:35], v[178:181], v[194:197], v[32:35]
	v_mfma_f32_16x16x32_bf16 v[20:23], v[170:173], v[202:205], v[20:23]
	v_mfma_f32_16x16x32_bf16 v[16:19], v[178:181], v[202:205], v[16:19]
	v_mfma_f32_16x16x32_bf16 v[4:7], v[170:173], v[210:213], v[4:7]
	s_setprio 2
	s_barrier
	v_mfma_f32_16x16x32_bf16 v[0:3], v[178:181], v[210:213], v[0:3]
	s_setprio 0
	s_add_u32 s4, s4, 0x100
	s_addc_u32 s5, s5, 0
	s_add_u32 s0, s0, 0x100
	s_addc_u32 s1, s1, 0
	s_cmp_ge_i32 s36, s51
	s_mov_b32 s34, s36
	s_cbranch_scc0 .LBB0_1339

; #define PG8_WAIT_V(n) asm volatile("s_waitcnt vmcnt(" #n ")" ::: "memory")
; #define PG8_WAIT_L(n) asm volatile("s_waitcnt lgkmcnt(" #n ")" ::: "memory")
; #define PG8_BAR __builtin_amdgcn_s_barrier()
; template <class Epi, class Sched, bool ALIGN_EPI = false, bool SP2 = false>
; __device__ __forceinline__ void gemm_phase(PG8_LAS unsigned char* lds, const Gemm g, const Sched& S, const Epi& E, const int wid) {
;     ...
;     for (;;) {
;         const bool has_next = S.next(ui + 1, nxt);
;         const char* nA = has_next ? (const char*)g.A + (size_t)nxt.pm * tstep : cA; const char* nB = has_next ? (const char*)g.Bt + (size_t)nxt.pn * tstep : cB;
;         for (int t = 0; t < nt; t += 2) {
;             const bool last = (t == nt - 2);
;             const char* a1 = cA + (size_t)(t + 1) * kstep;
;             const char* a2 = last ? nA : cA + (size_t)(t + 2) * kstep; const char* b2 = last ? nB : cB + (size_t)(t + 2) * kstep;
;             const char* a3 = a2 + kstep; const char* b3 = b2 + kstep;
;             if (last && has_next) S.a_ready(nxt);
;             if constexpr (SP2) {
;             PG8_LDB(B0, 0, 0); PG8_LDB(B1, 0, 1); PG8_SCHED; PG8_LDA(At, 0, 0); PG8_STAGE(PG8_SA(1, 1), a1 + hstep, voffA);
;             PG8_WAIT_V(8); PG8_WAIT_L(0); PG8_BAR; PG8_MMA(0, 0, At, B0); PG8_MMA(0, 1, At, B1); PG8_BAR; PG8_SCHED;
;             PG8_LDA(At, 0, 1); PG8_STAGE(PG8_SB(0, 0), b2, voffB); PG8_STAGE(PG8_SB(0, 1), b2 + hstep, voffB); PG8_STAGE(PG8_SA(0, 0), a2, voffA);
;             PG8_WAIT_V(8); PG8_WAIT_L(0); PG8_BAR; PG8_MMA(1, 0, At, B0); PG8_MMA(1, 1, At, B1); PG8_BAR; PG8_SCHED;
;             PG8_LDB(B0, 1, 0); PG8_LDB(B1, 1, 1); PG8_SCHED; PG8_LDA(At, 1, 0); PG8_STAGE(PG8_SA(0, 1), a2 + hstep, voffA);
;             PG8_WAIT_V(8); PG8_WAIT_L(0); PG8_BAR; PG8_MMA(0, 0, At, B0); PG8_MMA(0, 1, At, B1); PG8_BAR; PG8_SCHED;
;             PG8_LDA(At, 1, 1); PG8_STAGE(PG8_SB(1, 0), b3, voffB); PG8_STAGE(PG8_SB(1, 1), b3 + hstep, voffB); PG8_STAGE(PG8_SA(1, 0), a3, voffA);
;             PG8_WAIT_V(8); PG8_WAIT_L(0); PG8_BAR; PG8_MMA(1, 0, At, B0); PG8_MMA(1, 1, At, B1); PG8_BAR; PG8_SCHED;
;     ...
;         for (int a = 0; a < 2; ++a)
; #pragma unroll
;             for (int b = 0; b < 2; ++b)
; #pragma unroll
;                 for (int m = 0; m < 4; ++m)
; #pragma unroll
;                     for (int n = 0; n < 2; ++n) acc[a][b][m][n] = (f32x4){0.f, 0.f, 0.f, 0.f};
.LBB0_1493:
	s_andn2_b64 vcc, exec, s[22:23]
	s_cbranch_vccnz .Lz_FFN1
	s_add_u32 s4, s8, 0x80
	s_addc_u32 s5, s9, 0
	s_add_u32 s0, s6, 0x100
	s_addc_u32 s1, s7, 0
	s_mov_b32 s6, 0
	ds_read_b128 v[142:145], v149
	ds_read_b128 v[152:155], v149 offset:1024
	ds_read_b128 v[156:159], v149 offset:2048
	ds_read_b128 v[160:163], v149 offset:3072
	ds_read_b128 v[164:167], v150
	ds_read_b128 v[168:171], v150 offset:1024
	ds_read_b128 v[172:175], v150 offset:2048
	ds_read_b128 v[176:179], v150 offset:3072
	s_add_i32 s8, s6, 2
	s_add_u32 s9, s4, 0x80
	s_addc_u32 s7, s5, 0
	s_cmp_eq_u32 s55, s6
	s_cselect_b32 s6, s26, s9
	s_cselect_b32 s7, s27, s7
	s_cselect_b32 s65, s29, s1
	s_cselect_b32 s64, s28, s0
	v_lshl_add_u64 v[212:213], s[4:5], 0, v[136:137]
	s_add_i32 m0, s44, 0xc000
	ds_read_b128 v[180:183], v151
	ds_read_b128 v[184:187], v151 offset:1024
	ds_read_b128 v[188:191], v151 offset:2048
	ds_read_b128 v[192:195], v151 offset:3072
	ds_read_b128 v[196:199], v151 offset:4096
	ds_read_b128 v[200:203], v151 offset:5120
	ds_read_b128 v[204:207], v151 offset:6144
	ds_read_b128 v[208:211], v151 offset:7168
	global_load_lds_dwordx4 v[212:213], off
	v_lshl_add_u64 v[212:213], s[4:5], 0, v[138:139]
	s_add_i32 m0, s44, 0xe000
	s_nop 0
	global_load_lds_dwordx4 v[212:213], off
	s_waitcnt vmcnt(8)
	s_waitcnt lgkmcnt(0)
	s_setprio 1
	s_barrier
	v_mfma_f32_16x16x32_bf16 v[120:123], v[142:145], v[180:183], 0
	v_mfma_f32_16x16x32_bf16 v[112:115], v[156:159], v[180:183], 0
	v_mfma_f32_16x16x32_bf16 v[104:107], v[142:145], v[188:191], 0
	v_mfma_f32_16x16x32_bf16 v[96:99], v[156:159], v[188:191], 0
	v_mfma_f32_16x16x32_bf16 v[88:91], v[142:145], v[196:199], 0
	v_mfma_f32_16x16x32_bf16 v[80:83], v[156:159], v[196:199], 0
	v_mfma_f32_16x16x32_bf16 v[72:75], v[142:145], v[204:207], 0
	v_mfma_f32_16x16x32_bf16 v[64:67], v[156:159], v[204:207], 0
	v_mfma_f32_16x16x32_bf16 v[120:123], v[152:155], v[184:187], v[120:123]
	v_mfma_f32_16x16x32_bf16 v[112:115], v[160:163], v[184:187], v[112:115]
	v_mfma_f32_16x16x32_bf16 v[104:107], v[152:155], v[192:195], v[104:107]
	v_mfma_f32_16x16x32_bf16 v[96:99], v[160:163], v[192:195], v[96:99]
	v_mfma_f32_16x16x32_bf16 v[88:91], v[152:155], v[200:203], v[88:91]
	v_mfma_f32_16x16x32_bf16 v[80:83], v[160:163], v[200:203], v[80:83]
	v_mfma_f32_16x16x32_bf16 v[72:75], v[152:155], v[208:211], v[72:75]
	v_mfma_f32_16x16x32_bf16 v[64:67], v[160:163], v[208:211], v[64:67]
	v_mfma_f32_16x16x32_bf16 v[124:127], v[164:167], v[180:183], 0
	v_mfma_f32_16x16x32_bf16 v[116:119], v[172:175], v[180:183], 0
	v_mfma_f32_16x16x32_bf16 v[108:111], v[164:167], v[188:191], 0
	v_mfma_f32_16x16x32_bf16 v[100:103], v[172:175], v[188:191], 0
	v_mfma_f32_16x16x32_bf16 v[92:95], v[164:167], v[196:199], 0
	v_mfma_f32_16x16x32_bf16 v[84:87], v[172:175], v[196:199], 0
	v_mfma_f32_16x16x32_bf16 v[76:79], v[164:167], v[204:207], 0
	v_mfma_f32_16x16x32_bf16 v[68:71], v[172:175], v[204:207], 0
	v_mfma_f32_16x16x32_bf16 v[124:127], v[168:171], v[184:187], v[124:127]
	v_mfma_f32_16x16x32_bf16 v[116:119], v[176:179], v[184:187], v[116:119]
	v_mfma_f32_16x16x32_bf16 v[108:111], v[168:171], v[192:195], v[108:111]
	v_mfma_f32_16x16x32_bf16 v[100:103], v[176:179], v[192:195], v[100:103]
	v_mfma_f32_16x16x32_bf16 v[92:95], v[168:171], v[200:203], v[92:95]
	v_mfma_f32_16x16x32_bf16 v[84:87], v[176:179], v[200:203], v[84:87]
	v_mfma_f32_16x16x32_bf16 v[76:79], v[168:171], v[208:211], v[76:79]
	s_setprio 2
	s_barrier
	v_mfma_f32_16x16x32_bf16 v[68:71], v[176:179], v[208:211], v[68:71]
	s_setprio 0
	s_add_i32 s9, s57, s36
	v_lshl_add_u64 v[212:213], s[64:65], 0, v[132:133]
	s_mov_b32 m0, s9
	ds_read_b128 v[180:183], v151 offset:16384
	ds_read_b128 v[184:187], v151 offset:17408
	ds_read_b128 v[188:191], v151 offset:18432
	ds_read_b128 v[192:195], v151 offset:19456
	ds_read_b128 v[196:199], v151 offset:20480
	ds_read_b128 v[200:203], v151 offset:21504
	ds_read_b128 v[204:207], v151 offset:22528
	ds_read_b128 v[208:211], v151 offset:23552
	global_load_lds_dwordx4 v[212:213], off
	s_add_i32 m0, s9, 0x2000
	v_lshl_add_u64 v[214:215], s[64:65], 0, v[128:129]
	s_add_u32 s64, s64, s12
	s_addc_u32 s65, s65, s13
	s_add_i32 s9, s58, s36
	global_load_lds_dwordx4 v[214:215], off
	v_lshl_add_u64 v[216:217], s[64:65], 0, v[132:133]
	s_mov_b32 m0, s9
	v_lshl_add_u64 v[218:219], s[64:65], 0, v[128:129]
	global_load_lds_dwordx4 v[216:217], off
	s_add_i32 m0, s9, 0x2000
	v_lshl_add_u64 v[220:221], s[6:7], 0, v[134:135]
	global_load_lds_dwordx4 v[218:219], off
	s_mov_b32 m0, s44
	v_lshl_add_u64 v[222:223], s[6:7], 0, v[130:131]
	global_load_lds_dwordx4 v[220:221], off
	s_mov_b32 m0, s45
	s_nop 0
	global_load_lds_dwordx4 v[222:223], off
	s_waitcnt vmcnt(8)
	s_waitcnt lgkmcnt(0)
	s_setprio 1
	s_barrier
; #define PG8_STAGE(bufoff, gbase, voff) do { _Pragma("unroll") for (int _i = 0; _i < 2; ++_i) \
;         __builtin_amdgcn_global_load_lds((const unsigned*)((const char*)(gbase) + (voff)[_i]), (PG8_LAS unsigned*)(lds + (bufoff) + ldsw + _i * 8192), 16, 0, 0); } while (0)
; #define PG8_LDA(dst, b, h) do { _Pragma("unroll") for (int m = 0; m < 4; ++m) _Pragma("unroll") for (int k = 0; k < 2; ++k) dst[m][k] = *(const PG8_LAS bf16x8*)(lds + PG8_SA(b, h) + aoff + m * 2048 + k * 1024); } while (0)
; #define PG8_LDB(dst, b, h) do { _Pragma("unroll") for (int n = 0; n < 2; ++n) _Pragma("unroll") for (int k = 0; k < 2; ++k) dst[n][k] = *(const PG8_LAS bf16x8*)(lds + PG8_SB(b, h) + boff + n * 2048 + k * 1024); } while (0)
; #define PG8_MMA(ai, bj, At, Bt) do { __builtin_amdgcn_s_setprio(1); _Pragma("unroll") for (int m = 0; m < 4; ++m) _Pragma("unroll") for (int n = 0; n < 2; ++n) _Pragma("unroll") for (int k = 0; k < 2; ++k) \
;         acc[ai][bj][m][n] = __builtin_amdgcn_mfma_f32_16x16x32_bf16(Bt[n][k], At[m][k], acc[ai][bj][m][n], 0, 0, 0); __builtin_amdgcn_s_setprio(0); } while (0)
; #define PG8_BAR __builtin_amdgcn_s_barrier()
; template <class Epi, class Sched, bool ALIGN_EPI = false, bool SP2 = false>
; __device__ __forceinline__ void gemm_phase(PG8_LAS unsigned char* lds, const Gemm g, const Sched& S, const Epi& E, const int wid) {
;     ...
;             PG8_LDB(B0, 0, 0); PG8_LDB(B1, 0, 1); PG8_SCHED; PG8_LDA(At, 0, 0); PG8_STAGE(PG8_SA(1, 1), a1 + hstep, voffA);
;             PG8_WAIT_V(8); PG8_WAIT_L(0); PG8_BAR; PG8_MMA(0, 0, At, B0); PG8_MMA(0, 1, At, B1); PG8_BAR; PG8_SCHED;
;             PG8_LDA(At, 0, 1); PG8_STAGE(PG8_SB(0, 0), b2, voffB); PG8_STAGE(PG8_SB(0, 1), b2 + hstep, voffB); PG8_STAGE(PG8_SA(0, 0), a2, voffA);
;             PG8_WAIT_V(8); PG8_WAIT_L(0); PG8_BAR; PG8_MMA(1, 0, At, B0); PG8_MMA(1, 1, At, B1); PG8_BAR; PG8_SCHED;
;             PG8_LDB(B0, 1, 0); PG8_LDB(B1, 1, 1); PG8_SCHED; PG8_LDA(At, 1, 0); PG8_STAGE(PG8_SA(0, 1), a2 + hstep, voffA);
;             PG8_WAIT_V(8); PG8_WAIT_L(0); PG8_BAR; PG8_MMA(0, 0, At, B0); PG8_MMA(0, 1, At, B1); PG8_BAR; PG8_SCHED;
;             PG8_LDA(At, 1, 1); PG8_STAGE(PG8_SB(1, 0), b3, voffB); PG8_STAGE(PG8_SB(1, 1), b3 + hstep, voffB); PG8_STAGE(PG8_SA(1, 0), a3, voffA);
;             PG8_WAIT_V(8); PG8_WAIT_L(0); PG8_BAR; PG8_MMA(1, 0, At, B0); PG8_MMA(1, 1, At, B1); PG8_BAR; PG8_SCHED;
	v_mfma_f32_16x16x32_bf16 v[56:59], v[142:145], v[180:183], 0
	v_mfma_f32_16x16x32_bf16 v[48:51], v[156:159], v[180:183], 0
	v_mfma_f32_16x16x32_bf16 v[40:43], v[142:145], v[188:191], 0
	v_mfma_f32_16x16x32_bf16 v[32:35], v[156:159], v[188:191], 0
	v_mfma_f32_16x16x32_bf16 v[24:27], v[142:145], v[196:199], 0
	v_mfma_f32_16x16x32_bf16 v[16:19], v[156:159], v[196:199], 0
	v_mfma_f32_16x16x32_bf16 v[8:11], v[142:145], v[204:207], 0
	v_mfma_f32_16x16x32_bf16 v[4:7], v[156:159], v[204:207], 0
	v_mfma_f32_16x16x32_bf16 v[56:59], v[152:155], v[184:187], v[56:59]
	v_mfma_f32_16x16x32_bf16 v[48:51], v[160:163], v[184:187], v[48:51]
	v_mfma_f32_16x16x32_bf16 v[40:43], v[152:155], v[192:195], v[40:43]
	v_mfma_f32_16x16x32_bf16 v[32:35], v[160:163], v[192:195], v[32:35]
	v_mfma_f32_16x16x32_bf16 v[24:27], v[152:155], v[200:203], v[24:27]
	v_mfma_f32_16x16x32_bf16 v[16:19], v[160:163], v[200:203], v[16:19]
	v_mfma_f32_16x16x32_bf16 v[8:11], v[152:155], v[208:211], v[8:11]
	v_mfma_f32_16x16x32_bf16 v[4:7], v[160:163], v[208:211], v[4:7]
	v_mfma_f32_16x16x32_bf16 v[60:63], v[164:167], v[180:183], 0
	v_mfma_f32_16x16x32_bf16 v[52:55], v[172:175], v[180:183], 0
	v_mfma_f32_16x16x32_bf16 v[44:47], v[164:167], v[188:191], 0
	v_mfma_f32_16x16x32_bf16 v[36:39], v[172:175], v[188:191], 0
	v_mfma_f32_16x16x32_bf16 v[28:31], v[164:167], v[196:199], 0
	v_mfma_f32_16x16x32_bf16 v[20:23], v[172:175], v[196:199], 0
	v_mfma_f32_16x16x32_bf16 v[12:15], v[164:167], v[204:207], 0
	v_mfma_f32_16x16x32_bf16 v[0:3], v[172:175], v[204:207], 0
	v_mfma_f32_16x16x32_bf16 v[60:63], v[168:171], v[184:187], v[60:63]
	v_mfma_f32_16x16x32_bf16 v[52:55], v[176:179], v[184:187], v[52:55]
	v_mfma_f32_16x16x32_bf16 v[44:47], v[168:171], v[192:195], v[44:47]
	v_mfma_f32_16x16x32_bf16 v[36:39], v[176:179], v[192:195], v[36:39]
	v_mfma_f32_16x16x32_bf16 v[28:31], v[168:171], v[200:203], v[28:31]
	v_mfma_f32_16x16x32_bf16 v[20:23], v[176:179], v[200:203], v[20:23]
	v_mfma_f32_16x16x32_bf16 v[12:15], v[168:171], v[208:211], v[12:15]
	s_setprio 2
	s_barrier
	v_mfma_f32_16x16x32_bf16 v[0:3], v[176:179], v[208:211], v[0:3]
	s_setprio 0
	s_add_i32 s9, 0, 0x18000
	s_add_i32 s33, 0, 0x1c000
	v_add_u32_e32 v160, s9, v148
	v_add_u32_e32 v176, s33, v148
	ds_read_b128 v[142:145], v160
	ds_read_b128 v[152:155], v160 offset:1024
	ds_read_b128 v[156:159], v160 offset:2048
	ds_read_b128 v[160:163], v160 offset:3072
	ds_read_b128 v[164:167], v176
	ds_read_b128 v[168:171], v176 offset:1024
	ds_read_b128 v[172:175], v176 offset:2048
	ds_read_b128 v[176:179], v176 offset:3072
	s_add_u32 s6, s6, s12
	s_addc_u32 s7, s7, s13
	s_mov_b32 m0, s46
	v_lshl_add_u64 v[224:225], s[6:7], 0, v[134:135]
	ds_read_b128 v[180:183], v151 offset:32768
	ds_read_b128 v[184:187], v151 offset:33792
	ds_read_b128 v[188:191], v151 offset:34816
	ds_read_b128 v[192:195], v151 offset:35840
	ds_read_b128 v[196:199], v151 offset:36864
	ds_read_b128 v[200:203], v151 offset:37888
	ds_read_b128 v[204:207], v151 offset:38912
	ds_read_b128 v[208:211], v151 offset:39936
	global_load_lds_dwordx4 v[224:225], off
	v_lshl_add_u64 v[224:225], s[6:7], 0, v[130:131]
	s_mov_b32 m0, s47
	s_nop 0
	global_load_lds_dwordx4 v[224:225], off
	s_waitcnt vmcnt(8)
	s_waitcnt lgkmcnt(0)
	s_setprio 1
	s_barrier
	v_mfma_f32_16x16x32_bf16 v[120:123], v[142:145], v[180:183], v[120:123]
	v_mfma_f32_16x16x32_bf16 v[112:115], v[156:159], v[180:183], v[112:115]
	v_mfma_f32_16x16x32_bf16 v[104:107], v[142:145], v[188:191], v[104:107]
	v_mfma_f32_16x16x32_bf16 v[96:99], v[156:159], v[188:191], v[96:99]
	v_mfma_f32_16x16x32_bf16 v[88:91], v[142:145], v[196:199], v[88:91]
	v_mfma_f32_16x16x32_bf16 v[80:83], v[156:159], v[196:199], v[80:83]
	v_mfma_f32_16x16x32_bf16 v[72:75], v[142:145], v[204:207], v[72:75]
	v_mfma_f32_16x16x32_bf16 v[64:67], v[156:159], v[204:207], v[64:67]
	v_mfma_f32_16x16x32_bf16 v[120:123], v[152:155], v[184:187], v[120:123]
	v_mfma_f32_16x16x32_bf16 v[112:115], v[160:163], v[184:187], v[112:115]
	v_mfma_f32_16x16x32_bf16 v[104:107], v[152:155], v[192:195], v[104:107]
	v_mfma_f32_16x16x32_bf16 v[96:99], v[160:163], v[192:195], v[96:99]
	v_mfma_f32_16x16x32_bf16 v[88:91], v[152:155], v[200:203], v[88:91]
	v_mfma_f32_16x16x32_bf16 v[80:83], v[160:163], v[200:203], v[80:83]
	v_mfma_f32_16x16x32_bf16 v[72:75], v[152:155], v[208:211], v[72:75]
	v_mfma_f32_16x16x32_bf16 v[64:67], v[160:163], v[208:211], v[64:67]
	v_mfma_f32_16x16x32_bf16 v[124:127], v[164:167], v[180:183], v[124:127]
	v_mfma_f32_16x16x32_bf16 v[116:119], v[172:175], v[180:183], v[116:119]
	v_mfma_f32_16x16x32_bf16 v[108:111], v[164:167], v[188:191], v[108:111]
	v_mfma_f32_16x16x32_bf16 v[100:103], v[172:175], v[188:191], v[100:103]
	v_mfma_f32_16x16x32_bf16 v[92:95], v[164:167], v[196:199], v[92:95]
	v_mfma_f32_16x16x32_bf16 v[84:87], v[172:175], v[196:199], v[84:87]
	v_mfma_f32_16x16x32_bf16 v[76:79], v[164:167], v[204:207], v[76:79]
	v_mfma_f32_16x16x32_bf16 v[68:71], v[172:175], v[204:207], v[68:71]
	v_mfma_f32_16x16x32_bf16 v[124:127], v[168:171], v[184:187], v[124:127]
	v_mfma_f32_16x16x32_bf16 v[116:119], v[176:179], v[184:187], v[116:119]
	v_mfma_f32_16x16x32_bf16 v[108:111], v[168:171], v[192:195], v[108:111]
	v_mfma_f32_16x16x32_bf16 v[100:103], v[176:179], v[192:195], v[100:103]
	v_mfma_f32_16x16x32_bf16 v[92:95], v[168:171], v[200:203], v[92:95]
	v_mfma_f32_16x16x32_bf16 v[84:87], v[176:179], v[200:203], v[84:87]
	v_mfma_f32_16x16x32_bf16 v[76:79], v[168:171], v[208:211], v[76:79]
	s_setprio 2
	s_barrier
; #define PG8_STAGE(bufoff, gbase, voff) do { _Pragma("unroll") for (int _i = 0; _i < 2; ++_i) \
;         __builtin_amdgcn_global_load_lds((const unsigned*)((const char*)(gbase) + (voff)[_i]), (PG8_LAS unsigned*)(lds + (bufoff) + ldsw + _i * 8192), 16, 0, 0); } while (0)
; #define PG8_WAIT_V(n) asm volatile("s_waitcnt vmcnt(" #n ")" ::: "memory")
; #define PG8_WAIT_L(n) asm volatile("s_waitcnt lgkmcnt(" #n ")" ::: "memory")
; #define PG8_BAR __builtin_amdgcn_s_barrier()
; template <class Epi, class Sched, bool ALIGN_EPI = false, bool SP2 = false>
; __device__ __forceinline__ void gemm_phase(PG8_LAS unsigned char* lds, const Gemm g, const Sched& S, const Epi& E, const int wid) {
;     ...
;     for (;;) {
;         const bool has_next = S.next(ui + 1, nxt);
;         const char* nA = has_next ? (const char*)g.A + (size_t)nxt.pm * tstep : cA; const char* nB = has_next ? (const char*)g.Bt + (size_t)nxt.pn * tstep : cB;
;         for (int t = 0; t < nt; t += 2) {
;             const bool last = (t == nt - 2);
;             const char* a1 = cA + (size_t)(t + 1) * kstep;
;             const char* a2 = last ? nA : cA + (size_t)(t + 2) * kstep; const char* b2 = last ? nB : cB + (size_t)(t + 2) * kstep;
;             const char* a3 = a2 + kstep; const char* b3 = b2 + kstep;
;             if (last && has_next) S.a_ready(nxt);
;             if constexpr (SP2) {
;             PG8_LDB(B0, 0, 0); PG8_LDB(B1, 0, 1); PG8_SCHED; PG8_LDA(At, 0, 0); PG8_STAGE(PG8_SA(1, 1), a1 + hstep, voffA);
;             PG8_WAIT_V(8); PG8_WAIT_L(0); PG8_BAR; PG8_MMA(0, 0, At, B0); PG8_MMA(0, 1, At, B1); PG8_BAR; PG8_SCHED;
;             PG8_LDA(At, 0, 1); PG8_STAGE(PG8_SB(0, 0), b2, voffB); PG8_STAGE(PG8_SB(0, 1), b2 + hstep, voffB); PG8_STAGE(PG8_SA(0, 0), a2, voffA);
;             PG8_WAIT_V(8); PG8_WAIT_L(0); PG8_BAR; PG8_MMA(1, 0, At, B0); PG8_MMA(1, 1, At, B1); PG8_BAR; PG8_SCHED;
;             PG8_LDB(B0, 1, 0); PG8_LDB(B1, 1, 1); PG8_SCHED; PG8_LDA(At, 1, 0); PG8_STAGE(PG8_SA(0, 1), a2 + hstep, voffA);
;             PG8_WAIT_V(8); PG8_WAIT_L(0); PG8_BAR; PG8_MMA(0, 0, At, B0); PG8_MMA(0, 1, At, B1); PG8_BAR; PG8_SCHED;
;             PG8_LDA(At, 1, 1); PG8_STAGE(PG8_SB(1, 0), b3, voffB); PG8_STAGE(PG8_SB(1, 1), b3 + hstep, voffB); PG8_STAGE(PG8_SA(1, 0), a3, voffA);
;             PG8_WAIT_V(8); PG8_WAIT_L(0); PG8_BAR; PG8_MMA(1, 0, At, B0); PG8_MMA(1, 1, At, B1); PG8_BAR; PG8_SCHED;
	v_mfma_f32_16x16x32_bf16 v[68:71], v[176:179], v[208:211], v[68:71]
	s_setprio 0
	s_add_i32 s6, s9, s36
	v_lshl_add_u64 v[212:213], v[212:213], 0, s[20:21]
	s_mov_b32 m0, s6
	ds_read_b128 v[180:183], v151 offset:49152
	ds_read_b128 v[184:187], v151 offset:50176
	ds_read_b128 v[188:191], v151 offset:51200
	ds_read_b128 v[192:195], v151 offset:52224
	ds_read_b128 v[196:199], v151 offset:53248
	ds_read_b128 v[200:203], v151 offset:54272
	ds_read_b128 v[204:207], v151 offset:55296
	ds_read_b128 v[208:211], v151 offset:56320
	global_load_lds_dwordx4 v[212:213], off
	v_lshl_add_u64 v[212:213], v[214:215], 0, s[20:21]
	s_add_i32 m0, s6, 0x2000
	s_add_i32 s6, s33, s36
	global_load_lds_dwordx4 v[212:213], off
	v_lshl_add_u64 v[212:213], v[216:217], 0, s[20:21]
	s_mov_b32 m0, s6
	s_nop 0
	global_load_lds_dwordx4 v[212:213], off
	v_lshl_add_u64 v[212:213], v[218:219], 0, s[20:21]
	s_add_i32 m0, s6, 0x2000
	s_nop 0
	global_load_lds_dwordx4 v[212:213], off
	v_lshl_add_u64 v[212:213], v[220:221], 0, s[20:21]
	s_mov_b32 m0, s50
	s_nop 0
	global_load_lds_dwordx4 v[212:213], off
	v_lshl_add_u64 v[212:213], v[222:223], 0, s[20:21]
	s_mov_b32 m0, s51
	s_nop 0
	global_load_lds_dwordx4 v[212:213], off
	s_waitcnt vmcnt(8)
	s_waitcnt lgkmcnt(0)
	s_setprio 1
	s_barrier
	v_mfma_f32_16x16x32_bf16 v[56:59], v[142:145], v[180:183], v[56:59]
	v_mfma_f32_16x16x32_bf16 v[48:51], v[156:159], v[180:183], v[48:51]
	v_mfma_f32_16x16x32_bf16 v[40:43], v[142:145], v[188:191], v[40:43]
	v_mfma_f32_16x16x32_bf16 v[32:35], v[156:159], v[188:191], v[32:35]
	v_mfma_f32_16x16x32_bf16 v[24:27], v[142:145], v[196:199], v[24:27]
	v_mfma_f32_16x16x32_bf16 v[16:19], v[156:159], v[196:199], v[16:19]
	v_mfma_f32_16x16x32_bf16 v[8:11], v[142:145], v[204:207], v[8:11]
	v_mfma_f32_16x16x32_bf16 v[4:7], v[156:159], v[204:207], v[4:7]
	v_mfma_f32_16x16x32_bf16 v[56:59], v[152:155], v[184:187], v[56:59]
	v_mfma_f32_16x16x32_bf16 v[48:51], v[160:163], v[184:187], v[48:51]
	v_mfma_f32_16x16x32_bf16 v[40:43], v[152:155], v[192:195], v[40:43]
	v_mfma_f32_16x16x32_bf16 v[32:35], v[160:163], v[192:195], v[32:35]
	v_mfma_f32_16x16x32_bf16 v[24:27], v[152:155], v[200:203], v[24:27]
	v_mfma_f32_16x16x32_bf16 v[16:19], v[160:163], v[200:203], v[16:19]
	v_mfma_f32_16x16x32_bf16 v[8:11], v[152:155], v[208:211], v[8:11]
	v_mfma_f32_16x16x32_bf16 v[4:7], v[160:163], v[208:211], v[4:7]
	v_mfma_f32_16x16x32_bf16 v[60:63], v[164:167], v[180:183], v[60:63]
	v_mfma_f32_16x16x32_bf16 v[52:55], v[172:175], v[180:183], v[52:55]
	v_mfma_f32_16x16x32_bf16 v[44:47], v[164:167], v[188:191], v[44:47]
	v_mfma_f32_16x16x32_bf16 v[36:39], v[172:175], v[188:191], v[36:39]
	v_mfma_f32_16x16x32_bf16 v[28:31], v[164:167], v[196:199], v[28:31]
	v_mfma_f32_16x16x32_bf16 v[20:23], v[172:175], v[196:199], v[20:23]
	v_mfma_f32_16x16x32_bf16 v[12:15], v[164:167], v[204:207], v[12:15]
	v_mfma_f32_16x16x32_bf16 v[0:3], v[172:175], v[204:207], v[0:3]
	v_mfma_f32_16x16x32_bf16 v[60:63], v[168:171], v[184:187], v[60:63]
	v_mfma_f32_16x16x32_bf16 v[52:55], v[176:179], v[184:187], v[52:55]
	v_mfma_f32_16x16x32_bf16 v[44:47], v[168:171], v[192:195], v[44:47]
	v_mfma_f32_16x16x32_bf16 v[36:39], v[176:179], v[192:195], v[36:39]
	v_mfma_f32_16x16x32_bf16 v[28:31], v[168:171], v[200:203], v[28:31]
	v_mfma_f32_16x16x32_bf16 v[20:23], v[176:179], v[200:203], v[20:23]
	v_mfma_f32_16x16x32_bf16 v[12:15], v[168:171], v[208:211], v[12:15]
	s_setprio 2
	s_barrier
	v_mfma_f32_16x16x32_bf16 v[0:3], v[176:179], v[208:211], v[0:3]
	s_setprio 0
	s_add_u32 s4, s4, 0x100
	s_addc_u32 s5, s5, 0
	s_add_u32 s0, s0, 0x100
	s_addc_u32 s1, s1, 0
	s_cmp_ge_i32 s8, s52
	s_mov_b32 s6, s8
	s_cbranch_scc1 .LBB0_1496
.LBB0_1495:
	ds_read_b128 v[142:145], v149
	ds_read_b128 v[152:155], v149 offset:1024
	ds_read_b128 v[156:159], v149 offset:2048
	ds_read_b128 v[160:163], v149 offset:3072
	ds_read_b128 v[164:167], v150
	ds_read_b128 v[168:171], v150 offset:1024
	ds_read_b128 v[172:175], v150 offset:2048
	ds_read_b128 v[176:179], v150 offset:3072
	s_add_i32 s8, s6, 2
	s_add_u32 s9, s4, 0x80
	s_addc_u32 s7, s5, 0
	s_cmp_eq_u32 s55, s6
	s_cselect_b32 s6, s26, s9
	s_cselect_b32 s7, s27, s7
	s_cselect_b32 s65, s29, s1
	s_cselect_b32 s64, s28, s0
	v_lshl_add_u64 v[212:213], s[4:5], 0, v[136:137]
	s_add_i32 m0, s44, 0xc000
	ds_read_b128 v[180:183], v151
	ds_read_b128 v[184:187], v151 offset:1024
	ds_read_b128 v[188:191], v151 offset:2048
	ds_read_b128 v[192:195], v151 offset:3072
	ds_read_b128 v[196:199], v151 offset:4096
	ds_read_b128 v[200:203], v151 offset:5120
	ds_read_b128 v[204:207], v151 offset:6144
	ds_read_b128 v[208:211], v151 offset:7168
	global_load_lds_dwordx4 v[212:213], off
	v_lshl_add_u64 v[212:213], s[4:5], 0, v[138:139]
	s_add_i32 m0, s44, 0xe000
	s_nop 0
	global_load_lds_dwordx4 v[212:213], off
	s_waitcnt vmcnt(8)
	s_waitcnt lgkmcnt(0)
	s_setprio 1
	s_barrier
; #define PG8_STAGE(bufoff, gbase, voff) do { _Pragma("unroll") for (int _i = 0; _i < 2; ++_i) \
;         __builtin_amdgcn_global_load_lds((const unsigned*)((const char*)(gbase) + (voff)[_i]), (PG8_LAS unsigned*)(lds + (bufoff) + ldsw + _i * 8192), 16, 0, 0); } while (0)
; #define PG8_LDA(dst, b, h) do { _Pragma("unroll") for (int m = 0; m < 4; ++m) _Pragma("unroll") for (int k = 0; k < 2; ++k) dst[m][k] = *(const PG8_LAS bf16x8*)(lds + PG8_SA(b, h) + aoff + m * 2048 + k * 1024); } while (0)
; #define PG8_LDB(dst, b, h) do { _Pragma("unroll") for (int n = 0; n < 2; ++n) _Pragma("unroll") for (int k = 0; k < 2; ++k) dst[n][k] = *(const PG8_LAS bf16x8*)(lds + PG8_SB(b, h) + boff + n * 2048 + k * 1024); } while (0)
; #define PG8_MMA(ai, bj, At, Bt) do { __builtin_amdgcn_s_setprio(1); _Pragma("unroll") for (int m = 0; m < 4; ++m) _Pragma("unroll") for (int n = 0; n < 2; ++n) _Pragma("unroll") for (int k = 0; k < 2; ++k) \
;         acc[ai][bj][m][n] = __builtin_amdgcn_mfma_f32_16x16x32_bf16(Bt[n][k], At[m][k], acc[ai][bj][m][n], 0, 0, 0); __builtin_amdgcn_s_setprio(0); } while (0)
; #define PG8_BAR __builtin_amdgcn_s_barrier()
; template <class Epi, class Sched, bool ALIGN_EPI = false, bool SP2 = false>
; __device__ __forceinline__ void gemm_phase(PG8_LAS unsigned char* lds, const Gemm g, const Sched& S, const Epi& E, const int wid) {
;     ...
;             PG8_LDB(B0, 0, 0); PG8_LDB(B1, 0, 1); PG8_SCHED; PG8_LDA(At, 0, 0); PG8_STAGE(PG8_SA(1, 1), a1 + hstep, voffA);
;             PG8_WAIT_V(8); PG8_WAIT_L(0); PG8_BAR; PG8_MMA(0, 0, At, B0); PG8_MMA(0, 1, At, B1); PG8_BAR; PG8_SCHED;
;             PG8_LDA(At, 0, 1); PG8_STAGE(PG8_SB(0, 0), b2, voffB); PG8_STAGE(PG8_SB(0, 1), b2 + hstep, voffB); PG8_STAGE(PG8_SA(0, 0), a2, voffA);
;             PG8_WAIT_V(8); PG8_WAIT_L(0); PG8_BAR; PG8_MMA(1, 0, At, B0); PG8_MMA(1, 1, At, B1); PG8_BAR; PG8_SCHED;
;             PG8_LDB(B0, 1, 0); PG8_LDB(B1, 1, 1); PG8_SCHED; PG8_LDA(At, 1, 0); PG8_STAGE(PG8_SA(0, 1), a2 + hstep, voffA);
;             PG8_WAIT_V(8); PG8_WAIT_L(0); PG8_BAR; PG8_MMA(0, 0, At, B0); PG8_MMA(0, 1, At, B1); PG8_BAR; PG8_SCHED;
;             PG8_LDA(At, 1, 1); PG8_STAGE(PG8_SB(1, 0), b3, voffB); PG8_STAGE(PG8_SB(1, 1), b3 + hstep, voffB); PG8_STAGE(PG8_SA(1, 0), a3, voffA);
;             PG8_WAIT_V(8); PG8_WAIT_L(0); PG8_BAR; PG8_MMA(1, 0, At, B0); PG8_MMA(1, 1, At, B1); PG8_BAR; PG8_SCHED;
	v_mfma_f32_16x16x32_bf16 v[120:123], v[142:145], v[180:183], v[120:123]
	v_mfma_f32_16x16x32_bf16 v[112:115], v[156:159], v[180:183], v[112:115]
	v_mfma_f32_16x16x32_bf16 v[104:107], v[142:145], v[188:191], v[104:107]
	v_mfma_f32_16x16x32_bf16 v[96:99], v[156:159], v[188:191], v[96:99]
	v_mfma_f32_16x16x32_bf16 v[88:91], v[142:145], v[196:199], v[88:91]
	v_mfma_f32_16x16x32_bf16 v[80:83], v[156:159], v[196:199], v[80:83]
	v_mfma_f32_16x16x32_bf16 v[72:75], v[142:145], v[204:207], v[72:75]
	v_mfma_f32_16x16x32_bf16 v[64:67], v[156:159], v[204:207], v[64:67]
	v_mfma_f32_16x16x32_bf16 v[120:123], v[152:155], v[184:187], v[120:123]
	v_mfma_f32_16x16x32_bf16 v[112:115], v[160:163], v[184:187], v[112:115]
	v_mfma_f32_16x16x32_bf16 v[104:107], v[152:155], v[192:195], v[104:107]
	v_mfma_f32_16x16x32_bf16 v[96:99], v[160:163], v[192:195], v[96:99]
	v_mfma_f32_16x16x32_bf16 v[88:91], v[152:155], v[200:203], v[88:91]
	v_mfma_f32_16x16x32_bf16 v[80:83], v[160:163], v[200:203], v[80:83]
	v_mfma_f32_16x16x32_bf16 v[72:75], v[152:155], v[208:211], v[72:75]
	v_mfma_f32_16x16x32_bf16 v[64:67], v[160:163], v[208:211], v[64:67]
	v_mfma_f32_16x16x32_bf16 v[124:127], v[164:167], v[180:183], v[124:127]
	v_mfma_f32_16x16x32_bf16 v[116:119], v[172:175], v[180:183], v[116:119]
	v_mfma_f32_16x16x32_bf16 v[108:111], v[164:167], v[188:191], v[108:111]
	v_mfma_f32_16x16x32_bf16 v[100:103], v[172:175], v[188:191], v[100:103]
	v_mfma_f32_16x16x32_bf16 v[92:95], v[164:167], v[196:199], v[92:95]
	v_mfma_f32_16x16x32_bf16 v[84:87], v[172:175], v[196:199], v[84:87]
	v_mfma_f32_16x16x32_bf16 v[76:79], v[164:167], v[204:207], v[76:79]
	v_mfma_f32_16x16x32_bf16 v[68:71], v[172:175], v[204:207], v[68:71]
	v_mfma_f32_16x16x32_bf16 v[124:127], v[168:171], v[184:187], v[124:127]
	v_mfma_f32_16x16x32_bf16 v[116:119], v[176:179], v[184:187], v[116:119]
	v_mfma_f32_16x16x32_bf16 v[108:111], v[168:171], v[192:195], v[108:111]
	v_mfma_f32_16x16x32_bf16 v[100:103], v[176:179], v[192:195], v[100:103]
	v_mfma_f32_16x16x32_bf16 v[92:95], v[168:171], v[200:203], v[92:95]
	v_mfma_f32_16x16x32_bf16 v[84:87], v[176:179], v[200:203], v[84:87]
	v_mfma_f32_16x16x32_bf16 v[76:79], v[168:171], v[208:211], v[76:79]
	s_setprio 2
	s_barrier
	v_mfma_f32_16x16x32_bf16 v[68:71], v[176:179], v[208:211], v[68:71]
	s_setprio 0
	s_add_i32 s9, s57, s36
	v_lshl_add_u64 v[212:213], s[64:65], 0, v[132:133]
	s_mov_b32 m0, s9
	ds_read_b128 v[180:183], v151 offset:16384
	ds_read_b128 v[184:187], v151 offset:17408
	ds_read_b128 v[188:191], v151 offset:18432
	ds_read_b128 v[192:195], v151 offset:19456
	ds_read_b128 v[196:199], v151 offset:20480
	ds_read_b128 v[200:203], v151 offset:21504
	ds_read_b128 v[204:207], v151 offset:22528
	ds_read_b128 v[208:211], v151 offset:23552
	global_load_lds_dwordx4 v[212:213], off
	s_add_i32 m0, s9, 0x2000
	v_lshl_add_u64 v[214:215], s[64:65], 0, v[128:129]
	s_add_u32 s64, s64, s12
	s_addc_u32 s65, s65, s13
	s_add_i32 s9, s58, s36
	global_load_lds_dwordx4 v[214:215], off
	v_lshl_add_u64 v[216:217], s[64:65], 0, v[132:133]
	s_mov_b32 m0, s9
	v_lshl_add_u64 v[218:219], s[64:65], 0, v[128:129]
	global_load_lds_dwordx4 v[216:217], off
	s_add_i32 m0, s9, 0x2000
	v_lshl_add_u64 v[220:221], s[6:7], 0, v[134:135]
	global_load_lds_dwordx4 v[218:219], off
	s_mov_b32 m0, s44
	v_lshl_add_u64 v[222:223], s[6:7], 0, v[130:131]
	global_load_lds_dwordx4 v[220:221], off
	s_mov_b32 m0, s45
	s_nop 0
	global_load_lds_dwordx4 v[222:223], off
	s_waitcnt vmcnt(8)
	s_waitcnt lgkmcnt(0)
	s_setprio 1
	s_barrier
	v_mfma_f32_16x16x32_bf16 v[56:59], v[142:145], v[180:183], v[56:59]
	v_mfma_f32_16x16x32_bf16 v[48:51], v[156:159], v[180:183], v[48:51]
	v_mfma_f32_16x16x32_bf16 v[40:43], v[142:145], v[188:191], v[40:43]
	v_mfma_f32_16x16x32_bf16 v[32:35], v[156:159], v[188:191], v[32:35]
	v_mfma_f32_16x16x32_bf16 v[24:27], v[142:145], v[196:199], v[24:27]
	v_mfma_f32_16x16x32_bf16 v[16:19], v[156:159], v[196:199], v[16:19]
	v_mfma_f32_16x16x32_bf16 v[8:11], v[142:145], v[204:207], v[8:11]
	v_mfma_f32_16x16x32_bf16 v[4:7], v[156:159], v[204:207], v[4:7]
	v_mfma_f32_16x16x32_bf16 v[56:59], v[152:155], v[184:187], v[56:59]
	v_mfma_f32_16x16x32_bf16 v[48:51], v[160:163], v[184:187], v[48:51]
	v_mfma_f32_16x16x32_bf16 v[40:43], v[152:155], v[192:195], v[40:43]
	v_mfma_f32_16x16x32_bf16 v[32:35], v[160:163], v[192:195], v[32:35]
	v_mfma_f32_16x16x32_bf16 v[24:27], v[152:155], v[200:203], v[24:27]
	v_mfma_f32_16x16x32_bf16 v[16:19], v[160:163], v[200:203], v[16:19]
	v_mfma_f32_16x16x32_bf16 v[8:11], v[152:155], v[208:211], v[8:11]
	v_mfma_f32_16x16x32_bf16 v[4:7], v[160:163], v[208:211], v[4:7]
	v_mfma_f32_16x16x32_bf16 v[60:63], v[164:167], v[180:183], v[60:63]
	v_mfma_f32_16x16x32_bf16 v[52:55], v[172:175], v[180:183], v[52:55]
	v_mfma_f32_16x16x32_bf16 v[44:47], v[164:167], v[188:191], v[44:47]
	v_mfma_f32_16x16x32_bf16 v[36:39], v[172:175], v[188:191], v[36:39]
	v_mfma_f32_16x16x32_bf16 v[28:31], v[164:167], v[196:199], v[28:31]
	v_mfma_f32_16x16x32_bf16 v[20:23], v[172:175], v[196:199], v[20:23]
	v_mfma_f32_16x16x32_bf16 v[12:15], v[164:167], v[204:207], v[12:15]
	v_mfma_f32_16x16x32_bf16 v[0:3], v[172:175], v[204:207], v[0:3]
	v_mfma_f32_16x16x32_bf16 v[60:63], v[168:171], v[184:187], v[60:63]
	v_mfma_f32_16x16x32_bf16 v[52:55], v[176:179], v[184:187], v[52:55]
	v_mfma_f32_16x16x32_bf16 v[44:47], v[168:171], v[192:195], v[44:47]
	v_mfma_f32_16x16x32_bf16 v[36:39], v[176:179], v[192:195], v[36:39]
	v_mfma_f32_16x16x32_bf16 v[28:31], v[168:171], v[200:203], v[28:31]
	v_mfma_f32_16x16x32_bf16 v[20:23], v[176:179], v[200:203], v[20:23]
	v_mfma_f32_16x16x32_bf16 v[12:15], v[168:171], v[208:211], v[12:15]
	s_setprio 2
	s_barrier
; #define PG8_STAGE(bufoff, gbase, voff) do { _Pragma("unroll") for (int _i = 0; _i < 2; ++_i) \
;         __builtin_amdgcn_global_load_lds((const unsigned*)((const char*)(gbase) + (voff)[_i]), (PG8_LAS unsigned*)(lds + (bufoff) + ldsw + _i * 8192), 16, 0, 0); } while (0)
; #define PG8_LDA(dst, b, h) do { _Pragma("unroll") for (int m = 0; m < 4; ++m) _Pragma("unroll") for (int k = 0; k < 2; ++k) dst[m][k] = *(const PG8_LAS bf16x8*)(lds + PG8_SA(b, h) + aoff + m * 2048 + k * 1024); } while (0)
; #define PG8_LDB(dst, b, h) do { _Pragma("unroll") for (int n = 0; n < 2; ++n) _Pragma("unroll") for (int k = 0; k < 2; ++k) dst[n][k] = *(const PG8_LAS bf16x8*)(lds + PG8_SB(b, h) + boff + n * 2048 + k * 1024); } while (0)
; #define PG8_MMA(ai, bj, At, Bt) do { __builtin_amdgcn_s_setprio(1); _Pragma("unroll") for (int m = 0; m < 4; ++m) _Pragma("unroll") for (int n = 0; n < 2; ++n) _Pragma("unroll") for (int k = 0; k < 2; ++k) \
;         acc[ai][bj][m][n] = __builtin_amdgcn_mfma_f32_16x16x32_bf16(Bt[n][k], At[m][k], acc[ai][bj][m][n], 0, 0, 0); __builtin_amdgcn_s_setprio(0); } while (0)
; #define PG8_BAR __builtin_amdgcn_s_barrier()
; template <class Epi, class Sched, bool ALIGN_EPI = false, bool SP2 = false>
; __device__ __forceinline__ void gemm_phase(PG8_LAS unsigned char* lds, const Gemm g, const Sched& S, const Epi& E, const int wid) {
;     ...
;             PG8_LDB(B0, 0, 0); PG8_LDB(B1, 0, 1); PG8_SCHED; PG8_LDA(At, 0, 0); PG8_STAGE(PG8_SA(1, 1), a1 + hstep, voffA);
;             PG8_WAIT_V(8); PG8_WAIT_L(0); PG8_BAR; PG8_MMA(0, 0, At, B0); PG8_MMA(0, 1, At, B1); PG8_BAR; PG8_SCHED;
;             PG8_LDA(At, 0, 1); PG8_STAGE(PG8_SB(0, 0), b2, voffB); PG8_STAGE(PG8_SB(0, 1), b2 + hstep, voffB); PG8_STAGE(PG8_SA(0, 0), a2, voffA);
;             PG8_WAIT_V(8); PG8_WAIT_L(0); PG8_BAR; PG8_MMA(1, 0, At, B0); PG8_MMA(1, 1, At, B1); PG8_BAR; PG8_SCHED;
;             PG8_LDB(B0, 1, 0); PG8_LDB(B1, 1, 1); PG8_SCHED; PG8_LDA(At, 1, 0); PG8_STAGE(PG8_SA(0, 1), a2 + hstep, voffA);
;             PG8_WAIT_V(8); PG8_WAIT_L(0); PG8_BAR; PG8_MMA(0, 0, At, B0); PG8_MMA(0, 1, At, B1); PG8_BAR; PG8_SCHED;
;             PG8_LDA(At, 1, 1); PG8_STAGE(PG8_SB(1, 0), b3, voffB); PG8_STAGE(PG8_SB(1, 1), b3 + hstep, voffB); PG8_STAGE(PG8_SA(1, 0), a3, voffA);
;             PG8_WAIT_V(8); PG8_WAIT_L(0); PG8_BAR; PG8_MMA(1, 0, At, B0); PG8_MMA(1, 1, At, B1); PG8_BAR; PG8_SCHED;
	v_mfma_f32_16x16x32_bf16 v[0:3], v[176:179], v[208:211], v[0:3]
	s_setprio 0
	s_add_i32 s9, 0, 0x18000
	s_add_i32 s33, 0, 0x1c000
	v_add_u32_e32 v160, s9, v148
	v_add_u32_e32 v176, s33, v148
	ds_read_b128 v[142:145], v160
	ds_read_b128 v[152:155], v160 offset:1024
	ds_read_b128 v[156:159], v160 offset:2048
	ds_read_b128 v[160:163], v160 offset:3072
	ds_read_b128 v[164:167], v176
	ds_read_b128 v[168:171], v176 offset:1024
	ds_read_b128 v[172:175], v176 offset:2048
	ds_read_b128 v[176:179], v176 offset:3072
	s_add_u32 s6, s6, s12
	s_addc_u32 s7, s7, s13
	s_mov_b32 m0, s46
	v_lshl_add_u64 v[224:225], s[6:7], 0, v[134:135]
	ds_read_b128 v[180:183], v151 offset:32768
	ds_read_b128 v[184:187], v151 offset:33792
	ds_read_b128 v[188:191], v151 offset:34816
	ds_read_b128 v[192:195], v151 offset:35840
	ds_read_b128 v[196:199], v151 offset:36864
	ds_read_b128 v[200:203], v151 offset:37888
	ds_read_b128 v[204:207], v151 offset:38912
	ds_read_b128 v[208:211], v151 offset:39936
	global_load_lds_dwordx4 v[224:225], off
	v_lshl_add_u64 v[224:225], s[6:7], 0, v[130:131]
	s_mov_b32 m0, s47
	s_nop 0
	global_load_lds_dwordx4 v[224:225], off
	s_waitcnt vmcnt(8)
	s_waitcnt lgkmcnt(0)
	s_setprio 1
	s_barrier
	v_mfma_f32_16x16x32_bf16 v[120:123], v[142:145], v[180:183], v[120:123]
	v_mfma_f32_16x16x32_bf16 v[112:115], v[156:159], v[180:183], v[112:115]
	v_mfma_f32_16x16x32_bf16 v[104:107], v[142:145], v[188:191], v[104:107]
	v_mfma_f32_16x16x32_bf16 v[96:99], v[156:159], v[188:191], v[96:99]
	v_mfma_f32_16x16x32_bf16 v[88:91], v[142:145], v[196:199], v[88:91]
	v_mfma_f32_16x16x32_bf16 v[80:83], v[156:159], v[196:199], v[80:83]
	v_mfma_f32_16x16x32_bf16 v[72:75], v[142:145], v[204:207], v[72:75]
	v_mfma_f32_16x16x32_bf16 v[64:67], v[156:159], v[204:207], v[64:67]
	v_mfma_f32_16x16x32_bf16 v[120:123], v[152:155], v[184:187], v[120:123]
	v_mfma_f32_16x16x32_bf16 v[112:115], v[160:163], v[184:187], v[112:115]
	v_mfma_f32_16x16x32_bf16 v[104:107], v[152:155], v[192:195], v[104:107]
	v_mfma_f32_16x16x32_bf16 v[96:99], v[160:163], v[192:195], v[96:99]
	v_mfma_f32_16x16x32_bf16 v[88:91], v[152:155], v[200:203], v[88:91]
	v_mfma_f32_16x16x32_bf16 v[80:83], v[160:163], v[200:203], v[80:83]
	v_mfma_f32_16x16x32_bf16 v[72:75], v[152:155], v[208:211], v[72:75]
	v_mfma_f32_16x16x32_bf16 v[64:67], v[160:163], v[208:211], v[64:67]
	v_mfma_f32_16x16x32_bf16 v[124:127], v[164:167], v[180:183], v[124:127]
	v_mfma_f32_16x16x32_bf16 v[116:119], v[172:175], v[180:183], v[116:119]
	v_mfma_f32_16x16x32_bf16 v[108:111], v[164:167], v[188:191], v[108:111]
	v_mfma_f32_16x16x32_bf16 v[100:103], v[172:175], v[188:191], v[100:103]
	v_mfma_f32_16x16x32_bf16 v[92:95], v[164:167], v[196:199], v[92:95]
	v_mfma_f32_16x16x32_bf16 v[84:87], v[172:175], v[196:199], v[84:87]
	v_mfma_f32_16x16x32_bf16 v[76:79], v[164:167], v[204:207], v[76:79]
	v_mfma_f32_16x16x32_bf16 v[68:71], v[172:175], v[204:207], v[68:71]
	v_mfma_f32_16x16x32_bf16 v[124:127], v[168:171], v[184:187], v[124:127]
	v_mfma_f32_16x16x32_bf16 v[116:119], v[176:179], v[184:187], v[116:119]
	v_mfma_f32_16x16x32_bf16 v[108:111], v[168:171], v[192:195], v[108:111]
	v_mfma_f32_16x16x32_bf16 v[100:103], v[176:179], v[192:195], v[100:103]
	v_mfma_f32_16x16x32_bf16 v[92:95], v[168:171], v[200:203], v[92:95]
	v_mfma_f32_16x16x32_bf16 v[84:87], v[176:179], v[200:203], v[84:87]
	v_mfma_f32_16x16x32_bf16 v[76:79], v[168:171], v[208:211], v[76:79]
	s_setprio 2
	s_barrier
; #define PG8_STAGE(bufoff, gbase, voff) do { _Pragma("unroll") for (int _i = 0; _i < 2; ++_i) \
;         __builtin_amdgcn_global_load_lds((const unsigned*)((const char*)(gbase) + (voff)[_i]), (PG8_LAS unsigned*)(lds + (bufoff) + ldsw + _i * 8192), 16, 0, 0); } while (0)
; #define PG8_LDA(dst, b, h) do { _Pragma("unroll") for (int m = 0; m < 4; ++m) _Pragma("unroll") for (int k = 0; k < 2; ++k) dst[m][k] = *(const PG8_LAS bf16x8*)(lds + PG8_SA(b, h) + aoff + m * 2048 + k * 1024); } while (0)
; #define PG8_LDB(dst, b, h) do { _Pragma("unroll") for (int n = 0; n < 2; ++n) _Pragma("unroll") for (int k = 0; k < 2; ++k) dst[n][k] = *(const PG8_LAS bf16x8*)(lds + PG8_SB(b, h) + boff + n * 2048 + k * 1024); } while (0)
; #define PG8_MMA(ai, bj, At, Bt) do { __builtin_amdgcn_s_setprio(1); _Pragma("unroll") for (int m = 0; m < 4; ++m) _Pragma("unroll") for (int n = 0; n < 2; ++n) _Pragma("unroll") for (int k = 0; k < 2; ++k) \
;         acc[ai][bj][m][n] = __builtin_amdgcn_mfma_f32_16x16x32_bf16(Bt[n][k], At[m][k], acc[ai][bj][m][n], 0, 0, 0); __builtin_amdgcn_s_setprio(0); } while (0)
; #define PG8_BAR __builtin_amdgcn_s_barrier()
; template <class Epi, class Sched, bool ALIGN_EPI = false, bool SP2 = false>
; __device__ __forceinline__ void gemm_phase(PG8_LAS unsigned char* lds, const Gemm g, const Sched& S, const Epi& E, const int wid) {
;     ...
;             PG8_LDB(B0, 0, 0); PG8_LDB(B1, 0, 1); PG8_SCHED; PG8_LDA(At, 0, 0); PG8_STAGE(PG8_SA(1, 1), a1 + hstep, voffA);
;             PG8_WAIT_V(8); PG8_WAIT_L(0); PG8_BAR; PG8_MMA(0, 0, At, B0); PG8_MMA(0, 1, At, B1); PG8_BAR; PG8_SCHED;
;             PG8_LDA(At, 0, 1); PG8_STAGE(PG8_SB(0, 0), b2, voffB); PG8_STAGE(PG8_SB(0, 1), b2 + hstep, voffB); PG8_STAGE(PG8_SA(0, 0), a2, voffA);
;             PG8_WAIT_V(8); PG8_WAIT_L(0); PG8_BAR; PG8_MMA(1, 0, At, B0); PG8_MMA(1, 1, At, B1); PG8_BAR; PG8_SCHED;
;             PG8_LDB(B0, 1, 0); PG8_LDB(B1, 1, 1); PG8_SCHED; PG8_LDA(At, 1, 0); PG8_STAGE(PG8_SA(0, 1), a2 + hstep, voffA);
;             PG8_WAIT_V(8); PG8_WAIT_L(0); PG8_BAR; PG8_MMA(0, 0, At, B0); PG8_MMA(0, 1, At, B1); PG8_BAR; PG8_SCHED;
;             PG8_LDA(At, 1, 1); PG8_STAGE(PG8_SB(1, 0), b3, voffB); PG8_STAGE(PG8_SB(1, 1), b3 + hstep, voffB); PG8_STAGE(PG8_SA(1, 0), a3, voffA);
;             PG8_WAIT_V(8); PG8_WAIT_L(0); PG8_BAR; PG8_MMA(1, 0, At, B0); PG8_MMA(1, 1, At, B1); PG8_BAR; PG8_SCHED;
	v_mfma_f32_16x16x32_bf16 v[68:71], v[176:179], v[208:211], v[68:71]
	s_setprio 0
	s_add_i32 s6, s9, s36
	v_lshl_add_u64 v[212:213], v[212:213], 0, s[20:21]
	s_mov_b32 m0, s6
	ds_read_b128 v[180:183], v151 offset:49152
	ds_read_b128 v[184:187], v151 offset:50176
	ds_read_b128 v[188:191], v151 offset:51200
	ds_read_b128 v[192:195], v151 offset:52224
	ds_read_b128 v[196:199], v151 offset:53248
	ds_read_b128 v[200:203], v151 offset:54272
	ds_read_b128 v[204:207], v151 offset:55296
	ds_read_b128 v[208:211], v151 offset:56320
	global_load_lds_dwordx4 v[212:213], off
	v_lshl_add_u64 v[212:213], v[214:215], 0, s[20:21]
	s_add_i32 m0, s6, 0x2000
	s_add_i32 s6, s33, s36
	global_load_lds_dwordx4 v[212:213], off
	v_lshl_add_u64 v[212:213], v[216:217], 0, s[20:21]
	s_mov_b32 m0, s6
	s_nop 0
	global_load_lds_dwordx4 v[212:213], off
	v_lshl_add_u64 v[212:213], v[218:219], 0, s[20:21]
	s_add_i32 m0, s6, 0x2000
	s_nop 0
	global_load_lds_dwordx4 v[212:213], off
	v_lshl_add_u64 v[212:213], v[220:221], 0, s[20:21]
	s_mov_b32 m0, s50
	s_nop 0
	global_load_lds_dwordx4 v[212:213], off
	v_lshl_add_u64 v[212:213], v[222:223], 0, s[20:21]
	s_mov_b32 m0, s51
	s_nop 0
	global_load_lds_dwordx4 v[212:213], off
	s_waitcnt vmcnt(8)
	s_waitcnt lgkmcnt(0)
	s_setprio 1
	s_barrier
	v_mfma_f32_16x16x32_bf16 v[56:59], v[142:145], v[180:183], v[56:59]
	v_mfma_f32_16x16x32_bf16 v[48:51], v[156:159], v[180:183], v[48:51]
	v_mfma_f32_16x16x32_bf16 v[40:43], v[142:145], v[188:191], v[40:43]
	v_mfma_f32_16x16x32_bf16 v[32:35], v[156:159], v[188:191], v[32:35]
	v_mfma_f32_16x16x32_bf16 v[24:27], v[142:145], v[196:199], v[24:27]
	v_mfma_f32_16x16x32_bf16 v[16:19], v[156:159], v[196:199], v[16:19]
	v_mfma_f32_16x16x32_bf16 v[8:11], v[142:145], v[204:207], v[8:11]
	v_mfma_f32_16x16x32_bf16 v[4:7], v[156:159], v[204:207], v[4:7]
	v_mfma_f32_16x16x32_bf16 v[56:59], v[152:155], v[184:187], v[56:59]
	v_mfma_f32_16x16x32_bf16 v[48:51], v[160:163], v[184:187], v[48:51]
	v_mfma_f32_16x16x32_bf16 v[40:43], v[152:155], v[192:195], v[40:43]
	v_mfma_f32_16x16x32_bf16 v[32:35], v[160:163], v[192:195], v[32:35]
	v_mfma_f32_16x16x32_bf16 v[24:27], v[152:155], v[200:203], v[24:27]
	v_mfma_f32_16x16x32_bf16 v[16:19], v[160:163], v[200:203], v[16:19]
	v_mfma_f32_16x16x32_bf16 v[8:11], v[152:155], v[208:211], v[8:11]
	v_mfma_f32_16x16x32_bf16 v[4:7], v[160:163], v[208:211], v[4:7]
	v_mfma_f32_16x16x32_bf16 v[60:63], v[164:167], v[180:183], v[60:63]
	v_mfma_f32_16x16x32_bf16 v[52:55], v[172:175], v[180:183], v[52:55]
	v_mfma_f32_16x16x32_bf16 v[44:47], v[164:167], v[188:191], v[44:47]
	v_mfma_f32_16x16x32_bf16 v[36:39], v[172:175], v[188:191], v[36:39]
	v_mfma_f32_16x16x32_bf16 v[28:31], v[164:167], v[196:199], v[28:31]
	v_mfma_f32_16x16x32_bf16 v[20:23], v[172:175], v[196:199], v[20:23]
	v_mfma_f32_16x16x32_bf16 v[12:15], v[164:167], v[204:207], v[12:15]
	v_mfma_f32_16x16x32_bf16 v[0:3], v[172:175], v[204:207], v[0:3]
	v_mfma_f32_16x16x32_bf16 v[60:63], v[168:171], v[184:187], v[60:63]
	v_mfma_f32_16x16x32_bf16 v[52:55], v[176:179], v[184:187], v[52:55]
	v_mfma_f32_16x16x32_bf16 v[44:47], v[168:171], v[192:195], v[44:47]
	v_mfma_f32_16x16x32_bf16 v[36:39], v[176:179], v[192:195], v[36:39]
	v_mfma_f32_16x16x32_bf16 v[28:31], v[168:171], v[200:203], v[28:31]
	v_mfma_f32_16x16x32_bf16 v[20:23], v[176:179], v[200:203], v[20:23]
	v_mfma_f32_16x16x32_bf16 v[12:15], v[168:171], v[208:211], v[12:15]
	s_setprio 2
	s_barrier
	v_mfma_f32_16x16x32_bf16 v[0:3], v[176:179], v[208:211], v[0:3]
	s_setprio 0
	s_add_u32 s4, s4, 0x100
	s_addc_u32 s5, s5, 0
	s_add_u32 s0, s0, 0x100
	s_addc_u32 s1, s1, 0
	s_cmp_ge_i32 s8, s52
	s_mov_b32 s6, s8
	s_cbranch_scc0 .LBB0_1495

; #define PG8_WAIT_V(n) asm volatile("s_waitcnt vmcnt(" #n ")" ::: "memory")
; #define PG8_WAIT_L(n) asm volatile("s_waitcnt lgkmcnt(" #n ")" ::: "memory")
; #define PG8_BAR __builtin_amdgcn_s_barrier()
; template <class Epi, class Sched, bool ALIGN_EPI = false, bool SP2 = false>
; __device__ __forceinline__ void gemm_phase(PG8_LAS unsigned char* lds, const Gemm g, const Sched& S, const Epi& E, const int wid) {
;     ...
;     for (;;) {
;         const bool has_next = S.next(ui + 1, nxt);
;         const char* nA = has_next ? (const char*)g.A + (size_t)nxt.pm * tstep : cA; const char* nB = has_next ? (const char*)g.Bt + (size_t)nxt.pn * tstep : cB;
;         for (int t = 0; t < nt; t += 2) {
;             const bool last = (t == nt - 2);
;             const char* a1 = cA + (size_t)(t + 1) * kstep;
;             const char* a2 = last ? nA : cA + (size_t)(t + 2) * kstep; const char* b2 = last ? nB : cB + (size_t)(t + 2) * kstep;
;             const char* a3 = a2 + kstep; const char* b3 = b2 + kstep;
;             if (last && has_next) S.a_ready(nxt);
;             if constexpr (SP2) {
;             PG8_LDB(B0, 0, 0); PG8_LDB(B1, 0, 1); PG8_SCHED; PG8_LDA(At, 0, 0); PG8_STAGE(PG8_SA(1, 1), a1 + hstep, voffA);
;             PG8_WAIT_V(8); PG8_WAIT_L(0); PG8_BAR; PG8_MMA(0, 0, At, B0); PG8_MMA(0, 1, At, B1); PG8_BAR; PG8_SCHED;
;             PG8_LDA(At, 0, 1); PG8_STAGE(PG8_SB(0, 0), b2, voffB); PG8_STAGE(PG8_SB(0, 1), b2 + hstep, voffB); PG8_STAGE(PG8_SA(0, 0), a2, voffA);
;             PG8_WAIT_V(8); PG8_WAIT_L(0); PG8_BAR; PG8_MMA(1, 0, At, B0); PG8_MMA(1, 1, At, B1); PG8_BAR; PG8_SCHED;
;             PG8_LDB(B0, 1, 0); PG8_LDB(B1, 1, 1); PG8_SCHED; PG8_LDA(At, 1, 0); PG8_STAGE(PG8_SA(0, 1), a2 + hstep, voffA);
;             PG8_WAIT_V(8); PG8_WAIT_L(0); PG8_BAR; PG8_MMA(0, 0, At, B0); PG8_MMA(0, 1, At, B1); PG8_BAR; PG8_SCHED;
;             PG8_LDA(At, 1, 1); PG8_STAGE(PG8_SB(1, 0), b3, voffB); PG8_STAGE(PG8_SB(1, 1), b3 + hstep, voffB); PG8_STAGE(PG8_SA(1, 0), a3, voffA);
;             PG8_WAIT_V(8); PG8_WAIT_L(0); PG8_BAR; PG8_MMA(1, 0, At, B0); PG8_MMA(1, 1, At, B1); PG8_BAR; PG8_SCHED;
;     ...
;         for (int a = 0; a < 2; ++a)
; #pragma unroll
;             for (int b = 0; b < 2; ++b)
; #pragma unroll
;                 for (int m = 0; m < 4; ++m)
; #pragma unroll
;                     for (int n = 0; n < 2; ++n) acc[a][b][m][n] = (f32x4){0.f, 0.f, 0.f, 0.f};
.LBB0_1572:
	s_andn2_b64 vcc, exec, s[18:19]
	s_cbranch_vccnz .Lz_FFN2
	s_add_u32 s40, s40, 0x80
	s_addc_u32 s41, s41, 0
	s_add_u32 s73, s42, 0x100
	s_addc_u32 s74, s43, 0
	s_mov_b32 s42, 0
	ds_read_b128 v[146:149], v143
	ds_read_b128 v[150:153], v143 offset:1024
	ds_read_b128 v[154:157], v143 offset:2048
	ds_read_b128 v[158:161], v143 offset:3072
	ds_read_b128 v[162:165], v144
	ds_read_b128 v[166:169], v144 offset:1024
	ds_read_b128 v[170:173], v144 offset:2048
	ds_read_b128 v[174:177], v144 offset:3072
	s_add_i32 s75, s42, 2
	s_add_u32 s33, s40, 0x80
	s_addc_u32 s43, s41, 0
	s_cmp_eq_u32 s65, s42
	s_cselect_b32 s42, s2, s33
	s_cselect_b32 s43, s3, s43
	s_cselect_b32 s77, s39, s74
	s_cselect_b32 s76, s38, s73
	v_lshl_add_u64 v[138:139], s[40:41], 0, v[132:133]
	s_add_i32 m0, s55, 0xc000
	ds_read_b128 v[178:181], v145
	ds_read_b128 v[182:185], v145 offset:1024
	ds_read_b128 v[186:189], v145 offset:2048
	ds_read_b128 v[190:193], v145 offset:3072
	ds_read_b128 v[194:197], v145 offset:4096
	ds_read_b128 v[198:201], v145 offset:5120
	ds_read_b128 v[202:205], v145 offset:6144
	ds_read_b128 v[206:209], v145 offset:7168
	global_load_lds_dwordx4 v[138:139], off
	v_lshl_add_u64 v[138:139], s[40:41], 0, v[134:135]
	s_add_i32 m0, s55, 0xe000
	s_nop 0
	global_load_lds_dwordx4 v[138:139], off
	s_waitcnt vmcnt(8)
	s_waitcnt lgkmcnt(0)
	s_setprio 1
	s_barrier
	v_mfma_f32_16x16x32_bf16 v[124:127], v[146:149], v[178:181], 0
	v_mfma_f32_16x16x32_bf16 v[120:123], v[154:157], v[178:181], 0
	v_mfma_f32_16x16x32_bf16 v[108:111], v[146:149], v[186:189], 0
	v_mfma_f32_16x16x32_bf16 v[104:107], v[154:157], v[186:189], 0
	v_mfma_f32_16x16x32_bf16 v[92:95], v[146:149], v[194:197], 0
	v_mfma_f32_16x16x32_bf16 v[88:91], v[154:157], v[194:197], 0
	v_mfma_f32_16x16x32_bf16 v[76:79], v[146:149], v[202:205], 0
	v_mfma_f32_16x16x32_bf16 v[72:75], v[154:157], v[202:205], 0
	v_mfma_f32_16x16x32_bf16 v[124:127], v[150:153], v[182:185], v[124:127]
	v_mfma_f32_16x16x32_bf16 v[120:123], v[158:161], v[182:185], v[120:123]
	v_mfma_f32_16x16x32_bf16 v[108:111], v[150:153], v[190:193], v[108:111]
	v_mfma_f32_16x16x32_bf16 v[104:107], v[158:161], v[190:193], v[104:107]
	v_mfma_f32_16x16x32_bf16 v[92:95], v[150:153], v[198:201], v[92:95]
	v_mfma_f32_16x16x32_bf16 v[88:91], v[158:161], v[198:201], v[88:91]
	v_mfma_f32_16x16x32_bf16 v[76:79], v[150:153], v[206:209], v[76:79]
	v_mfma_f32_16x16x32_bf16 v[72:75], v[158:161], v[206:209], v[72:75]
	v_mfma_f32_16x16x32_bf16 v[116:119], v[162:165], v[178:181], 0
	v_mfma_f32_16x16x32_bf16 v[112:115], v[170:173], v[178:181], 0
	v_mfma_f32_16x16x32_bf16 v[100:103], v[162:165], v[186:189], 0
	v_mfma_f32_16x16x32_bf16 v[96:99], v[170:173], v[186:189], 0
	v_mfma_f32_16x16x32_bf16 v[84:87], v[162:165], v[194:197], 0
	v_mfma_f32_16x16x32_bf16 v[80:83], v[170:173], v[194:197], 0
	v_mfma_f32_16x16x32_bf16 v[68:71], v[162:165], v[202:205], 0
	v_mfma_f32_16x16x32_bf16 v[64:67], v[170:173], v[202:205], 0
	v_mfma_f32_16x16x32_bf16 v[116:119], v[166:169], v[182:185], v[116:119]
	v_mfma_f32_16x16x32_bf16 v[112:115], v[174:177], v[182:185], v[112:115]
	v_mfma_f32_16x16x32_bf16 v[100:103], v[166:169], v[190:193], v[100:103]
	v_mfma_f32_16x16x32_bf16 v[96:99], v[174:177], v[190:193], v[96:99]
	v_mfma_f32_16x16x32_bf16 v[84:87], v[166:169], v[198:201], v[84:87]
	v_mfma_f32_16x16x32_bf16 v[80:83], v[174:177], v[198:201], v[80:83]
	v_mfma_f32_16x16x32_bf16 v[68:71], v[166:169], v[206:209], v[68:71]
	s_setprio 2
	s_barrier
	v_mfma_f32_16x16x32_bf16 v[64:67], v[174:177], v[206:209], v[64:67]
	s_setprio 0
	s_add_i32 s33, s67, s47
	v_lshl_add_u64 v[138:139], s[76:77], 0, v[130:131]
	s_mov_b32 m0, s33
	ds_read_b128 v[178:181], v145 offset:16384
	ds_read_b128 v[182:185], v145 offset:17408
	ds_read_b128 v[186:189], v145 offset:18432
	ds_read_b128 v[190:193], v145 offset:19456
	ds_read_b128 v[194:197], v145 offset:20480
	ds_read_b128 v[198:201], v145 offset:21504
	ds_read_b128 v[202:205], v145 offset:22528
	ds_read_b128 v[206:209], v145 offset:23552
	global_load_lds_dwordx4 v[138:139], off
	s_add_i32 m0, s33, 0x2000
	v_lshl_add_u64 v[210:211], s[76:77], 0, v[128:129]
	s_add_u32 s76, s76, s8
	s_addc_u32 s77, s77, s9
	s_add_i32 s33, s68, s47
	global_load_lds_dwordx4 v[210:211], off
	v_lshl_add_u64 v[212:213], s[76:77], 0, v[130:131]
	s_mov_b32 m0, s33
	v_lshl_add_u64 v[214:215], s[76:77], 0, v[128:129]
	global_load_lds_dwordx4 v[212:213], off
	s_add_i32 m0, s33, 0x2000
	v_lshl_add_u64 v[216:217], s[42:43], 0, v[130:131]
	global_load_lds_dwordx4 v[214:215], off
	s_mov_b32 m0, s55
	v_lshl_add_u64 v[218:219], s[42:43], 0, v[128:129]
	global_load_lds_dwordx4 v[216:217], off
	s_mov_b32 m0, s56
	s_nop 0
	global_load_lds_dwordx4 v[218:219], off
	s_waitcnt vmcnt(8)
	s_waitcnt lgkmcnt(0)
	s_setprio 1
	s_barrier
; #define PG8_STAGE(bufoff, gbase, voff) do { _Pragma("unroll") for (int _i = 0; _i < 2; ++_i) \
;         __builtin_amdgcn_global_load_lds((const unsigned*)((const char*)(gbase) + (voff)[_i]), (PG8_LAS unsigned*)(lds + (bufoff) + ldsw + _i * 8192), 16, 0, 0); } while (0)
; #define PG8_LDA(dst, b, h) do { _Pragma("unroll") for (int m = 0; m < 4; ++m) _Pragma("unroll") for (int k = 0; k < 2; ++k) dst[m][k] = *(const PG8_LAS bf16x8*)(lds + PG8_SA(b, h) + aoff + m * 2048 + k * 1024); } while (0)
; #define PG8_LDB(dst, b, h) do { _Pragma("unroll") for (int n = 0; n < 2; ++n) _Pragma("unroll") for (int k = 0; k < 2; ++k) dst[n][k] = *(const PG8_LAS bf16x8*)(lds + PG8_SB(b, h) + boff + n * 2048 + k * 1024); } while (0)
; #define PG8_MMA(ai, bj, At, Bt) do { __builtin_amdgcn_s_setprio(1); _Pragma("unroll") for (int m = 0; m < 4; ++m) _Pragma("unroll") for (int n = 0; n < 2; ++n) _Pragma("unroll") for (int k = 0; k < 2; ++k) \
;         acc[ai][bj][m][n] = __builtin_amdgcn_mfma_f32_16x16x32_bf16(Bt[n][k], At[m][k], acc[ai][bj][m][n], 0, 0, 0); __builtin_amdgcn_s_setprio(0); } while (0)
; #define PG8_WAIT_V(n) asm volatile("s_waitcnt vmcnt(" #n ")" ::: "memory")
; #define PG8_WAIT_L(n) asm volatile("s_waitcnt lgkmcnt(" #n ")" ::: "memory")
; #define PG8_BAR __builtin_amdgcn_s_barrier()
; #define PG8_SCHED __builtin_amdgcn_sched_barrier(0)
; template <class Epi, class Sched, bool ALIGN_EPI = false, bool SP2 = false>
; __device__ __forceinline__ void gemm_phase(PG8_LAS unsigned char* lds, const Gemm g, const Sched& S, const Epi& E, const int wid) {
;     ...
;             PG8_WAIT_V(8); PG8_WAIT_L(0); PG8_BAR; PG8_MMA(0, 0, At, B0); PG8_MMA(0, 1, At, B1); PG8_BAR; PG8_SCHED;
;             PG8_LDA(At, 0, 1); PG8_STAGE(PG8_SB(0, 0), b2, voffB); PG8_STAGE(PG8_SB(0, 1), b2 + hstep, voffB); PG8_STAGE(PG8_SA(0, 0), a2, voffA);
;             PG8_WAIT_V(8); PG8_WAIT_L(0); PG8_BAR; PG8_MMA(1, 0, At, B0); PG8_MMA(1, 1, At, B1); PG8_BAR; PG8_SCHED;
;             PG8_LDB(B0, 1, 0); PG8_LDB(B1, 1, 1); PG8_SCHED; PG8_LDA(At, 1, 0); PG8_STAGE(PG8_SA(0, 1), a2 + hstep, voffA);
;             PG8_WAIT_V(8); PG8_WAIT_L(0); PG8_BAR; PG8_MMA(0, 0, At, B0); PG8_MMA(0, 1, At, B1); PG8_BAR; PG8_SCHED;
	v_mfma_f32_16x16x32_bf16 v[60:63], v[146:149], v[178:181], 0
	v_mfma_f32_16x16x32_bf16 v[56:59], v[154:157], v[178:181], 0
	v_mfma_f32_16x16x32_bf16 v[44:47], v[146:149], v[186:189], 0
	v_mfma_f32_16x16x32_bf16 v[40:43], v[154:157], v[186:189], 0
	v_mfma_f32_16x16x32_bf16 v[28:31], v[146:149], v[194:197], 0
	v_mfma_f32_16x16x32_bf16 v[24:27], v[154:157], v[194:197], 0
	v_mfma_f32_16x16x32_bf16 v[12:15], v[146:149], v[202:205], 0
	v_mfma_f32_16x16x32_bf16 v[8:11], v[154:157], v[202:205], 0
	v_mfma_f32_16x16x32_bf16 v[60:63], v[150:153], v[182:185], v[60:63]
	v_mfma_f32_16x16x32_bf16 v[56:59], v[158:161], v[182:185], v[56:59]
	v_mfma_f32_16x16x32_bf16 v[44:47], v[150:153], v[190:193], v[44:47]
	v_mfma_f32_16x16x32_bf16 v[40:43], v[158:161], v[190:193], v[40:43]
	v_mfma_f32_16x16x32_bf16 v[28:31], v[150:153], v[198:201], v[28:31]
	v_mfma_f32_16x16x32_bf16 v[24:27], v[158:161], v[198:201], v[24:27]
	v_mfma_f32_16x16x32_bf16 v[12:15], v[150:153], v[206:209], v[12:15]
	v_mfma_f32_16x16x32_bf16 v[8:11], v[158:161], v[206:209], v[8:11]
	v_mfma_f32_16x16x32_bf16 v[52:55], v[162:165], v[178:181], 0
	v_mfma_f32_16x16x32_bf16 v[48:51], v[170:173], v[178:181], 0
	v_mfma_f32_16x16x32_bf16 v[36:39], v[162:165], v[186:189], 0
	v_mfma_f32_16x16x32_bf16 v[32:35], v[170:173], v[186:189], 0
	v_mfma_f32_16x16x32_bf16 v[20:23], v[162:165], v[194:197], 0
	v_mfma_f32_16x16x32_bf16 v[16:19], v[170:173], v[194:197], 0
	v_mfma_f32_16x16x32_bf16 v[4:7], v[162:165], v[202:205], 0
	v_mfma_f32_16x16x32_bf16 v[0:3], v[170:173], v[202:205], 0
	v_mfma_f32_16x16x32_bf16 v[52:55], v[166:169], v[182:185], v[52:55]
	v_mfma_f32_16x16x32_bf16 v[48:51], v[174:177], v[182:185], v[48:51]
	v_mfma_f32_16x16x32_bf16 v[36:39], v[166:169], v[190:193], v[36:39]
	v_mfma_f32_16x16x32_bf16 v[32:35], v[174:177], v[190:193], v[32:35]
	v_mfma_f32_16x16x32_bf16 v[20:23], v[166:169], v[198:201], v[20:23]
	v_mfma_f32_16x16x32_bf16 v[16:19], v[174:177], v[198:201], v[16:19]
	v_mfma_f32_16x16x32_bf16 v[4:7], v[166:169], v[206:209], v[4:7]
	s_setprio 2
	s_barrier
	v_mfma_f32_16x16x32_bf16 v[0:3], v[174:177], v[206:209], v[0:3]
	s_setprio 0
	s_add_i32 s33, 0, 0x18000
	s_add_i32 s76, 0, 0x1c000
	v_add_u32_e32 v158, s33, v142
	v_add_u32_e32 v174, s76, v142
	ds_read_b128 v[146:149], v158
	ds_read_b128 v[150:153], v158 offset:1024
	ds_read_b128 v[154:157], v158 offset:2048
	ds_read_b128 v[158:161], v158 offset:3072
	ds_read_b128 v[162:165], v174
	ds_read_b128 v[166:169], v174 offset:1024
	ds_read_b128 v[170:173], v174 offset:2048
	ds_read_b128 v[174:177], v174 offset:3072
	s_add_u32 s42, s42, s8
	s_addc_u32 s43, s43, s9
	s_mov_b32 m0, s57
	v_lshl_add_u64 v[220:221], s[42:43], 0, v[130:131]
	ds_read_b128 v[178:181], v145 offset:32768
	ds_read_b128 v[182:185], v145 offset:33792
	ds_read_b128 v[186:189], v145 offset:34816
	ds_read_b128 v[190:193], v145 offset:35840
	ds_read_b128 v[194:197], v145 offset:36864
	ds_read_b128 v[198:201], v145 offset:37888
	ds_read_b128 v[202:205], v145 offset:38912
	ds_read_b128 v[206:209], v145 offset:39936
	global_load_lds_dwordx4 v[220:221], off
	v_lshl_add_u64 v[220:221], s[42:43], 0, v[128:129]
	s_mov_b32 m0, s58
	s_nop 0
	global_load_lds_dwordx4 v[220:221], off
	s_waitcnt vmcnt(8)
	s_waitcnt lgkmcnt(0)
	s_setprio 1
	s_barrier
	v_mfma_f32_16x16x32_bf16 v[124:127], v[146:149], v[178:181], v[124:127]
	v_mfma_f32_16x16x32_bf16 v[120:123], v[154:157], v[178:181], v[120:123]
	v_mfma_f32_16x16x32_bf16 v[108:111], v[146:149], v[186:189], v[108:111]
	v_mfma_f32_16x16x32_bf16 v[104:107], v[154:157], v[186:189], v[104:107]
	v_mfma_f32_16x16x32_bf16 v[92:95], v[146:149], v[194:197], v[92:95]
	v_mfma_f32_16x16x32_bf16 v[88:91], v[154:157], v[194:197], v[88:91]
	v_mfma_f32_16x16x32_bf16 v[76:79], v[146:149], v[202:205], v[76:79]
	v_mfma_f32_16x16x32_bf16 v[72:75], v[154:157], v[202:205], v[72:75]
	v_mfma_f32_16x16x32_bf16 v[124:127], v[150:153], v[182:185], v[124:127]
	v_mfma_f32_16x16x32_bf16 v[120:123], v[158:161], v[182:185], v[120:123]
	v_mfma_f32_16x16x32_bf16 v[108:111], v[150:153], v[190:193], v[108:111]
	v_mfma_f32_16x16x32_bf16 v[104:107], v[158:161], v[190:193], v[104:107]
	v_mfma_f32_16x16x32_bf16 v[92:95], v[150:153], v[198:201], v[92:95]
	v_mfma_f32_16x16x32_bf16 v[88:91], v[158:161], v[198:201], v[88:91]
	v_mfma_f32_16x16x32_bf16 v[76:79], v[150:153], v[206:209], v[76:79]
	v_mfma_f32_16x16x32_bf16 v[72:75], v[158:161], v[206:209], v[72:75]
	v_mfma_f32_16x16x32_bf16 v[116:119], v[162:165], v[178:181], v[116:119]
	v_mfma_f32_16x16x32_bf16 v[112:115], v[170:173], v[178:181], v[112:115]
	v_mfma_f32_16x16x32_bf16 v[100:103], v[162:165], v[186:189], v[100:103]
	v_mfma_f32_16x16x32_bf16 v[96:99], v[170:173], v[186:189], v[96:99]
	v_mfma_f32_16x16x32_bf16 v[84:87], v[162:165], v[194:197], v[84:87]
	v_mfma_f32_16x16x32_bf16 v[80:83], v[170:173], v[194:197], v[80:83]
	v_mfma_f32_16x16x32_bf16 v[68:71], v[162:165], v[202:205], v[68:71]
	v_mfma_f32_16x16x32_bf16 v[64:67], v[170:173], v[202:205], v[64:67]
	v_mfma_f32_16x16x32_bf16 v[116:119], v[166:169], v[182:185], v[116:119]
	v_mfma_f32_16x16x32_bf16 v[112:115], v[174:177], v[182:185], v[112:115]
	v_mfma_f32_16x16x32_bf16 v[100:103], v[166:169], v[190:193], v[100:103]
	v_mfma_f32_16x16x32_bf16 v[96:99], v[174:177], v[190:193], v[96:99]
	v_mfma_f32_16x16x32_bf16 v[84:87], v[166:169], v[198:201], v[84:87]
	v_mfma_f32_16x16x32_bf16 v[80:83], v[174:177], v[198:201], v[80:83]
	v_mfma_f32_16x16x32_bf16 v[68:71], v[166:169], v[206:209], v[68:71]
	s_setprio 2
	s_barrier
; #define PG8_STAGE(bufoff, gbase, voff) do { _Pragma("unroll") for (int _i = 0; _i < 2; ++_i) \
;         __builtin_amdgcn_global_load_lds((const unsigned*)((const char*)(gbase) + (voff)[_i]), (PG8_LAS unsigned*)(lds + (bufoff) + ldsw + _i * 8192), 16, 0, 0); } while (0)
; #define PG8_LDA(dst, b, h) do { _Pragma("unroll") for (int m = 0; m < 4; ++m) _Pragma("unroll") for (int k = 0; k < 2; ++k) dst[m][k] = *(const PG8_LAS bf16x8*)(lds + PG8_SA(b, h) + aoff + m * 2048 + k * 1024); } while (0)
; #define PG8_WAIT_V(n) asm volatile("s_waitcnt vmcnt(" #n ")" ::: "memory")
; #define PG8_WAIT_L(n) asm volatile("s_waitcnt lgkmcnt(" #n ")" ::: "memory")
; #define PG8_BAR __builtin_amdgcn_s_barrier()
; template <class Epi, class Sched, bool ALIGN_EPI = false, bool SP2 = false>
; __device__ __forceinline__ void gemm_phase(PG8_LAS unsigned char* lds, const Gemm g, const Sched& S, const Epi& E, const int wid) {
;     ...
;         for (int t = 0; t < nt; t += 2) {
;             const bool last = (t == nt - 2);
;             const char* a1 = cA + (size_t)(t + 1) * kstep;
;             const char* a2 = last ? nA : cA + (size_t)(t + 2) * kstep; const char* b2 = last ? nB : cB + (size_t)(t + 2) * kstep;
;             const char* a3 = a2 + kstep; const char* b3 = b2 + kstep;
;             if (last && has_next) S.a_ready(nxt);
;             if constexpr (SP2) {
;             PG8_LDB(B0, 0, 0); PG8_LDB(B1, 0, 1); PG8_SCHED; PG8_LDA(At, 0, 0); PG8_STAGE(PG8_SA(1, 1), a1 + hstep, voffA);
;             PG8_WAIT_V(8); PG8_WAIT_L(0); PG8_BAR; PG8_MMA(0, 0, At, B0); PG8_MMA(0, 1, At, B1); PG8_BAR; PG8_SCHED;
;             PG8_LDA(At, 0, 1); PG8_STAGE(PG8_SB(0, 0), b2, voffB); PG8_STAGE(PG8_SB(0, 1), b2 + hstep, voffB); PG8_STAGE(PG8_SA(0, 0), a2, voffA);
;             PG8_WAIT_V(8); PG8_WAIT_L(0); PG8_BAR; PG8_MMA(1, 0, At, B0); PG8_MMA(1, 1, At, B1); PG8_BAR; PG8_SCHED;
;             PG8_LDB(B0, 1, 0); PG8_LDB(B1, 1, 1); PG8_SCHED; PG8_LDA(At, 1, 0); PG8_STAGE(PG8_SA(0, 1), a2 + hstep, voffA);
;             PG8_WAIT_V(8); PG8_WAIT_L(0); PG8_BAR; PG8_MMA(0, 0, At, B0); PG8_MMA(0, 1, At, B1); PG8_BAR; PG8_SCHED;
;             PG8_LDA(At, 1, 1); PG8_STAGE(PG8_SB(1, 0), b3, voffB); PG8_STAGE(PG8_SB(1, 1), b3 + hstep, voffB); PG8_STAGE(PG8_SA(1, 0), a3, voffA);
;             PG8_WAIT_V(8); PG8_WAIT_L(0); PG8_BAR; PG8_MMA(1, 0, At, B0); PG8_MMA(1, 1, At, B1); PG8_BAR; PG8_SCHED;
	v_mfma_f32_16x16x32_bf16 v[64:67], v[174:177], v[206:209], v[64:67]
	s_setprio 0
	s_add_i32 s33, s33, s47
	v_lshl_add_u64 v[138:139], v[138:139], 0, s[16:17]
	s_mov_b32 m0, s33
	ds_read_b128 v[178:181], v145 offset:49152
	ds_read_b128 v[182:185], v145 offset:50176
	ds_read_b128 v[186:189], v145 offset:51200
	ds_read_b128 v[190:193], v145 offset:52224
	ds_read_b128 v[194:197], v145 offset:53248
	ds_read_b128 v[198:201], v145 offset:54272
	ds_read_b128 v[202:205], v145 offset:55296
	ds_read_b128 v[206:209], v145 offset:56320
	global_load_lds_dwordx4 v[138:139], off
	v_lshl_add_u64 v[138:139], v[210:211], 0, s[16:17]
	s_add_i32 m0, s33, 0x2000
	s_add_i32 s33, s76, s47
	global_load_lds_dwordx4 v[138:139], off
	v_lshl_add_u64 v[138:139], v[212:213], 0, s[16:17]
	s_mov_b32 m0, s33
	s_nop 0
	global_load_lds_dwordx4 v[138:139], off
	v_lshl_add_u64 v[138:139], v[214:215], 0, s[16:17]
	s_add_i32 m0, s33, 0x2000
	s_nop 0
	global_load_lds_dwordx4 v[138:139], off
	v_lshl_add_u64 v[138:139], v[216:217], 0, s[16:17]
	s_mov_b32 m0, s60
	s_nop 0
	global_load_lds_dwordx4 v[138:139], off
	v_lshl_add_u64 v[138:139], v[218:219], 0, s[16:17]
	s_mov_b32 m0, s61
	s_nop 0
	global_load_lds_dwordx4 v[138:139], off
	s_waitcnt vmcnt(8)
	s_waitcnt lgkmcnt(0)
	s_setprio 1
	s_barrier
	v_mfma_f32_16x16x32_bf16 v[60:63], v[146:149], v[178:181], v[60:63]
	v_mfma_f32_16x16x32_bf16 v[56:59], v[154:157], v[178:181], v[56:59]
	v_mfma_f32_16x16x32_bf16 v[44:47], v[146:149], v[186:189], v[44:47]
	v_mfma_f32_16x16x32_bf16 v[40:43], v[154:157], v[186:189], v[40:43]
	v_mfma_f32_16x16x32_bf16 v[28:31], v[146:149], v[194:197], v[28:31]
	v_mfma_f32_16x16x32_bf16 v[24:27], v[154:157], v[194:197], v[24:27]
	v_mfma_f32_16x16x32_bf16 v[12:15], v[146:149], v[202:205], v[12:15]
	v_mfma_f32_16x16x32_bf16 v[8:11], v[154:157], v[202:205], v[8:11]
	v_mfma_f32_16x16x32_bf16 v[60:63], v[150:153], v[182:185], v[60:63]
	v_mfma_f32_16x16x32_bf16 v[56:59], v[158:161], v[182:185], v[56:59]
	v_mfma_f32_16x16x32_bf16 v[44:47], v[150:153], v[190:193], v[44:47]
	v_mfma_f32_16x16x32_bf16 v[40:43], v[158:161], v[190:193], v[40:43]
	v_mfma_f32_16x16x32_bf16 v[28:31], v[150:153], v[198:201], v[28:31]
	v_mfma_f32_16x16x32_bf16 v[24:27], v[158:161], v[198:201], v[24:27]
	v_mfma_f32_16x16x32_bf16 v[12:15], v[150:153], v[206:209], v[12:15]
	v_mfma_f32_16x16x32_bf16 v[8:11], v[158:161], v[206:209], v[8:11]
	v_mfma_f32_16x16x32_bf16 v[52:55], v[162:165], v[178:181], v[52:55]
	v_mfma_f32_16x16x32_bf16 v[48:51], v[170:173], v[178:181], v[48:51]
	v_mfma_f32_16x16x32_bf16 v[36:39], v[162:165], v[186:189], v[36:39]
	v_mfma_f32_16x16x32_bf16 v[32:35], v[170:173], v[186:189], v[32:35]
	v_mfma_f32_16x16x32_bf16 v[20:23], v[162:165], v[194:197], v[20:23]
	v_mfma_f32_16x16x32_bf16 v[16:19], v[170:173], v[194:197], v[16:19]
	v_mfma_f32_16x16x32_bf16 v[4:7], v[162:165], v[202:205], v[4:7]
	v_mfma_f32_16x16x32_bf16 v[0:3], v[170:173], v[202:205], v[0:3]
	v_mfma_f32_16x16x32_bf16 v[52:55], v[166:169], v[182:185], v[52:55]
	v_mfma_f32_16x16x32_bf16 v[48:51], v[174:177], v[182:185], v[48:51]
	v_mfma_f32_16x16x32_bf16 v[36:39], v[166:169], v[190:193], v[36:39]
	v_mfma_f32_16x16x32_bf16 v[32:35], v[174:177], v[190:193], v[32:35]
	v_mfma_f32_16x16x32_bf16 v[20:23], v[166:169], v[198:201], v[20:23]
	v_mfma_f32_16x16x32_bf16 v[16:19], v[174:177], v[198:201], v[16:19]
	v_mfma_f32_16x16x32_bf16 v[4:7], v[166:169], v[206:209], v[4:7]
	s_setprio 2
	s_barrier
	v_mfma_f32_16x16x32_bf16 v[0:3], v[174:177], v[206:209], v[0:3]
	s_setprio 0
	s_add_u32 s40, s40, 0x100
	s_addc_u32 s41, s41, 0
	s_add_u32 s73, s73, 0x100
	s_addc_u32 s74, s74, 0
	s_cmp_ge_i32 s75, s62
	s_mov_b32 s42, s75
	s_cbranch_scc1 .LBB0_1575
.LBB0_1574:
	ds_read_b128 v[146:149], v143
	ds_read_b128 v[150:153], v143 offset:1024
	ds_read_b128 v[154:157], v143 offset:2048
	ds_read_b128 v[158:161], v143 offset:3072
	ds_read_b128 v[162:165], v144
	ds_read_b128 v[166:169], v144 offset:1024
	ds_read_b128 v[170:173], v144 offset:2048
	ds_read_b128 v[174:177], v144 offset:3072
	s_add_i32 s75, s42, 2
	s_add_u32 s33, s40, 0x80
	s_addc_u32 s43, s41, 0
	s_cmp_eq_u32 s65, s42
	s_cselect_b32 s42, s2, s33
	s_cselect_b32 s43, s3, s43
	s_cselect_b32 s77, s39, s74
	s_cselect_b32 s76, s38, s73
	v_lshl_add_u64 v[138:139], s[40:41], 0, v[132:133]
	s_add_i32 m0, s55, 0xc000
	ds_read_b128 v[178:181], v145
	ds_read_b128 v[182:185], v145 offset:1024
	ds_read_b128 v[186:189], v145 offset:2048
	ds_read_b128 v[190:193], v145 offset:3072
	ds_read_b128 v[194:197], v145 offset:4096
	ds_read_b128 v[198:201], v145 offset:5120
	ds_read_b128 v[202:205], v145 offset:6144
	ds_read_b128 v[206:209], v145 offset:7168
	global_load_lds_dwordx4 v[138:139], off
	v_lshl_add_u64 v[138:139], s[40:41], 0, v[134:135]
	s_add_i32 m0, s55, 0xe000
	s_nop 0
	global_load_lds_dwordx4 v[138:139], off
	s_waitcnt vmcnt(8)
	s_waitcnt lgkmcnt(0)
	s_setprio 1
	s_barrier
; #define PG8_STAGE(bufoff, gbase, voff) do { _Pragma("unroll") for (int _i = 0; _i < 2; ++_i) \
;         __builtin_amdgcn_global_load_lds((const unsigned*)((const char*)(gbase) + (voff)[_i]), (PG8_LAS unsigned*)(lds + (bufoff) + ldsw + _i * 8192), 16, 0, 0); } while (0)
; #define PG8_LDA(dst, b, h) do { _Pragma("unroll") for (int m = 0; m < 4; ++m) _Pragma("unroll") for (int k = 0; k < 2; ++k) dst[m][k] = *(const PG8_LAS bf16x8*)(lds + PG8_SA(b, h) + aoff + m * 2048 + k * 1024); } while (0)
; #define PG8_LDB(dst, b, h) do { _Pragma("unroll") for (int n = 0; n < 2; ++n) _Pragma("unroll") for (int k = 0; k < 2; ++k) dst[n][k] = *(const PG8_LAS bf16x8*)(lds + PG8_SB(b, h) + boff + n * 2048 + k * 1024); } while (0)
; #define PG8_MMA(ai, bj, At, Bt) do { __builtin_amdgcn_s_setprio(1); _Pragma("unroll") for (int m = 0; m < 4; ++m) _Pragma("unroll") for (int n = 0; n < 2; ++n) _Pragma("unroll") for (int k = 0; k < 2; ++k) \
;         acc[ai][bj][m][n] = __builtin_amdgcn_mfma_f32_16x16x32_bf16(Bt[n][k], At[m][k], acc[ai][bj][m][n], 0, 0, 0); __builtin_amdgcn_s_setprio(0); } while (0)
; #define PG8_WAIT_V(n) asm volatile("s_waitcnt vmcnt(" #n ")" ::: "memory")
; #define PG8_WAIT_L(n) asm volatile("s_waitcnt lgkmcnt(" #n ")" ::: "memory")
; #define PG8_BAR __builtin_amdgcn_s_barrier()
; #define PG8_SCHED __builtin_amdgcn_sched_barrier(0)
; template <class Epi, class Sched, bool ALIGN_EPI = false, bool SP2 = false>
; __device__ __forceinline__ void gemm_phase(PG8_LAS unsigned char* lds, const Gemm g, const Sched& S, const Epi& E, const int wid) {
;     ...
;             if constexpr (SP2) {
;             PG8_LDB(B0, 0, 0); PG8_LDB(B1, 0, 1); PG8_SCHED; PG8_LDA(At, 0, 0); PG8_STAGE(PG8_SA(1, 1), a1 + hstep, voffA);
;             PG8_WAIT_V(8); PG8_WAIT_L(0); PG8_BAR; PG8_MMA(0, 0, At, B0); PG8_MMA(0, 1, At, B1); PG8_BAR; PG8_SCHED;
;             PG8_LDA(At, 0, 1); PG8_STAGE(PG8_SB(0, 0), b2, voffB); PG8_STAGE(PG8_SB(0, 1), b2 + hstep, voffB); PG8_STAGE(PG8_SA(0, 0), a2, voffA);
;             PG8_WAIT_V(8); PG8_WAIT_L(0); PG8_BAR; PG8_MMA(1, 0, At, B0); PG8_MMA(1, 1, At, B1); PG8_BAR; PG8_SCHED;
	v_mfma_f32_16x16x32_bf16 v[124:127], v[146:149], v[178:181], v[124:127]
	v_mfma_f32_16x16x32_bf16 v[120:123], v[154:157], v[178:181], v[120:123]
	v_mfma_f32_16x16x32_bf16 v[108:111], v[146:149], v[186:189], v[108:111]
	v_mfma_f32_16x16x32_bf16 v[104:107], v[154:157], v[186:189], v[104:107]
	v_mfma_f32_16x16x32_bf16 v[92:95], v[146:149], v[194:197], v[92:95]
	v_mfma_f32_16x16x32_bf16 v[88:91], v[154:157], v[194:197], v[88:91]
	v_mfma_f32_16x16x32_bf16 v[76:79], v[146:149], v[202:205], v[76:79]
	v_mfma_f32_16x16x32_bf16 v[72:75], v[154:157], v[202:205], v[72:75]
	v_mfma_f32_16x16x32_bf16 v[124:127], v[150:153], v[182:185], v[124:127]
	v_mfma_f32_16x16x32_bf16 v[120:123], v[158:161], v[182:185], v[120:123]
	v_mfma_f32_16x16x32_bf16 v[108:111], v[150:153], v[190:193], v[108:111]
	v_mfma_f32_16x16x32_bf16 v[104:107], v[158:161], v[190:193], v[104:107]
	v_mfma_f32_16x16x32_bf16 v[92:95], v[150:153], v[198:201], v[92:95]
	v_mfma_f32_16x16x32_bf16 v[88:91], v[158:161], v[198:201], v[88:91]
	v_mfma_f32_16x16x32_bf16 v[76:79], v[150:153], v[206:209], v[76:79]
	v_mfma_f32_16x16x32_bf16 v[72:75], v[158:161], v[206:209], v[72:75]
	v_mfma_f32_16x16x32_bf16 v[116:119], v[162:165], v[178:181], v[116:119]
	v_mfma_f32_16x16x32_bf16 v[112:115], v[170:173], v[178:181], v[112:115]
	v_mfma_f32_16x16x32_bf16 v[100:103], v[162:165], v[186:189], v[100:103]
	v_mfma_f32_16x16x32_bf16 v[96:99], v[170:173], v[186:189], v[96:99]
	v_mfma_f32_16x16x32_bf16 v[84:87], v[162:165], v[194:197], v[84:87]
	v_mfma_f32_16x16x32_bf16 v[80:83], v[170:173], v[194:197], v[80:83]
	v_mfma_f32_16x16x32_bf16 v[68:71], v[162:165], v[202:205], v[68:71]
	v_mfma_f32_16x16x32_bf16 v[64:67], v[170:173], v[202:205], v[64:67]
	v_mfma_f32_16x16x32_bf16 v[116:119], v[166:169], v[182:185], v[116:119]
	v_mfma_f32_16x16x32_bf16 v[112:115], v[174:177], v[182:185], v[112:115]
	v_mfma_f32_16x16x32_bf16 v[100:103], v[166:169], v[190:193], v[100:103]
	v_mfma_f32_16x16x32_bf16 v[96:99], v[174:177], v[190:193], v[96:99]
	v_mfma_f32_16x16x32_bf16 v[84:87], v[166:169], v[198:201], v[84:87]
	v_mfma_f32_16x16x32_bf16 v[80:83], v[174:177], v[198:201], v[80:83]
	v_mfma_f32_16x16x32_bf16 v[68:71], v[166:169], v[206:209], v[68:71]
	s_setprio 2
	s_barrier
	v_mfma_f32_16x16x32_bf16 v[64:67], v[174:177], v[206:209], v[64:67]
	s_setprio 0
	s_add_i32 s33, s67, s47
	v_lshl_add_u64 v[138:139], s[76:77], 0, v[130:131]
	s_mov_b32 m0, s33
	ds_read_b128 v[178:181], v145 offset:16384
	ds_read_b128 v[182:185], v145 offset:17408
	ds_read_b128 v[186:189], v145 offset:18432
	ds_read_b128 v[190:193], v145 offset:19456
	ds_read_b128 v[194:197], v145 offset:20480
	ds_read_b128 v[198:201], v145 offset:21504
	ds_read_b128 v[202:205], v145 offset:22528
	ds_read_b128 v[206:209], v145 offset:23552
	global_load_lds_dwordx4 v[138:139], off
	s_add_i32 m0, s33, 0x2000
	v_lshl_add_u64 v[210:211], s[76:77], 0, v[128:129]
	s_add_u32 s76, s76, s8
	s_addc_u32 s77, s77, s9
	s_add_i32 s33, s68, s47
	global_load_lds_dwordx4 v[210:211], off
	v_lshl_add_u64 v[212:213], s[76:77], 0, v[130:131]
	s_mov_b32 m0, s33
	v_lshl_add_u64 v[214:215], s[76:77], 0, v[128:129]
	global_load_lds_dwordx4 v[212:213], off
	s_add_i32 m0, s33, 0x2000
	v_lshl_add_u64 v[216:217], s[42:43], 0, v[130:131]
	global_load_lds_dwordx4 v[214:215], off
	s_mov_b32 m0, s55
	v_lshl_add_u64 v[218:219], s[42:43], 0, v[128:129]
	global_load_lds_dwordx4 v[216:217], off
	s_mov_b32 m0, s56
	s_nop 0
	global_load_lds_dwordx4 v[218:219], off
	s_waitcnt vmcnt(8)
	s_waitcnt lgkmcnt(0)
	s_setprio 1
	s_barrier
	v_mfma_f32_16x16x32_bf16 v[60:63], v[146:149], v[178:181], v[60:63]
	v_mfma_f32_16x16x32_bf16 v[56:59], v[154:157], v[178:181], v[56:59]
	v_mfma_f32_16x16x32_bf16 v[44:47], v[146:149], v[186:189], v[44:47]
	v_mfma_f32_16x16x32_bf16 v[40:43], v[154:157], v[186:189], v[40:43]
	v_mfma_f32_16x16x32_bf16 v[28:31], v[146:149], v[194:197], v[28:31]
	v_mfma_f32_16x16x32_bf16 v[24:27], v[154:157], v[194:197], v[24:27]
	v_mfma_f32_16x16x32_bf16 v[12:15], v[146:149], v[202:205], v[12:15]
	v_mfma_f32_16x16x32_bf16 v[8:11], v[154:157], v[202:205], v[8:11]
	v_mfma_f32_16x16x32_bf16 v[60:63], v[150:153], v[182:185], v[60:63]
	v_mfma_f32_16x16x32_bf16 v[56:59], v[158:161], v[182:185], v[56:59]
	v_mfma_f32_16x16x32_bf16 v[44:47], v[150:153], v[190:193], v[44:47]
	v_mfma_f32_16x16x32_bf16 v[40:43], v[158:161], v[190:193], v[40:43]
	v_mfma_f32_16x16x32_bf16 v[28:31], v[150:153], v[198:201], v[28:31]
	v_mfma_f32_16x16x32_bf16 v[24:27], v[158:161], v[198:201], v[24:27]
	v_mfma_f32_16x16x32_bf16 v[12:15], v[150:153], v[206:209], v[12:15]
	v_mfma_f32_16x16x32_bf16 v[8:11], v[158:161], v[206:209], v[8:11]
	v_mfma_f32_16x16x32_bf16 v[52:55], v[162:165], v[178:181], v[52:55]
	v_mfma_f32_16x16x32_bf16 v[48:51], v[170:173], v[178:181], v[48:51]
	v_mfma_f32_16x16x32_bf16 v[36:39], v[162:165], v[186:189], v[36:39]
	v_mfma_f32_16x16x32_bf16 v[32:35], v[170:173], v[186:189], v[32:35]
	v_mfma_f32_16x16x32_bf16 v[20:23], v[162:165], v[194:197], v[20:23]
	v_mfma_f32_16x16x32_bf16 v[16:19], v[170:173], v[194:197], v[16:19]
	v_mfma_f32_16x16x32_bf16 v[4:7], v[162:165], v[202:205], v[4:7]
	v_mfma_f32_16x16x32_bf16 v[0:3], v[170:173], v[202:205], v[0:3]
	v_mfma_f32_16x16x32_bf16 v[52:55], v[166:169], v[182:185], v[52:55]
	v_mfma_f32_16x16x32_bf16 v[48:51], v[174:177], v[182:185], v[48:51]
	v_mfma_f32_16x16x32_bf16 v[36:39], v[166:169], v[190:193], v[36:39]
	v_mfma_f32_16x16x32_bf16 v[32:35], v[174:177], v[190:193], v[32:35]
	v_mfma_f32_16x16x32_bf16 v[20:23], v[166:169], v[198:201], v[20:23]
	v_mfma_f32_16x16x32_bf16 v[16:19], v[174:177], v[198:201], v[16:19]
	v_mfma_f32_16x16x32_bf16 v[4:7], v[166:169], v[206:209], v[4:7]
	s_setprio 2
	s_barrier
; #define PG8_STAGE(bufoff, gbase, voff) do { _Pragma("unroll") for (int _i = 0; _i < 2; ++_i) \
;         __builtin_amdgcn_global_load_lds((const unsigned*)((const char*)(gbase) + (voff)[_i]), (PG8_LAS unsigned*)(lds + (bufoff) + ldsw + _i * 8192), 16, 0, 0); } while (0)
; #define PG8_LDA(dst, b, h) do { _Pragma("unroll") for (int m = 0; m < 4; ++m) _Pragma("unroll") for (int k = 0; k < 2; ++k) dst[m][k] = *(const PG8_LAS bf16x8*)(lds + PG8_SA(b, h) + aoff + m * 2048 + k * 1024); } while (0)
; #define PG8_LDB(dst, b, h) do { _Pragma("unroll") for (int n = 0; n < 2; ++n) _Pragma("unroll") for (int k = 0; k < 2; ++k) dst[n][k] = *(const PG8_LAS bf16x8*)(lds + PG8_SB(b, h) + boff + n * 2048 + k * 1024); } while (0)
; #define PG8_MMA(ai, bj, At, Bt) do { __builtin_amdgcn_s_setprio(1); _Pragma("unroll") for (int m = 0; m < 4; ++m) _Pragma("unroll") for (int n = 0; n < 2; ++n) _Pragma("unroll") for (int k = 0; k < 2; ++k) \
;         acc[ai][bj][m][n] = __builtin_amdgcn_mfma_f32_16x16x32_bf16(Bt[n][k], At[m][k], acc[ai][bj][m][n], 0, 0, 0); __builtin_amdgcn_s_setprio(0); } while (0)
; #define PG8_WAIT_V(n) asm volatile("s_waitcnt vmcnt(" #n ")" ::: "memory")
; #define PG8_WAIT_L(n) asm volatile("s_waitcnt lgkmcnt(" #n ")" ::: "memory")
; #define PG8_BAR __builtin_amdgcn_s_barrier()
; #define PG8_SCHED __builtin_amdgcn_sched_barrier(0)
; template <class Epi, class Sched, bool ALIGN_EPI = false, bool SP2 = false>
; __device__ __forceinline__ void gemm_phase(PG8_LAS unsigned char* lds, const Gemm g, const Sched& S, const Epi& E, const int wid) {
;     ...
;             PG8_WAIT_V(8); PG8_WAIT_L(0); PG8_BAR; PG8_MMA(1, 0, At, B0); PG8_MMA(1, 1, At, B1); PG8_BAR; PG8_SCHED;
;             PG8_LDB(B0, 1, 0); PG8_LDB(B1, 1, 1); PG8_SCHED; PG8_LDA(At, 1, 0); PG8_STAGE(PG8_SA(0, 1), a2 + hstep, voffA);
;             PG8_WAIT_V(8); PG8_WAIT_L(0); PG8_BAR; PG8_MMA(0, 0, At, B0); PG8_MMA(0, 1, At, B1); PG8_BAR; PG8_SCHED;
	v_mfma_f32_16x16x32_bf16 v[0:3], v[174:177], v[206:209], v[0:3]
	s_setprio 0
	s_add_i32 s33, 0, 0x18000
	s_add_i32 s76, 0, 0x1c000
	v_add_u32_e32 v158, s33, v142
	v_add_u32_e32 v174, s76, v142
	ds_read_b128 v[146:149], v158
	ds_read_b128 v[150:153], v158 offset:1024
	ds_read_b128 v[154:157], v158 offset:2048
	ds_read_b128 v[158:161], v158 offset:3072
	ds_read_b128 v[162:165], v174
	ds_read_b128 v[166:169], v174 offset:1024
	ds_read_b128 v[170:173], v174 offset:2048
	ds_read_b128 v[174:177], v174 offset:3072
	s_add_u32 s42, s42, s8
	s_addc_u32 s43, s43, s9
	s_mov_b32 m0, s57
	v_lshl_add_u64 v[220:221], s[42:43], 0, v[130:131]
	ds_read_b128 v[178:181], v145 offset:32768
	ds_read_b128 v[182:185], v145 offset:33792
	ds_read_b128 v[186:189], v145 offset:34816
	ds_read_b128 v[190:193], v145 offset:35840
	ds_read_b128 v[194:197], v145 offset:36864
	ds_read_b128 v[198:201], v145 offset:37888
	ds_read_b128 v[202:205], v145 offset:38912
	ds_read_b128 v[206:209], v145 offset:39936
	global_load_lds_dwordx4 v[220:221], off
	v_lshl_add_u64 v[220:221], s[42:43], 0, v[128:129]
	s_mov_b32 m0, s58
	s_nop 0
	global_load_lds_dwordx4 v[220:221], off
	s_waitcnt vmcnt(8)
	s_waitcnt lgkmcnt(0)
	s_setprio 1
	s_barrier
	v_mfma_f32_16x16x32_bf16 v[124:127], v[146:149], v[178:181], v[124:127]
	v_mfma_f32_16x16x32_bf16 v[120:123], v[154:157], v[178:181], v[120:123]
	v_mfma_f32_16x16x32_bf16 v[108:111], v[146:149], v[186:189], v[108:111]
	v_mfma_f32_16x16x32_bf16 v[104:107], v[154:157], v[186:189], v[104:107]
	v_mfma_f32_16x16x32_bf16 v[92:95], v[146:149], v[194:197], v[92:95]
	v_mfma_f32_16x16x32_bf16 v[88:91], v[154:157], v[194:197], v[88:91]
	v_mfma_f32_16x16x32_bf16 v[76:79], v[146:149], v[202:205], v[76:79]
	v_mfma_f32_16x16x32_bf16 v[72:75], v[154:157], v[202:205], v[72:75]
	v_mfma_f32_16x16x32_bf16 v[124:127], v[150:153], v[182:185], v[124:127]
	v_mfma_f32_16x16x32_bf16 v[120:123], v[158:161], v[182:185], v[120:123]
	v_mfma_f32_16x16x32_bf16 v[108:111], v[150:153], v[190:193], v[108:111]
	v_mfma_f32_16x16x32_bf16 v[104:107], v[158:161], v[190:193], v[104:107]
	v_mfma_f32_16x16x32_bf16 v[92:95], v[150:153], v[198:201], v[92:95]
	v_mfma_f32_16x16x32_bf16 v[88:91], v[158:161], v[198:201], v[88:91]
	v_mfma_f32_16x16x32_bf16 v[76:79], v[150:153], v[206:209], v[76:79]
	v_mfma_f32_16x16x32_bf16 v[72:75], v[158:161], v[206:209], v[72:75]
	v_mfma_f32_16x16x32_bf16 v[116:119], v[162:165], v[178:181], v[116:119]
	v_mfma_f32_16x16x32_bf16 v[112:115], v[170:173], v[178:181], v[112:115]
	v_mfma_f32_16x16x32_bf16 v[100:103], v[162:165], v[186:189], v[100:103]
	v_mfma_f32_16x16x32_bf16 v[96:99], v[170:173], v[186:189], v[96:99]
	v_mfma_f32_16x16x32_bf16 v[84:87], v[162:165], v[194:197], v[84:87]
	v_mfma_f32_16x16x32_bf16 v[80:83], v[170:173], v[194:197], v[80:83]
	v_mfma_f32_16x16x32_bf16 v[68:71], v[162:165], v[202:205], v[68:71]
	v_mfma_f32_16x16x32_bf16 v[64:67], v[170:173], v[202:205], v[64:67]
	v_mfma_f32_16x16x32_bf16 v[116:119], v[166:169], v[182:185], v[116:119]
	v_mfma_f32_16x16x32_bf16 v[112:115], v[174:177], v[182:185], v[112:115]
	v_mfma_f32_16x16x32_bf16 v[100:103], v[166:169], v[190:193], v[100:103]
	v_mfma_f32_16x16x32_bf16 v[96:99], v[174:177], v[190:193], v[96:99]
	v_mfma_f32_16x16x32_bf16 v[84:87], v[166:169], v[198:201], v[84:87]
	v_mfma_f32_16x16x32_bf16 v[80:83], v[174:177], v[198:201], v[80:83]
	v_mfma_f32_16x16x32_bf16 v[68:71], v[166:169], v[206:209], v[68:71]
	s_setprio 2
	s_barrier
; #define PG8_STAGE(bufoff, gbase, voff) do { _Pragma("unroll") for (int _i = 0; _i < 2; ++_i) \
;         __builtin_amdgcn_global_load_lds((const unsigned*)((const char*)(gbase) + (voff)[_i]), (PG8_LAS unsigned*)(lds + (bufoff) + ldsw + _i * 8192), 16, 0, 0); } while (0)
; #define PG8_LDA(dst, b, h) do { _Pragma("unroll") for (int m = 0; m < 4; ++m) _Pragma("unroll") for (int k = 0; k < 2; ++k) dst[m][k] = *(const PG8_LAS bf16x8*)(lds + PG8_SA(b, h) + aoff + m * 2048 + k * 1024); } while (0)
; #define PG8_WAIT_V(n) asm volatile("s_waitcnt vmcnt(" #n ")" ::: "memory")
; #define PG8_WAIT_L(n) asm volatile("s_waitcnt lgkmcnt(" #n ")" ::: "memory")
; #define PG8_BAR __builtin_amdgcn_s_barrier()
; template <class Epi, class Sched, bool ALIGN_EPI = false, bool SP2 = false>
; __device__ __forceinline__ void gemm_phase(PG8_LAS unsigned char* lds, const Gemm g, const Sched& S, const Epi& E, const int wid) {
;     ...
;         for (int t = 0; t < nt; t += 2) {
;             const bool last = (t == nt - 2);
;             const char* a1 = cA + (size_t)(t + 1) * kstep;
;             const char* a2 = last ? nA : cA + (size_t)(t + 2) * kstep; const char* b2 = last ? nB : cB + (size_t)(t + 2) * kstep;
;             const char* a3 = a2 + kstep; const char* b3 = b2 + kstep;
;             if (last && has_next) S.a_ready(nxt);
;             if constexpr (SP2) {
;             PG8_LDB(B0, 0, 0); PG8_LDB(B1, 0, 1); PG8_SCHED; PG8_LDA(At, 0, 0); PG8_STAGE(PG8_SA(1, 1), a1 + hstep, voffA);
;             PG8_WAIT_V(8); PG8_WAIT_L(0); PG8_BAR; PG8_MMA(0, 0, At, B0); PG8_MMA(0, 1, At, B1); PG8_BAR; PG8_SCHED;
;             PG8_LDA(At, 0, 1); PG8_STAGE(PG8_SB(0, 0), b2, voffB); PG8_STAGE(PG8_SB(0, 1), b2 + hstep, voffB); PG8_STAGE(PG8_SA(0, 0), a2, voffA);
;             PG8_WAIT_V(8); PG8_WAIT_L(0); PG8_BAR; PG8_MMA(1, 0, At, B0); PG8_MMA(1, 1, At, B1); PG8_BAR; PG8_SCHED;
;             PG8_LDB(B0, 1, 0); PG8_LDB(B1, 1, 1); PG8_SCHED; PG8_LDA(At, 1, 0); PG8_STAGE(PG8_SA(0, 1), a2 + hstep, voffA);
;             PG8_WAIT_V(8); PG8_WAIT_L(0); PG8_BAR; PG8_MMA(0, 0, At, B0); PG8_MMA(0, 1, At, B1); PG8_BAR; PG8_SCHED;
;             PG8_LDA(At, 1, 1); PG8_STAGE(PG8_SB(1, 0), b3, voffB); PG8_STAGE(PG8_SB(1, 1), b3 + hstep, voffB); PG8_STAGE(PG8_SA(1, 0), a3, voffA);
;             PG8_WAIT_V(8); PG8_WAIT_L(0); PG8_BAR; PG8_MMA(1, 0, At, B0); PG8_MMA(1, 1, At, B1); PG8_BAR; PG8_SCHED;
	v_mfma_f32_16x16x32_bf16 v[64:67], v[174:177], v[206:209], v[64:67]
	s_setprio 0
	s_add_i32 s33, s33, s47
	v_lshl_add_u64 v[138:139], v[138:139], 0, s[16:17]
	s_mov_b32 m0, s33
	ds_read_b128 v[178:181], v145 offset:49152
	ds_read_b128 v[182:185], v145 offset:50176
	ds_read_b128 v[186:189], v145 offset:51200
	ds_read_b128 v[190:193], v145 offset:52224
	ds_read_b128 v[194:197], v145 offset:53248
	ds_read_b128 v[198:201], v145 offset:54272
	ds_read_b128 v[202:205], v145 offset:55296
	ds_read_b128 v[206:209], v145 offset:56320
	global_load_lds_dwordx4 v[138:139], off
	v_lshl_add_u64 v[138:139], v[210:211], 0, s[16:17]
	s_add_i32 m0, s33, 0x2000
	s_add_i32 s33, s76, s47
	global_load_lds_dwordx4 v[138:139], off
	v_lshl_add_u64 v[138:139], v[212:213], 0, s[16:17]
	s_mov_b32 m0, s33
	s_nop 0
	global_load_lds_dwordx4 v[138:139], off
	v_lshl_add_u64 v[138:139], v[214:215], 0, s[16:17]
	s_add_i32 m0, s33, 0x2000
	s_nop 0
	global_load_lds_dwordx4 v[138:139], off
	v_lshl_add_u64 v[138:139], v[216:217], 0, s[16:17]
	s_mov_b32 m0, s60
	s_nop 0
	global_load_lds_dwordx4 v[138:139], off
	v_lshl_add_u64 v[138:139], v[218:219], 0, s[16:17]
	s_mov_b32 m0, s61
	s_nop 0
	global_load_lds_dwordx4 v[138:139], off
	s_waitcnt vmcnt(8)
	s_waitcnt lgkmcnt(0)
	s_setprio 1
	s_barrier
	v_mfma_f32_16x16x32_bf16 v[60:63], v[146:149], v[178:181], v[60:63]
	v_mfma_f32_16x16x32_bf16 v[56:59], v[154:157], v[178:181], v[56:59]
	v_mfma_f32_16x16x32_bf16 v[44:47], v[146:149], v[186:189], v[44:47]
	v_mfma_f32_16x16x32_bf16 v[40:43], v[154:157], v[186:189], v[40:43]
	v_mfma_f32_16x16x32_bf16 v[28:31], v[146:149], v[194:197], v[28:31]
	v_mfma_f32_16x16x32_bf16 v[24:27], v[154:157], v[194:197], v[24:27]
	v_mfma_f32_16x16x32_bf16 v[12:15], v[146:149], v[202:205], v[12:15]
	v_mfma_f32_16x16x32_bf16 v[8:11], v[154:157], v[202:205], v[8:11]
	v_mfma_f32_16x16x32_bf16 v[60:63], v[150:153], v[182:185], v[60:63]
	v_mfma_f32_16x16x32_bf16 v[56:59], v[158:161], v[182:185], v[56:59]
	v_mfma_f32_16x16x32_bf16 v[44:47], v[150:153], v[190:193], v[44:47]
	v_mfma_f32_16x16x32_bf16 v[40:43], v[158:161], v[190:193], v[40:43]
	v_mfma_f32_16x16x32_bf16 v[28:31], v[150:153], v[198:201], v[28:31]
	v_mfma_f32_16x16x32_bf16 v[24:27], v[158:161], v[198:201], v[24:27]
	v_mfma_f32_16x16x32_bf16 v[12:15], v[150:153], v[206:209], v[12:15]
	v_mfma_f32_16x16x32_bf16 v[8:11], v[158:161], v[206:209], v[8:11]
	v_mfma_f32_16x16x32_bf16 v[52:55], v[162:165], v[178:181], v[52:55]
	v_mfma_f32_16x16x32_bf16 v[48:51], v[170:173], v[178:181], v[48:51]
	v_mfma_f32_16x16x32_bf16 v[36:39], v[162:165], v[186:189], v[36:39]
	v_mfma_f32_16x16x32_bf16 v[32:35], v[170:173], v[186:189], v[32:35]
	v_mfma_f32_16x16x32_bf16 v[20:23], v[162:165], v[194:197], v[20:23]
	v_mfma_f32_16x16x32_bf16 v[16:19], v[170:173], v[194:197], v[16:19]
	v_mfma_f32_16x16x32_bf16 v[4:7], v[162:165], v[202:205], v[4:7]
	v_mfma_f32_16x16x32_bf16 v[0:3], v[170:173], v[202:205], v[0:3]
	v_mfma_f32_16x16x32_bf16 v[52:55], v[166:169], v[182:185], v[52:55]
	v_mfma_f32_16x16x32_bf16 v[48:51], v[174:177], v[182:185], v[48:51]
	v_mfma_f32_16x16x32_bf16 v[36:39], v[166:169], v[190:193], v[36:39]
	v_mfma_f32_16x16x32_bf16 v[32:35], v[174:177], v[190:193], v[32:35]
	v_mfma_f32_16x16x32_bf16 v[20:23], v[166:169], v[198:201], v[20:23]
	v_mfma_f32_16x16x32_bf16 v[16:19], v[174:177], v[198:201], v[16:19]
	v_mfma_f32_16x16x32_bf16 v[4:7], v[166:169], v[206:209], v[4:7]
	s_setprio 2
	s_barrier
	v_mfma_f32_16x16x32_bf16 v[0:3], v[174:177], v[206:209], v[0:3]
	s_setprio 0
	s_add_u32 s40, s40, 0x100
	s_addc_u32 s41, s41, 0
	s_add_u32 s73, s73, 0x100
	s_addc_u32 s74, s74, 0
	s_cmp_ge_i32 s75, s62
	s_mov_b32 s42, s75
	s_cbranch_scc0 .LBB0_1574
